# adaLN norm phases P1/P10: write-through (sc1) 16-byte stores so the XCD barrier's L2 write-back has little left to flush
# baseline (speedup 1.0000x reference)
.LBB0_234:
	s_mov_b64 s[0:1], s[78:79]
	s_load_dwordx2 s[12:13], s[0:1], 0x100
	s_mov_b64 s[0:1], s[78:79]
	s_load_dwordx2 s[0:1], s[0:1], 0x100
	s_mul_i32 s60, s80, 0x3020000
	s_waitcnt lgkmcnt(0)
	v_writelane_b32 v253, s0, 42
	s_nop 1
	v_writelane_b32 v253, s1, 43
	s_mov_b64 s[0:1], s[78:79]
	s_load_dwordx2 s[14:15], s[0:1], 0x100
	s_mov_b64 s[0:1], s[78:79]
	s_load_dwordx2 s[10:11], s[0:1], 0x98
	s_mov_b64 s[0:1], s[78:79]
	s_load_dwordx2 s[0:1], s[0:1], 0xa0
	s_waitcnt lgkmcnt(0)
	v_writelane_b32 v253, s0, 44
	s_nop 1
	v_writelane_b32 v253, s1, 45
	s_mov_b64 s[0:1], s[78:79]
	s_load_dwordx2 s[6:7], s[0:1], 0xa8
	s_mov_b64 s[0:1], s[78:79]
	s_load_dwordx2 s[8:9], s[0:1], 0xb0
	s_mov_b64 s[0:1], s[78:79]
	s_load_dwordx2 s[0:1], s[0:1], 0xb8
	s_waitcnt lgkmcnt(0)
	v_writelane_b32 v253, s0, 46
	s_nop 1
	v_writelane_b32 v253, s1, 47
	s_mov_b64 s[0:1], -1
	v_readlane_b32 s4, v253, 38
	v_readlane_b32 s5, v253, 39
	s_andn2_b64 vcc, exec, s[4:5]
	s_nop 0
	v_cndmask_b32_e64 v0, 0, 1, s[4:5]
	v_cmp_ne_u32_e64 s[18:19], 1, v0
	s_mul_i32 s4, s80, 0xc6000
	s_nop 0
	v_writelane_b32 v253, s18, 48
	s_nop 1
	v_writelane_b32 v253, s19, 49
	v_writelane_b32 v253, s4, 50
	s_cbranch_vccnz .LBB0_377
	s_mov_b64 s[0:1], s[78:79]
	s_mov_b64 s[18:19], s[78:79]
	s_mov_b64 s[20:21], s[78:79]
	s_mov_b64 s[4:5], s[78:79]
	v_mov_b32_e32 v0, v224
	v_readlane_b32 s44, v253, 18
	v_readfirstlane_b32 s22, v0
	s_ashr_i32 s22, s22, 6
	s_add_i32 s36, s22, s70
	s_cmp_gt_i32 s36, 0x11fff
	v_readlane_b32 s45, v253, 19
	s_mov_b32 s46, 0x3a800000
	s_cbranch_scc1 .LBB0_238
	s_waitcnt lgkmcnt(0)
	s_load_dwordx2 s[0:1], s[78:79], 0x100
	s_load_dwordx2 s[20:21], s[78:79], 0x30
	s_load_dwordx2 s[4:5], s[78:79], 0xf8
	v_readfirstlane_b32 s36, v224
	v_and_b32_e32 v51, 63, v224
	v_lshlrev_b32_e32 v148, 5, v51
	v_lshlrev_b32_e32 v51, 4, v51
	v_add_u32_e32 v149, 0x1000, v51
	v_mov_b32_e32 v50, 0x3a800000
	s_lshr_b32 s36, s36, 6
	s_add_i32 s36, s36, s70
	s_lshr_b32 s35, s36, 6
	s_and_b32 s36, s36, 63
	s_mul_i32 s37, s35, 0x900
	s_lshl_b32 s31, s36, 5
	s_add_i32 s31, s31, s37
	s_addk_i32 s31, 0x100
	s_lshl_b32 s34, s36, 2
	s_add_i32 s34, s34, s37
	s_lshl_b32 s36, s80, 12
	s_mul_i32 s37, s80, 0xc6000
	s_waitcnt lgkmcnt(0)
	s_add_u32 s20, s20, s36
	s_addc_u32 s21, s21, 0
	s_sub_u32 s18, s0, 0xa4c000
	s_subb_u32 s19, s1, 0
	s_add_u32 s22, s0, 0x63c8000
	s_addc_u32 s23, s1, 0
	s_add_u32 s22, s22, s37
	s_addc_u32 s23, s23, 0
	global_load_dwordx4 v[32:35], v148, s[20:21]
	global_load_dwordx4 v[36:39], v148, s[20:21] offset:16
	global_load_dwordx4 v[40:43], v148, s[20:21] offset:2048
	global_load_dwordx4 v[44:47], v148, s[20:21] offset:2064
	s_add_u32 s0, s22, 0xc0000
	s_addc_u32 s1, s23, 0
	s_add_u32 s20, s0, 0x1000
	s_addc_u32 s21, s1, 0
	global_load_dwordx4 v[100:103], v148, s[0:1]
	global_load_dwordx4 v[104:107], v148, s[0:1] offset:16
	global_load_dwordx4 v[108:111], v148, s[0:1] offset:2048
	global_load_dwordx4 v[112:115], v148, s[0:1] offset:2064
	global_load_dwordx4 v[84:87], v148, s[20:21]
	global_load_dwordx4 v[88:91], v148, s[20:21] offset:16
	global_load_dwordx4 v[92:95], v148, s[20:21] offset:2048
	global_load_dwordx4 v[96:99], v148, s[20:21] offset:2064
	s_lshl_b32 s36, s34, 11
	s_add_u32 s24, s4, s36
	s_addc_u32 s25, s5, 0
	s_cmp_lt_u32 s36, 0x7000000
	s_cselect_b32 s26, s24, s18
	s_cselect_b32 s27, s25, s19
	s_cselect_b32 s37, 0x9000000, s36
	s_add_u32 s26, s26, s37
	s_addc_u32 s27, s27, 0
	global_load_dwordx4 v[0:3], v51, s[24:25]
	global_load_dwordx4 v[4:7], v51, s[24:25] offset:1024
	global_load_dwordx4 v[8:11], v51, s[24:25] offset:2048
	global_load_dwordx4 v[12:15], v51, s[24:25] offset:3072
	global_load_dwordx4 v[16:19], v149, s[24:25]
	global_load_dwordx4 v[20:23], v149, s[24:25] offset:1024
	global_load_dwordx4 v[24:27], v149, s[24:25] offset:2048
	global_load_dwordx4 v[28:31], v149, s[24:25] offset:3072
	s_waitcnt vmcnt(0)
	v_pk_add_f32 v[84:85], v[84:85], 1.0 op_sel_hi:[1,0]
	v_pk_add_f32 v[86:87], v[86:87], 1.0 op_sel_hi:[1,0]
	v_pk_add_f32 v[88:89], v[88:89], 1.0 op_sel_hi:[1,0]
	v_pk_add_f32 v[90:91], v[90:91], 1.0 op_sel_hi:[1,0]
	v_pk_add_f32 v[92:93], v[92:93], 1.0 op_sel_hi:[1,0]
	v_pk_add_f32 v[94:95], v[94:95], 1.0 op_sel_hi:[1,0]
	v_pk_add_f32 v[96:97], v[96:97], 1.0 op_sel_hi:[1,0]
	v_pk_add_f32 v[98:99], v[98:99], 1.0 op_sel_hi:[1,0]
	v_lshlrev_b32_e32 v116, 16, v0
	v_and_b32_e32 v117, 0xffff0000, v0
	v_lshlrev_b32_e32 v118, 16, v1
	v_and_b32_e32 v119, 0xffff0000, v1
	v_lshlrev_b32_e32 v120, 16, v2
	v_and_b32_e32 v121, 0xffff0000, v2
	v_lshlrev_b32_e32 v122, 16, v3
	v_and_b32_e32 v123, 0xffff0000, v3
	v_lshlrev_b32_e32 v124, 16, v4
	v_and_b32_e32 v125, 0xffff0000, v4
	v_lshlrev_b32_e32 v126, 16, v5
	v_and_b32_e32 v127, 0xffff0000, v5
	v_lshlrev_b32_e32 v128, 16, v6
	v_and_b32_e32 v129, 0xffff0000, v6
	v_lshlrev_b32_e32 v130, 16, v7
	v_and_b32_e32 v131, 0xffff0000, v7
	v_pk_mul_f32 v[132:133], v[116:117], v[116:117]
	v_pk_fma_f32 v[132:133], v[118:119], v[118:119], v[132:133]
	v_pk_fma_f32 v[132:133], v[120:121], v[120:121], v[132:133]
	v_pk_fma_f32 v[132:133], v[122:123], v[122:123], v[132:133]
	v_pk_fma_f32 v[132:133], v[124:125], v[124:125], v[132:133]
	v_pk_fma_f32 v[132:133], v[126:127], v[126:127], v[132:133]
	v_pk_fma_f32 v[132:133], v[128:129], v[128:129], v[132:133]
	v_pk_fma_f32 v[132:133], v[130:131], v[130:131], v[132:133]
	v_lshlrev_b32_e32 v116, 16, v8
	v_and_b32_e32 v117, 0xffff0000, v8
	v_lshlrev_b32_e32 v118, 16, v9
	v_and_b32_e32 v119, 0xffff0000, v9
	v_lshlrev_b32_e32 v120, 16, v10
	v_and_b32_e32 v121, 0xffff0000, v10
	v_lshlrev_b32_e32 v122, 16, v11
	v_and_b32_e32 v123, 0xffff0000, v11
	v_lshlrev_b32_e32 v124, 16, v12
	v_and_b32_e32 v125, 0xffff0000, v12
	v_lshlrev_b32_e32 v126, 16, v13
	v_and_b32_e32 v127, 0xffff0000, v13
	v_lshlrev_b32_e32 v128, 16, v14
	v_and_b32_e32 v129, 0xffff0000, v14
	v_lshlrev_b32_e32 v130, 16, v15
	v_and_b32_e32 v131, 0xffff0000, v15
	v_pk_mul_f32 v[134:135], v[116:117], v[116:117]
	v_pk_fma_f32 v[134:135], v[118:119], v[118:119], v[134:135]
	v_pk_fma_f32 v[134:135], v[120:121], v[120:121], v[134:135]
	v_pk_fma_f32 v[134:135], v[122:123], v[122:123], v[134:135]
	v_pk_fma_f32 v[134:135], v[124:125], v[124:125], v[134:135]
	v_pk_fma_f32 v[134:135], v[126:127], v[126:127], v[134:135]
	v_pk_fma_f32 v[134:135], v[128:129], v[128:129], v[134:135]
	v_pk_fma_f32 v[134:135], v[130:131], v[130:131], v[134:135]
	v_lshlrev_b32_e32 v116, 16, v16
	v_and_b32_e32 v117, 0xffff0000, v16
	v_lshlrev_b32_e32 v118, 16, v17
	v_and_b32_e32 v119, 0xffff0000, v17
	v_lshlrev_b32_e32 v120, 16, v18
	v_and_b32_e32 v121, 0xffff0000, v18
	v_lshlrev_b32_e32 v122, 16, v19
	v_and_b32_e32 v123, 0xffff0000, v19
	v_lshlrev_b32_e32 v124, 16, v20
	v_and_b32_e32 v125, 0xffff0000, v20
	v_lshlrev_b32_e32 v126, 16, v21
	v_and_b32_e32 v127, 0xffff0000, v21
	v_lshlrev_b32_e32 v128, 16, v22
	v_and_b32_e32 v129, 0xffff0000, v22
	v_lshlrev_b32_e32 v130, 16, v23
	v_and_b32_e32 v131, 0xffff0000, v23
	v_pk_mul_f32 v[136:137], v[116:117], v[116:117]
	v_pk_fma_f32 v[136:137], v[118:119], v[118:119], v[136:137]
	v_pk_fma_f32 v[136:137], v[120:121], v[120:121], v[136:137]
	v_pk_fma_f32 v[136:137], v[122:123], v[122:123], v[136:137]
	v_pk_fma_f32 v[136:137], v[124:125], v[124:125], v[136:137]
	v_pk_fma_f32 v[136:137], v[126:127], v[126:127], v[136:137]
	v_pk_fma_f32 v[136:137], v[128:129], v[128:129], v[136:137]
	v_pk_fma_f32 v[136:137], v[130:131], v[130:131], v[136:137]
	v_lshlrev_b32_e32 v116, 16, v24
	v_and_b32_e32 v117, 0xffff0000, v24
	v_lshlrev_b32_e32 v118, 16, v25
	v_and_b32_e32 v119, 0xffff0000, v25
	v_lshlrev_b32_e32 v120, 16, v26
	v_and_b32_e32 v121, 0xffff0000, v26
	v_lshlrev_b32_e32 v122, 16, v27
	v_and_b32_e32 v123, 0xffff0000, v27
	v_lshlrev_b32_e32 v124, 16, v28
	v_and_b32_e32 v125, 0xffff0000, v28
	v_lshlrev_b32_e32 v126, 16, v29
	v_and_b32_e32 v127, 0xffff0000, v29
	v_lshlrev_b32_e32 v128, 16, v30
	v_and_b32_e32 v129, 0xffff0000, v30
	v_lshlrev_b32_e32 v130, 16, v31
	v_and_b32_e32 v131, 0xffff0000, v31
	v_pk_mul_f32 v[138:139], v[116:117], v[116:117]
	v_pk_fma_f32 v[138:139], v[118:119], v[118:119], v[138:139]
	v_pk_fma_f32 v[138:139], v[120:121], v[120:121], v[138:139]
	v_pk_fma_f32 v[138:139], v[122:123], v[122:123], v[138:139]
	v_pk_fma_f32 v[138:139], v[124:125], v[124:125], v[138:139]
	v_pk_fma_f32 v[138:139], v[126:127], v[126:127], v[138:139]
	v_pk_fma_f32 v[138:139], v[128:129], v[128:129], v[138:139]
	v_pk_fma_f32 v[138:139], v[130:131], v[130:131], v[138:139]
	v_add_f32_e32 v132, v132, v133
	v_add_f32_e32 v134, v134, v135
	v_add_f32_e32 v136, v136, v137
	v_add_f32_e32 v138, v138, v139
	s_nop 1
	v_add_f32_dpp v132, v132, v132 row_shr:1 row_mask:0xf bank_mask:0xf bound_ctrl:1
	v_add_f32_dpp v134, v134, v134 row_shr:1 row_mask:0xf bank_mask:0xf bound_ctrl:1
	v_add_f32_dpp v136, v136, v136 row_shr:1 row_mask:0xf bank_mask:0xf bound_ctrl:1
	v_add_f32_dpp v138, v138, v138 row_shr:1 row_mask:0xf bank_mask:0xf bound_ctrl:1
	v_add_f32_dpp v132, v132, v132 row_shr:2 row_mask:0xf bank_mask:0xf bound_ctrl:1
	v_add_f32_dpp v134, v134, v134 row_shr:2 row_mask:0xf bank_mask:0xf bound_ctrl:1
	v_add_f32_dpp v136, v136, v136 row_shr:2 row_mask:0xf bank_mask:0xf bound_ctrl:1
	v_add_f32_dpp v138, v138, v138 row_shr:2 row_mask:0xf bank_mask:0xf bound_ctrl:1
	v_add_f32_dpp v132, v132, v132 row_shr:4 row_mask:0xf bank_mask:0xf bound_ctrl:1
	v_add_f32_dpp v134, v134, v134 row_shr:4 row_mask:0xf bank_mask:0xf bound_ctrl:1
	v_add_f32_dpp v136, v136, v136 row_shr:4 row_mask:0xf bank_mask:0xf bound_ctrl:1
	v_add_f32_dpp v138, v138, v138 row_shr:4 row_mask:0xf bank_mask:0xf bound_ctrl:1
	v_add_f32_dpp v132, v132, v132 row_shr:8 row_mask:0xf bank_mask:0xf bound_ctrl:1
	v_add_f32_dpp v134, v134, v134 row_shr:8 row_mask:0xf bank_mask:0xf bound_ctrl:1
	v_add_f32_dpp v136, v136, v136 row_shr:8 row_mask:0xf bank_mask:0xf bound_ctrl:1
	v_add_f32_dpp v138, v138, v138 row_shr:8 row_mask:0xf bank_mask:0xf bound_ctrl:1
	v_add_f32_dpp v132, v132, v132 row_bcast:15 row_mask:0xa bank_mask:0xf
	v_add_f32_dpp v134, v134, v134 row_bcast:15 row_mask:0xa bank_mask:0xf
	v_add_f32_dpp v136, v136, v136 row_bcast:15 row_mask:0xa bank_mask:0xf
	v_add_f32_dpp v138, v138, v138 row_bcast:15 row_mask:0xa bank_mask:0xf
	v_add_f32_dpp v132, v132, v132 row_bcast:31 row_mask:0xc bank_mask:0xf
	v_add_f32_dpp v134, v134, v134 row_bcast:31 row_mask:0xc bank_mask:0xf
	v_add_f32_dpp v136, v136, v136 row_bcast:31 row_mask:0xc bank_mask:0xf
	v_add_f32_dpp v138, v138, v138 row_bcast:31 row_mask:0xc bank_mask:0xf
	s_nop 1
	v_readlane_b32 s32, v132, 63
	v_readlane_b32 s28, v134, 63
	v_readlane_b32 s29, v136, 63
	v_readlane_b32 s30, v138, 63
	s_nop 1
	v_mov_b32_e32 v140, s32
	v_mov_b32_e32 v142, s28
	v_mov_b32_e32 v144, s29
	v_mov_b32_e32 v146, s30
	v_fmaak_f32 v140, v140, v50, 0x358637bd
	v_fmaak_f32 v142, v142, v50, 0x358637bd
	v_fmaak_f32 v144, v144, v50, 0x358637bd
	v_fmaak_f32 v146, v146, v50, 0x358637bd
	v_rsq_f32_e32 v140, v140
	v_rsq_f32_e32 v142, v142
	v_rsq_f32_e32 v144, v144
	v_rsq_f32_e32 v146, v146
	s_nop 0
	v_lshlrev_b32_e32 v116, 16, v0
	v_and_b32_e32 v117, 0xffff0000, v0
	v_lshlrev_b32_e32 v118, 16, v1
	v_and_b32_e32 v119, 0xffff0000, v1
	v_lshlrev_b32_e32 v120, 16, v2
	v_and_b32_e32 v121, 0xffff0000, v2
	v_lshlrev_b32_e32 v122, 16, v3
	v_and_b32_e32 v123, 0xffff0000, v3
	v_lshlrev_b32_e32 v124, 16, v4
	v_and_b32_e32 v125, 0xffff0000, v4
	v_lshlrev_b32_e32 v126, 16, v5
	v_and_b32_e32 v127, 0xffff0000, v5
	v_lshlrev_b32_e32 v128, 16, v6
	v_and_b32_e32 v129, 0xffff0000, v6
	v_lshlrev_b32_e32 v130, 16, v7
	v_and_b32_e32 v131, 0xffff0000, v7
	v_pk_mul_f32 v[116:117], v[140:141], v[116:117] op_sel_hi:[0,1]
	v_pk_mul_f32 v[118:119], v[140:141], v[118:119] op_sel_hi:[0,1]
	v_pk_mul_f32 v[120:121], v[140:141], v[120:121] op_sel_hi:[0,1]
	v_pk_mul_f32 v[122:123], v[140:141], v[122:123] op_sel_hi:[0,1]
	v_pk_mul_f32 v[124:125], v[140:141], v[124:125] op_sel_hi:[0,1]
	v_pk_mul_f32 v[126:127], v[140:141], v[126:127] op_sel_hi:[0,1]
	v_pk_mul_f32 v[128:129], v[140:141], v[128:129] op_sel_hi:[0,1]
	v_pk_mul_f32 v[130:131], v[140:141], v[130:131] op_sel_hi:[0,1]
	v_pk_mul_f32 v[116:117], v[116:117], v[32:33]
	v_pk_mul_f32 v[118:119], v[118:119], v[34:35]
	v_pk_mul_f32 v[120:121], v[120:121], v[36:37]
	v_pk_mul_f32 v[122:123], v[122:123], v[38:39]
	v_pk_mul_f32 v[124:125], v[124:125], v[40:41]
	v_pk_mul_f32 v[126:127], v[126:127], v[42:43]
	v_pk_mul_f32 v[128:129], v[128:129], v[44:45]
	v_pk_mul_f32 v[130:131], v[130:131], v[46:47]
	v_pk_fma_f32 v[116:117], v[116:117], v[84:85], v[100:101]
	v_pk_fma_f32 v[118:119], v[118:119], v[86:87], v[102:103]
	v_pk_fma_f32 v[120:121], v[120:121], v[88:89], v[104:105]
	v_pk_fma_f32 v[122:123], v[122:123], v[90:91], v[106:107]
	v_pk_fma_f32 v[124:125], v[124:125], v[92:93], v[108:109]
	v_pk_fma_f32 v[126:127], v[126:127], v[94:95], v[110:111]
	v_pk_fma_f32 v[128:129], v[128:129], v[96:97], v[112:113]
	v_pk_fma_f32 v[130:131], v[130:131], v[98:99], v[114:115]
	v_cvt_pk_bf16_f32 v164, v116, v117
	v_cvt_pk_bf16_f32 v165, v118, v119
	v_cvt_pk_bf16_f32 v166, v120, v121
	v_cvt_pk_bf16_f32 v167, v122, v123
	v_cvt_pk_bf16_f32 v168, v124, v125
	v_cvt_pk_bf16_f32 v169, v126, v127
	v_cvt_pk_bf16_f32 v170, v128, v129
	v_cvt_pk_bf16_f32 v171, v130, v131
	global_store_dwordx4 v51, v[164:167], s[26:27] sc1
	global_store_dwordx4 v51, v[168:171], s[26:27] offset:1024 sc1
	v_lshlrev_b32_e32 v116, 16, v8
	v_and_b32_e32 v117, 0xffff0000, v8
	v_lshlrev_b32_e32 v118, 16, v9
	v_and_b32_e32 v119, 0xffff0000, v9
	v_lshlrev_b32_e32 v120, 16, v10
	v_and_b32_e32 v121, 0xffff0000, v10
	v_lshlrev_b32_e32 v122, 16, v11
	v_and_b32_e32 v123, 0xffff0000, v11
	v_lshlrev_b32_e32 v124, 16, v12
	v_and_b32_e32 v125, 0xffff0000, v12
	v_lshlrev_b32_e32 v126, 16, v13
	v_and_b32_e32 v127, 0xffff0000, v13
	v_lshlrev_b32_e32 v128, 16, v14
	v_and_b32_e32 v129, 0xffff0000, v14
	v_lshlrev_b32_e32 v130, 16, v15
	v_and_b32_e32 v131, 0xffff0000, v15
	v_pk_mul_f32 v[116:117], v[142:143], v[116:117] op_sel_hi:[0,1]
	v_pk_mul_f32 v[118:119], v[142:143], v[118:119] op_sel_hi:[0,1]
	v_pk_mul_f32 v[120:121], v[142:143], v[120:121] op_sel_hi:[0,1]
	v_pk_mul_f32 v[122:123], v[142:143], v[122:123] op_sel_hi:[0,1]
	v_pk_mul_f32 v[124:125], v[142:143], v[124:125] op_sel_hi:[0,1]
	v_pk_mul_f32 v[126:127], v[142:143], v[126:127] op_sel_hi:[0,1]
	v_pk_mul_f32 v[128:129], v[142:143], v[128:129] op_sel_hi:[0,1]
	v_pk_mul_f32 v[130:131], v[142:143], v[130:131] op_sel_hi:[0,1]
	v_pk_mul_f32 v[116:117], v[116:117], v[32:33]
	v_pk_mul_f32 v[118:119], v[118:119], v[34:35]
	v_pk_mul_f32 v[120:121], v[120:121], v[36:37]
	v_pk_mul_f32 v[122:123], v[122:123], v[38:39]
	v_pk_mul_f32 v[124:125], v[124:125], v[40:41]
	v_pk_mul_f32 v[126:127], v[126:127], v[42:43]
	v_pk_mul_f32 v[128:129], v[128:129], v[44:45]
	v_pk_mul_f32 v[130:131], v[130:131], v[46:47]
	v_pk_fma_f32 v[116:117], v[116:117], v[84:85], v[100:101]
	v_pk_fma_f32 v[118:119], v[118:119], v[86:87], v[102:103]
	v_pk_fma_f32 v[120:121], v[120:121], v[88:89], v[104:105]
	v_pk_fma_f32 v[122:123], v[122:123], v[90:91], v[106:107]
	v_pk_fma_f32 v[124:125], v[124:125], v[92:93], v[108:109]
	v_pk_fma_f32 v[126:127], v[126:127], v[94:95], v[110:111]
	v_pk_fma_f32 v[128:129], v[128:129], v[96:97], v[112:113]
	v_pk_fma_f32 v[130:131], v[130:131], v[98:99], v[114:115]
	v_cvt_pk_bf16_f32 v172, v116, v117
	v_cvt_pk_bf16_f32 v173, v118, v119
	v_cvt_pk_bf16_f32 v174, v120, v121
	v_cvt_pk_bf16_f32 v175, v122, v123
	v_cvt_pk_bf16_f32 v176, v124, v125
	v_cvt_pk_bf16_f32 v177, v126, v127
	v_cvt_pk_bf16_f32 v178, v128, v129
	v_cvt_pk_bf16_f32 v179, v130, v131
	global_store_dwordx4 v51, v[172:175], s[26:27] offset:2048 sc1
	global_store_dwordx4 v51, v[176:179], s[26:27] offset:3072 sc1
	v_lshlrev_b32_e32 v116, 16, v16
	v_and_b32_e32 v117, 0xffff0000, v16
	v_lshlrev_b32_e32 v118, 16, v17
	v_and_b32_e32 v119, 0xffff0000, v17
	v_lshlrev_b32_e32 v120, 16, v18
	v_and_b32_e32 v121, 0xffff0000, v18
	v_lshlrev_b32_e32 v122, 16, v19
	v_and_b32_e32 v123, 0xffff0000, v19
	v_lshlrev_b32_e32 v124, 16, v20
	v_and_b32_e32 v125, 0xffff0000, v20
	v_lshlrev_b32_e32 v126, 16, v21
	v_and_b32_e32 v127, 0xffff0000, v21
	v_lshlrev_b32_e32 v128, 16, v22
	v_and_b32_e32 v129, 0xffff0000, v22
	v_lshlrev_b32_e32 v130, 16, v23
	v_and_b32_e32 v131, 0xffff0000, v23
	v_pk_mul_f32 v[116:117], v[144:145], v[116:117] op_sel_hi:[0,1]
	v_pk_mul_f32 v[118:119], v[144:145], v[118:119] op_sel_hi:[0,1]
	v_pk_mul_f32 v[120:121], v[144:145], v[120:121] op_sel_hi:[0,1]
	v_pk_mul_f32 v[122:123], v[144:145], v[122:123] op_sel_hi:[0,1]
	v_pk_mul_f32 v[124:125], v[144:145], v[124:125] op_sel_hi:[0,1]
	v_pk_mul_f32 v[126:127], v[144:145], v[126:127] op_sel_hi:[0,1]
	v_pk_mul_f32 v[128:129], v[144:145], v[128:129] op_sel_hi:[0,1]
	v_pk_mul_f32 v[130:131], v[144:145], v[130:131] op_sel_hi:[0,1]
	v_pk_mul_f32 v[116:117], v[116:117], v[32:33]
	v_pk_mul_f32 v[118:119], v[118:119], v[34:35]
	v_pk_mul_f32 v[120:121], v[120:121], v[36:37]
	v_pk_mul_f32 v[122:123], v[122:123], v[38:39]
	v_pk_mul_f32 v[124:125], v[124:125], v[40:41]
	v_pk_mul_f32 v[126:127], v[126:127], v[42:43]
	v_pk_mul_f32 v[128:129], v[128:129], v[44:45]
	v_pk_mul_f32 v[130:131], v[130:131], v[46:47]
	v_pk_fma_f32 v[116:117], v[116:117], v[84:85], v[100:101]
	v_pk_fma_f32 v[118:119], v[118:119], v[86:87], v[102:103]
	v_pk_fma_f32 v[120:121], v[120:121], v[88:89], v[104:105]
	v_pk_fma_f32 v[122:123], v[122:123], v[90:91], v[106:107]
	v_pk_fma_f32 v[124:125], v[124:125], v[92:93], v[108:109]
	v_pk_fma_f32 v[126:127], v[126:127], v[94:95], v[110:111]
	v_pk_fma_f32 v[128:129], v[128:129], v[96:97], v[112:113]
	v_pk_fma_f32 v[130:131], v[130:131], v[98:99], v[114:115]
	v_cvt_pk_bf16_f32 v164, v116, v117
	v_cvt_pk_bf16_f32 v165, v118, v119
	v_cvt_pk_bf16_f32 v166, v120, v121
	v_cvt_pk_bf16_f32 v167, v122, v123
	v_cvt_pk_bf16_f32 v168, v124, v125
	v_cvt_pk_bf16_f32 v169, v126, v127
	v_cvt_pk_bf16_f32 v170, v128, v129
	v_cvt_pk_bf16_f32 v171, v130, v131
	global_store_dwordx4 v149, v[164:167], s[26:27] sc1
	global_store_dwordx4 v149, v[168:171], s[26:27] offset:1024 sc1
	v_lshlrev_b32_e32 v116, 16, v24
	v_and_b32_e32 v117, 0xffff0000, v24
	v_lshlrev_b32_e32 v118, 16, v25
	v_and_b32_e32 v119, 0xffff0000, v25
	v_lshlrev_b32_e32 v120, 16, v26
	v_and_b32_e32 v121, 0xffff0000, v26
	v_lshlrev_b32_e32 v122, 16, v27
	v_and_b32_e32 v123, 0xffff0000, v27
	v_lshlrev_b32_e32 v124, 16, v28
	v_and_b32_e32 v125, 0xffff0000, v28
	v_lshlrev_b32_e32 v126, 16, v29
	v_and_b32_e32 v127, 0xffff0000, v29
	v_lshlrev_b32_e32 v128, 16, v30
	v_and_b32_e32 v129, 0xffff0000, v30
	v_lshlrev_b32_e32 v130, 16, v31
	v_and_b32_e32 v131, 0xffff0000, v31
	v_pk_mul_f32 v[116:117], v[146:147], v[116:117] op_sel_hi:[0,1]
	v_pk_mul_f32 v[118:119], v[146:147], v[118:119] op_sel_hi:[0,1]
	v_pk_mul_f32 v[120:121], v[146:147], v[120:121] op_sel_hi:[0,1]
	v_pk_mul_f32 v[122:123], v[146:147], v[122:123] op_sel_hi:[0,1]
	v_pk_mul_f32 v[124:125], v[146:147], v[124:125] op_sel_hi:[0,1]
	v_pk_mul_f32 v[126:127], v[146:147], v[126:127] op_sel_hi:[0,1]
	v_pk_mul_f32 v[128:129], v[146:147], v[128:129] op_sel_hi:[0,1]
	v_pk_mul_f32 v[130:131], v[146:147], v[130:131] op_sel_hi:[0,1]
	v_pk_mul_f32 v[116:117], v[116:117], v[32:33]
	v_pk_mul_f32 v[118:119], v[118:119], v[34:35]
	v_pk_mul_f32 v[120:121], v[120:121], v[36:37]
	v_pk_mul_f32 v[122:123], v[122:123], v[38:39]
	v_pk_mul_f32 v[124:125], v[124:125], v[40:41]
	v_pk_mul_f32 v[126:127], v[126:127], v[42:43]
	v_pk_mul_f32 v[128:129], v[128:129], v[44:45]
	v_pk_mul_f32 v[130:131], v[130:131], v[46:47]
	v_pk_fma_f32 v[116:117], v[116:117], v[84:85], v[100:101]
	v_pk_fma_f32 v[118:119], v[118:119], v[86:87], v[102:103]
	v_pk_fma_f32 v[120:121], v[120:121], v[88:89], v[104:105]
	v_pk_fma_f32 v[122:123], v[122:123], v[90:91], v[106:107]
	v_pk_fma_f32 v[124:125], v[124:125], v[92:93], v[108:109]
	v_pk_fma_f32 v[126:127], v[126:127], v[94:95], v[110:111]
	v_pk_fma_f32 v[128:129], v[128:129], v[96:97], v[112:113]
	v_pk_fma_f32 v[130:131], v[130:131], v[98:99], v[114:115]
	v_cvt_pk_bf16_f32 v172, v116, v117
	v_cvt_pk_bf16_f32 v173, v118, v119
	v_cvt_pk_bf16_f32 v174, v120, v121
	v_cvt_pk_bf16_f32 v175, v122, v123
	v_cvt_pk_bf16_f32 v176, v124, v125
	v_cvt_pk_bf16_f32 v177, v126, v127
	v_cvt_pk_bf16_f32 v178, v128, v129
	v_cvt_pk_bf16_f32 v179, v130, v131
	global_store_dwordx4 v149, v[172:175], s[26:27] offset:2048 sc1
	global_store_dwordx4 v149, v[176:179], s[26:27] offset:3072 sc1
	s_mul_i32 s36, s35, 0x6000
	s_add_u32 s0, s22, s36
	s_addc_u32 s1, s23, 0
	s_add_u32 s20, s0, 0x1000
	s_addc_u32 s21, s1, 0
	global_load_dwordx4 v[100:103], v148, s[0:1]
	global_load_dwordx4 v[104:107], v148, s[0:1] offset:16
	global_load_dwordx4 v[108:111], v148, s[0:1] offset:2048
	global_load_dwordx4 v[112:115], v148, s[0:1] offset:2064
	global_load_dwordx4 v[84:87], v148, s[20:21]
	global_load_dwordx4 v[88:91], v148, s[20:21] offset:16
	global_load_dwordx4 v[92:95], v148, s[20:21] offset:2048
	global_load_dwordx4 v[96:99], v148, s[20:21] offset:2064
	s_lshl_b32 s36, s31, 11
	s_add_u32 s24, s4, s36
	s_addc_u32 s25, s5, 0
	s_cmp_lt_u32 s36, 0x7000000
	s_cselect_b32 s26, s24, s18
	s_cselect_b32 s27, s25, s19
	s_cselect_b32 s37, 0x9000000, s36
	s_add_u32 s26, s26, s37
	s_addc_u32 s27, s27, 0
	global_load_dwordx4 v[52:55], v51, s[24:25]
	global_load_dwordx4 v[56:59], v51, s[24:25] offset:1024
	global_load_dwordx4 v[60:63], v51, s[24:25] offset:2048
	global_load_dwordx4 v[64:67], v51, s[24:25] offset:3072
	global_load_dwordx4 v[68:71], v149, s[24:25]
	global_load_dwordx4 v[72:75], v149, s[24:25] offset:1024
	global_load_dwordx4 v[76:79], v149, s[24:25] offset:2048
	global_load_dwordx4 v[80:83], v149, s[24:25] offset:3072
	s_waitcnt vmcnt(0)
	v_pk_add_f32 v[84:85], v[84:85], 1.0 op_sel_hi:[1,0]
	v_pk_add_f32 v[86:87], v[86:87], 1.0 op_sel_hi:[1,0]
	v_pk_add_f32 v[88:89], v[88:89], 1.0 op_sel_hi:[1,0]
	v_pk_add_f32 v[90:91], v[90:91], 1.0 op_sel_hi:[1,0]
	v_pk_add_f32 v[92:93], v[92:93], 1.0 op_sel_hi:[1,0]
	v_pk_add_f32 v[94:95], v[94:95], 1.0 op_sel_hi:[1,0]
	v_pk_add_f32 v[96:97], v[96:97], 1.0 op_sel_hi:[1,0]
	v_pk_add_f32 v[98:99], v[98:99], 1.0 op_sel_hi:[1,0]
	s_add_u32 s24, s24, 0x2000
	s_addc_u32 s25, s25, 0
	global_load_dwordx4 v[0:3], v51, s[24:25]
	global_load_dwordx4 v[4:7], v51, s[24:25] offset:1024
	global_load_dwordx4 v[8:11], v51, s[24:25] offset:2048
	global_load_dwordx4 v[12:15], v51, s[24:25] offset:3072
	global_load_dwordx4 v[16:19], v149, s[24:25]
	global_load_dwordx4 v[20:23], v149, s[24:25] offset:1024
	global_load_dwordx4 v[24:27], v149, s[24:25] offset:2048
	global_load_dwordx4 v[28:31], v149, s[24:25] offset:3072
	v_lshlrev_b32_e32 v116, 16, v52
	v_and_b32_e32 v117, 0xffff0000, v52
	v_lshlrev_b32_e32 v118, 16, v53
	v_and_b32_e32 v119, 0xffff0000, v53
	v_lshlrev_b32_e32 v120, 16, v54
	v_and_b32_e32 v121, 0xffff0000, v54
	v_lshlrev_b32_e32 v122, 16, v55
	v_and_b32_e32 v123, 0xffff0000, v55
	v_lshlrev_b32_e32 v124, 16, v56
	v_and_b32_e32 v125, 0xffff0000, v56
	v_lshlrev_b32_e32 v126, 16, v57
	v_and_b32_e32 v127, 0xffff0000, v57
	v_lshlrev_b32_e32 v128, 16, v58
	v_and_b32_e32 v129, 0xffff0000, v58
	v_lshlrev_b32_e32 v130, 16, v59
	v_and_b32_e32 v131, 0xffff0000, v59
	v_pk_mul_f32 v[132:133], v[116:117], v[116:117]
	v_pk_fma_f32 v[132:133], v[118:119], v[118:119], v[132:133]
	v_pk_fma_f32 v[132:133], v[120:121], v[120:121], v[132:133]
	v_pk_fma_f32 v[132:133], v[122:123], v[122:123], v[132:133]
	v_pk_fma_f32 v[132:133], v[124:125], v[124:125], v[132:133]
	v_pk_fma_f32 v[132:133], v[126:127], v[126:127], v[132:133]
	v_pk_fma_f32 v[132:133], v[128:129], v[128:129], v[132:133]
	v_pk_fma_f32 v[132:133], v[130:131], v[130:131], v[132:133]
	v_lshlrev_b32_e32 v116, 16, v60
	v_and_b32_e32 v117, 0xffff0000, v60
	v_lshlrev_b32_e32 v118, 16, v61
	v_and_b32_e32 v119, 0xffff0000, v61
	v_lshlrev_b32_e32 v120, 16, v62
	v_and_b32_e32 v121, 0xffff0000, v62
	v_lshlrev_b32_e32 v122, 16, v63
	v_and_b32_e32 v123, 0xffff0000, v63
	v_lshlrev_b32_e32 v124, 16, v64
	v_and_b32_e32 v125, 0xffff0000, v64
	v_lshlrev_b32_e32 v126, 16, v65
	v_and_b32_e32 v127, 0xffff0000, v65
	v_lshlrev_b32_e32 v128, 16, v66
	v_and_b32_e32 v129, 0xffff0000, v66
	v_lshlrev_b32_e32 v130, 16, v67
	v_and_b32_e32 v131, 0xffff0000, v67
	v_pk_mul_f32 v[134:135], v[116:117], v[116:117]
	v_pk_fma_f32 v[134:135], v[118:119], v[118:119], v[134:135]
	v_pk_fma_f32 v[134:135], v[120:121], v[120:121], v[134:135]
	v_pk_fma_f32 v[134:135], v[122:123], v[122:123], v[134:135]
	v_pk_fma_f32 v[134:135], v[124:125], v[124:125], v[134:135]
	v_pk_fma_f32 v[134:135], v[126:127], v[126:127], v[134:135]
	v_pk_fma_f32 v[134:135], v[128:129], v[128:129], v[134:135]
	v_pk_fma_f32 v[134:135], v[130:131], v[130:131], v[134:135]
	v_lshlrev_b32_e32 v116, 16, v68
	v_and_b32_e32 v117, 0xffff0000, v68
	v_lshlrev_b32_e32 v118, 16, v69
	v_and_b32_e32 v119, 0xffff0000, v69
	v_lshlrev_b32_e32 v120, 16, v70
	v_and_b32_e32 v121, 0xffff0000, v70
	v_lshlrev_b32_e32 v122, 16, v71
	v_and_b32_e32 v123, 0xffff0000, v71
	v_lshlrev_b32_e32 v124, 16, v72
	v_and_b32_e32 v125, 0xffff0000, v72
	v_lshlrev_b32_e32 v126, 16, v73
	v_and_b32_e32 v127, 0xffff0000, v73
	v_lshlrev_b32_e32 v128, 16, v74
	v_and_b32_e32 v129, 0xffff0000, v74
	v_lshlrev_b32_e32 v130, 16, v75
	v_and_b32_e32 v131, 0xffff0000, v75
	v_pk_mul_f32 v[136:137], v[116:117], v[116:117]
	v_pk_fma_f32 v[136:137], v[118:119], v[118:119], v[136:137]
	v_pk_fma_f32 v[136:137], v[120:121], v[120:121], v[136:137]
	v_pk_fma_f32 v[136:137], v[122:123], v[122:123], v[136:137]
	v_pk_fma_f32 v[136:137], v[124:125], v[124:125], v[136:137]
	v_pk_fma_f32 v[136:137], v[126:127], v[126:127], v[136:137]
	v_pk_fma_f32 v[136:137], v[128:129], v[128:129], v[136:137]
	v_pk_fma_f32 v[136:137], v[130:131], v[130:131], v[136:137]
	v_lshlrev_b32_e32 v116, 16, v76
	v_and_b32_e32 v117, 0xffff0000, v76
	v_lshlrev_b32_e32 v118, 16, v77
	v_and_b32_e32 v119, 0xffff0000, v77
	v_lshlrev_b32_e32 v120, 16, v78
	v_and_b32_e32 v121, 0xffff0000, v78
	v_lshlrev_b32_e32 v122, 16, v79
	v_and_b32_e32 v123, 0xffff0000, v79
	v_lshlrev_b32_e32 v124, 16, v80
	v_and_b32_e32 v125, 0xffff0000, v80
	v_lshlrev_b32_e32 v126, 16, v81
	v_and_b32_e32 v127, 0xffff0000, v81
	v_lshlrev_b32_e32 v128, 16, v82
	v_and_b32_e32 v129, 0xffff0000, v82
	v_lshlrev_b32_e32 v130, 16, v83
	v_and_b32_e32 v131, 0xffff0000, v83
	v_pk_mul_f32 v[138:139], v[116:117], v[116:117]
	v_pk_fma_f32 v[138:139], v[118:119], v[118:119], v[138:139]
	v_pk_fma_f32 v[138:139], v[120:121], v[120:121], v[138:139]
	v_pk_fma_f32 v[138:139], v[122:123], v[122:123], v[138:139]
	v_pk_fma_f32 v[138:139], v[124:125], v[124:125], v[138:139]
	v_pk_fma_f32 v[138:139], v[126:127], v[126:127], v[138:139]
	v_pk_fma_f32 v[138:139], v[128:129], v[128:129], v[138:139]
	v_pk_fma_f32 v[138:139], v[130:131], v[130:131], v[138:139]
	v_add_f32_e32 v132, v132, v133
	v_add_f32_e32 v134, v134, v135
	v_add_f32_e32 v136, v136, v137
	v_add_f32_e32 v138, v138, v139
	s_nop 1
	v_add_f32_dpp v132, v132, v132 row_shr:1 row_mask:0xf bank_mask:0xf bound_ctrl:1
	v_add_f32_dpp v134, v134, v134 row_shr:1 row_mask:0xf bank_mask:0xf bound_ctrl:1
	v_add_f32_dpp v136, v136, v136 row_shr:1 row_mask:0xf bank_mask:0xf bound_ctrl:1
	v_add_f32_dpp v138, v138, v138 row_shr:1 row_mask:0xf bank_mask:0xf bound_ctrl:1
	v_add_f32_dpp v132, v132, v132 row_shr:2 row_mask:0xf bank_mask:0xf bound_ctrl:1
	v_add_f32_dpp v134, v134, v134 row_shr:2 row_mask:0xf bank_mask:0xf bound_ctrl:1
	v_add_f32_dpp v136, v136, v136 row_shr:2 row_mask:0xf bank_mask:0xf bound_ctrl:1
	v_add_f32_dpp v138, v138, v138 row_shr:2 row_mask:0xf bank_mask:0xf bound_ctrl:1
	v_add_f32_dpp v132, v132, v132 row_shr:4 row_mask:0xf bank_mask:0xf bound_ctrl:1
	v_add_f32_dpp v134, v134, v134 row_shr:4 row_mask:0xf bank_mask:0xf bound_ctrl:1
	v_add_f32_dpp v136, v136, v136 row_shr:4 row_mask:0xf bank_mask:0xf bound_ctrl:1
	v_add_f32_dpp v138, v138, v138 row_shr:4 row_mask:0xf bank_mask:0xf bound_ctrl:1
	v_add_f32_dpp v132, v132, v132 row_shr:8 row_mask:0xf bank_mask:0xf bound_ctrl:1
	v_add_f32_dpp v134, v134, v134 row_shr:8 row_mask:0xf bank_mask:0xf bound_ctrl:1
	v_add_f32_dpp v136, v136, v136 row_shr:8 row_mask:0xf bank_mask:0xf bound_ctrl:1
	v_add_f32_dpp v138, v138, v138 row_shr:8 row_mask:0xf bank_mask:0xf bound_ctrl:1
	v_add_f32_dpp v132, v132, v132 row_bcast:15 row_mask:0xa bank_mask:0xf
	v_add_f32_dpp v134, v134, v134 row_bcast:15 row_mask:0xa bank_mask:0xf
	v_add_f32_dpp v136, v136, v136 row_bcast:15 row_mask:0xa bank_mask:0xf
	v_add_f32_dpp v138, v138, v138 row_bcast:15 row_mask:0xa bank_mask:0xf
	v_add_f32_dpp v132, v132, v132 row_bcast:31 row_mask:0xc bank_mask:0xf
	v_add_f32_dpp v134, v134, v134 row_bcast:31 row_mask:0xc bank_mask:0xf
	v_add_f32_dpp v136, v136, v136 row_bcast:31 row_mask:0xc bank_mask:0xf
	v_add_f32_dpp v138, v138, v138 row_bcast:31 row_mask:0xc bank_mask:0xf
	s_nop 1
	v_readlane_b32 s32, v132, 63
	v_readlane_b32 s28, v134, 63
	v_readlane_b32 s29, v136, 63
	v_readlane_b32 s30, v138, 63
	s_nop 1
	v_mov_b32_e32 v140, s32
	v_mov_b32_e32 v142, s28
	v_mov_b32_e32 v144, s29
	v_mov_b32_e32 v146, s30
	v_fmaak_f32 v140, v140, v50, 0x358637bd
	v_fmaak_f32 v142, v142, v50, 0x358637bd
	v_fmaak_f32 v144, v144, v50, 0x358637bd
	v_fmaak_f32 v146, v146, v50, 0x358637bd
	v_rsq_f32_e32 v140, v140
	v_rsq_f32_e32 v142, v142
	v_rsq_f32_e32 v144, v144
	v_rsq_f32_e32 v146, v146
	s_nop 0
	v_lshlrev_b32_e32 v116, 16, v52
	v_and_b32_e32 v117, 0xffff0000, v52
	v_lshlrev_b32_e32 v118, 16, v53
	v_and_b32_e32 v119, 0xffff0000, v53
	v_lshlrev_b32_e32 v120, 16, v54
	v_and_b32_e32 v121, 0xffff0000, v54
	v_lshlrev_b32_e32 v122, 16, v55
	v_and_b32_e32 v123, 0xffff0000, v55
	v_lshlrev_b32_e32 v124, 16, v56
	v_and_b32_e32 v125, 0xffff0000, v56
	v_lshlrev_b32_e32 v126, 16, v57
	v_and_b32_e32 v127, 0xffff0000, v57
	v_lshlrev_b32_e32 v128, 16, v58
	v_and_b32_e32 v129, 0xffff0000, v58
	v_lshlrev_b32_e32 v130, 16, v59
	v_and_b32_e32 v131, 0xffff0000, v59
	v_pk_mul_f32 v[116:117], v[140:141], v[116:117] op_sel_hi:[0,1]
	v_pk_mul_f32 v[118:119], v[140:141], v[118:119] op_sel_hi:[0,1]
	v_pk_mul_f32 v[120:121], v[140:141], v[120:121] op_sel_hi:[0,1]
	v_pk_mul_f32 v[122:123], v[140:141], v[122:123] op_sel_hi:[0,1]
	v_pk_mul_f32 v[124:125], v[140:141], v[124:125] op_sel_hi:[0,1]
	v_pk_mul_f32 v[126:127], v[140:141], v[126:127] op_sel_hi:[0,1]
	v_pk_mul_f32 v[128:129], v[140:141], v[128:129] op_sel_hi:[0,1]
	v_pk_mul_f32 v[130:131], v[140:141], v[130:131] op_sel_hi:[0,1]
	v_pk_mul_f32 v[116:117], v[116:117], v[32:33]
	v_pk_mul_f32 v[118:119], v[118:119], v[34:35]
	v_pk_mul_f32 v[120:121], v[120:121], v[36:37]
	v_pk_mul_f32 v[122:123], v[122:123], v[38:39]
	v_pk_mul_f32 v[124:125], v[124:125], v[40:41]
	v_pk_mul_f32 v[126:127], v[126:127], v[42:43]
	v_pk_mul_f32 v[128:129], v[128:129], v[44:45]
	v_pk_mul_f32 v[130:131], v[130:131], v[46:47]
	v_pk_fma_f32 v[116:117], v[116:117], v[84:85], v[100:101]
	v_pk_fma_f32 v[118:119], v[118:119], v[86:87], v[102:103]
	v_pk_fma_f32 v[120:121], v[120:121], v[88:89], v[104:105]
	v_pk_fma_f32 v[122:123], v[122:123], v[90:91], v[106:107]
	v_pk_fma_f32 v[124:125], v[124:125], v[92:93], v[108:109]
	v_pk_fma_f32 v[126:127], v[126:127], v[94:95], v[110:111]
	v_pk_fma_f32 v[128:129], v[128:129], v[96:97], v[112:113]
	v_pk_fma_f32 v[130:131], v[130:131], v[98:99], v[114:115]
	v_cvt_pk_bf16_f32 v164, v116, v117
	v_cvt_pk_bf16_f32 v165, v118, v119
	v_cvt_pk_bf16_f32 v166, v120, v121
	v_cvt_pk_bf16_f32 v167, v122, v123
	v_cvt_pk_bf16_f32 v168, v124, v125
	v_cvt_pk_bf16_f32 v169, v126, v127
	v_cvt_pk_bf16_f32 v170, v128, v129
	v_cvt_pk_bf16_f32 v171, v130, v131
	global_store_dwordx4 v51, v[164:167], s[26:27] sc1
	global_store_dwordx4 v51, v[168:171], s[26:27] offset:1024 sc1
	v_lshlrev_b32_e32 v116, 16, v60
	v_and_b32_e32 v117, 0xffff0000, v60
	v_lshlrev_b32_e32 v118, 16, v61
	v_and_b32_e32 v119, 0xffff0000, v61
	v_lshlrev_b32_e32 v120, 16, v62
	v_and_b32_e32 v121, 0xffff0000, v62
	v_lshlrev_b32_e32 v122, 16, v63
	v_and_b32_e32 v123, 0xffff0000, v63
	v_lshlrev_b32_e32 v124, 16, v64
	v_and_b32_e32 v125, 0xffff0000, v64
	v_lshlrev_b32_e32 v126, 16, v65
	v_and_b32_e32 v127, 0xffff0000, v65
	v_lshlrev_b32_e32 v128, 16, v66
	v_and_b32_e32 v129, 0xffff0000, v66
	v_lshlrev_b32_e32 v130, 16, v67
	v_and_b32_e32 v131, 0xffff0000, v67
	v_pk_mul_f32 v[116:117], v[142:143], v[116:117] op_sel_hi:[0,1]
	v_pk_mul_f32 v[118:119], v[142:143], v[118:119] op_sel_hi:[0,1]
	v_pk_mul_f32 v[120:121], v[142:143], v[120:121] op_sel_hi:[0,1]
	v_pk_mul_f32 v[122:123], v[142:143], v[122:123] op_sel_hi:[0,1]
	v_pk_mul_f32 v[124:125], v[142:143], v[124:125] op_sel_hi:[0,1]
	v_pk_mul_f32 v[126:127], v[142:143], v[126:127] op_sel_hi:[0,1]
	v_pk_mul_f32 v[128:129], v[142:143], v[128:129] op_sel_hi:[0,1]
	v_pk_mul_f32 v[130:131], v[142:143], v[130:131] op_sel_hi:[0,1]
	v_pk_mul_f32 v[116:117], v[116:117], v[32:33]
	v_pk_mul_f32 v[118:119], v[118:119], v[34:35]
	v_pk_mul_f32 v[120:121], v[120:121], v[36:37]
	v_pk_mul_f32 v[122:123], v[122:123], v[38:39]
	v_pk_mul_f32 v[124:125], v[124:125], v[40:41]
	v_pk_mul_f32 v[126:127], v[126:127], v[42:43]
	v_pk_mul_f32 v[128:129], v[128:129], v[44:45]
	v_pk_mul_f32 v[130:131], v[130:131], v[46:47]
	v_pk_fma_f32 v[116:117], v[116:117], v[84:85], v[100:101]
	v_pk_fma_f32 v[118:119], v[118:119], v[86:87], v[102:103]
	v_pk_fma_f32 v[120:121], v[120:121], v[88:89], v[104:105]
	v_pk_fma_f32 v[122:123], v[122:123], v[90:91], v[106:107]
	v_pk_fma_f32 v[124:125], v[124:125], v[92:93], v[108:109]
	v_pk_fma_f32 v[126:127], v[126:127], v[94:95], v[110:111]
	v_pk_fma_f32 v[128:129], v[128:129], v[96:97], v[112:113]
	v_pk_fma_f32 v[130:131], v[130:131], v[98:99], v[114:115]
	v_cvt_pk_bf16_f32 v172, v116, v117
	v_cvt_pk_bf16_f32 v173, v118, v119
	v_cvt_pk_bf16_f32 v174, v120, v121
	v_cvt_pk_bf16_f32 v175, v122, v123
	v_cvt_pk_bf16_f32 v176, v124, v125
	v_cvt_pk_bf16_f32 v177, v126, v127
	v_cvt_pk_bf16_f32 v178, v128, v129
	v_cvt_pk_bf16_f32 v179, v130, v131
	global_store_dwordx4 v51, v[172:175], s[26:27] offset:2048 sc1
	global_store_dwordx4 v51, v[176:179], s[26:27] offset:3072 sc1
	v_lshlrev_b32_e32 v116, 16, v68
	v_and_b32_e32 v117, 0xffff0000, v68
	v_lshlrev_b32_e32 v118, 16, v69
	v_and_b32_e32 v119, 0xffff0000, v69
	v_lshlrev_b32_e32 v120, 16, v70
	v_and_b32_e32 v121, 0xffff0000, v70
	v_lshlrev_b32_e32 v122, 16, v71
	v_and_b32_e32 v123, 0xffff0000, v71
	v_lshlrev_b32_e32 v124, 16, v72
	v_and_b32_e32 v125, 0xffff0000, v72
	v_lshlrev_b32_e32 v126, 16, v73
	v_and_b32_e32 v127, 0xffff0000, v73
	v_lshlrev_b32_e32 v128, 16, v74
	v_and_b32_e32 v129, 0xffff0000, v74
	v_lshlrev_b32_e32 v130, 16, v75
	v_and_b32_e32 v131, 0xffff0000, v75
	v_pk_mul_f32 v[116:117], v[144:145], v[116:117] op_sel_hi:[0,1]
	v_pk_mul_f32 v[118:119], v[144:145], v[118:119] op_sel_hi:[0,1]
	v_pk_mul_f32 v[120:121], v[144:145], v[120:121] op_sel_hi:[0,1]
	v_pk_mul_f32 v[122:123], v[144:145], v[122:123] op_sel_hi:[0,1]
	v_pk_mul_f32 v[124:125], v[144:145], v[124:125] op_sel_hi:[0,1]
	v_pk_mul_f32 v[126:127], v[144:145], v[126:127] op_sel_hi:[0,1]
	v_pk_mul_f32 v[128:129], v[144:145], v[128:129] op_sel_hi:[0,1]
	v_pk_mul_f32 v[130:131], v[144:145], v[130:131] op_sel_hi:[0,1]
	v_pk_mul_f32 v[116:117], v[116:117], v[32:33]
	v_pk_mul_f32 v[118:119], v[118:119], v[34:35]
	v_pk_mul_f32 v[120:121], v[120:121], v[36:37]
	v_pk_mul_f32 v[122:123], v[122:123], v[38:39]
	v_pk_mul_f32 v[124:125], v[124:125], v[40:41]
	v_pk_mul_f32 v[126:127], v[126:127], v[42:43]
	v_pk_mul_f32 v[128:129], v[128:129], v[44:45]
	v_pk_mul_f32 v[130:131], v[130:131], v[46:47]
	v_pk_fma_f32 v[116:117], v[116:117], v[84:85], v[100:101]
	v_pk_fma_f32 v[118:119], v[118:119], v[86:87], v[102:103]
	v_pk_fma_f32 v[120:121], v[120:121], v[88:89], v[104:105]
	v_pk_fma_f32 v[122:123], v[122:123], v[90:91], v[106:107]
	v_pk_fma_f32 v[124:125], v[124:125], v[92:93], v[108:109]
	v_pk_fma_f32 v[126:127], v[126:127], v[94:95], v[110:111]
	v_pk_fma_f32 v[128:129], v[128:129], v[96:97], v[112:113]
	v_pk_fma_f32 v[130:131], v[130:131], v[98:99], v[114:115]
	v_cvt_pk_bf16_f32 v164, v116, v117
	v_cvt_pk_bf16_f32 v165, v118, v119
	v_cvt_pk_bf16_f32 v166, v120, v121
	v_cvt_pk_bf16_f32 v167, v122, v123
	v_cvt_pk_bf16_f32 v168, v124, v125
	v_cvt_pk_bf16_f32 v169, v126, v127
	v_cvt_pk_bf16_f32 v170, v128, v129
	v_cvt_pk_bf16_f32 v171, v130, v131
	global_store_dwordx4 v149, v[164:167], s[26:27] sc1
	global_store_dwordx4 v149, v[168:171], s[26:27] offset:1024 sc1
	v_lshlrev_b32_e32 v116, 16, v76
	v_and_b32_e32 v117, 0xffff0000, v76
	v_lshlrev_b32_e32 v118, 16, v77
	v_and_b32_e32 v119, 0xffff0000, v77
	v_lshlrev_b32_e32 v120, 16, v78
	v_and_b32_e32 v121, 0xffff0000, v78
	v_lshlrev_b32_e32 v122, 16, v79
	v_and_b32_e32 v123, 0xffff0000, v79
	v_lshlrev_b32_e32 v124, 16, v80
	v_and_b32_e32 v125, 0xffff0000, v80
	v_lshlrev_b32_e32 v126, 16, v81
	v_and_b32_e32 v127, 0xffff0000, v81
	v_lshlrev_b32_e32 v128, 16, v82
	v_and_b32_e32 v129, 0xffff0000, v82
	v_lshlrev_b32_e32 v130, 16, v83
	v_and_b32_e32 v131, 0xffff0000, v83
	v_pk_mul_f32 v[116:117], v[146:147], v[116:117] op_sel_hi:[0,1]
	v_pk_mul_f32 v[118:119], v[146:147], v[118:119] op_sel_hi:[0,1]
	v_pk_mul_f32 v[120:121], v[146:147], v[120:121] op_sel_hi:[0,1]
	v_pk_mul_f32 v[122:123], v[146:147], v[122:123] op_sel_hi:[0,1]
	v_pk_mul_f32 v[124:125], v[146:147], v[124:125] op_sel_hi:[0,1]
	v_pk_mul_f32 v[126:127], v[146:147], v[126:127] op_sel_hi:[0,1]
	v_pk_mul_f32 v[128:129], v[146:147], v[128:129] op_sel_hi:[0,1]
	v_pk_mul_f32 v[130:131], v[146:147], v[130:131] op_sel_hi:[0,1]
	v_pk_mul_f32 v[116:117], v[116:117], v[32:33]
	v_pk_mul_f32 v[118:119], v[118:119], v[34:35]
	v_pk_mul_f32 v[120:121], v[120:121], v[36:37]
	v_pk_mul_f32 v[122:123], v[122:123], v[38:39]
	v_pk_mul_f32 v[124:125], v[124:125], v[40:41]
	v_pk_mul_f32 v[126:127], v[126:127], v[42:43]
	v_pk_mul_f32 v[128:129], v[128:129], v[44:45]
	v_pk_mul_f32 v[130:131], v[130:131], v[46:47]
	v_pk_fma_f32 v[116:117], v[116:117], v[84:85], v[100:101]
	v_pk_fma_f32 v[118:119], v[118:119], v[86:87], v[102:103]
	v_pk_fma_f32 v[120:121], v[120:121], v[88:89], v[104:105]
	v_pk_fma_f32 v[122:123], v[122:123], v[90:91], v[106:107]
	v_pk_fma_f32 v[124:125], v[124:125], v[92:93], v[108:109]
	v_pk_fma_f32 v[126:127], v[126:127], v[94:95], v[110:111]
	v_pk_fma_f32 v[128:129], v[128:129], v[96:97], v[112:113]
	v_pk_fma_f32 v[130:131], v[130:131], v[98:99], v[114:115]
	v_cvt_pk_bf16_f32 v172, v116, v117
	v_cvt_pk_bf16_f32 v173, v118, v119
	v_cvt_pk_bf16_f32 v174, v120, v121
	v_cvt_pk_bf16_f32 v175, v122, v123
	v_cvt_pk_bf16_f32 v176, v124, v125
	v_cvt_pk_bf16_f32 v177, v126, v127
	v_cvt_pk_bf16_f32 v178, v128, v129
	v_cvt_pk_bf16_f32 v179, v130, v131
	global_store_dwordx4 v149, v[172:175], s[26:27] offset:2048 sc1
	global_store_dwordx4 v149, v[176:179], s[26:27] offset:3072 sc1
	s_add_u32 s26, s26, 0x2000
	s_addc_u32 s27, s27, 0
	s_add_u32 s24, s24, 0x2000
	s_addc_u32 s25, s25, 0
	global_load_dwordx4 v[52:55], v51, s[24:25]
	global_load_dwordx4 v[56:59], v51, s[24:25] offset:1024
	global_load_dwordx4 v[60:63], v51, s[24:25] offset:2048
	global_load_dwordx4 v[64:67], v51, s[24:25] offset:3072
	global_load_dwordx4 v[68:71], v149, s[24:25]
	global_load_dwordx4 v[72:75], v149, s[24:25] offset:1024
	global_load_dwordx4 v[76:79], v149, s[24:25] offset:2048
	global_load_dwordx4 v[80:83], v149, s[24:25] offset:3072
	s_waitcnt vmcnt(16)
	v_lshlrev_b32_e32 v116, 16, v0
	v_and_b32_e32 v117, 0xffff0000, v0
	v_lshlrev_b32_e32 v118, 16, v1
	v_and_b32_e32 v119, 0xffff0000, v1
	v_lshlrev_b32_e32 v120, 16, v2
	v_and_b32_e32 v121, 0xffff0000, v2
	v_lshlrev_b32_e32 v122, 16, v3
	v_and_b32_e32 v123, 0xffff0000, v3
	v_lshlrev_b32_e32 v124, 16, v4
	v_and_b32_e32 v125, 0xffff0000, v4
	v_lshlrev_b32_e32 v126, 16, v5
	v_and_b32_e32 v127, 0xffff0000, v5
	v_lshlrev_b32_e32 v128, 16, v6
	v_and_b32_e32 v129, 0xffff0000, v6
	v_lshlrev_b32_e32 v130, 16, v7
	v_and_b32_e32 v131, 0xffff0000, v7
	v_pk_mul_f32 v[132:133], v[116:117], v[116:117]
	v_pk_fma_f32 v[132:133], v[118:119], v[118:119], v[132:133]
	v_pk_fma_f32 v[132:133], v[120:121], v[120:121], v[132:133]
	v_pk_fma_f32 v[132:133], v[122:123], v[122:123], v[132:133]
	v_pk_fma_f32 v[132:133], v[124:125], v[124:125], v[132:133]
	v_pk_fma_f32 v[132:133], v[126:127], v[126:127], v[132:133]
	v_pk_fma_f32 v[132:133], v[128:129], v[128:129], v[132:133]
	v_pk_fma_f32 v[132:133], v[130:131], v[130:131], v[132:133]
	v_lshlrev_b32_e32 v116, 16, v8
	v_and_b32_e32 v117, 0xffff0000, v8
	v_lshlrev_b32_e32 v118, 16, v9
	v_and_b32_e32 v119, 0xffff0000, v9
	v_lshlrev_b32_e32 v120, 16, v10
	v_and_b32_e32 v121, 0xffff0000, v10
	v_lshlrev_b32_e32 v122, 16, v11
	v_and_b32_e32 v123, 0xffff0000, v11
	v_lshlrev_b32_e32 v124, 16, v12
	v_and_b32_e32 v125, 0xffff0000, v12
	v_lshlrev_b32_e32 v126, 16, v13
	v_and_b32_e32 v127, 0xffff0000, v13
	v_lshlrev_b32_e32 v128, 16, v14
	v_and_b32_e32 v129, 0xffff0000, v14
	v_lshlrev_b32_e32 v130, 16, v15
	v_and_b32_e32 v131, 0xffff0000, v15
	v_pk_mul_f32 v[134:135], v[116:117], v[116:117]
	v_pk_fma_f32 v[134:135], v[118:119], v[118:119], v[134:135]
	v_pk_fma_f32 v[134:135], v[120:121], v[120:121], v[134:135]
	v_pk_fma_f32 v[134:135], v[122:123], v[122:123], v[134:135]
	v_pk_fma_f32 v[134:135], v[124:125], v[124:125], v[134:135]
	v_pk_fma_f32 v[134:135], v[126:127], v[126:127], v[134:135]
	v_pk_fma_f32 v[134:135], v[128:129], v[128:129], v[134:135]
	v_pk_fma_f32 v[134:135], v[130:131], v[130:131], v[134:135]
	v_lshlrev_b32_e32 v116, 16, v16
	v_and_b32_e32 v117, 0xffff0000, v16
	v_lshlrev_b32_e32 v118, 16, v17
	v_and_b32_e32 v119, 0xffff0000, v17
	v_lshlrev_b32_e32 v120, 16, v18
	v_and_b32_e32 v121, 0xffff0000, v18
	v_lshlrev_b32_e32 v122, 16, v19
	v_and_b32_e32 v123, 0xffff0000, v19
	v_lshlrev_b32_e32 v124, 16, v20
	v_and_b32_e32 v125, 0xffff0000, v20
	v_lshlrev_b32_e32 v126, 16, v21
	v_and_b32_e32 v127, 0xffff0000, v21
	v_lshlrev_b32_e32 v128, 16, v22
	v_and_b32_e32 v129, 0xffff0000, v22
	v_lshlrev_b32_e32 v130, 16, v23
	v_and_b32_e32 v131, 0xffff0000, v23
	v_pk_mul_f32 v[136:137], v[116:117], v[116:117]
	v_pk_fma_f32 v[136:137], v[118:119], v[118:119], v[136:137]
	v_pk_fma_f32 v[136:137], v[120:121], v[120:121], v[136:137]
	v_pk_fma_f32 v[136:137], v[122:123], v[122:123], v[136:137]
	v_pk_fma_f32 v[136:137], v[124:125], v[124:125], v[136:137]
	v_pk_fma_f32 v[136:137], v[126:127], v[126:127], v[136:137]
	v_pk_fma_f32 v[136:137], v[128:129], v[128:129], v[136:137]
	v_pk_fma_f32 v[136:137], v[130:131], v[130:131], v[136:137]
	v_lshlrev_b32_e32 v116, 16, v24
	v_and_b32_e32 v117, 0xffff0000, v24
	v_lshlrev_b32_e32 v118, 16, v25
	v_and_b32_e32 v119, 0xffff0000, v25
	v_lshlrev_b32_e32 v120, 16, v26
	v_and_b32_e32 v121, 0xffff0000, v26
	v_lshlrev_b32_e32 v122, 16, v27
	v_and_b32_e32 v123, 0xffff0000, v27
	v_lshlrev_b32_e32 v124, 16, v28
	v_and_b32_e32 v125, 0xffff0000, v28
	v_lshlrev_b32_e32 v126, 16, v29
	v_and_b32_e32 v127, 0xffff0000, v29
	v_lshlrev_b32_e32 v128, 16, v30
	v_and_b32_e32 v129, 0xffff0000, v30
	v_lshlrev_b32_e32 v130, 16, v31
	v_and_b32_e32 v131, 0xffff0000, v31
	v_pk_mul_f32 v[138:139], v[116:117], v[116:117]
	v_pk_fma_f32 v[138:139], v[118:119], v[118:119], v[138:139]
	v_pk_fma_f32 v[138:139], v[120:121], v[120:121], v[138:139]
	v_pk_fma_f32 v[138:139], v[122:123], v[122:123], v[138:139]
	v_pk_fma_f32 v[138:139], v[124:125], v[124:125], v[138:139]
	v_pk_fma_f32 v[138:139], v[126:127], v[126:127], v[138:139]
	v_pk_fma_f32 v[138:139], v[128:129], v[128:129], v[138:139]
	v_pk_fma_f32 v[138:139], v[130:131], v[130:131], v[138:139]
	v_add_f32_e32 v132, v132, v133
	v_add_f32_e32 v134, v134, v135
	v_add_f32_e32 v136, v136, v137
	v_add_f32_e32 v138, v138, v139
	s_nop 1
	v_add_f32_dpp v132, v132, v132 row_shr:1 row_mask:0xf bank_mask:0xf bound_ctrl:1
	v_add_f32_dpp v134, v134, v134 row_shr:1 row_mask:0xf bank_mask:0xf bound_ctrl:1
	v_add_f32_dpp v136, v136, v136 row_shr:1 row_mask:0xf bank_mask:0xf bound_ctrl:1
	v_add_f32_dpp v138, v138, v138 row_shr:1 row_mask:0xf bank_mask:0xf bound_ctrl:1
	v_add_f32_dpp v132, v132, v132 row_shr:2 row_mask:0xf bank_mask:0xf bound_ctrl:1
	v_add_f32_dpp v134, v134, v134 row_shr:2 row_mask:0xf bank_mask:0xf bound_ctrl:1
	v_add_f32_dpp v136, v136, v136 row_shr:2 row_mask:0xf bank_mask:0xf bound_ctrl:1
	v_add_f32_dpp v138, v138, v138 row_shr:2 row_mask:0xf bank_mask:0xf bound_ctrl:1
	v_add_f32_dpp v132, v132, v132 row_shr:4 row_mask:0xf bank_mask:0xf bound_ctrl:1
	v_add_f32_dpp v134, v134, v134 row_shr:4 row_mask:0xf bank_mask:0xf bound_ctrl:1
	v_add_f32_dpp v136, v136, v136 row_shr:4 row_mask:0xf bank_mask:0xf bound_ctrl:1
	v_add_f32_dpp v138, v138, v138 row_shr:4 row_mask:0xf bank_mask:0xf bound_ctrl:1
	v_add_f32_dpp v132, v132, v132 row_shr:8 row_mask:0xf bank_mask:0xf bound_ctrl:1
	v_add_f32_dpp v134, v134, v134 row_shr:8 row_mask:0xf bank_mask:0xf bound_ctrl:1
	v_add_f32_dpp v136, v136, v136 row_shr:8 row_mask:0xf bank_mask:0xf bound_ctrl:1
	v_add_f32_dpp v138, v138, v138 row_shr:8 row_mask:0xf bank_mask:0xf bound_ctrl:1
	v_add_f32_dpp v132, v132, v132 row_bcast:15 row_mask:0xa bank_mask:0xf
	v_add_f32_dpp v134, v134, v134 row_bcast:15 row_mask:0xa bank_mask:0xf
	v_add_f32_dpp v136, v136, v136 row_bcast:15 row_mask:0xa bank_mask:0xf
	v_add_f32_dpp v138, v138, v138 row_bcast:15 row_mask:0xa bank_mask:0xf
	v_add_f32_dpp v132, v132, v132 row_bcast:31 row_mask:0xc bank_mask:0xf
	v_add_f32_dpp v134, v134, v134 row_bcast:31 row_mask:0xc bank_mask:0xf
	v_add_f32_dpp v136, v136, v136 row_bcast:31 row_mask:0xc bank_mask:0xf
	v_add_f32_dpp v138, v138, v138 row_bcast:31 row_mask:0xc bank_mask:0xf
	s_nop 1
	v_readlane_b32 s32, v132, 63
	v_readlane_b32 s28, v134, 63
	v_readlane_b32 s29, v136, 63
	v_readlane_b32 s30, v138, 63
	s_nop 1
	v_mov_b32_e32 v140, s32
	v_mov_b32_e32 v142, s28
	v_mov_b32_e32 v144, s29
	v_mov_b32_e32 v146, s30
	v_fmaak_f32 v140, v140, v50, 0x358637bd
	v_fmaak_f32 v142, v142, v50, 0x358637bd
	v_fmaak_f32 v144, v144, v50, 0x358637bd
	v_fmaak_f32 v146, v146, v50, 0x358637bd
	v_rsq_f32_e32 v140, v140
	v_rsq_f32_e32 v142, v142
	v_rsq_f32_e32 v144, v144
	v_rsq_f32_e32 v146, v146
	s_nop 0
	v_lshlrev_b32_e32 v116, 16, v0
	v_and_b32_e32 v117, 0xffff0000, v0
	v_lshlrev_b32_e32 v118, 16, v1
	v_and_b32_e32 v119, 0xffff0000, v1
	v_lshlrev_b32_e32 v120, 16, v2
	v_and_b32_e32 v121, 0xffff0000, v2
	v_lshlrev_b32_e32 v122, 16, v3
	v_and_b32_e32 v123, 0xffff0000, v3
	v_lshlrev_b32_e32 v124, 16, v4
	v_and_b32_e32 v125, 0xffff0000, v4
	v_lshlrev_b32_e32 v126, 16, v5
	v_and_b32_e32 v127, 0xffff0000, v5
	v_lshlrev_b32_e32 v128, 16, v6
	v_and_b32_e32 v129, 0xffff0000, v6
	v_lshlrev_b32_e32 v130, 16, v7
	v_and_b32_e32 v131, 0xffff0000, v7
	v_pk_mul_f32 v[116:117], v[140:141], v[116:117] op_sel_hi:[0,1]
	v_pk_mul_f32 v[118:119], v[140:141], v[118:119] op_sel_hi:[0,1]
	v_pk_mul_f32 v[120:121], v[140:141], v[120:121] op_sel_hi:[0,1]
	v_pk_mul_f32 v[122:123], v[140:141], v[122:123] op_sel_hi:[0,1]
	v_pk_mul_f32 v[124:125], v[140:141], v[124:125] op_sel_hi:[0,1]
	v_pk_mul_f32 v[126:127], v[140:141], v[126:127] op_sel_hi:[0,1]
	v_pk_mul_f32 v[128:129], v[140:141], v[128:129] op_sel_hi:[0,1]
	v_pk_mul_f32 v[130:131], v[140:141], v[130:131] op_sel_hi:[0,1]
	v_pk_mul_f32 v[116:117], v[116:117], v[32:33]
	v_pk_mul_f32 v[118:119], v[118:119], v[34:35]
	v_pk_mul_f32 v[120:121], v[120:121], v[36:37]
	v_pk_mul_f32 v[122:123], v[122:123], v[38:39]
	v_pk_mul_f32 v[124:125], v[124:125], v[40:41]
	v_pk_mul_f32 v[126:127], v[126:127], v[42:43]
	v_pk_mul_f32 v[128:129], v[128:129], v[44:45]
	v_pk_mul_f32 v[130:131], v[130:131], v[46:47]
	v_pk_fma_f32 v[116:117], v[116:117], v[84:85], v[100:101]
	v_pk_fma_f32 v[118:119], v[118:119], v[86:87], v[102:103]
	v_pk_fma_f32 v[120:121], v[120:121], v[88:89], v[104:105]
	v_pk_fma_f32 v[122:123], v[122:123], v[90:91], v[106:107]
	v_pk_fma_f32 v[124:125], v[124:125], v[92:93], v[108:109]
	v_pk_fma_f32 v[126:127], v[126:127], v[94:95], v[110:111]
	v_pk_fma_f32 v[128:129], v[128:129], v[96:97], v[112:113]
	v_pk_fma_f32 v[130:131], v[130:131], v[98:99], v[114:115]
	v_cvt_pk_bf16_f32 v172, v116, v117
	v_cvt_pk_bf16_f32 v173, v118, v119
	v_cvt_pk_bf16_f32 v174, v120, v121
	v_cvt_pk_bf16_f32 v175, v122, v123
	v_cvt_pk_bf16_f32 v176, v124, v125
	v_cvt_pk_bf16_f32 v177, v126, v127
	v_cvt_pk_bf16_f32 v178, v128, v129
	v_cvt_pk_bf16_f32 v179, v130, v131
	global_store_dwordx4 v51, v[172:175], s[26:27] sc1
	global_store_dwordx4 v51, v[176:179], s[26:27] offset:1024 sc1
	v_lshlrev_b32_e32 v116, 16, v8
	v_and_b32_e32 v117, 0xffff0000, v8
	v_lshlrev_b32_e32 v118, 16, v9
	v_and_b32_e32 v119, 0xffff0000, v9
	v_lshlrev_b32_e32 v120, 16, v10
	v_and_b32_e32 v121, 0xffff0000, v10
	v_lshlrev_b32_e32 v122, 16, v11
	v_and_b32_e32 v123, 0xffff0000, v11
	v_lshlrev_b32_e32 v124, 16, v12
	v_and_b32_e32 v125, 0xffff0000, v12
	v_lshlrev_b32_e32 v126, 16, v13
	v_and_b32_e32 v127, 0xffff0000, v13
	v_lshlrev_b32_e32 v128, 16, v14
	v_and_b32_e32 v129, 0xffff0000, v14
	v_lshlrev_b32_e32 v130, 16, v15
	v_and_b32_e32 v131, 0xffff0000, v15
	v_pk_mul_f32 v[116:117], v[142:143], v[116:117] op_sel_hi:[0,1]
	v_pk_mul_f32 v[118:119], v[142:143], v[118:119] op_sel_hi:[0,1]
	v_pk_mul_f32 v[120:121], v[142:143], v[120:121] op_sel_hi:[0,1]
	v_pk_mul_f32 v[122:123], v[142:143], v[122:123] op_sel_hi:[0,1]
	v_pk_mul_f32 v[124:125], v[142:143], v[124:125] op_sel_hi:[0,1]
	v_pk_mul_f32 v[126:127], v[142:143], v[126:127] op_sel_hi:[0,1]
	v_pk_mul_f32 v[128:129], v[142:143], v[128:129] op_sel_hi:[0,1]
	v_pk_mul_f32 v[130:131], v[142:143], v[130:131] op_sel_hi:[0,1]
	v_pk_mul_f32 v[116:117], v[116:117], v[32:33]
	v_pk_mul_f32 v[118:119], v[118:119], v[34:35]
	v_pk_mul_f32 v[120:121], v[120:121], v[36:37]
	v_pk_mul_f32 v[122:123], v[122:123], v[38:39]
	v_pk_mul_f32 v[124:125], v[124:125], v[40:41]
	v_pk_mul_f32 v[126:127], v[126:127], v[42:43]
	v_pk_mul_f32 v[128:129], v[128:129], v[44:45]
	v_pk_mul_f32 v[130:131], v[130:131], v[46:47]
	v_pk_fma_f32 v[116:117], v[116:117], v[84:85], v[100:101]
	v_pk_fma_f32 v[118:119], v[118:119], v[86:87], v[102:103]
	v_pk_fma_f32 v[120:121], v[120:121], v[88:89], v[104:105]
	v_pk_fma_f32 v[122:123], v[122:123], v[90:91], v[106:107]
	v_pk_fma_f32 v[124:125], v[124:125], v[92:93], v[108:109]
	v_pk_fma_f32 v[126:127], v[126:127], v[94:95], v[110:111]
	v_pk_fma_f32 v[128:129], v[128:129], v[96:97], v[112:113]
	v_pk_fma_f32 v[130:131], v[130:131], v[98:99], v[114:115]
	v_cvt_pk_bf16_f32 v164, v116, v117
	v_cvt_pk_bf16_f32 v165, v118, v119
	v_cvt_pk_bf16_f32 v166, v120, v121
	v_cvt_pk_bf16_f32 v167, v122, v123
	v_cvt_pk_bf16_f32 v168, v124, v125
	v_cvt_pk_bf16_f32 v169, v126, v127
	v_cvt_pk_bf16_f32 v170, v128, v129
	v_cvt_pk_bf16_f32 v171, v130, v131
	global_store_dwordx4 v51, v[164:167], s[26:27] offset:2048 sc1
	global_store_dwordx4 v51, v[168:171], s[26:27] offset:3072 sc1
	v_lshlrev_b32_e32 v116, 16, v16
	v_and_b32_e32 v117, 0xffff0000, v16
	v_lshlrev_b32_e32 v118, 16, v17
	v_and_b32_e32 v119, 0xffff0000, v17
	v_lshlrev_b32_e32 v120, 16, v18
	v_and_b32_e32 v121, 0xffff0000, v18
	v_lshlrev_b32_e32 v122, 16, v19
	v_and_b32_e32 v123, 0xffff0000, v19
	v_lshlrev_b32_e32 v124, 16, v20
	v_and_b32_e32 v125, 0xffff0000, v20
	v_lshlrev_b32_e32 v126, 16, v21
	v_and_b32_e32 v127, 0xffff0000, v21
	v_lshlrev_b32_e32 v128, 16, v22
	v_and_b32_e32 v129, 0xffff0000, v22
	v_lshlrev_b32_e32 v130, 16, v23
	v_and_b32_e32 v131, 0xffff0000, v23
	v_pk_mul_f32 v[116:117], v[144:145], v[116:117] op_sel_hi:[0,1]
	v_pk_mul_f32 v[118:119], v[144:145], v[118:119] op_sel_hi:[0,1]
	v_pk_mul_f32 v[120:121], v[144:145], v[120:121] op_sel_hi:[0,1]
	v_pk_mul_f32 v[122:123], v[144:145], v[122:123] op_sel_hi:[0,1]
	v_pk_mul_f32 v[124:125], v[144:145], v[124:125] op_sel_hi:[0,1]
	v_pk_mul_f32 v[126:127], v[144:145], v[126:127] op_sel_hi:[0,1]
	v_pk_mul_f32 v[128:129], v[144:145], v[128:129] op_sel_hi:[0,1]
	v_pk_mul_f32 v[130:131], v[144:145], v[130:131] op_sel_hi:[0,1]
	v_pk_mul_f32 v[116:117], v[116:117], v[32:33]
	v_pk_mul_f32 v[118:119], v[118:119], v[34:35]
	v_pk_mul_f32 v[120:121], v[120:121], v[36:37]
	v_pk_mul_f32 v[122:123], v[122:123], v[38:39]
	v_pk_mul_f32 v[124:125], v[124:125], v[40:41]
	v_pk_mul_f32 v[126:127], v[126:127], v[42:43]
	v_pk_mul_f32 v[128:129], v[128:129], v[44:45]
	v_pk_mul_f32 v[130:131], v[130:131], v[46:47]
	v_pk_fma_f32 v[116:117], v[116:117], v[84:85], v[100:101]
	v_pk_fma_f32 v[118:119], v[118:119], v[86:87], v[102:103]
	v_pk_fma_f32 v[120:121], v[120:121], v[88:89], v[104:105]
	v_pk_fma_f32 v[122:123], v[122:123], v[90:91], v[106:107]
	v_pk_fma_f32 v[124:125], v[124:125], v[92:93], v[108:109]
	v_pk_fma_f32 v[126:127], v[126:127], v[94:95], v[110:111]
	v_pk_fma_f32 v[128:129], v[128:129], v[96:97], v[112:113]
	v_pk_fma_f32 v[130:131], v[130:131], v[98:99], v[114:115]
	v_cvt_pk_bf16_f32 v172, v116, v117
	v_cvt_pk_bf16_f32 v173, v118, v119
	v_cvt_pk_bf16_f32 v174, v120, v121
	v_cvt_pk_bf16_f32 v175, v122, v123
	v_cvt_pk_bf16_f32 v176, v124, v125
	v_cvt_pk_bf16_f32 v177, v126, v127
	v_cvt_pk_bf16_f32 v178, v128, v129
	v_cvt_pk_bf16_f32 v179, v130, v131
	global_store_dwordx4 v149, v[172:175], s[26:27] sc1
	global_store_dwordx4 v149, v[176:179], s[26:27] offset:1024 sc1
	v_lshlrev_b32_e32 v116, 16, v24
	v_and_b32_e32 v117, 0xffff0000, v24
	v_lshlrev_b32_e32 v118, 16, v25
	v_and_b32_e32 v119, 0xffff0000, v25
	v_lshlrev_b32_e32 v120, 16, v26
	v_and_b32_e32 v121, 0xffff0000, v26
	v_lshlrev_b32_e32 v122, 16, v27
	v_and_b32_e32 v123, 0xffff0000, v27
	v_lshlrev_b32_e32 v124, 16, v28
	v_and_b32_e32 v125, 0xffff0000, v28
	v_lshlrev_b32_e32 v126, 16, v29
	v_and_b32_e32 v127, 0xffff0000, v29
	v_lshlrev_b32_e32 v128, 16, v30
	v_and_b32_e32 v129, 0xffff0000, v30
	v_lshlrev_b32_e32 v130, 16, v31
	v_and_b32_e32 v131, 0xffff0000, v31
	v_pk_mul_f32 v[116:117], v[146:147], v[116:117] op_sel_hi:[0,1]
	v_pk_mul_f32 v[118:119], v[146:147], v[118:119] op_sel_hi:[0,1]
	v_pk_mul_f32 v[120:121], v[146:147], v[120:121] op_sel_hi:[0,1]
	v_pk_mul_f32 v[122:123], v[146:147], v[122:123] op_sel_hi:[0,1]
	v_pk_mul_f32 v[124:125], v[146:147], v[124:125] op_sel_hi:[0,1]
	v_pk_mul_f32 v[126:127], v[146:147], v[126:127] op_sel_hi:[0,1]
	v_pk_mul_f32 v[128:129], v[146:147], v[128:129] op_sel_hi:[0,1]
	v_pk_mul_f32 v[130:131], v[146:147], v[130:131] op_sel_hi:[0,1]
	v_pk_mul_f32 v[116:117], v[116:117], v[32:33]
	v_pk_mul_f32 v[118:119], v[118:119], v[34:35]
	v_pk_mul_f32 v[120:121], v[120:121], v[36:37]
	v_pk_mul_f32 v[122:123], v[122:123], v[38:39]
	v_pk_mul_f32 v[124:125], v[124:125], v[40:41]
	v_pk_mul_f32 v[126:127], v[126:127], v[42:43]
	v_pk_mul_f32 v[128:129], v[128:129], v[44:45]
	v_pk_mul_f32 v[130:131], v[130:131], v[46:47]
	v_pk_fma_f32 v[116:117], v[116:117], v[84:85], v[100:101]
	v_pk_fma_f32 v[118:119], v[118:119], v[86:87], v[102:103]
	v_pk_fma_f32 v[120:121], v[120:121], v[88:89], v[104:105]
	v_pk_fma_f32 v[122:123], v[122:123], v[90:91], v[106:107]
	v_pk_fma_f32 v[124:125], v[124:125], v[92:93], v[108:109]
	v_pk_fma_f32 v[126:127], v[126:127], v[94:95], v[110:111]
	v_pk_fma_f32 v[128:129], v[128:129], v[96:97], v[112:113]
	v_pk_fma_f32 v[130:131], v[130:131], v[98:99], v[114:115]
	v_cvt_pk_bf16_f32 v164, v116, v117
	v_cvt_pk_bf16_f32 v165, v118, v119
	v_cvt_pk_bf16_f32 v166, v120, v121
	v_cvt_pk_bf16_f32 v167, v122, v123
	v_cvt_pk_bf16_f32 v168, v124, v125
	v_cvt_pk_bf16_f32 v169, v126, v127
	v_cvt_pk_bf16_f32 v170, v128, v129
	v_cvt_pk_bf16_f32 v171, v130, v131
	global_store_dwordx4 v149, v[164:167], s[26:27] offset:2048 sc1
	global_store_dwordx4 v149, v[168:171], s[26:27] offset:3072 sc1
	s_add_u32 s26, s26, 0x2000
	s_addc_u32 s27, s27, 0
	s_add_u32 s24, s24, 0x2000
	s_addc_u32 s25, s25, 0
	global_load_dwordx4 v[0:3], v51, s[24:25]
	global_load_dwordx4 v[4:7], v51, s[24:25] offset:1024
	global_load_dwordx4 v[8:11], v51, s[24:25] offset:2048
	global_load_dwordx4 v[12:15], v51, s[24:25] offset:3072
	global_load_dwordx4 v[16:19], v149, s[24:25]
	global_load_dwordx4 v[20:23], v149, s[24:25] offset:1024
	global_load_dwordx4 v[24:27], v149, s[24:25] offset:2048
	global_load_dwordx4 v[28:31], v149, s[24:25] offset:3072
	s_waitcnt vmcnt(16)
	v_lshlrev_b32_e32 v116, 16, v52
	v_and_b32_e32 v117, 0xffff0000, v52
	v_lshlrev_b32_e32 v118, 16, v53
	v_and_b32_e32 v119, 0xffff0000, v53
	v_lshlrev_b32_e32 v120, 16, v54
	v_and_b32_e32 v121, 0xffff0000, v54
	v_lshlrev_b32_e32 v122, 16, v55
	v_and_b32_e32 v123, 0xffff0000, v55
	v_lshlrev_b32_e32 v124, 16, v56
	v_and_b32_e32 v125, 0xffff0000, v56
	v_lshlrev_b32_e32 v126, 16, v57
	v_and_b32_e32 v127, 0xffff0000, v57
	v_lshlrev_b32_e32 v128, 16, v58
	v_and_b32_e32 v129, 0xffff0000, v58
	v_lshlrev_b32_e32 v130, 16, v59
	v_and_b32_e32 v131, 0xffff0000, v59
	v_pk_mul_f32 v[132:133], v[116:117], v[116:117]
	v_pk_fma_f32 v[132:133], v[118:119], v[118:119], v[132:133]
	v_pk_fma_f32 v[132:133], v[120:121], v[120:121], v[132:133]
	v_pk_fma_f32 v[132:133], v[122:123], v[122:123], v[132:133]
	v_pk_fma_f32 v[132:133], v[124:125], v[124:125], v[132:133]
	v_pk_fma_f32 v[132:133], v[126:127], v[126:127], v[132:133]
	v_pk_fma_f32 v[132:133], v[128:129], v[128:129], v[132:133]
	v_pk_fma_f32 v[132:133], v[130:131], v[130:131], v[132:133]
	v_lshlrev_b32_e32 v116, 16, v60
	v_and_b32_e32 v117, 0xffff0000, v60
	v_lshlrev_b32_e32 v118, 16, v61
	v_and_b32_e32 v119, 0xffff0000, v61
	v_lshlrev_b32_e32 v120, 16, v62
	v_and_b32_e32 v121, 0xffff0000, v62
	v_lshlrev_b32_e32 v122, 16, v63
	v_and_b32_e32 v123, 0xffff0000, v63
	v_lshlrev_b32_e32 v124, 16, v64
	v_and_b32_e32 v125, 0xffff0000, v64
	v_lshlrev_b32_e32 v126, 16, v65
	v_and_b32_e32 v127, 0xffff0000, v65
	v_lshlrev_b32_e32 v128, 16, v66
	v_and_b32_e32 v129, 0xffff0000, v66
	v_lshlrev_b32_e32 v130, 16, v67
	v_and_b32_e32 v131, 0xffff0000, v67
	v_pk_mul_f32 v[134:135], v[116:117], v[116:117]
	v_pk_fma_f32 v[134:135], v[118:119], v[118:119], v[134:135]
	v_pk_fma_f32 v[134:135], v[120:121], v[120:121], v[134:135]
	v_pk_fma_f32 v[134:135], v[122:123], v[122:123], v[134:135]
	v_pk_fma_f32 v[134:135], v[124:125], v[124:125], v[134:135]
	v_pk_fma_f32 v[134:135], v[126:127], v[126:127], v[134:135]
	v_pk_fma_f32 v[134:135], v[128:129], v[128:129], v[134:135]
	v_pk_fma_f32 v[134:135], v[130:131], v[130:131], v[134:135]
	v_lshlrev_b32_e32 v116, 16, v68
	v_and_b32_e32 v117, 0xffff0000, v68
	v_lshlrev_b32_e32 v118, 16, v69
	v_and_b32_e32 v119, 0xffff0000, v69
	v_lshlrev_b32_e32 v120, 16, v70
	v_and_b32_e32 v121, 0xffff0000, v70
	v_lshlrev_b32_e32 v122, 16, v71
	v_and_b32_e32 v123, 0xffff0000, v71
	v_lshlrev_b32_e32 v124, 16, v72
	v_and_b32_e32 v125, 0xffff0000, v72
	v_lshlrev_b32_e32 v126, 16, v73
	v_and_b32_e32 v127, 0xffff0000, v73
	v_lshlrev_b32_e32 v128, 16, v74
	v_and_b32_e32 v129, 0xffff0000, v74
	v_lshlrev_b32_e32 v130, 16, v75
	v_and_b32_e32 v131, 0xffff0000, v75
	v_pk_mul_f32 v[136:137], v[116:117], v[116:117]
	v_pk_fma_f32 v[136:137], v[118:119], v[118:119], v[136:137]
	v_pk_fma_f32 v[136:137], v[120:121], v[120:121], v[136:137]
	v_pk_fma_f32 v[136:137], v[122:123], v[122:123], v[136:137]
	v_pk_fma_f32 v[136:137], v[124:125], v[124:125], v[136:137]
	v_pk_fma_f32 v[136:137], v[126:127], v[126:127], v[136:137]
	v_pk_fma_f32 v[136:137], v[128:129], v[128:129], v[136:137]
	v_pk_fma_f32 v[136:137], v[130:131], v[130:131], v[136:137]
	v_lshlrev_b32_e32 v116, 16, v76
	v_and_b32_e32 v117, 0xffff0000, v76
	v_lshlrev_b32_e32 v118, 16, v77
	v_and_b32_e32 v119, 0xffff0000, v77
	v_lshlrev_b32_e32 v120, 16, v78
	v_and_b32_e32 v121, 0xffff0000, v78
	v_lshlrev_b32_e32 v122, 16, v79
	v_and_b32_e32 v123, 0xffff0000, v79
	v_lshlrev_b32_e32 v124, 16, v80
	v_and_b32_e32 v125, 0xffff0000, v80
	v_lshlrev_b32_e32 v126, 16, v81
	v_and_b32_e32 v127, 0xffff0000, v81
	v_lshlrev_b32_e32 v128, 16, v82
	v_and_b32_e32 v129, 0xffff0000, v82
	v_lshlrev_b32_e32 v130, 16, v83
	v_and_b32_e32 v131, 0xffff0000, v83
	v_pk_mul_f32 v[138:139], v[116:117], v[116:117]
	v_pk_fma_f32 v[138:139], v[118:119], v[118:119], v[138:139]
	v_pk_fma_f32 v[138:139], v[120:121], v[120:121], v[138:139]
	v_pk_fma_f32 v[138:139], v[122:123], v[122:123], v[138:139]
	v_pk_fma_f32 v[138:139], v[124:125], v[124:125], v[138:139]
	v_pk_fma_f32 v[138:139], v[126:127], v[126:127], v[138:139]
	v_pk_fma_f32 v[138:139], v[128:129], v[128:129], v[138:139]
	v_pk_fma_f32 v[138:139], v[130:131], v[130:131], v[138:139]
	v_add_f32_e32 v132, v132, v133
	v_add_f32_e32 v134, v134, v135
	v_add_f32_e32 v136, v136, v137
	v_add_f32_e32 v138, v138, v139
	s_nop 1
	v_add_f32_dpp v132, v132, v132 row_shr:1 row_mask:0xf bank_mask:0xf bound_ctrl:1
	v_add_f32_dpp v134, v134, v134 row_shr:1 row_mask:0xf bank_mask:0xf bound_ctrl:1
	v_add_f32_dpp v136, v136, v136 row_shr:1 row_mask:0xf bank_mask:0xf bound_ctrl:1
	v_add_f32_dpp v138, v138, v138 row_shr:1 row_mask:0xf bank_mask:0xf bound_ctrl:1
	v_add_f32_dpp v132, v132, v132 row_shr:2 row_mask:0xf bank_mask:0xf bound_ctrl:1
	v_add_f32_dpp v134, v134, v134 row_shr:2 row_mask:0xf bank_mask:0xf bound_ctrl:1
	v_add_f32_dpp v136, v136, v136 row_shr:2 row_mask:0xf bank_mask:0xf bound_ctrl:1
	v_add_f32_dpp v138, v138, v138 row_shr:2 row_mask:0xf bank_mask:0xf bound_ctrl:1
	v_add_f32_dpp v132, v132, v132 row_shr:4 row_mask:0xf bank_mask:0xf bound_ctrl:1
	v_add_f32_dpp v134, v134, v134 row_shr:4 row_mask:0xf bank_mask:0xf bound_ctrl:1
	v_add_f32_dpp v136, v136, v136 row_shr:4 row_mask:0xf bank_mask:0xf bound_ctrl:1
	v_add_f32_dpp v138, v138, v138 row_shr:4 row_mask:0xf bank_mask:0xf bound_ctrl:1
	v_add_f32_dpp v132, v132, v132 row_shr:8 row_mask:0xf bank_mask:0xf bound_ctrl:1
	v_add_f32_dpp v134, v134, v134 row_shr:8 row_mask:0xf bank_mask:0xf bound_ctrl:1
	v_add_f32_dpp v136, v136, v136 row_shr:8 row_mask:0xf bank_mask:0xf bound_ctrl:1
	v_add_f32_dpp v138, v138, v138 row_shr:8 row_mask:0xf bank_mask:0xf bound_ctrl:1
	v_add_f32_dpp v132, v132, v132 row_bcast:15 row_mask:0xa bank_mask:0xf
	v_add_f32_dpp v134, v134, v134 row_bcast:15 row_mask:0xa bank_mask:0xf
	v_add_f32_dpp v136, v136, v136 row_bcast:15 row_mask:0xa bank_mask:0xf
	v_add_f32_dpp v138, v138, v138 row_bcast:15 row_mask:0xa bank_mask:0xf
	v_add_f32_dpp v132, v132, v132 row_bcast:31 row_mask:0xc bank_mask:0xf
	v_add_f32_dpp v134, v134, v134 row_bcast:31 row_mask:0xc bank_mask:0xf
	v_add_f32_dpp v136, v136, v136 row_bcast:31 row_mask:0xc bank_mask:0xf
	v_add_f32_dpp v138, v138, v138 row_bcast:31 row_mask:0xc bank_mask:0xf
	s_nop 1
	v_readlane_b32 s32, v132, 63
	v_readlane_b32 s28, v134, 63
	v_readlane_b32 s29, v136, 63
	v_readlane_b32 s30, v138, 63
	s_nop 1
	v_mov_b32_e32 v140, s32
	v_mov_b32_e32 v142, s28
	v_mov_b32_e32 v144, s29
	v_mov_b32_e32 v146, s30
	v_fmaak_f32 v140, v140, v50, 0x358637bd
	v_fmaak_f32 v142, v142, v50, 0x358637bd
	v_fmaak_f32 v144, v144, v50, 0x358637bd
	v_fmaak_f32 v146, v146, v50, 0x358637bd
	v_rsq_f32_e32 v140, v140
	v_rsq_f32_e32 v142, v142
	v_rsq_f32_e32 v144, v144
	v_rsq_f32_e32 v146, v146
	s_nop 0
	v_lshlrev_b32_e32 v116, 16, v52
	v_and_b32_e32 v117, 0xffff0000, v52
	v_lshlrev_b32_e32 v118, 16, v53
	v_and_b32_e32 v119, 0xffff0000, v53
	v_lshlrev_b32_e32 v120, 16, v54
	v_and_b32_e32 v121, 0xffff0000, v54
	v_lshlrev_b32_e32 v122, 16, v55
	v_and_b32_e32 v123, 0xffff0000, v55
	v_lshlrev_b32_e32 v124, 16, v56
	v_and_b32_e32 v125, 0xffff0000, v56
	v_lshlrev_b32_e32 v126, 16, v57
	v_and_b32_e32 v127, 0xffff0000, v57
	v_lshlrev_b32_e32 v128, 16, v58
	v_and_b32_e32 v129, 0xffff0000, v58
	v_lshlrev_b32_e32 v130, 16, v59
	v_and_b32_e32 v131, 0xffff0000, v59
	v_pk_mul_f32 v[116:117], v[140:141], v[116:117] op_sel_hi:[0,1]
	v_pk_mul_f32 v[118:119], v[140:141], v[118:119] op_sel_hi:[0,1]
	v_pk_mul_f32 v[120:121], v[140:141], v[120:121] op_sel_hi:[0,1]
	v_pk_mul_f32 v[122:123], v[140:141], v[122:123] op_sel_hi:[0,1]
	v_pk_mul_f32 v[124:125], v[140:141], v[124:125] op_sel_hi:[0,1]
	v_pk_mul_f32 v[126:127], v[140:141], v[126:127] op_sel_hi:[0,1]
	v_pk_mul_f32 v[128:129], v[140:141], v[128:129] op_sel_hi:[0,1]
	v_pk_mul_f32 v[130:131], v[140:141], v[130:131] op_sel_hi:[0,1]
	v_pk_mul_f32 v[116:117], v[116:117], v[32:33]
	v_pk_mul_f32 v[118:119], v[118:119], v[34:35]
	v_pk_mul_f32 v[120:121], v[120:121], v[36:37]
	v_pk_mul_f32 v[122:123], v[122:123], v[38:39]
	v_pk_mul_f32 v[124:125], v[124:125], v[40:41]
	v_pk_mul_f32 v[126:127], v[126:127], v[42:43]
	v_pk_mul_f32 v[128:129], v[128:129], v[44:45]
	v_pk_mul_f32 v[130:131], v[130:131], v[46:47]
	v_pk_fma_f32 v[116:117], v[116:117], v[84:85], v[100:101]
	v_pk_fma_f32 v[118:119], v[118:119], v[86:87], v[102:103]
	v_pk_fma_f32 v[120:121], v[120:121], v[88:89], v[104:105]
	v_pk_fma_f32 v[122:123], v[122:123], v[90:91], v[106:107]
	v_pk_fma_f32 v[124:125], v[124:125], v[92:93], v[108:109]
	v_pk_fma_f32 v[126:127], v[126:127], v[94:95], v[110:111]
	v_pk_fma_f32 v[128:129], v[128:129], v[96:97], v[112:113]
	v_pk_fma_f32 v[130:131], v[130:131], v[98:99], v[114:115]
	v_cvt_pk_bf16_f32 v164, v116, v117
	v_cvt_pk_bf16_f32 v165, v118, v119
	v_cvt_pk_bf16_f32 v166, v120, v121
	v_cvt_pk_bf16_f32 v167, v122, v123
	v_cvt_pk_bf16_f32 v168, v124, v125
	v_cvt_pk_bf16_f32 v169, v126, v127
	v_cvt_pk_bf16_f32 v170, v128, v129
	v_cvt_pk_bf16_f32 v171, v130, v131
	global_store_dwordx4 v51, v[164:167], s[26:27] sc1
	global_store_dwordx4 v51, v[168:171], s[26:27] offset:1024 sc1
	v_lshlrev_b32_e32 v116, 16, v60
	v_and_b32_e32 v117, 0xffff0000, v60
	v_lshlrev_b32_e32 v118, 16, v61
	v_and_b32_e32 v119, 0xffff0000, v61
	v_lshlrev_b32_e32 v120, 16, v62
	v_and_b32_e32 v121, 0xffff0000, v62
	v_lshlrev_b32_e32 v122, 16, v63
	v_and_b32_e32 v123, 0xffff0000, v63
	v_lshlrev_b32_e32 v124, 16, v64
	v_and_b32_e32 v125, 0xffff0000, v64
	v_lshlrev_b32_e32 v126, 16, v65
	v_and_b32_e32 v127, 0xffff0000, v65
	v_lshlrev_b32_e32 v128, 16, v66
	v_and_b32_e32 v129, 0xffff0000, v66
	v_lshlrev_b32_e32 v130, 16, v67
	v_and_b32_e32 v131, 0xffff0000, v67
	v_pk_mul_f32 v[116:117], v[142:143], v[116:117] op_sel_hi:[0,1]
	v_pk_mul_f32 v[118:119], v[142:143], v[118:119] op_sel_hi:[0,1]
	v_pk_mul_f32 v[120:121], v[142:143], v[120:121] op_sel_hi:[0,1]
	v_pk_mul_f32 v[122:123], v[142:143], v[122:123] op_sel_hi:[0,1]
	v_pk_mul_f32 v[124:125], v[142:143], v[124:125] op_sel_hi:[0,1]
	v_pk_mul_f32 v[126:127], v[142:143], v[126:127] op_sel_hi:[0,1]
	v_pk_mul_f32 v[128:129], v[142:143], v[128:129] op_sel_hi:[0,1]
	v_pk_mul_f32 v[130:131], v[142:143], v[130:131] op_sel_hi:[0,1]
	v_pk_mul_f32 v[116:117], v[116:117], v[32:33]
	v_pk_mul_f32 v[118:119], v[118:119], v[34:35]
	v_pk_mul_f32 v[120:121], v[120:121], v[36:37]
	v_pk_mul_f32 v[122:123], v[122:123], v[38:39]
	v_pk_mul_f32 v[124:125], v[124:125], v[40:41]
	v_pk_mul_f32 v[126:127], v[126:127], v[42:43]
	v_pk_mul_f32 v[128:129], v[128:129], v[44:45]
	v_pk_mul_f32 v[130:131], v[130:131], v[46:47]
	v_pk_fma_f32 v[116:117], v[116:117], v[84:85], v[100:101]
	v_pk_fma_f32 v[118:119], v[118:119], v[86:87], v[102:103]
	v_pk_fma_f32 v[120:121], v[120:121], v[88:89], v[104:105]
	v_pk_fma_f32 v[122:123], v[122:123], v[90:91], v[106:107]
	v_pk_fma_f32 v[124:125], v[124:125], v[92:93], v[108:109]
	v_pk_fma_f32 v[126:127], v[126:127], v[94:95], v[110:111]
	v_pk_fma_f32 v[128:129], v[128:129], v[96:97], v[112:113]
	v_pk_fma_f32 v[130:131], v[130:131], v[98:99], v[114:115]
	v_cvt_pk_bf16_f32 v172, v116, v117
	v_cvt_pk_bf16_f32 v173, v118, v119
	v_cvt_pk_bf16_f32 v174, v120, v121
	v_cvt_pk_bf16_f32 v175, v122, v123
	v_cvt_pk_bf16_f32 v176, v124, v125
	v_cvt_pk_bf16_f32 v177, v126, v127
	v_cvt_pk_bf16_f32 v178, v128, v129
	v_cvt_pk_bf16_f32 v179, v130, v131
	global_store_dwordx4 v51, v[172:175], s[26:27] offset:2048 sc1
	global_store_dwordx4 v51, v[176:179], s[26:27] offset:3072 sc1
	v_lshlrev_b32_e32 v116, 16, v68
	v_and_b32_e32 v117, 0xffff0000, v68
	v_lshlrev_b32_e32 v118, 16, v69
	v_and_b32_e32 v119, 0xffff0000, v69
	v_lshlrev_b32_e32 v120, 16, v70
	v_and_b32_e32 v121, 0xffff0000, v70
	v_lshlrev_b32_e32 v122, 16, v71
	v_and_b32_e32 v123, 0xffff0000, v71
	v_lshlrev_b32_e32 v124, 16, v72
	v_and_b32_e32 v125, 0xffff0000, v72
	v_lshlrev_b32_e32 v126, 16, v73
	v_and_b32_e32 v127, 0xffff0000, v73
	v_lshlrev_b32_e32 v128, 16, v74
	v_and_b32_e32 v129, 0xffff0000, v74
	v_lshlrev_b32_e32 v130, 16, v75
	v_and_b32_e32 v131, 0xffff0000, v75
	v_pk_mul_f32 v[116:117], v[144:145], v[116:117] op_sel_hi:[0,1]
	v_pk_mul_f32 v[118:119], v[144:145], v[118:119] op_sel_hi:[0,1]
	v_pk_mul_f32 v[120:121], v[144:145], v[120:121] op_sel_hi:[0,1]
	v_pk_mul_f32 v[122:123], v[144:145], v[122:123] op_sel_hi:[0,1]
	v_pk_mul_f32 v[124:125], v[144:145], v[124:125] op_sel_hi:[0,1]
	v_pk_mul_f32 v[126:127], v[144:145], v[126:127] op_sel_hi:[0,1]
	v_pk_mul_f32 v[128:129], v[144:145], v[128:129] op_sel_hi:[0,1]
	v_pk_mul_f32 v[130:131], v[144:145], v[130:131] op_sel_hi:[0,1]
	v_pk_mul_f32 v[116:117], v[116:117], v[32:33]
	v_pk_mul_f32 v[118:119], v[118:119], v[34:35]
	v_pk_mul_f32 v[120:121], v[120:121], v[36:37]
	v_pk_mul_f32 v[122:123], v[122:123], v[38:39]
	v_pk_mul_f32 v[124:125], v[124:125], v[40:41]
	v_pk_mul_f32 v[126:127], v[126:127], v[42:43]
	v_pk_mul_f32 v[128:129], v[128:129], v[44:45]
	v_pk_mul_f32 v[130:131], v[130:131], v[46:47]
	v_pk_fma_f32 v[116:117], v[116:117], v[84:85], v[100:101]
	v_pk_fma_f32 v[118:119], v[118:119], v[86:87], v[102:103]
	v_pk_fma_f32 v[120:121], v[120:121], v[88:89], v[104:105]
	v_pk_fma_f32 v[122:123], v[122:123], v[90:91], v[106:107]
	v_pk_fma_f32 v[124:125], v[124:125], v[92:93], v[108:109]
	v_pk_fma_f32 v[126:127], v[126:127], v[94:95], v[110:111]
	v_pk_fma_f32 v[128:129], v[128:129], v[96:97], v[112:113]
	v_pk_fma_f32 v[130:131], v[130:131], v[98:99], v[114:115]
	v_cvt_pk_bf16_f32 v164, v116, v117
	v_cvt_pk_bf16_f32 v165, v118, v119
	v_cvt_pk_bf16_f32 v166, v120, v121
	v_cvt_pk_bf16_f32 v167, v122, v123
	v_cvt_pk_bf16_f32 v168, v124, v125
	v_cvt_pk_bf16_f32 v169, v126, v127
	v_cvt_pk_bf16_f32 v170, v128, v129
	v_cvt_pk_bf16_f32 v171, v130, v131
	global_store_dwordx4 v149, v[164:167], s[26:27] sc1
	global_store_dwordx4 v149, v[168:171], s[26:27] offset:1024 sc1
	v_lshlrev_b32_e32 v116, 16, v76
	v_and_b32_e32 v117, 0xffff0000, v76
	v_lshlrev_b32_e32 v118, 16, v77
	v_and_b32_e32 v119, 0xffff0000, v77
	v_lshlrev_b32_e32 v120, 16, v78
	v_and_b32_e32 v121, 0xffff0000, v78
	v_lshlrev_b32_e32 v122, 16, v79
	v_and_b32_e32 v123, 0xffff0000, v79
	v_lshlrev_b32_e32 v124, 16, v80
	v_and_b32_e32 v125, 0xffff0000, v80
	v_lshlrev_b32_e32 v126, 16, v81
	v_and_b32_e32 v127, 0xffff0000, v81
	v_lshlrev_b32_e32 v128, 16, v82
	v_and_b32_e32 v129, 0xffff0000, v82
	v_lshlrev_b32_e32 v130, 16, v83
	v_and_b32_e32 v131, 0xffff0000, v83
	v_pk_mul_f32 v[116:117], v[146:147], v[116:117] op_sel_hi:[0,1]
	v_pk_mul_f32 v[118:119], v[146:147], v[118:119] op_sel_hi:[0,1]
	v_pk_mul_f32 v[120:121], v[146:147], v[120:121] op_sel_hi:[0,1]
	v_pk_mul_f32 v[122:123], v[146:147], v[122:123] op_sel_hi:[0,1]
	v_pk_mul_f32 v[124:125], v[146:147], v[124:125] op_sel_hi:[0,1]
	v_pk_mul_f32 v[126:127], v[146:147], v[126:127] op_sel_hi:[0,1]
	v_pk_mul_f32 v[128:129], v[146:147], v[128:129] op_sel_hi:[0,1]
	v_pk_mul_f32 v[130:131], v[146:147], v[130:131] op_sel_hi:[0,1]
	v_pk_mul_f32 v[116:117], v[116:117], v[32:33]
	v_pk_mul_f32 v[118:119], v[118:119], v[34:35]
	v_pk_mul_f32 v[120:121], v[120:121], v[36:37]
	v_pk_mul_f32 v[122:123], v[122:123], v[38:39]
	v_pk_mul_f32 v[124:125], v[124:125], v[40:41]
	v_pk_mul_f32 v[126:127], v[126:127], v[42:43]
	v_pk_mul_f32 v[128:129], v[128:129], v[44:45]
	v_pk_mul_f32 v[130:131], v[130:131], v[46:47]
	v_pk_fma_f32 v[116:117], v[116:117], v[84:85], v[100:101]
	v_pk_fma_f32 v[118:119], v[118:119], v[86:87], v[102:103]
	v_pk_fma_f32 v[120:121], v[120:121], v[88:89], v[104:105]
	v_pk_fma_f32 v[122:123], v[122:123], v[90:91], v[106:107]
	v_pk_fma_f32 v[124:125], v[124:125], v[92:93], v[108:109]
	v_pk_fma_f32 v[126:127], v[126:127], v[94:95], v[110:111]
	v_pk_fma_f32 v[128:129], v[128:129], v[96:97], v[112:113]
	v_pk_fma_f32 v[130:131], v[130:131], v[98:99], v[114:115]
	v_cvt_pk_bf16_f32 v172, v116, v117
	v_cvt_pk_bf16_f32 v173, v118, v119
	v_cvt_pk_bf16_f32 v174, v120, v121
	v_cvt_pk_bf16_f32 v175, v122, v123
	v_cvt_pk_bf16_f32 v176, v124, v125
	v_cvt_pk_bf16_f32 v177, v126, v127
	v_cvt_pk_bf16_f32 v178, v128, v129
	v_cvt_pk_bf16_f32 v179, v130, v131
	global_store_dwordx4 v149, v[172:175], s[26:27] offset:2048 sc1
	global_store_dwordx4 v149, v[176:179], s[26:27] offset:3072 sc1
	s_add_u32 s26, s26, 0x2000
	s_addc_u32 s27, s27, 0
	s_add_u32 s24, s24, 0x2000
	s_addc_u32 s25, s25, 0
	global_load_dwordx4 v[52:55], v51, s[24:25]
	global_load_dwordx4 v[56:59], v51, s[24:25] offset:1024
	global_load_dwordx4 v[60:63], v51, s[24:25] offset:2048
	global_load_dwordx4 v[64:67], v51, s[24:25] offset:3072
	global_load_dwordx4 v[68:71], v149, s[24:25]
	global_load_dwordx4 v[72:75], v149, s[24:25] offset:1024
	global_load_dwordx4 v[76:79], v149, s[24:25] offset:2048
	global_load_dwordx4 v[80:83], v149, s[24:25] offset:3072
	s_waitcnt vmcnt(16)
	v_lshlrev_b32_e32 v116, 16, v0
	v_and_b32_e32 v117, 0xffff0000, v0
	v_lshlrev_b32_e32 v118, 16, v1
	v_and_b32_e32 v119, 0xffff0000, v1
	v_lshlrev_b32_e32 v120, 16, v2
	v_and_b32_e32 v121, 0xffff0000, v2
	v_lshlrev_b32_e32 v122, 16, v3
	v_and_b32_e32 v123, 0xffff0000, v3
	v_lshlrev_b32_e32 v124, 16, v4
	v_and_b32_e32 v125, 0xffff0000, v4
	v_lshlrev_b32_e32 v126, 16, v5
	v_and_b32_e32 v127, 0xffff0000, v5
	v_lshlrev_b32_e32 v128, 16, v6
	v_and_b32_e32 v129, 0xffff0000, v6
	v_lshlrev_b32_e32 v130, 16, v7
	v_and_b32_e32 v131, 0xffff0000, v7
	v_pk_mul_f32 v[132:133], v[116:117], v[116:117]
	v_pk_fma_f32 v[132:133], v[118:119], v[118:119], v[132:133]
	v_pk_fma_f32 v[132:133], v[120:121], v[120:121], v[132:133]
	v_pk_fma_f32 v[132:133], v[122:123], v[122:123], v[132:133]
	v_pk_fma_f32 v[132:133], v[124:125], v[124:125], v[132:133]
	v_pk_fma_f32 v[132:133], v[126:127], v[126:127], v[132:133]
	v_pk_fma_f32 v[132:133], v[128:129], v[128:129], v[132:133]
	v_pk_fma_f32 v[132:133], v[130:131], v[130:131], v[132:133]
	v_lshlrev_b32_e32 v116, 16, v8
	v_and_b32_e32 v117, 0xffff0000, v8
	v_lshlrev_b32_e32 v118, 16, v9
	v_and_b32_e32 v119, 0xffff0000, v9
	v_lshlrev_b32_e32 v120, 16, v10
	v_and_b32_e32 v121, 0xffff0000, v10
	v_lshlrev_b32_e32 v122, 16, v11
	v_and_b32_e32 v123, 0xffff0000, v11
	v_lshlrev_b32_e32 v124, 16, v12
	v_and_b32_e32 v125, 0xffff0000, v12
	v_lshlrev_b32_e32 v126, 16, v13
	v_and_b32_e32 v127, 0xffff0000, v13
	v_lshlrev_b32_e32 v128, 16, v14
	v_and_b32_e32 v129, 0xffff0000, v14
	v_lshlrev_b32_e32 v130, 16, v15
	v_and_b32_e32 v131, 0xffff0000, v15
	v_pk_mul_f32 v[134:135], v[116:117], v[116:117]
	v_pk_fma_f32 v[134:135], v[118:119], v[118:119], v[134:135]
	v_pk_fma_f32 v[134:135], v[120:121], v[120:121], v[134:135]
	v_pk_fma_f32 v[134:135], v[122:123], v[122:123], v[134:135]
	v_pk_fma_f32 v[134:135], v[124:125], v[124:125], v[134:135]
	v_pk_fma_f32 v[134:135], v[126:127], v[126:127], v[134:135]
	v_pk_fma_f32 v[134:135], v[128:129], v[128:129], v[134:135]
	v_pk_fma_f32 v[134:135], v[130:131], v[130:131], v[134:135]
	v_lshlrev_b32_e32 v116, 16, v16
	v_and_b32_e32 v117, 0xffff0000, v16
	v_lshlrev_b32_e32 v118, 16, v17
	v_and_b32_e32 v119, 0xffff0000, v17
	v_lshlrev_b32_e32 v120, 16, v18
	v_and_b32_e32 v121, 0xffff0000, v18
	v_lshlrev_b32_e32 v122, 16, v19
	v_and_b32_e32 v123, 0xffff0000, v19
	v_lshlrev_b32_e32 v124, 16, v20
	v_and_b32_e32 v125, 0xffff0000, v20
	v_lshlrev_b32_e32 v126, 16, v21
	v_and_b32_e32 v127, 0xffff0000, v21
	v_lshlrev_b32_e32 v128, 16, v22
	v_and_b32_e32 v129, 0xffff0000, v22
	v_lshlrev_b32_e32 v130, 16, v23
	v_and_b32_e32 v131, 0xffff0000, v23
	v_pk_mul_f32 v[136:137], v[116:117], v[116:117]
	v_pk_fma_f32 v[136:137], v[118:119], v[118:119], v[136:137]
	v_pk_fma_f32 v[136:137], v[120:121], v[120:121], v[136:137]
	v_pk_fma_f32 v[136:137], v[122:123], v[122:123], v[136:137]
	v_pk_fma_f32 v[136:137], v[124:125], v[124:125], v[136:137]
	v_pk_fma_f32 v[136:137], v[126:127], v[126:127], v[136:137]
	v_pk_fma_f32 v[136:137], v[128:129], v[128:129], v[136:137]
	v_pk_fma_f32 v[136:137], v[130:131], v[130:131], v[136:137]
	v_lshlrev_b32_e32 v116, 16, v24
	v_and_b32_e32 v117, 0xffff0000, v24
	v_lshlrev_b32_e32 v118, 16, v25
	v_and_b32_e32 v119, 0xffff0000, v25
	v_lshlrev_b32_e32 v120, 16, v26
	v_and_b32_e32 v121, 0xffff0000, v26
	v_lshlrev_b32_e32 v122, 16, v27
	v_and_b32_e32 v123, 0xffff0000, v27
	v_lshlrev_b32_e32 v124, 16, v28
	v_and_b32_e32 v125, 0xffff0000, v28
	v_lshlrev_b32_e32 v126, 16, v29
	v_and_b32_e32 v127, 0xffff0000, v29
	v_lshlrev_b32_e32 v128, 16, v30
	v_and_b32_e32 v129, 0xffff0000, v30
	v_lshlrev_b32_e32 v130, 16, v31
	v_and_b32_e32 v131, 0xffff0000, v31
	v_pk_mul_f32 v[138:139], v[116:117], v[116:117]
	v_pk_fma_f32 v[138:139], v[118:119], v[118:119], v[138:139]
	v_pk_fma_f32 v[138:139], v[120:121], v[120:121], v[138:139]
	v_pk_fma_f32 v[138:139], v[122:123], v[122:123], v[138:139]
	v_pk_fma_f32 v[138:139], v[124:125], v[124:125], v[138:139]
	v_pk_fma_f32 v[138:139], v[126:127], v[126:127], v[138:139]
	v_pk_fma_f32 v[138:139], v[128:129], v[128:129], v[138:139]
	v_pk_fma_f32 v[138:139], v[130:131], v[130:131], v[138:139]
	v_add_f32_e32 v132, v132, v133
	v_add_f32_e32 v134, v134, v135
	v_add_f32_e32 v136, v136, v137
	v_add_f32_e32 v138, v138, v139
	s_nop 1
	v_add_f32_dpp v132, v132, v132 row_shr:1 row_mask:0xf bank_mask:0xf bound_ctrl:1
	v_add_f32_dpp v134, v134, v134 row_shr:1 row_mask:0xf bank_mask:0xf bound_ctrl:1
	v_add_f32_dpp v136, v136, v136 row_shr:1 row_mask:0xf bank_mask:0xf bound_ctrl:1
	v_add_f32_dpp v138, v138, v138 row_shr:1 row_mask:0xf bank_mask:0xf bound_ctrl:1
	v_add_f32_dpp v132, v132, v132 row_shr:2 row_mask:0xf bank_mask:0xf bound_ctrl:1
	v_add_f32_dpp v134, v134, v134 row_shr:2 row_mask:0xf bank_mask:0xf bound_ctrl:1
	v_add_f32_dpp v136, v136, v136 row_shr:2 row_mask:0xf bank_mask:0xf bound_ctrl:1
	v_add_f32_dpp v138, v138, v138 row_shr:2 row_mask:0xf bank_mask:0xf bound_ctrl:1
	v_add_f32_dpp v132, v132, v132 row_shr:4 row_mask:0xf bank_mask:0xf bound_ctrl:1
	v_add_f32_dpp v134, v134, v134 row_shr:4 row_mask:0xf bank_mask:0xf bound_ctrl:1
	v_add_f32_dpp v136, v136, v136 row_shr:4 row_mask:0xf bank_mask:0xf bound_ctrl:1
	v_add_f32_dpp v138, v138, v138 row_shr:4 row_mask:0xf bank_mask:0xf bound_ctrl:1
	v_add_f32_dpp v132, v132, v132 row_shr:8 row_mask:0xf bank_mask:0xf bound_ctrl:1
	v_add_f32_dpp v134, v134, v134 row_shr:8 row_mask:0xf bank_mask:0xf bound_ctrl:1
	v_add_f32_dpp v136, v136, v136 row_shr:8 row_mask:0xf bank_mask:0xf bound_ctrl:1
	v_add_f32_dpp v138, v138, v138 row_shr:8 row_mask:0xf bank_mask:0xf bound_ctrl:1
	v_add_f32_dpp v132, v132, v132 row_bcast:15 row_mask:0xa bank_mask:0xf
	v_add_f32_dpp v134, v134, v134 row_bcast:15 row_mask:0xa bank_mask:0xf
	v_add_f32_dpp v136, v136, v136 row_bcast:15 row_mask:0xa bank_mask:0xf
	v_add_f32_dpp v138, v138, v138 row_bcast:15 row_mask:0xa bank_mask:0xf
	v_add_f32_dpp v132, v132, v132 row_bcast:31 row_mask:0xc bank_mask:0xf
	v_add_f32_dpp v134, v134, v134 row_bcast:31 row_mask:0xc bank_mask:0xf
	v_add_f32_dpp v136, v136, v136 row_bcast:31 row_mask:0xc bank_mask:0xf
	v_add_f32_dpp v138, v138, v138 row_bcast:31 row_mask:0xc bank_mask:0xf
	s_nop 1
	v_readlane_b32 s32, v132, 63
	v_readlane_b32 s28, v134, 63
	v_readlane_b32 s29, v136, 63
	v_readlane_b32 s30, v138, 63
	s_nop 1
	v_mov_b32_e32 v140, s32
	v_mov_b32_e32 v142, s28
	v_mov_b32_e32 v144, s29
	v_mov_b32_e32 v146, s30
	v_fmaak_f32 v140, v140, v50, 0x358637bd
	v_fmaak_f32 v142, v142, v50, 0x358637bd
	v_fmaak_f32 v144, v144, v50, 0x358637bd
	v_fmaak_f32 v146, v146, v50, 0x358637bd
	v_rsq_f32_e32 v140, v140
	v_rsq_f32_e32 v142, v142
	v_rsq_f32_e32 v144, v144
	v_rsq_f32_e32 v146, v146
	s_nop 0
	v_lshlrev_b32_e32 v116, 16, v0
	v_and_b32_e32 v117, 0xffff0000, v0
	v_lshlrev_b32_e32 v118, 16, v1
	v_and_b32_e32 v119, 0xffff0000, v1
	v_lshlrev_b32_e32 v120, 16, v2
	v_and_b32_e32 v121, 0xffff0000, v2
	v_lshlrev_b32_e32 v122, 16, v3
	v_and_b32_e32 v123, 0xffff0000, v3
	v_lshlrev_b32_e32 v124, 16, v4
	v_and_b32_e32 v125, 0xffff0000, v4
	v_lshlrev_b32_e32 v126, 16, v5
	v_and_b32_e32 v127, 0xffff0000, v5
	v_lshlrev_b32_e32 v128, 16, v6
	v_and_b32_e32 v129, 0xffff0000, v6
	v_lshlrev_b32_e32 v130, 16, v7
	v_and_b32_e32 v131, 0xffff0000, v7
	v_pk_mul_f32 v[116:117], v[140:141], v[116:117] op_sel_hi:[0,1]
	v_pk_mul_f32 v[118:119], v[140:141], v[118:119] op_sel_hi:[0,1]
	v_pk_mul_f32 v[120:121], v[140:141], v[120:121] op_sel_hi:[0,1]
	v_pk_mul_f32 v[122:123], v[140:141], v[122:123] op_sel_hi:[0,1]
	v_pk_mul_f32 v[124:125], v[140:141], v[124:125] op_sel_hi:[0,1]
	v_pk_mul_f32 v[126:127], v[140:141], v[126:127] op_sel_hi:[0,1]
	v_pk_mul_f32 v[128:129], v[140:141], v[128:129] op_sel_hi:[0,1]
	v_pk_mul_f32 v[130:131], v[140:141], v[130:131] op_sel_hi:[0,1]
	v_pk_mul_f32 v[116:117], v[116:117], v[32:33]
	v_pk_mul_f32 v[118:119], v[118:119], v[34:35]
	v_pk_mul_f32 v[120:121], v[120:121], v[36:37]
	v_pk_mul_f32 v[122:123], v[122:123], v[38:39]
	v_pk_mul_f32 v[124:125], v[124:125], v[40:41]
	v_pk_mul_f32 v[126:127], v[126:127], v[42:43]
	v_pk_mul_f32 v[128:129], v[128:129], v[44:45]
	v_pk_mul_f32 v[130:131], v[130:131], v[46:47]
	v_pk_fma_f32 v[116:117], v[116:117], v[84:85], v[100:101]
	v_pk_fma_f32 v[118:119], v[118:119], v[86:87], v[102:103]
	v_pk_fma_f32 v[120:121], v[120:121], v[88:89], v[104:105]
	v_pk_fma_f32 v[122:123], v[122:123], v[90:91], v[106:107]
	v_pk_fma_f32 v[124:125], v[124:125], v[92:93], v[108:109]
	v_pk_fma_f32 v[126:127], v[126:127], v[94:95], v[110:111]
	v_pk_fma_f32 v[128:129], v[128:129], v[96:97], v[112:113]
	v_pk_fma_f32 v[130:131], v[130:131], v[98:99], v[114:115]
	v_cvt_pk_bf16_f32 v172, v116, v117
	v_cvt_pk_bf16_f32 v173, v118, v119
	v_cvt_pk_bf16_f32 v174, v120, v121
	v_cvt_pk_bf16_f32 v175, v122, v123
	v_cvt_pk_bf16_f32 v176, v124, v125
	v_cvt_pk_bf16_f32 v177, v126, v127
	v_cvt_pk_bf16_f32 v178, v128, v129
	v_cvt_pk_bf16_f32 v179, v130, v131
	global_store_dwordx4 v51, v[172:175], s[26:27] sc1
	global_store_dwordx4 v51, v[176:179], s[26:27] offset:1024 sc1
	v_lshlrev_b32_e32 v116, 16, v8
	v_and_b32_e32 v117, 0xffff0000, v8
	v_lshlrev_b32_e32 v118, 16, v9
	v_and_b32_e32 v119, 0xffff0000, v9
	v_lshlrev_b32_e32 v120, 16, v10
	v_and_b32_e32 v121, 0xffff0000, v10
	v_lshlrev_b32_e32 v122, 16, v11
	v_and_b32_e32 v123, 0xffff0000, v11
	v_lshlrev_b32_e32 v124, 16, v12
	v_and_b32_e32 v125, 0xffff0000, v12
	v_lshlrev_b32_e32 v126, 16, v13
	v_and_b32_e32 v127, 0xffff0000, v13
	v_lshlrev_b32_e32 v128, 16, v14
	v_and_b32_e32 v129, 0xffff0000, v14
	v_lshlrev_b32_e32 v130, 16, v15
	v_and_b32_e32 v131, 0xffff0000, v15
	v_pk_mul_f32 v[116:117], v[142:143], v[116:117] op_sel_hi:[0,1]
	v_pk_mul_f32 v[118:119], v[142:143], v[118:119] op_sel_hi:[0,1]
	v_pk_mul_f32 v[120:121], v[142:143], v[120:121] op_sel_hi:[0,1]
	v_pk_mul_f32 v[122:123], v[142:143], v[122:123] op_sel_hi:[0,1]
	v_pk_mul_f32 v[124:125], v[142:143], v[124:125] op_sel_hi:[0,1]
	v_pk_mul_f32 v[126:127], v[142:143], v[126:127] op_sel_hi:[0,1]
	v_pk_mul_f32 v[128:129], v[142:143], v[128:129] op_sel_hi:[0,1]
	v_pk_mul_f32 v[130:131], v[142:143], v[130:131] op_sel_hi:[0,1]
	v_pk_mul_f32 v[116:117], v[116:117], v[32:33]
	v_pk_mul_f32 v[118:119], v[118:119], v[34:35]
	v_pk_mul_f32 v[120:121], v[120:121], v[36:37]
	v_pk_mul_f32 v[122:123], v[122:123], v[38:39]
	v_pk_mul_f32 v[124:125], v[124:125], v[40:41]
	v_pk_mul_f32 v[126:127], v[126:127], v[42:43]
	v_pk_mul_f32 v[128:129], v[128:129], v[44:45]
	v_pk_mul_f32 v[130:131], v[130:131], v[46:47]
	v_pk_fma_f32 v[116:117], v[116:117], v[84:85], v[100:101]
	v_pk_fma_f32 v[118:119], v[118:119], v[86:87], v[102:103]
	v_pk_fma_f32 v[120:121], v[120:121], v[88:89], v[104:105]
	v_pk_fma_f32 v[122:123], v[122:123], v[90:91], v[106:107]
	v_pk_fma_f32 v[124:125], v[124:125], v[92:93], v[108:109]
	v_pk_fma_f32 v[126:127], v[126:127], v[94:95], v[110:111]
	v_pk_fma_f32 v[128:129], v[128:129], v[96:97], v[112:113]
	v_pk_fma_f32 v[130:131], v[130:131], v[98:99], v[114:115]
	v_cvt_pk_bf16_f32 v164, v116, v117
	v_cvt_pk_bf16_f32 v165, v118, v119
	v_cvt_pk_bf16_f32 v166, v120, v121
	v_cvt_pk_bf16_f32 v167, v122, v123
	v_cvt_pk_bf16_f32 v168, v124, v125
	v_cvt_pk_bf16_f32 v169, v126, v127
	v_cvt_pk_bf16_f32 v170, v128, v129
	v_cvt_pk_bf16_f32 v171, v130, v131
	global_store_dwordx4 v51, v[164:167], s[26:27] offset:2048 sc1
	global_store_dwordx4 v51, v[168:171], s[26:27] offset:3072 sc1
	v_lshlrev_b32_e32 v116, 16, v16
	v_and_b32_e32 v117, 0xffff0000, v16
	v_lshlrev_b32_e32 v118, 16, v17
	v_and_b32_e32 v119, 0xffff0000, v17
	v_lshlrev_b32_e32 v120, 16, v18
	v_and_b32_e32 v121, 0xffff0000, v18
	v_lshlrev_b32_e32 v122, 16, v19
	v_and_b32_e32 v123, 0xffff0000, v19
	v_lshlrev_b32_e32 v124, 16, v20
	v_and_b32_e32 v125, 0xffff0000, v20
	v_lshlrev_b32_e32 v126, 16, v21
	v_and_b32_e32 v127, 0xffff0000, v21
	v_lshlrev_b32_e32 v128, 16, v22
	v_and_b32_e32 v129, 0xffff0000, v22
	v_lshlrev_b32_e32 v130, 16, v23
	v_and_b32_e32 v131, 0xffff0000, v23
	v_pk_mul_f32 v[116:117], v[144:145], v[116:117] op_sel_hi:[0,1]
	v_pk_mul_f32 v[118:119], v[144:145], v[118:119] op_sel_hi:[0,1]
	v_pk_mul_f32 v[120:121], v[144:145], v[120:121] op_sel_hi:[0,1]
	v_pk_mul_f32 v[122:123], v[144:145], v[122:123] op_sel_hi:[0,1]
	v_pk_mul_f32 v[124:125], v[144:145], v[124:125] op_sel_hi:[0,1]
	v_pk_mul_f32 v[126:127], v[144:145], v[126:127] op_sel_hi:[0,1]
	v_pk_mul_f32 v[128:129], v[144:145], v[128:129] op_sel_hi:[0,1]
	v_pk_mul_f32 v[130:131], v[144:145], v[130:131] op_sel_hi:[0,1]
	v_pk_mul_f32 v[116:117], v[116:117], v[32:33]
	v_pk_mul_f32 v[118:119], v[118:119], v[34:35]
	v_pk_mul_f32 v[120:121], v[120:121], v[36:37]
	v_pk_mul_f32 v[122:123], v[122:123], v[38:39]
	v_pk_mul_f32 v[124:125], v[124:125], v[40:41]
	v_pk_mul_f32 v[126:127], v[126:127], v[42:43]
	v_pk_mul_f32 v[128:129], v[128:129], v[44:45]
	v_pk_mul_f32 v[130:131], v[130:131], v[46:47]
	v_pk_fma_f32 v[116:117], v[116:117], v[84:85], v[100:101]
	v_pk_fma_f32 v[118:119], v[118:119], v[86:87], v[102:103]
	v_pk_fma_f32 v[120:121], v[120:121], v[88:89], v[104:105]
	v_pk_fma_f32 v[122:123], v[122:123], v[90:91], v[106:107]
	v_pk_fma_f32 v[124:125], v[124:125], v[92:93], v[108:109]
	v_pk_fma_f32 v[126:127], v[126:127], v[94:95], v[110:111]
	v_pk_fma_f32 v[128:129], v[128:129], v[96:97], v[112:113]
	v_pk_fma_f32 v[130:131], v[130:131], v[98:99], v[114:115]
	v_cvt_pk_bf16_f32 v172, v116, v117
	v_cvt_pk_bf16_f32 v173, v118, v119
	v_cvt_pk_bf16_f32 v174, v120, v121
	v_cvt_pk_bf16_f32 v175, v122, v123
	v_cvt_pk_bf16_f32 v176, v124, v125
	v_cvt_pk_bf16_f32 v177, v126, v127
	v_cvt_pk_bf16_f32 v178, v128, v129
	v_cvt_pk_bf16_f32 v179, v130, v131
	global_store_dwordx4 v149, v[172:175], s[26:27] sc1
	global_store_dwordx4 v149, v[176:179], s[26:27] offset:1024 sc1
	v_lshlrev_b32_e32 v116, 16, v24
	v_and_b32_e32 v117, 0xffff0000, v24
	v_lshlrev_b32_e32 v118, 16, v25
	v_and_b32_e32 v119, 0xffff0000, v25
	v_lshlrev_b32_e32 v120, 16, v26
	v_and_b32_e32 v121, 0xffff0000, v26
	v_lshlrev_b32_e32 v122, 16, v27
	v_and_b32_e32 v123, 0xffff0000, v27
	v_lshlrev_b32_e32 v124, 16, v28
	v_and_b32_e32 v125, 0xffff0000, v28
	v_lshlrev_b32_e32 v126, 16, v29
	v_and_b32_e32 v127, 0xffff0000, v29
	v_lshlrev_b32_e32 v128, 16, v30
	v_and_b32_e32 v129, 0xffff0000, v30
	v_lshlrev_b32_e32 v130, 16, v31
	v_and_b32_e32 v131, 0xffff0000, v31
	v_pk_mul_f32 v[116:117], v[146:147], v[116:117] op_sel_hi:[0,1]
	v_pk_mul_f32 v[118:119], v[146:147], v[118:119] op_sel_hi:[0,1]
	v_pk_mul_f32 v[120:121], v[146:147], v[120:121] op_sel_hi:[0,1]
	v_pk_mul_f32 v[122:123], v[146:147], v[122:123] op_sel_hi:[0,1]
	v_pk_mul_f32 v[124:125], v[146:147], v[124:125] op_sel_hi:[0,1]
	v_pk_mul_f32 v[126:127], v[146:147], v[126:127] op_sel_hi:[0,1]
	v_pk_mul_f32 v[128:129], v[146:147], v[128:129] op_sel_hi:[0,1]
	v_pk_mul_f32 v[130:131], v[146:147], v[130:131] op_sel_hi:[0,1]
	v_pk_mul_f32 v[116:117], v[116:117], v[32:33]
	v_pk_mul_f32 v[118:119], v[118:119], v[34:35]
	v_pk_mul_f32 v[120:121], v[120:121], v[36:37]
	v_pk_mul_f32 v[122:123], v[122:123], v[38:39]
	v_pk_mul_f32 v[124:125], v[124:125], v[40:41]
	v_pk_mul_f32 v[126:127], v[126:127], v[42:43]
	v_pk_mul_f32 v[128:129], v[128:129], v[44:45]
	v_pk_mul_f32 v[130:131], v[130:131], v[46:47]
	v_pk_fma_f32 v[116:117], v[116:117], v[84:85], v[100:101]
	v_pk_fma_f32 v[118:119], v[118:119], v[86:87], v[102:103]
	v_pk_fma_f32 v[120:121], v[120:121], v[88:89], v[104:105]
	v_pk_fma_f32 v[122:123], v[122:123], v[90:91], v[106:107]
	v_pk_fma_f32 v[124:125], v[124:125], v[92:93], v[108:109]
	v_pk_fma_f32 v[126:127], v[126:127], v[94:95], v[110:111]
	v_pk_fma_f32 v[128:129], v[128:129], v[96:97], v[112:113]
	v_pk_fma_f32 v[130:131], v[130:131], v[98:99], v[114:115]
	v_cvt_pk_bf16_f32 v164, v116, v117
	v_cvt_pk_bf16_f32 v165, v118, v119
	v_cvt_pk_bf16_f32 v166, v120, v121
	v_cvt_pk_bf16_f32 v167, v122, v123
	v_cvt_pk_bf16_f32 v168, v124, v125
	v_cvt_pk_bf16_f32 v169, v126, v127
	v_cvt_pk_bf16_f32 v170, v128, v129
	v_cvt_pk_bf16_f32 v171, v130, v131
	global_store_dwordx4 v149, v[164:167], s[26:27] offset:2048 sc1
	global_store_dwordx4 v149, v[168:171], s[26:27] offset:3072 sc1
	s_add_u32 s26, s26, 0x2000
	s_addc_u32 s27, s27, 0
	s_add_u32 s24, s24, 0x2000
	s_addc_u32 s25, s25, 0
	global_load_dwordx4 v[0:3], v51, s[24:25]
	global_load_dwordx4 v[4:7], v51, s[24:25] offset:1024
	global_load_dwordx4 v[8:11], v51, s[24:25] offset:2048
	global_load_dwordx4 v[12:15], v51, s[24:25] offset:3072
	global_load_dwordx4 v[16:19], v149, s[24:25]
	global_load_dwordx4 v[20:23], v149, s[24:25] offset:1024
	global_load_dwordx4 v[24:27], v149, s[24:25] offset:2048
	global_load_dwordx4 v[28:31], v149, s[24:25] offset:3072
	s_waitcnt vmcnt(16)
	v_lshlrev_b32_e32 v116, 16, v52
	v_and_b32_e32 v117, 0xffff0000, v52
	v_lshlrev_b32_e32 v118, 16, v53
	v_and_b32_e32 v119, 0xffff0000, v53
	v_lshlrev_b32_e32 v120, 16, v54
	v_and_b32_e32 v121, 0xffff0000, v54
	v_lshlrev_b32_e32 v122, 16, v55
	v_and_b32_e32 v123, 0xffff0000, v55
	v_lshlrev_b32_e32 v124, 16, v56
	v_and_b32_e32 v125, 0xffff0000, v56
	v_lshlrev_b32_e32 v126, 16, v57
	v_and_b32_e32 v127, 0xffff0000, v57
	v_lshlrev_b32_e32 v128, 16, v58
	v_and_b32_e32 v129, 0xffff0000, v58
	v_lshlrev_b32_e32 v130, 16, v59
	v_and_b32_e32 v131, 0xffff0000, v59
	v_pk_mul_f32 v[132:133], v[116:117], v[116:117]
	v_pk_fma_f32 v[132:133], v[118:119], v[118:119], v[132:133]
	v_pk_fma_f32 v[132:133], v[120:121], v[120:121], v[132:133]
	v_pk_fma_f32 v[132:133], v[122:123], v[122:123], v[132:133]
	v_pk_fma_f32 v[132:133], v[124:125], v[124:125], v[132:133]
	v_pk_fma_f32 v[132:133], v[126:127], v[126:127], v[132:133]
	v_pk_fma_f32 v[132:133], v[128:129], v[128:129], v[132:133]
	v_pk_fma_f32 v[132:133], v[130:131], v[130:131], v[132:133]
	v_lshlrev_b32_e32 v116, 16, v60
	v_and_b32_e32 v117, 0xffff0000, v60
	v_lshlrev_b32_e32 v118, 16, v61
	v_and_b32_e32 v119, 0xffff0000, v61
	v_lshlrev_b32_e32 v120, 16, v62
	v_and_b32_e32 v121, 0xffff0000, v62
	v_lshlrev_b32_e32 v122, 16, v63
	v_and_b32_e32 v123, 0xffff0000, v63
	v_lshlrev_b32_e32 v124, 16, v64
	v_and_b32_e32 v125, 0xffff0000, v64
	v_lshlrev_b32_e32 v126, 16, v65
	v_and_b32_e32 v127, 0xffff0000, v65
	v_lshlrev_b32_e32 v128, 16, v66
	v_and_b32_e32 v129, 0xffff0000, v66
	v_lshlrev_b32_e32 v130, 16, v67
	v_and_b32_e32 v131, 0xffff0000, v67
	v_pk_mul_f32 v[134:135], v[116:117], v[116:117]
	v_pk_fma_f32 v[134:135], v[118:119], v[118:119], v[134:135]
	v_pk_fma_f32 v[134:135], v[120:121], v[120:121], v[134:135]
	v_pk_fma_f32 v[134:135], v[122:123], v[122:123], v[134:135]
	v_pk_fma_f32 v[134:135], v[124:125], v[124:125], v[134:135]
	v_pk_fma_f32 v[134:135], v[126:127], v[126:127], v[134:135]
	v_pk_fma_f32 v[134:135], v[128:129], v[128:129], v[134:135]
	v_pk_fma_f32 v[134:135], v[130:131], v[130:131], v[134:135]
	v_lshlrev_b32_e32 v116, 16, v68
	v_and_b32_e32 v117, 0xffff0000, v68
	v_lshlrev_b32_e32 v118, 16, v69
	v_and_b32_e32 v119, 0xffff0000, v69
	v_lshlrev_b32_e32 v120, 16, v70
	v_and_b32_e32 v121, 0xffff0000, v70
	v_lshlrev_b32_e32 v122, 16, v71
	v_and_b32_e32 v123, 0xffff0000, v71
	v_lshlrev_b32_e32 v124, 16, v72
	v_and_b32_e32 v125, 0xffff0000, v72
	v_lshlrev_b32_e32 v126, 16, v73
	v_and_b32_e32 v127, 0xffff0000, v73
	v_lshlrev_b32_e32 v128, 16, v74
	v_and_b32_e32 v129, 0xffff0000, v74
	v_lshlrev_b32_e32 v130, 16, v75
	v_and_b32_e32 v131, 0xffff0000, v75
	v_pk_mul_f32 v[136:137], v[116:117], v[116:117]
	v_pk_fma_f32 v[136:137], v[118:119], v[118:119], v[136:137]
	v_pk_fma_f32 v[136:137], v[120:121], v[120:121], v[136:137]
	v_pk_fma_f32 v[136:137], v[122:123], v[122:123], v[136:137]
	v_pk_fma_f32 v[136:137], v[124:125], v[124:125], v[136:137]
	v_pk_fma_f32 v[136:137], v[126:127], v[126:127], v[136:137]
	v_pk_fma_f32 v[136:137], v[128:129], v[128:129], v[136:137]
	v_pk_fma_f32 v[136:137], v[130:131], v[130:131], v[136:137]
	v_lshlrev_b32_e32 v116, 16, v76
	v_and_b32_e32 v117, 0xffff0000, v76
	v_lshlrev_b32_e32 v118, 16, v77
	v_and_b32_e32 v119, 0xffff0000, v77
	v_lshlrev_b32_e32 v120, 16, v78
	v_and_b32_e32 v121, 0xffff0000, v78
	v_lshlrev_b32_e32 v122, 16, v79
	v_and_b32_e32 v123, 0xffff0000, v79
	v_lshlrev_b32_e32 v124, 16, v80
	v_and_b32_e32 v125, 0xffff0000, v80
	v_lshlrev_b32_e32 v126, 16, v81
	v_and_b32_e32 v127, 0xffff0000, v81
	v_lshlrev_b32_e32 v128, 16, v82
	v_and_b32_e32 v129, 0xffff0000, v82
	v_lshlrev_b32_e32 v130, 16, v83
	v_and_b32_e32 v131, 0xffff0000, v83
	v_pk_mul_f32 v[138:139], v[116:117], v[116:117]
	v_pk_fma_f32 v[138:139], v[118:119], v[118:119], v[138:139]
	v_pk_fma_f32 v[138:139], v[120:121], v[120:121], v[138:139]
	v_pk_fma_f32 v[138:139], v[122:123], v[122:123], v[138:139]
	v_pk_fma_f32 v[138:139], v[124:125], v[124:125], v[138:139]
	v_pk_fma_f32 v[138:139], v[126:127], v[126:127], v[138:139]
	v_pk_fma_f32 v[138:139], v[128:129], v[128:129], v[138:139]
	v_pk_fma_f32 v[138:139], v[130:131], v[130:131], v[138:139]
	v_add_f32_e32 v132, v132, v133
	v_add_f32_e32 v134, v134, v135
	v_add_f32_e32 v136, v136, v137
	v_add_f32_e32 v138, v138, v139
	s_nop 1
	v_add_f32_dpp v132, v132, v132 row_shr:1 row_mask:0xf bank_mask:0xf bound_ctrl:1
	v_add_f32_dpp v134, v134, v134 row_shr:1 row_mask:0xf bank_mask:0xf bound_ctrl:1
	v_add_f32_dpp v136, v136, v136 row_shr:1 row_mask:0xf bank_mask:0xf bound_ctrl:1
	v_add_f32_dpp v138, v138, v138 row_shr:1 row_mask:0xf bank_mask:0xf bound_ctrl:1
	v_add_f32_dpp v132, v132, v132 row_shr:2 row_mask:0xf bank_mask:0xf bound_ctrl:1
	v_add_f32_dpp v134, v134, v134 row_shr:2 row_mask:0xf bank_mask:0xf bound_ctrl:1
	v_add_f32_dpp v136, v136, v136 row_shr:2 row_mask:0xf bank_mask:0xf bound_ctrl:1
	v_add_f32_dpp v138, v138, v138 row_shr:2 row_mask:0xf bank_mask:0xf bound_ctrl:1
	v_add_f32_dpp v132, v132, v132 row_shr:4 row_mask:0xf bank_mask:0xf bound_ctrl:1
	v_add_f32_dpp v134, v134, v134 row_shr:4 row_mask:0xf bank_mask:0xf bound_ctrl:1
	v_add_f32_dpp v136, v136, v136 row_shr:4 row_mask:0xf bank_mask:0xf bound_ctrl:1
	v_add_f32_dpp v138, v138, v138 row_shr:4 row_mask:0xf bank_mask:0xf bound_ctrl:1
	v_add_f32_dpp v132, v132, v132 row_shr:8 row_mask:0xf bank_mask:0xf bound_ctrl:1
	v_add_f32_dpp v134, v134, v134 row_shr:8 row_mask:0xf bank_mask:0xf bound_ctrl:1
	v_add_f32_dpp v136, v136, v136 row_shr:8 row_mask:0xf bank_mask:0xf bound_ctrl:1
	v_add_f32_dpp v138, v138, v138 row_shr:8 row_mask:0xf bank_mask:0xf bound_ctrl:1
	v_add_f32_dpp v132, v132, v132 row_bcast:15 row_mask:0xa bank_mask:0xf
	v_add_f32_dpp v134, v134, v134 row_bcast:15 row_mask:0xa bank_mask:0xf
	v_add_f32_dpp v136, v136, v136 row_bcast:15 row_mask:0xa bank_mask:0xf
	v_add_f32_dpp v138, v138, v138 row_bcast:15 row_mask:0xa bank_mask:0xf
	v_add_f32_dpp v132, v132, v132 row_bcast:31 row_mask:0xc bank_mask:0xf
	v_add_f32_dpp v134, v134, v134 row_bcast:31 row_mask:0xc bank_mask:0xf
	v_add_f32_dpp v136, v136, v136 row_bcast:31 row_mask:0xc bank_mask:0xf
	v_add_f32_dpp v138, v138, v138 row_bcast:31 row_mask:0xc bank_mask:0xf
	s_nop 1
	v_readlane_b32 s32, v132, 63
	v_readlane_b32 s28, v134, 63
	v_readlane_b32 s29, v136, 63
	v_readlane_b32 s30, v138, 63
	s_nop 1
	v_mov_b32_e32 v140, s32
	v_mov_b32_e32 v142, s28
	v_mov_b32_e32 v144, s29
	v_mov_b32_e32 v146, s30
	v_fmaak_f32 v140, v140, v50, 0x358637bd
	v_fmaak_f32 v142, v142, v50, 0x358637bd
	v_fmaak_f32 v144, v144, v50, 0x358637bd
	v_fmaak_f32 v146, v146, v50, 0x358637bd
	v_rsq_f32_e32 v140, v140
	v_rsq_f32_e32 v142, v142
	v_rsq_f32_e32 v144, v144
	v_rsq_f32_e32 v146, v146
	s_nop 0
	v_lshlrev_b32_e32 v116, 16, v52
	v_and_b32_e32 v117, 0xffff0000, v52
	v_lshlrev_b32_e32 v118, 16, v53
	v_and_b32_e32 v119, 0xffff0000, v53
	v_lshlrev_b32_e32 v120, 16, v54
	v_and_b32_e32 v121, 0xffff0000, v54
	v_lshlrev_b32_e32 v122, 16, v55
	v_and_b32_e32 v123, 0xffff0000, v55
	v_lshlrev_b32_e32 v124, 16, v56
	v_and_b32_e32 v125, 0xffff0000, v56
	v_lshlrev_b32_e32 v126, 16, v57
	v_and_b32_e32 v127, 0xffff0000, v57
	v_lshlrev_b32_e32 v128, 16, v58
	v_and_b32_e32 v129, 0xffff0000, v58
	v_lshlrev_b32_e32 v130, 16, v59
	v_and_b32_e32 v131, 0xffff0000, v59
	v_pk_mul_f32 v[116:117], v[140:141], v[116:117] op_sel_hi:[0,1]
	v_pk_mul_f32 v[118:119], v[140:141], v[118:119] op_sel_hi:[0,1]
	v_pk_mul_f32 v[120:121], v[140:141], v[120:121] op_sel_hi:[0,1]
	v_pk_mul_f32 v[122:123], v[140:141], v[122:123] op_sel_hi:[0,1]
	v_pk_mul_f32 v[124:125], v[140:141], v[124:125] op_sel_hi:[0,1]
	v_pk_mul_f32 v[126:127], v[140:141], v[126:127] op_sel_hi:[0,1]
	v_pk_mul_f32 v[128:129], v[140:141], v[128:129] op_sel_hi:[0,1]
	v_pk_mul_f32 v[130:131], v[140:141], v[130:131] op_sel_hi:[0,1]
	v_pk_mul_f32 v[116:117], v[116:117], v[32:33]
	v_pk_mul_f32 v[118:119], v[118:119], v[34:35]
	v_pk_mul_f32 v[120:121], v[120:121], v[36:37]
	v_pk_mul_f32 v[122:123], v[122:123], v[38:39]
	v_pk_mul_f32 v[124:125], v[124:125], v[40:41]
	v_pk_mul_f32 v[126:127], v[126:127], v[42:43]
	v_pk_mul_f32 v[128:129], v[128:129], v[44:45]
	v_pk_mul_f32 v[130:131], v[130:131], v[46:47]
	v_pk_fma_f32 v[116:117], v[116:117], v[84:85], v[100:101]
	v_pk_fma_f32 v[118:119], v[118:119], v[86:87], v[102:103]
	v_pk_fma_f32 v[120:121], v[120:121], v[88:89], v[104:105]
	v_pk_fma_f32 v[122:123], v[122:123], v[90:91], v[106:107]
	v_pk_fma_f32 v[124:125], v[124:125], v[92:93], v[108:109]
	v_pk_fma_f32 v[126:127], v[126:127], v[94:95], v[110:111]
	v_pk_fma_f32 v[128:129], v[128:129], v[96:97], v[112:113]
	v_pk_fma_f32 v[130:131], v[130:131], v[98:99], v[114:115]
	v_cvt_pk_bf16_f32 v164, v116, v117
	v_cvt_pk_bf16_f32 v165, v118, v119
	v_cvt_pk_bf16_f32 v166, v120, v121
	v_cvt_pk_bf16_f32 v167, v122, v123
	v_cvt_pk_bf16_f32 v168, v124, v125
	v_cvt_pk_bf16_f32 v169, v126, v127
	v_cvt_pk_bf16_f32 v170, v128, v129
	v_cvt_pk_bf16_f32 v171, v130, v131
	global_store_dwordx4 v51, v[164:167], s[26:27] sc1
	global_store_dwordx4 v51, v[168:171], s[26:27] offset:1024 sc1
	v_lshlrev_b32_e32 v116, 16, v60
	v_and_b32_e32 v117, 0xffff0000, v60
	v_lshlrev_b32_e32 v118, 16, v61
	v_and_b32_e32 v119, 0xffff0000, v61
	v_lshlrev_b32_e32 v120, 16, v62
	v_and_b32_e32 v121, 0xffff0000, v62
	v_lshlrev_b32_e32 v122, 16, v63
	v_and_b32_e32 v123, 0xffff0000, v63
	v_lshlrev_b32_e32 v124, 16, v64
	v_and_b32_e32 v125, 0xffff0000, v64
	v_lshlrev_b32_e32 v126, 16, v65
	v_and_b32_e32 v127, 0xffff0000, v65
	v_lshlrev_b32_e32 v128, 16, v66
	v_and_b32_e32 v129, 0xffff0000, v66
	v_lshlrev_b32_e32 v130, 16, v67
	v_and_b32_e32 v131, 0xffff0000, v67
	v_pk_mul_f32 v[116:117], v[142:143], v[116:117] op_sel_hi:[0,1]
	v_pk_mul_f32 v[118:119], v[142:143], v[118:119] op_sel_hi:[0,1]
	v_pk_mul_f32 v[120:121], v[142:143], v[120:121] op_sel_hi:[0,1]
	v_pk_mul_f32 v[122:123], v[142:143], v[122:123] op_sel_hi:[0,1]
	v_pk_mul_f32 v[124:125], v[142:143], v[124:125] op_sel_hi:[0,1]
	v_pk_mul_f32 v[126:127], v[142:143], v[126:127] op_sel_hi:[0,1]
	v_pk_mul_f32 v[128:129], v[142:143], v[128:129] op_sel_hi:[0,1]
	v_pk_mul_f32 v[130:131], v[142:143], v[130:131] op_sel_hi:[0,1]
	v_pk_mul_f32 v[116:117], v[116:117], v[32:33]
	v_pk_mul_f32 v[118:119], v[118:119], v[34:35]
	v_pk_mul_f32 v[120:121], v[120:121], v[36:37]
	v_pk_mul_f32 v[122:123], v[122:123], v[38:39]
	v_pk_mul_f32 v[124:125], v[124:125], v[40:41]
	v_pk_mul_f32 v[126:127], v[126:127], v[42:43]
	v_pk_mul_f32 v[128:129], v[128:129], v[44:45]
	v_pk_mul_f32 v[130:131], v[130:131], v[46:47]
	v_pk_fma_f32 v[116:117], v[116:117], v[84:85], v[100:101]
	v_pk_fma_f32 v[118:119], v[118:119], v[86:87], v[102:103]
	v_pk_fma_f32 v[120:121], v[120:121], v[88:89], v[104:105]
	v_pk_fma_f32 v[122:123], v[122:123], v[90:91], v[106:107]
	v_pk_fma_f32 v[124:125], v[124:125], v[92:93], v[108:109]
	v_pk_fma_f32 v[126:127], v[126:127], v[94:95], v[110:111]
	v_pk_fma_f32 v[128:129], v[128:129], v[96:97], v[112:113]
	v_pk_fma_f32 v[130:131], v[130:131], v[98:99], v[114:115]
	v_cvt_pk_bf16_f32 v172, v116, v117
	v_cvt_pk_bf16_f32 v173, v118, v119
	v_cvt_pk_bf16_f32 v174, v120, v121
	v_cvt_pk_bf16_f32 v175, v122, v123
	v_cvt_pk_bf16_f32 v176, v124, v125
	v_cvt_pk_bf16_f32 v177, v126, v127
	v_cvt_pk_bf16_f32 v178, v128, v129
	v_cvt_pk_bf16_f32 v179, v130, v131
	global_store_dwordx4 v51, v[172:175], s[26:27] offset:2048 sc1
	global_store_dwordx4 v51, v[176:179], s[26:27] offset:3072 sc1
	v_lshlrev_b32_e32 v116, 16, v68
	v_and_b32_e32 v117, 0xffff0000, v68
	v_lshlrev_b32_e32 v118, 16, v69
	v_and_b32_e32 v119, 0xffff0000, v69
	v_lshlrev_b32_e32 v120, 16, v70
	v_and_b32_e32 v121, 0xffff0000, v70
	v_lshlrev_b32_e32 v122, 16, v71
	v_and_b32_e32 v123, 0xffff0000, v71
	v_lshlrev_b32_e32 v124, 16, v72
	v_and_b32_e32 v125, 0xffff0000, v72
	v_lshlrev_b32_e32 v126, 16, v73
	v_and_b32_e32 v127, 0xffff0000, v73
	v_lshlrev_b32_e32 v128, 16, v74
	v_and_b32_e32 v129, 0xffff0000, v74
	v_lshlrev_b32_e32 v130, 16, v75
	v_and_b32_e32 v131, 0xffff0000, v75
	v_pk_mul_f32 v[116:117], v[144:145], v[116:117] op_sel_hi:[0,1]
	v_pk_mul_f32 v[118:119], v[144:145], v[118:119] op_sel_hi:[0,1]
	v_pk_mul_f32 v[120:121], v[144:145], v[120:121] op_sel_hi:[0,1]
	v_pk_mul_f32 v[122:123], v[144:145], v[122:123] op_sel_hi:[0,1]
	v_pk_mul_f32 v[124:125], v[144:145], v[124:125] op_sel_hi:[0,1]
	v_pk_mul_f32 v[126:127], v[144:145], v[126:127] op_sel_hi:[0,1]
	v_pk_mul_f32 v[128:129], v[144:145], v[128:129] op_sel_hi:[0,1]
	v_pk_mul_f32 v[130:131], v[144:145], v[130:131] op_sel_hi:[0,1]
	v_pk_mul_f32 v[116:117], v[116:117], v[32:33]
	v_pk_mul_f32 v[118:119], v[118:119], v[34:35]
	v_pk_mul_f32 v[120:121], v[120:121], v[36:37]
	v_pk_mul_f32 v[122:123], v[122:123], v[38:39]
	v_pk_mul_f32 v[124:125], v[124:125], v[40:41]
	v_pk_mul_f32 v[126:127], v[126:127], v[42:43]
	v_pk_mul_f32 v[128:129], v[128:129], v[44:45]
	v_pk_mul_f32 v[130:131], v[130:131], v[46:47]
	v_pk_fma_f32 v[116:117], v[116:117], v[84:85], v[100:101]
	v_pk_fma_f32 v[118:119], v[118:119], v[86:87], v[102:103]
	v_pk_fma_f32 v[120:121], v[120:121], v[88:89], v[104:105]
	v_pk_fma_f32 v[122:123], v[122:123], v[90:91], v[106:107]
	v_pk_fma_f32 v[124:125], v[124:125], v[92:93], v[108:109]
	v_pk_fma_f32 v[126:127], v[126:127], v[94:95], v[110:111]
	v_pk_fma_f32 v[128:129], v[128:129], v[96:97], v[112:113]
	v_pk_fma_f32 v[130:131], v[130:131], v[98:99], v[114:115]
	v_cvt_pk_bf16_f32 v164, v116, v117
	v_cvt_pk_bf16_f32 v165, v118, v119
	v_cvt_pk_bf16_f32 v166, v120, v121
	v_cvt_pk_bf16_f32 v167, v122, v123
	v_cvt_pk_bf16_f32 v168, v124, v125
	v_cvt_pk_bf16_f32 v169, v126, v127
	v_cvt_pk_bf16_f32 v170, v128, v129
	v_cvt_pk_bf16_f32 v171, v130, v131
	global_store_dwordx4 v149, v[164:167], s[26:27] sc1
	global_store_dwordx4 v149, v[168:171], s[26:27] offset:1024 sc1
	v_lshlrev_b32_e32 v116, 16, v76
	v_and_b32_e32 v117, 0xffff0000, v76
	v_lshlrev_b32_e32 v118, 16, v77
	v_and_b32_e32 v119, 0xffff0000, v77
	v_lshlrev_b32_e32 v120, 16, v78
	v_and_b32_e32 v121, 0xffff0000, v78
	v_lshlrev_b32_e32 v122, 16, v79
	v_and_b32_e32 v123, 0xffff0000, v79
	v_lshlrev_b32_e32 v124, 16, v80
	v_and_b32_e32 v125, 0xffff0000, v80
	v_lshlrev_b32_e32 v126, 16, v81
	v_and_b32_e32 v127, 0xffff0000, v81
	v_lshlrev_b32_e32 v128, 16, v82
	v_and_b32_e32 v129, 0xffff0000, v82
	v_lshlrev_b32_e32 v130, 16, v83
	v_and_b32_e32 v131, 0xffff0000, v83
	v_pk_mul_f32 v[116:117], v[146:147], v[116:117] op_sel_hi:[0,1]
	v_pk_mul_f32 v[118:119], v[146:147], v[118:119] op_sel_hi:[0,1]
	v_pk_mul_f32 v[120:121], v[146:147], v[120:121] op_sel_hi:[0,1]
	v_pk_mul_f32 v[122:123], v[146:147], v[122:123] op_sel_hi:[0,1]
	v_pk_mul_f32 v[124:125], v[146:147], v[124:125] op_sel_hi:[0,1]
	v_pk_mul_f32 v[126:127], v[146:147], v[126:127] op_sel_hi:[0,1]
	v_pk_mul_f32 v[128:129], v[146:147], v[128:129] op_sel_hi:[0,1]
	v_pk_mul_f32 v[130:131], v[146:147], v[130:131] op_sel_hi:[0,1]
	v_pk_mul_f32 v[116:117], v[116:117], v[32:33]
	v_pk_mul_f32 v[118:119], v[118:119], v[34:35]
	v_pk_mul_f32 v[120:121], v[120:121], v[36:37]
	v_pk_mul_f32 v[122:123], v[122:123], v[38:39]
	v_pk_mul_f32 v[124:125], v[124:125], v[40:41]
	v_pk_mul_f32 v[126:127], v[126:127], v[42:43]
	v_pk_mul_f32 v[128:129], v[128:129], v[44:45]
	v_pk_mul_f32 v[130:131], v[130:131], v[46:47]
	v_pk_fma_f32 v[116:117], v[116:117], v[84:85], v[100:101]
	v_pk_fma_f32 v[118:119], v[118:119], v[86:87], v[102:103]
	v_pk_fma_f32 v[120:121], v[120:121], v[88:89], v[104:105]
	v_pk_fma_f32 v[122:123], v[122:123], v[90:91], v[106:107]
	v_pk_fma_f32 v[124:125], v[124:125], v[92:93], v[108:109]
	v_pk_fma_f32 v[126:127], v[126:127], v[94:95], v[110:111]
	v_pk_fma_f32 v[128:129], v[128:129], v[96:97], v[112:113]
	v_pk_fma_f32 v[130:131], v[130:131], v[98:99], v[114:115]
	v_cvt_pk_bf16_f32 v172, v116, v117
	v_cvt_pk_bf16_f32 v173, v118, v119
	v_cvt_pk_bf16_f32 v174, v120, v121
	v_cvt_pk_bf16_f32 v175, v122, v123
	v_cvt_pk_bf16_f32 v176, v124, v125
	v_cvt_pk_bf16_f32 v177, v126, v127
	v_cvt_pk_bf16_f32 v178, v128, v129
	v_cvt_pk_bf16_f32 v179, v130, v131
	global_store_dwordx4 v149, v[172:175], s[26:27] offset:2048 sc1
	global_store_dwordx4 v149, v[176:179], s[26:27] offset:3072 sc1
	s_add_u32 s26, s26, 0x2000
	s_addc_u32 s27, s27, 0
	s_add_u32 s24, s24, 0x2000
	s_addc_u32 s25, s25, 0
	global_load_dwordx4 v[52:55], v51, s[24:25]
	global_load_dwordx4 v[56:59], v51, s[24:25] offset:1024
	global_load_dwordx4 v[60:63], v51, s[24:25] offset:2048
	global_load_dwordx4 v[64:67], v51, s[24:25] offset:3072
	global_load_dwordx4 v[68:71], v149, s[24:25]
	global_load_dwordx4 v[72:75], v149, s[24:25] offset:1024
	global_load_dwordx4 v[76:79], v149, s[24:25] offset:2048
	global_load_dwordx4 v[80:83], v149, s[24:25] offset:3072
	s_waitcnt vmcnt(16)
	v_lshlrev_b32_e32 v116, 16, v0
	v_and_b32_e32 v117, 0xffff0000, v0
	v_lshlrev_b32_e32 v118, 16, v1
	v_and_b32_e32 v119, 0xffff0000, v1
	v_lshlrev_b32_e32 v120, 16, v2
	v_and_b32_e32 v121, 0xffff0000, v2
	v_lshlrev_b32_e32 v122, 16, v3
	v_and_b32_e32 v123, 0xffff0000, v3
	v_lshlrev_b32_e32 v124, 16, v4
	v_and_b32_e32 v125, 0xffff0000, v4
	v_lshlrev_b32_e32 v126, 16, v5
	v_and_b32_e32 v127, 0xffff0000, v5
	v_lshlrev_b32_e32 v128, 16, v6
	v_and_b32_e32 v129, 0xffff0000, v6
	v_lshlrev_b32_e32 v130, 16, v7
	v_and_b32_e32 v131, 0xffff0000, v7
	v_pk_mul_f32 v[132:133], v[116:117], v[116:117]
	v_pk_fma_f32 v[132:133], v[118:119], v[118:119], v[132:133]
	v_pk_fma_f32 v[132:133], v[120:121], v[120:121], v[132:133]
	v_pk_fma_f32 v[132:133], v[122:123], v[122:123], v[132:133]
	v_pk_fma_f32 v[132:133], v[124:125], v[124:125], v[132:133]
	v_pk_fma_f32 v[132:133], v[126:127], v[126:127], v[132:133]
	v_pk_fma_f32 v[132:133], v[128:129], v[128:129], v[132:133]
	v_pk_fma_f32 v[132:133], v[130:131], v[130:131], v[132:133]
	v_lshlrev_b32_e32 v116, 16, v8
	v_and_b32_e32 v117, 0xffff0000, v8
	v_lshlrev_b32_e32 v118, 16, v9
	v_and_b32_e32 v119, 0xffff0000, v9
	v_lshlrev_b32_e32 v120, 16, v10
	v_and_b32_e32 v121, 0xffff0000, v10
	v_lshlrev_b32_e32 v122, 16, v11
	v_and_b32_e32 v123, 0xffff0000, v11
	v_lshlrev_b32_e32 v124, 16, v12
	v_and_b32_e32 v125, 0xffff0000, v12
	v_lshlrev_b32_e32 v126, 16, v13
	v_and_b32_e32 v127, 0xffff0000, v13
	v_lshlrev_b32_e32 v128, 16, v14
	v_and_b32_e32 v129, 0xffff0000, v14
	v_lshlrev_b32_e32 v130, 16, v15
	v_and_b32_e32 v131, 0xffff0000, v15
	v_pk_mul_f32 v[134:135], v[116:117], v[116:117]
	v_pk_fma_f32 v[134:135], v[118:119], v[118:119], v[134:135]
	v_pk_fma_f32 v[134:135], v[120:121], v[120:121], v[134:135]
	v_pk_fma_f32 v[134:135], v[122:123], v[122:123], v[134:135]
	v_pk_fma_f32 v[134:135], v[124:125], v[124:125], v[134:135]
	v_pk_fma_f32 v[134:135], v[126:127], v[126:127], v[134:135]
	v_pk_fma_f32 v[134:135], v[128:129], v[128:129], v[134:135]
	v_pk_fma_f32 v[134:135], v[130:131], v[130:131], v[134:135]
	v_lshlrev_b32_e32 v116, 16, v16
	v_and_b32_e32 v117, 0xffff0000, v16
	v_lshlrev_b32_e32 v118, 16, v17
	v_and_b32_e32 v119, 0xffff0000, v17
	v_lshlrev_b32_e32 v120, 16, v18
	v_and_b32_e32 v121, 0xffff0000, v18
	v_lshlrev_b32_e32 v122, 16, v19
	v_and_b32_e32 v123, 0xffff0000, v19
	v_lshlrev_b32_e32 v124, 16, v20
	v_and_b32_e32 v125, 0xffff0000, v20
	v_lshlrev_b32_e32 v126, 16, v21
	v_and_b32_e32 v127, 0xffff0000, v21
	v_lshlrev_b32_e32 v128, 16, v22
	v_and_b32_e32 v129, 0xffff0000, v22
	v_lshlrev_b32_e32 v130, 16, v23
	v_and_b32_e32 v131, 0xffff0000, v23
	v_pk_mul_f32 v[136:137], v[116:117], v[116:117]
	v_pk_fma_f32 v[136:137], v[118:119], v[118:119], v[136:137]
	v_pk_fma_f32 v[136:137], v[120:121], v[120:121], v[136:137]
	v_pk_fma_f32 v[136:137], v[122:123], v[122:123], v[136:137]
	v_pk_fma_f32 v[136:137], v[124:125], v[124:125], v[136:137]
	v_pk_fma_f32 v[136:137], v[126:127], v[126:127], v[136:137]
	v_pk_fma_f32 v[136:137], v[128:129], v[128:129], v[136:137]
	v_pk_fma_f32 v[136:137], v[130:131], v[130:131], v[136:137]
	v_lshlrev_b32_e32 v116, 16, v24
	v_and_b32_e32 v117, 0xffff0000, v24
	v_lshlrev_b32_e32 v118, 16, v25
	v_and_b32_e32 v119, 0xffff0000, v25
	v_lshlrev_b32_e32 v120, 16, v26
	v_and_b32_e32 v121, 0xffff0000, v26
	v_lshlrev_b32_e32 v122, 16, v27
	v_and_b32_e32 v123, 0xffff0000, v27
	v_lshlrev_b32_e32 v124, 16, v28
	v_and_b32_e32 v125, 0xffff0000, v28
	v_lshlrev_b32_e32 v126, 16, v29
	v_and_b32_e32 v127, 0xffff0000, v29
	v_lshlrev_b32_e32 v128, 16, v30
	v_and_b32_e32 v129, 0xffff0000, v30
	v_lshlrev_b32_e32 v130, 16, v31
	v_and_b32_e32 v131, 0xffff0000, v31
	v_pk_mul_f32 v[138:139], v[116:117], v[116:117]
	v_pk_fma_f32 v[138:139], v[118:119], v[118:119], v[138:139]
	v_pk_fma_f32 v[138:139], v[120:121], v[120:121], v[138:139]
	v_pk_fma_f32 v[138:139], v[122:123], v[122:123], v[138:139]
	v_pk_fma_f32 v[138:139], v[124:125], v[124:125], v[138:139]
	v_pk_fma_f32 v[138:139], v[126:127], v[126:127], v[138:139]
	v_pk_fma_f32 v[138:139], v[128:129], v[128:129], v[138:139]
	v_pk_fma_f32 v[138:139], v[130:131], v[130:131], v[138:139]
	v_add_f32_e32 v132, v132, v133
	v_add_f32_e32 v134, v134, v135
	v_add_f32_e32 v136, v136, v137
	v_add_f32_e32 v138, v138, v139
	s_nop 1
	v_add_f32_dpp v132, v132, v132 row_shr:1 row_mask:0xf bank_mask:0xf bound_ctrl:1
	v_add_f32_dpp v134, v134, v134 row_shr:1 row_mask:0xf bank_mask:0xf bound_ctrl:1
	v_add_f32_dpp v136, v136, v136 row_shr:1 row_mask:0xf bank_mask:0xf bound_ctrl:1
	v_add_f32_dpp v138, v138, v138 row_shr:1 row_mask:0xf bank_mask:0xf bound_ctrl:1
	v_add_f32_dpp v132, v132, v132 row_shr:2 row_mask:0xf bank_mask:0xf bound_ctrl:1
	v_add_f32_dpp v134, v134, v134 row_shr:2 row_mask:0xf bank_mask:0xf bound_ctrl:1
	v_add_f32_dpp v136, v136, v136 row_shr:2 row_mask:0xf bank_mask:0xf bound_ctrl:1
	v_add_f32_dpp v138, v138, v138 row_shr:2 row_mask:0xf bank_mask:0xf bound_ctrl:1
	v_add_f32_dpp v132, v132, v132 row_shr:4 row_mask:0xf bank_mask:0xf bound_ctrl:1
	v_add_f32_dpp v134, v134, v134 row_shr:4 row_mask:0xf bank_mask:0xf bound_ctrl:1
	v_add_f32_dpp v136, v136, v136 row_shr:4 row_mask:0xf bank_mask:0xf bound_ctrl:1
	v_add_f32_dpp v138, v138, v138 row_shr:4 row_mask:0xf bank_mask:0xf bound_ctrl:1
	v_add_f32_dpp v132, v132, v132 row_shr:8 row_mask:0xf bank_mask:0xf bound_ctrl:1
	v_add_f32_dpp v134, v134, v134 row_shr:8 row_mask:0xf bank_mask:0xf bound_ctrl:1
	v_add_f32_dpp v136, v136, v136 row_shr:8 row_mask:0xf bank_mask:0xf bound_ctrl:1
	v_add_f32_dpp v138, v138, v138 row_shr:8 row_mask:0xf bank_mask:0xf bound_ctrl:1
	v_add_f32_dpp v132, v132, v132 row_bcast:15 row_mask:0xa bank_mask:0xf
	v_add_f32_dpp v134, v134, v134 row_bcast:15 row_mask:0xa bank_mask:0xf
	v_add_f32_dpp v136, v136, v136 row_bcast:15 row_mask:0xa bank_mask:0xf
	v_add_f32_dpp v138, v138, v138 row_bcast:15 row_mask:0xa bank_mask:0xf
	v_add_f32_dpp v132, v132, v132 row_bcast:31 row_mask:0xc bank_mask:0xf
	v_add_f32_dpp v134, v134, v134 row_bcast:31 row_mask:0xc bank_mask:0xf
	v_add_f32_dpp v136, v136, v136 row_bcast:31 row_mask:0xc bank_mask:0xf
	v_add_f32_dpp v138, v138, v138 row_bcast:31 row_mask:0xc bank_mask:0xf
	s_nop 1
	v_readlane_b32 s32, v132, 63
	v_readlane_b32 s28, v134, 63
	v_readlane_b32 s29, v136, 63
	v_readlane_b32 s30, v138, 63
	s_nop 1
	v_mov_b32_e32 v140, s32
	v_mov_b32_e32 v142, s28
	v_mov_b32_e32 v144, s29
	v_mov_b32_e32 v146, s30
	v_fmaak_f32 v140, v140, v50, 0x358637bd
	v_fmaak_f32 v142, v142, v50, 0x358637bd
	v_fmaak_f32 v144, v144, v50, 0x358637bd
	v_fmaak_f32 v146, v146, v50, 0x358637bd
	v_rsq_f32_e32 v140, v140
	v_rsq_f32_e32 v142, v142
	v_rsq_f32_e32 v144, v144
	v_rsq_f32_e32 v146, v146
	s_nop 0
	v_lshlrev_b32_e32 v116, 16, v0
	v_and_b32_e32 v117, 0xffff0000, v0
	v_lshlrev_b32_e32 v118, 16, v1
	v_and_b32_e32 v119, 0xffff0000, v1
	v_lshlrev_b32_e32 v120, 16, v2
	v_and_b32_e32 v121, 0xffff0000, v2
	v_lshlrev_b32_e32 v122, 16, v3
	v_and_b32_e32 v123, 0xffff0000, v3
	v_lshlrev_b32_e32 v124, 16, v4
	v_and_b32_e32 v125, 0xffff0000, v4
	v_lshlrev_b32_e32 v126, 16, v5
	v_and_b32_e32 v127, 0xffff0000, v5
	v_lshlrev_b32_e32 v128, 16, v6
	v_and_b32_e32 v129, 0xffff0000, v6
	v_lshlrev_b32_e32 v130, 16, v7
	v_and_b32_e32 v131, 0xffff0000, v7
	v_pk_mul_f32 v[116:117], v[140:141], v[116:117] op_sel_hi:[0,1]
	v_pk_mul_f32 v[118:119], v[140:141], v[118:119] op_sel_hi:[0,1]
	v_pk_mul_f32 v[120:121], v[140:141], v[120:121] op_sel_hi:[0,1]
	v_pk_mul_f32 v[122:123], v[140:141], v[122:123] op_sel_hi:[0,1]
	v_pk_mul_f32 v[124:125], v[140:141], v[124:125] op_sel_hi:[0,1]
	v_pk_mul_f32 v[126:127], v[140:141], v[126:127] op_sel_hi:[0,1]
	v_pk_mul_f32 v[128:129], v[140:141], v[128:129] op_sel_hi:[0,1]
	v_pk_mul_f32 v[130:131], v[140:141], v[130:131] op_sel_hi:[0,1]
	v_pk_mul_f32 v[116:117], v[116:117], v[32:33]
	v_pk_mul_f32 v[118:119], v[118:119], v[34:35]
	v_pk_mul_f32 v[120:121], v[120:121], v[36:37]
	v_pk_mul_f32 v[122:123], v[122:123], v[38:39]
	v_pk_mul_f32 v[124:125], v[124:125], v[40:41]
	v_pk_mul_f32 v[126:127], v[126:127], v[42:43]
	v_pk_mul_f32 v[128:129], v[128:129], v[44:45]
	v_pk_mul_f32 v[130:131], v[130:131], v[46:47]
	v_pk_fma_f32 v[116:117], v[116:117], v[84:85], v[100:101]
	v_pk_fma_f32 v[118:119], v[118:119], v[86:87], v[102:103]
	v_pk_fma_f32 v[120:121], v[120:121], v[88:89], v[104:105]
	v_pk_fma_f32 v[122:123], v[122:123], v[90:91], v[106:107]
	v_pk_fma_f32 v[124:125], v[124:125], v[92:93], v[108:109]
	v_pk_fma_f32 v[126:127], v[126:127], v[94:95], v[110:111]
	v_pk_fma_f32 v[128:129], v[128:129], v[96:97], v[112:113]
	v_pk_fma_f32 v[130:131], v[130:131], v[98:99], v[114:115]
	v_cvt_pk_bf16_f32 v172, v116, v117
	v_cvt_pk_bf16_f32 v173, v118, v119
	v_cvt_pk_bf16_f32 v174, v120, v121
	v_cvt_pk_bf16_f32 v175, v122, v123
	v_cvt_pk_bf16_f32 v176, v124, v125
	v_cvt_pk_bf16_f32 v177, v126, v127
	v_cvt_pk_bf16_f32 v178, v128, v129
	v_cvt_pk_bf16_f32 v179, v130, v131
	global_store_dwordx4 v51, v[172:175], s[26:27] sc1
	global_store_dwordx4 v51, v[176:179], s[26:27] offset:1024 sc1
	v_lshlrev_b32_e32 v116, 16, v8
	v_and_b32_e32 v117, 0xffff0000, v8
	v_lshlrev_b32_e32 v118, 16, v9
	v_and_b32_e32 v119, 0xffff0000, v9
	v_lshlrev_b32_e32 v120, 16, v10
	v_and_b32_e32 v121, 0xffff0000, v10
	v_lshlrev_b32_e32 v122, 16, v11
	v_and_b32_e32 v123, 0xffff0000, v11
	v_lshlrev_b32_e32 v124, 16, v12
	v_and_b32_e32 v125, 0xffff0000, v12
	v_lshlrev_b32_e32 v126, 16, v13
	v_and_b32_e32 v127, 0xffff0000, v13
	v_lshlrev_b32_e32 v128, 16, v14
	v_and_b32_e32 v129, 0xffff0000, v14
	v_lshlrev_b32_e32 v130, 16, v15
	v_and_b32_e32 v131, 0xffff0000, v15
	v_pk_mul_f32 v[116:117], v[142:143], v[116:117] op_sel_hi:[0,1]
	v_pk_mul_f32 v[118:119], v[142:143], v[118:119] op_sel_hi:[0,1]
	v_pk_mul_f32 v[120:121], v[142:143], v[120:121] op_sel_hi:[0,1]
	v_pk_mul_f32 v[122:123], v[142:143], v[122:123] op_sel_hi:[0,1]
	v_pk_mul_f32 v[124:125], v[142:143], v[124:125] op_sel_hi:[0,1]
	v_pk_mul_f32 v[126:127], v[142:143], v[126:127] op_sel_hi:[0,1]
	v_pk_mul_f32 v[128:129], v[142:143], v[128:129] op_sel_hi:[0,1]
	v_pk_mul_f32 v[130:131], v[142:143], v[130:131] op_sel_hi:[0,1]
	v_pk_mul_f32 v[116:117], v[116:117], v[32:33]
	v_pk_mul_f32 v[118:119], v[118:119], v[34:35]
	v_pk_mul_f32 v[120:121], v[120:121], v[36:37]
	v_pk_mul_f32 v[122:123], v[122:123], v[38:39]
	v_pk_mul_f32 v[124:125], v[124:125], v[40:41]
	v_pk_mul_f32 v[126:127], v[126:127], v[42:43]
	v_pk_mul_f32 v[128:129], v[128:129], v[44:45]
	v_pk_mul_f32 v[130:131], v[130:131], v[46:47]
	v_pk_fma_f32 v[116:117], v[116:117], v[84:85], v[100:101]
	v_pk_fma_f32 v[118:119], v[118:119], v[86:87], v[102:103]
	v_pk_fma_f32 v[120:121], v[120:121], v[88:89], v[104:105]
	v_pk_fma_f32 v[122:123], v[122:123], v[90:91], v[106:107]
	v_pk_fma_f32 v[124:125], v[124:125], v[92:93], v[108:109]
	v_pk_fma_f32 v[126:127], v[126:127], v[94:95], v[110:111]
	v_pk_fma_f32 v[128:129], v[128:129], v[96:97], v[112:113]
	v_pk_fma_f32 v[130:131], v[130:131], v[98:99], v[114:115]
	v_cvt_pk_bf16_f32 v164, v116, v117
	v_cvt_pk_bf16_f32 v165, v118, v119
	v_cvt_pk_bf16_f32 v166, v120, v121
	v_cvt_pk_bf16_f32 v167, v122, v123
	v_cvt_pk_bf16_f32 v168, v124, v125
	v_cvt_pk_bf16_f32 v169, v126, v127
	v_cvt_pk_bf16_f32 v170, v128, v129
	v_cvt_pk_bf16_f32 v171, v130, v131
	global_store_dwordx4 v51, v[164:167], s[26:27] offset:2048 sc1
	global_store_dwordx4 v51, v[168:171], s[26:27] offset:3072 sc1
	v_lshlrev_b32_e32 v116, 16, v16
	v_and_b32_e32 v117, 0xffff0000, v16
	v_lshlrev_b32_e32 v118, 16, v17
	v_and_b32_e32 v119, 0xffff0000, v17
	v_lshlrev_b32_e32 v120, 16, v18
	v_and_b32_e32 v121, 0xffff0000, v18
	v_lshlrev_b32_e32 v122, 16, v19
	v_and_b32_e32 v123, 0xffff0000, v19
	v_lshlrev_b32_e32 v124, 16, v20
	v_and_b32_e32 v125, 0xffff0000, v20
	v_lshlrev_b32_e32 v126, 16, v21
	v_and_b32_e32 v127, 0xffff0000, v21
	v_lshlrev_b32_e32 v128, 16, v22
	v_and_b32_e32 v129, 0xffff0000, v22
	v_lshlrev_b32_e32 v130, 16, v23
	v_and_b32_e32 v131, 0xffff0000, v23
	v_pk_mul_f32 v[116:117], v[144:145], v[116:117] op_sel_hi:[0,1]
	v_pk_mul_f32 v[118:119], v[144:145], v[118:119] op_sel_hi:[0,1]
	v_pk_mul_f32 v[120:121], v[144:145], v[120:121] op_sel_hi:[0,1]
	v_pk_mul_f32 v[122:123], v[144:145], v[122:123] op_sel_hi:[0,1]
	v_pk_mul_f32 v[124:125], v[144:145], v[124:125] op_sel_hi:[0,1]
	v_pk_mul_f32 v[126:127], v[144:145], v[126:127] op_sel_hi:[0,1]
	v_pk_mul_f32 v[128:129], v[144:145], v[128:129] op_sel_hi:[0,1]
	v_pk_mul_f32 v[130:131], v[144:145], v[130:131] op_sel_hi:[0,1]
	v_pk_mul_f32 v[116:117], v[116:117], v[32:33]
	v_pk_mul_f32 v[118:119], v[118:119], v[34:35]
	v_pk_mul_f32 v[120:121], v[120:121], v[36:37]
	v_pk_mul_f32 v[122:123], v[122:123], v[38:39]
	v_pk_mul_f32 v[124:125], v[124:125], v[40:41]
	v_pk_mul_f32 v[126:127], v[126:127], v[42:43]
	v_pk_mul_f32 v[128:129], v[128:129], v[44:45]
	v_pk_mul_f32 v[130:131], v[130:131], v[46:47]
	v_pk_fma_f32 v[116:117], v[116:117], v[84:85], v[100:101]
	v_pk_fma_f32 v[118:119], v[118:119], v[86:87], v[102:103]
	v_pk_fma_f32 v[120:121], v[120:121], v[88:89], v[104:105]
	v_pk_fma_f32 v[122:123], v[122:123], v[90:91], v[106:107]
	v_pk_fma_f32 v[124:125], v[124:125], v[92:93], v[108:109]
	v_pk_fma_f32 v[126:127], v[126:127], v[94:95], v[110:111]
	v_pk_fma_f32 v[128:129], v[128:129], v[96:97], v[112:113]
	v_pk_fma_f32 v[130:131], v[130:131], v[98:99], v[114:115]
	v_cvt_pk_bf16_f32 v172, v116, v117
	v_cvt_pk_bf16_f32 v173, v118, v119
	v_cvt_pk_bf16_f32 v174, v120, v121
	v_cvt_pk_bf16_f32 v175, v122, v123
	v_cvt_pk_bf16_f32 v176, v124, v125
	v_cvt_pk_bf16_f32 v177, v126, v127
	v_cvt_pk_bf16_f32 v178, v128, v129
	v_cvt_pk_bf16_f32 v179, v130, v131
	global_store_dwordx4 v149, v[172:175], s[26:27] sc1
	global_store_dwordx4 v149, v[176:179], s[26:27] offset:1024 sc1
	v_lshlrev_b32_e32 v116, 16, v24
	v_and_b32_e32 v117, 0xffff0000, v24
	v_lshlrev_b32_e32 v118, 16, v25
	v_and_b32_e32 v119, 0xffff0000, v25
	v_lshlrev_b32_e32 v120, 16, v26
	v_and_b32_e32 v121, 0xffff0000, v26
	v_lshlrev_b32_e32 v122, 16, v27
	v_and_b32_e32 v123, 0xffff0000, v27
	v_lshlrev_b32_e32 v124, 16, v28
	v_and_b32_e32 v125, 0xffff0000, v28
	v_lshlrev_b32_e32 v126, 16, v29
	v_and_b32_e32 v127, 0xffff0000, v29
	v_lshlrev_b32_e32 v128, 16, v30
	v_and_b32_e32 v129, 0xffff0000, v30
	v_lshlrev_b32_e32 v130, 16, v31
	v_and_b32_e32 v131, 0xffff0000, v31
	v_pk_mul_f32 v[116:117], v[146:147], v[116:117] op_sel_hi:[0,1]
	v_pk_mul_f32 v[118:119], v[146:147], v[118:119] op_sel_hi:[0,1]
	v_pk_mul_f32 v[120:121], v[146:147], v[120:121] op_sel_hi:[0,1]
	v_pk_mul_f32 v[122:123], v[146:147], v[122:123] op_sel_hi:[0,1]
	v_pk_mul_f32 v[124:125], v[146:147], v[124:125] op_sel_hi:[0,1]
	v_pk_mul_f32 v[126:127], v[146:147], v[126:127] op_sel_hi:[0,1]
	v_pk_mul_f32 v[128:129], v[146:147], v[128:129] op_sel_hi:[0,1]
	v_pk_mul_f32 v[130:131], v[146:147], v[130:131] op_sel_hi:[0,1]
	v_pk_mul_f32 v[116:117], v[116:117], v[32:33]
	v_pk_mul_f32 v[118:119], v[118:119], v[34:35]
	v_pk_mul_f32 v[120:121], v[120:121], v[36:37]
	v_pk_mul_f32 v[122:123], v[122:123], v[38:39]
	v_pk_mul_f32 v[124:125], v[124:125], v[40:41]
	v_pk_mul_f32 v[126:127], v[126:127], v[42:43]
	v_pk_mul_f32 v[128:129], v[128:129], v[44:45]
	v_pk_mul_f32 v[130:131], v[130:131], v[46:47]
	v_pk_fma_f32 v[116:117], v[116:117], v[84:85], v[100:101]
	v_pk_fma_f32 v[118:119], v[118:119], v[86:87], v[102:103]
	v_pk_fma_f32 v[120:121], v[120:121], v[88:89], v[104:105]
	v_pk_fma_f32 v[122:123], v[122:123], v[90:91], v[106:107]
	v_pk_fma_f32 v[124:125], v[124:125], v[92:93], v[108:109]
	v_pk_fma_f32 v[126:127], v[126:127], v[94:95], v[110:111]
	v_pk_fma_f32 v[128:129], v[128:129], v[96:97], v[112:113]
	v_pk_fma_f32 v[130:131], v[130:131], v[98:99], v[114:115]
	v_cvt_pk_bf16_f32 v164, v116, v117
	v_cvt_pk_bf16_f32 v165, v118, v119
	v_cvt_pk_bf16_f32 v166, v120, v121
	v_cvt_pk_bf16_f32 v167, v122, v123
	v_cvt_pk_bf16_f32 v168, v124, v125
	v_cvt_pk_bf16_f32 v169, v126, v127
	v_cvt_pk_bf16_f32 v170, v128, v129
	v_cvt_pk_bf16_f32 v171, v130, v131
	global_store_dwordx4 v149, v[164:167], s[26:27] offset:2048 sc1
	global_store_dwordx4 v149, v[168:171], s[26:27] offset:3072 sc1
	s_add_u32 s26, s26, 0x2000
	s_addc_u32 s27, s27, 0
	s_add_u32 s24, s24, 0x2000
	s_addc_u32 s25, s25, 0
	global_load_dwordx4 v[0:3], v51, s[24:25]
	global_load_dwordx4 v[4:7], v51, s[24:25] offset:1024
	global_load_dwordx4 v[8:11], v51, s[24:25] offset:2048
	global_load_dwordx4 v[12:15], v51, s[24:25] offset:3072
	global_load_dwordx4 v[16:19], v149, s[24:25]
	global_load_dwordx4 v[20:23], v149, s[24:25] offset:1024
	global_load_dwordx4 v[24:27], v149, s[24:25] offset:2048
	global_load_dwordx4 v[28:31], v149, s[24:25] offset:3072
	s_waitcnt vmcnt(16)
	v_lshlrev_b32_e32 v116, 16, v52
	v_and_b32_e32 v117, 0xffff0000, v52
	v_lshlrev_b32_e32 v118, 16, v53
	v_and_b32_e32 v119, 0xffff0000, v53
	v_lshlrev_b32_e32 v120, 16, v54
	v_and_b32_e32 v121, 0xffff0000, v54
	v_lshlrev_b32_e32 v122, 16, v55
	v_and_b32_e32 v123, 0xffff0000, v55
	v_lshlrev_b32_e32 v124, 16, v56
	v_and_b32_e32 v125, 0xffff0000, v56
	v_lshlrev_b32_e32 v126, 16, v57
	v_and_b32_e32 v127, 0xffff0000, v57
	v_lshlrev_b32_e32 v128, 16, v58
	v_and_b32_e32 v129, 0xffff0000, v58
	v_lshlrev_b32_e32 v130, 16, v59
	v_and_b32_e32 v131, 0xffff0000, v59
	v_pk_mul_f32 v[132:133], v[116:117], v[116:117]
	v_pk_fma_f32 v[132:133], v[118:119], v[118:119], v[132:133]
	v_pk_fma_f32 v[132:133], v[120:121], v[120:121], v[132:133]
	v_pk_fma_f32 v[132:133], v[122:123], v[122:123], v[132:133]
	v_pk_fma_f32 v[132:133], v[124:125], v[124:125], v[132:133]
	v_pk_fma_f32 v[132:133], v[126:127], v[126:127], v[132:133]
	v_pk_fma_f32 v[132:133], v[128:129], v[128:129], v[132:133]
	v_pk_fma_f32 v[132:133], v[130:131], v[130:131], v[132:133]
	v_lshlrev_b32_e32 v116, 16, v60
	v_and_b32_e32 v117, 0xffff0000, v60
	v_lshlrev_b32_e32 v118, 16, v61
	v_and_b32_e32 v119, 0xffff0000, v61
	v_lshlrev_b32_e32 v120, 16, v62
	v_and_b32_e32 v121, 0xffff0000, v62
	v_lshlrev_b32_e32 v122, 16, v63
	v_and_b32_e32 v123, 0xffff0000, v63
	v_lshlrev_b32_e32 v124, 16, v64
	v_and_b32_e32 v125, 0xffff0000, v64
	v_lshlrev_b32_e32 v126, 16, v65
	v_and_b32_e32 v127, 0xffff0000, v65
	v_lshlrev_b32_e32 v128, 16, v66
	v_and_b32_e32 v129, 0xffff0000, v66
	v_lshlrev_b32_e32 v130, 16, v67
	v_and_b32_e32 v131, 0xffff0000, v67
	v_pk_mul_f32 v[134:135], v[116:117], v[116:117]
	v_pk_fma_f32 v[134:135], v[118:119], v[118:119], v[134:135]
	v_pk_fma_f32 v[134:135], v[120:121], v[120:121], v[134:135]
	v_pk_fma_f32 v[134:135], v[122:123], v[122:123], v[134:135]
	v_pk_fma_f32 v[134:135], v[124:125], v[124:125], v[134:135]
	v_pk_fma_f32 v[134:135], v[126:127], v[126:127], v[134:135]
	v_pk_fma_f32 v[134:135], v[128:129], v[128:129], v[134:135]
	v_pk_fma_f32 v[134:135], v[130:131], v[130:131], v[134:135]
	v_lshlrev_b32_e32 v116, 16, v68
	v_and_b32_e32 v117, 0xffff0000, v68
	v_lshlrev_b32_e32 v118, 16, v69
	v_and_b32_e32 v119, 0xffff0000, v69
	v_lshlrev_b32_e32 v120, 16, v70
	v_and_b32_e32 v121, 0xffff0000, v70
	v_lshlrev_b32_e32 v122, 16, v71
	v_and_b32_e32 v123, 0xffff0000, v71
	v_lshlrev_b32_e32 v124, 16, v72
	v_and_b32_e32 v125, 0xffff0000, v72
	v_lshlrev_b32_e32 v126, 16, v73
	v_and_b32_e32 v127, 0xffff0000, v73
	v_lshlrev_b32_e32 v128, 16, v74
	v_and_b32_e32 v129, 0xffff0000, v74
	v_lshlrev_b32_e32 v130, 16, v75
	v_and_b32_e32 v131, 0xffff0000, v75
	v_pk_mul_f32 v[136:137], v[116:117], v[116:117]
	v_pk_fma_f32 v[136:137], v[118:119], v[118:119], v[136:137]
	v_pk_fma_f32 v[136:137], v[120:121], v[120:121], v[136:137]
	v_pk_fma_f32 v[136:137], v[122:123], v[122:123], v[136:137]
	v_pk_fma_f32 v[136:137], v[124:125], v[124:125], v[136:137]
	v_pk_fma_f32 v[136:137], v[126:127], v[126:127], v[136:137]
	v_pk_fma_f32 v[136:137], v[128:129], v[128:129], v[136:137]
	v_pk_fma_f32 v[136:137], v[130:131], v[130:131], v[136:137]
	v_lshlrev_b32_e32 v116, 16, v76
	v_and_b32_e32 v117, 0xffff0000, v76
	v_lshlrev_b32_e32 v118, 16, v77
	v_and_b32_e32 v119, 0xffff0000, v77
	v_lshlrev_b32_e32 v120, 16, v78
	v_and_b32_e32 v121, 0xffff0000, v78
	v_lshlrev_b32_e32 v122, 16, v79
	v_and_b32_e32 v123, 0xffff0000, v79
	v_lshlrev_b32_e32 v124, 16, v80
	v_and_b32_e32 v125, 0xffff0000, v80
	v_lshlrev_b32_e32 v126, 16, v81
	v_and_b32_e32 v127, 0xffff0000, v81
	v_lshlrev_b32_e32 v128, 16, v82
	v_and_b32_e32 v129, 0xffff0000, v82
	v_lshlrev_b32_e32 v130, 16, v83
	v_and_b32_e32 v131, 0xffff0000, v83
	v_pk_mul_f32 v[138:139], v[116:117], v[116:117]
	v_pk_fma_f32 v[138:139], v[118:119], v[118:119], v[138:139]
	v_pk_fma_f32 v[138:139], v[120:121], v[120:121], v[138:139]
	v_pk_fma_f32 v[138:139], v[122:123], v[122:123], v[138:139]
	v_pk_fma_f32 v[138:139], v[124:125], v[124:125], v[138:139]
	v_pk_fma_f32 v[138:139], v[126:127], v[126:127], v[138:139]
	v_pk_fma_f32 v[138:139], v[128:129], v[128:129], v[138:139]
	v_pk_fma_f32 v[138:139], v[130:131], v[130:131], v[138:139]
	v_add_f32_e32 v132, v132, v133
	v_add_f32_e32 v134, v134, v135
	v_add_f32_e32 v136, v136, v137
	v_add_f32_e32 v138, v138, v139
	s_nop 1
	v_add_f32_dpp v132, v132, v132 row_shr:1 row_mask:0xf bank_mask:0xf bound_ctrl:1
	v_add_f32_dpp v134, v134, v134 row_shr:1 row_mask:0xf bank_mask:0xf bound_ctrl:1
	v_add_f32_dpp v136, v136, v136 row_shr:1 row_mask:0xf bank_mask:0xf bound_ctrl:1
	v_add_f32_dpp v138, v138, v138 row_shr:1 row_mask:0xf bank_mask:0xf bound_ctrl:1
	v_add_f32_dpp v132, v132, v132 row_shr:2 row_mask:0xf bank_mask:0xf bound_ctrl:1
	v_add_f32_dpp v134, v134, v134 row_shr:2 row_mask:0xf bank_mask:0xf bound_ctrl:1
	v_add_f32_dpp v136, v136, v136 row_shr:2 row_mask:0xf bank_mask:0xf bound_ctrl:1
	v_add_f32_dpp v138, v138, v138 row_shr:2 row_mask:0xf bank_mask:0xf bound_ctrl:1
	v_add_f32_dpp v132, v132, v132 row_shr:4 row_mask:0xf bank_mask:0xf bound_ctrl:1
	v_add_f32_dpp v134, v134, v134 row_shr:4 row_mask:0xf bank_mask:0xf bound_ctrl:1
	v_add_f32_dpp v136, v136, v136 row_shr:4 row_mask:0xf bank_mask:0xf bound_ctrl:1
	v_add_f32_dpp v138, v138, v138 row_shr:4 row_mask:0xf bank_mask:0xf bound_ctrl:1
	v_add_f32_dpp v132, v132, v132 row_shr:8 row_mask:0xf bank_mask:0xf bound_ctrl:1
	v_add_f32_dpp v134, v134, v134 row_shr:8 row_mask:0xf bank_mask:0xf bound_ctrl:1
	v_add_f32_dpp v136, v136, v136 row_shr:8 row_mask:0xf bank_mask:0xf bound_ctrl:1
	v_add_f32_dpp v138, v138, v138 row_shr:8 row_mask:0xf bank_mask:0xf bound_ctrl:1
	v_add_f32_dpp v132, v132, v132 row_bcast:15 row_mask:0xa bank_mask:0xf
	v_add_f32_dpp v134, v134, v134 row_bcast:15 row_mask:0xa bank_mask:0xf
	v_add_f32_dpp v136, v136, v136 row_bcast:15 row_mask:0xa bank_mask:0xf
	v_add_f32_dpp v138, v138, v138 row_bcast:15 row_mask:0xa bank_mask:0xf
	v_add_f32_dpp v132, v132, v132 row_bcast:31 row_mask:0xc bank_mask:0xf
	v_add_f32_dpp v134, v134, v134 row_bcast:31 row_mask:0xc bank_mask:0xf
	v_add_f32_dpp v136, v136, v136 row_bcast:31 row_mask:0xc bank_mask:0xf
	v_add_f32_dpp v138, v138, v138 row_bcast:31 row_mask:0xc bank_mask:0xf
	s_nop 1
	v_readlane_b32 s32, v132, 63
	v_readlane_b32 s28, v134, 63
	v_readlane_b32 s29, v136, 63
	v_readlane_b32 s30, v138, 63
	s_nop 1
	v_mov_b32_e32 v140, s32
	v_mov_b32_e32 v142, s28
	v_mov_b32_e32 v144, s29
	v_mov_b32_e32 v146, s30
	v_fmaak_f32 v140, v140, v50, 0x358637bd
	v_fmaak_f32 v142, v142, v50, 0x358637bd
	v_fmaak_f32 v144, v144, v50, 0x358637bd
	v_fmaak_f32 v146, v146, v50, 0x358637bd
	v_rsq_f32_e32 v140, v140
	v_rsq_f32_e32 v142, v142
	v_rsq_f32_e32 v144, v144
	v_rsq_f32_e32 v146, v146
	s_nop 0
	v_lshlrev_b32_e32 v116, 16, v52
	v_and_b32_e32 v117, 0xffff0000, v52
	v_lshlrev_b32_e32 v118, 16, v53
	v_and_b32_e32 v119, 0xffff0000, v53
	v_lshlrev_b32_e32 v120, 16, v54
	v_and_b32_e32 v121, 0xffff0000, v54
	v_lshlrev_b32_e32 v122, 16, v55
	v_and_b32_e32 v123, 0xffff0000, v55
	v_lshlrev_b32_e32 v124, 16, v56
	v_and_b32_e32 v125, 0xffff0000, v56
	v_lshlrev_b32_e32 v126, 16, v57
	v_and_b32_e32 v127, 0xffff0000, v57
	v_lshlrev_b32_e32 v128, 16, v58
	v_and_b32_e32 v129, 0xffff0000, v58
	v_lshlrev_b32_e32 v130, 16, v59
	v_and_b32_e32 v131, 0xffff0000, v59
	v_pk_mul_f32 v[116:117], v[140:141], v[116:117] op_sel_hi:[0,1]
	v_pk_mul_f32 v[118:119], v[140:141], v[118:119] op_sel_hi:[0,1]
	v_pk_mul_f32 v[120:121], v[140:141], v[120:121] op_sel_hi:[0,1]
	v_pk_mul_f32 v[122:123], v[140:141], v[122:123] op_sel_hi:[0,1]
	v_pk_mul_f32 v[124:125], v[140:141], v[124:125] op_sel_hi:[0,1]
	v_pk_mul_f32 v[126:127], v[140:141], v[126:127] op_sel_hi:[0,1]
	v_pk_mul_f32 v[128:129], v[140:141], v[128:129] op_sel_hi:[0,1]
	v_pk_mul_f32 v[130:131], v[140:141], v[130:131] op_sel_hi:[0,1]
	v_pk_mul_f32 v[116:117], v[116:117], v[32:33]
	v_pk_mul_f32 v[118:119], v[118:119], v[34:35]
	v_pk_mul_f32 v[120:121], v[120:121], v[36:37]
	v_pk_mul_f32 v[122:123], v[122:123], v[38:39]
	v_pk_mul_f32 v[124:125], v[124:125], v[40:41]
	v_pk_mul_f32 v[126:127], v[126:127], v[42:43]
	v_pk_mul_f32 v[128:129], v[128:129], v[44:45]
	v_pk_mul_f32 v[130:131], v[130:131], v[46:47]
	v_pk_fma_f32 v[116:117], v[116:117], v[84:85], v[100:101]
	v_pk_fma_f32 v[118:119], v[118:119], v[86:87], v[102:103]
	v_pk_fma_f32 v[120:121], v[120:121], v[88:89], v[104:105]
	v_pk_fma_f32 v[122:123], v[122:123], v[90:91], v[106:107]
	v_pk_fma_f32 v[124:125], v[124:125], v[92:93], v[108:109]
	v_pk_fma_f32 v[126:127], v[126:127], v[94:95], v[110:111]
	v_pk_fma_f32 v[128:129], v[128:129], v[96:97], v[112:113]
	v_pk_fma_f32 v[130:131], v[130:131], v[98:99], v[114:115]
	v_cvt_pk_bf16_f32 v164, v116, v117
	v_cvt_pk_bf16_f32 v165, v118, v119
	v_cvt_pk_bf16_f32 v166, v120, v121
	v_cvt_pk_bf16_f32 v167, v122, v123
	v_cvt_pk_bf16_f32 v168, v124, v125
	v_cvt_pk_bf16_f32 v169, v126, v127
	v_cvt_pk_bf16_f32 v170, v128, v129
	v_cvt_pk_bf16_f32 v171, v130, v131
	global_store_dwordx4 v51, v[164:167], s[26:27] sc1
	global_store_dwordx4 v51, v[168:171], s[26:27] offset:1024 sc1
	v_lshlrev_b32_e32 v116, 16, v60
	v_and_b32_e32 v117, 0xffff0000, v60
	v_lshlrev_b32_e32 v118, 16, v61
	v_and_b32_e32 v119, 0xffff0000, v61
	v_lshlrev_b32_e32 v120, 16, v62
	v_and_b32_e32 v121, 0xffff0000, v62
	v_lshlrev_b32_e32 v122, 16, v63
	v_and_b32_e32 v123, 0xffff0000, v63
	v_lshlrev_b32_e32 v124, 16, v64
	v_and_b32_e32 v125, 0xffff0000, v64
	v_lshlrev_b32_e32 v126, 16, v65
	v_and_b32_e32 v127, 0xffff0000, v65
	v_lshlrev_b32_e32 v128, 16, v66
	v_and_b32_e32 v129, 0xffff0000, v66
	v_lshlrev_b32_e32 v130, 16, v67
	v_and_b32_e32 v131, 0xffff0000, v67
	v_pk_mul_f32 v[116:117], v[142:143], v[116:117] op_sel_hi:[0,1]
	v_pk_mul_f32 v[118:119], v[142:143], v[118:119] op_sel_hi:[0,1]
	v_pk_mul_f32 v[120:121], v[142:143], v[120:121] op_sel_hi:[0,1]
	v_pk_mul_f32 v[122:123], v[142:143], v[122:123] op_sel_hi:[0,1]
	v_pk_mul_f32 v[124:125], v[142:143], v[124:125] op_sel_hi:[0,1]
	v_pk_mul_f32 v[126:127], v[142:143], v[126:127] op_sel_hi:[0,1]
	v_pk_mul_f32 v[128:129], v[142:143], v[128:129] op_sel_hi:[0,1]
	v_pk_mul_f32 v[130:131], v[142:143], v[130:131] op_sel_hi:[0,1]
	v_pk_mul_f32 v[116:117], v[116:117], v[32:33]
	v_pk_mul_f32 v[118:119], v[118:119], v[34:35]
	v_pk_mul_f32 v[120:121], v[120:121], v[36:37]
	v_pk_mul_f32 v[122:123], v[122:123], v[38:39]
	v_pk_mul_f32 v[124:125], v[124:125], v[40:41]
	v_pk_mul_f32 v[126:127], v[126:127], v[42:43]
	v_pk_mul_f32 v[128:129], v[128:129], v[44:45]
	v_pk_mul_f32 v[130:131], v[130:131], v[46:47]
	v_pk_fma_f32 v[116:117], v[116:117], v[84:85], v[100:101]
	v_pk_fma_f32 v[118:119], v[118:119], v[86:87], v[102:103]
	v_pk_fma_f32 v[120:121], v[120:121], v[88:89], v[104:105]
	v_pk_fma_f32 v[122:123], v[122:123], v[90:91], v[106:107]
	v_pk_fma_f32 v[124:125], v[124:125], v[92:93], v[108:109]
	v_pk_fma_f32 v[126:127], v[126:127], v[94:95], v[110:111]
	v_pk_fma_f32 v[128:129], v[128:129], v[96:97], v[112:113]
	v_pk_fma_f32 v[130:131], v[130:131], v[98:99], v[114:115]
	v_cvt_pk_bf16_f32 v172, v116, v117
	v_cvt_pk_bf16_f32 v173, v118, v119
	v_cvt_pk_bf16_f32 v174, v120, v121
	v_cvt_pk_bf16_f32 v175, v122, v123
	v_cvt_pk_bf16_f32 v176, v124, v125
	v_cvt_pk_bf16_f32 v177, v126, v127
	v_cvt_pk_bf16_f32 v178, v128, v129
	v_cvt_pk_bf16_f32 v179, v130, v131
	global_store_dwordx4 v51, v[172:175], s[26:27] offset:2048 sc1
	global_store_dwordx4 v51, v[176:179], s[26:27] offset:3072 sc1
	v_lshlrev_b32_e32 v116, 16, v68
	v_and_b32_e32 v117, 0xffff0000, v68
	v_lshlrev_b32_e32 v118, 16, v69
	v_and_b32_e32 v119, 0xffff0000, v69
	v_lshlrev_b32_e32 v120, 16, v70
	v_and_b32_e32 v121, 0xffff0000, v70
	v_lshlrev_b32_e32 v122, 16, v71
	v_and_b32_e32 v123, 0xffff0000, v71
	v_lshlrev_b32_e32 v124, 16, v72
	v_and_b32_e32 v125, 0xffff0000, v72
	v_lshlrev_b32_e32 v126, 16, v73
	v_and_b32_e32 v127, 0xffff0000, v73
	v_lshlrev_b32_e32 v128, 16, v74
	v_and_b32_e32 v129, 0xffff0000, v74
	v_lshlrev_b32_e32 v130, 16, v75
	v_and_b32_e32 v131, 0xffff0000, v75
	v_pk_mul_f32 v[116:117], v[144:145], v[116:117] op_sel_hi:[0,1]
	v_pk_mul_f32 v[118:119], v[144:145], v[118:119] op_sel_hi:[0,1]
	v_pk_mul_f32 v[120:121], v[144:145], v[120:121] op_sel_hi:[0,1]
	v_pk_mul_f32 v[122:123], v[144:145], v[122:123] op_sel_hi:[0,1]
	v_pk_mul_f32 v[124:125], v[144:145], v[124:125] op_sel_hi:[0,1]
	v_pk_mul_f32 v[126:127], v[144:145], v[126:127] op_sel_hi:[0,1]
	v_pk_mul_f32 v[128:129], v[144:145], v[128:129] op_sel_hi:[0,1]
	v_pk_mul_f32 v[130:131], v[144:145], v[130:131] op_sel_hi:[0,1]
	v_pk_mul_f32 v[116:117], v[116:117], v[32:33]
	v_pk_mul_f32 v[118:119], v[118:119], v[34:35]
	v_pk_mul_f32 v[120:121], v[120:121], v[36:37]
	v_pk_mul_f32 v[122:123], v[122:123], v[38:39]
	v_pk_mul_f32 v[124:125], v[124:125], v[40:41]
	v_pk_mul_f32 v[126:127], v[126:127], v[42:43]
	v_pk_mul_f32 v[128:129], v[128:129], v[44:45]
	v_pk_mul_f32 v[130:131], v[130:131], v[46:47]
	v_pk_fma_f32 v[116:117], v[116:117], v[84:85], v[100:101]
	v_pk_fma_f32 v[118:119], v[118:119], v[86:87], v[102:103]
	v_pk_fma_f32 v[120:121], v[120:121], v[88:89], v[104:105]
	v_pk_fma_f32 v[122:123], v[122:123], v[90:91], v[106:107]
	v_pk_fma_f32 v[124:125], v[124:125], v[92:93], v[108:109]
	v_pk_fma_f32 v[126:127], v[126:127], v[94:95], v[110:111]
	v_pk_fma_f32 v[128:129], v[128:129], v[96:97], v[112:113]
	v_pk_fma_f32 v[130:131], v[130:131], v[98:99], v[114:115]
	v_cvt_pk_bf16_f32 v164, v116, v117
	v_cvt_pk_bf16_f32 v165, v118, v119
	v_cvt_pk_bf16_f32 v166, v120, v121
	v_cvt_pk_bf16_f32 v167, v122, v123
	v_cvt_pk_bf16_f32 v168, v124, v125
	v_cvt_pk_bf16_f32 v169, v126, v127
	v_cvt_pk_bf16_f32 v170, v128, v129
	v_cvt_pk_bf16_f32 v171, v130, v131
	global_store_dwordx4 v149, v[164:167], s[26:27] sc1
	global_store_dwordx4 v149, v[168:171], s[26:27] offset:1024 sc1
	v_lshlrev_b32_e32 v116, 16, v76
	v_and_b32_e32 v117, 0xffff0000, v76
	v_lshlrev_b32_e32 v118, 16, v77
	v_and_b32_e32 v119, 0xffff0000, v77
	v_lshlrev_b32_e32 v120, 16, v78
	v_and_b32_e32 v121, 0xffff0000, v78
	v_lshlrev_b32_e32 v122, 16, v79
	v_and_b32_e32 v123, 0xffff0000, v79
	v_lshlrev_b32_e32 v124, 16, v80
	v_and_b32_e32 v125, 0xffff0000, v80
	v_lshlrev_b32_e32 v126, 16, v81
	v_and_b32_e32 v127, 0xffff0000, v81
	v_lshlrev_b32_e32 v128, 16, v82
	v_and_b32_e32 v129, 0xffff0000, v82
	v_lshlrev_b32_e32 v130, 16, v83
	v_and_b32_e32 v131, 0xffff0000, v83
	v_pk_mul_f32 v[116:117], v[146:147], v[116:117] op_sel_hi:[0,1]
	v_pk_mul_f32 v[118:119], v[146:147], v[118:119] op_sel_hi:[0,1]
	v_pk_mul_f32 v[120:121], v[146:147], v[120:121] op_sel_hi:[0,1]
	v_pk_mul_f32 v[122:123], v[146:147], v[122:123] op_sel_hi:[0,1]
	v_pk_mul_f32 v[124:125], v[146:147], v[124:125] op_sel_hi:[0,1]
	v_pk_mul_f32 v[126:127], v[146:147], v[126:127] op_sel_hi:[0,1]
	v_pk_mul_f32 v[128:129], v[146:147], v[128:129] op_sel_hi:[0,1]
	v_pk_mul_f32 v[130:131], v[146:147], v[130:131] op_sel_hi:[0,1]
	v_pk_mul_f32 v[116:117], v[116:117], v[32:33]
	v_pk_mul_f32 v[118:119], v[118:119], v[34:35]
	v_pk_mul_f32 v[120:121], v[120:121], v[36:37]
	v_pk_mul_f32 v[122:123], v[122:123], v[38:39]
	v_pk_mul_f32 v[124:125], v[124:125], v[40:41]
	v_pk_mul_f32 v[126:127], v[126:127], v[42:43]
	v_pk_mul_f32 v[128:129], v[128:129], v[44:45]
	v_pk_mul_f32 v[130:131], v[130:131], v[46:47]
	v_pk_fma_f32 v[116:117], v[116:117], v[84:85], v[100:101]
	v_pk_fma_f32 v[118:119], v[118:119], v[86:87], v[102:103]
	v_pk_fma_f32 v[120:121], v[120:121], v[88:89], v[104:105]
	v_pk_fma_f32 v[122:123], v[122:123], v[90:91], v[106:107]
	v_pk_fma_f32 v[124:125], v[124:125], v[92:93], v[108:109]
	v_pk_fma_f32 v[126:127], v[126:127], v[94:95], v[110:111]
	v_pk_fma_f32 v[128:129], v[128:129], v[96:97], v[112:113]
	v_pk_fma_f32 v[130:131], v[130:131], v[98:99], v[114:115]
	v_cvt_pk_bf16_f32 v172, v116, v117
	v_cvt_pk_bf16_f32 v173, v118, v119
	v_cvt_pk_bf16_f32 v174, v120, v121
	v_cvt_pk_bf16_f32 v175, v122, v123
	v_cvt_pk_bf16_f32 v176, v124, v125
	v_cvt_pk_bf16_f32 v177, v126, v127
	v_cvt_pk_bf16_f32 v178, v128, v129
	v_cvt_pk_bf16_f32 v179, v130, v131
	global_store_dwordx4 v149, v[172:175], s[26:27] offset:2048 sc1
	global_store_dwordx4 v149, v[176:179], s[26:27] offset:3072 sc1
	s_add_u32 s26, s26, 0x2000
	s_addc_u32 s27, s27, 0
	s_waitcnt vmcnt(8)
	v_lshlrev_b32_e32 v116, 16, v0
	v_and_b32_e32 v117, 0xffff0000, v0
	v_lshlrev_b32_e32 v118, 16, v1
	v_and_b32_e32 v119, 0xffff0000, v1
	v_lshlrev_b32_e32 v120, 16, v2
	v_and_b32_e32 v121, 0xffff0000, v2
	v_lshlrev_b32_e32 v122, 16, v3
	v_and_b32_e32 v123, 0xffff0000, v3
	v_lshlrev_b32_e32 v124, 16, v4
	v_and_b32_e32 v125, 0xffff0000, v4
	v_lshlrev_b32_e32 v126, 16, v5
	v_and_b32_e32 v127, 0xffff0000, v5
	v_lshlrev_b32_e32 v128, 16, v6
	v_and_b32_e32 v129, 0xffff0000, v6
	v_lshlrev_b32_e32 v130, 16, v7
	v_and_b32_e32 v131, 0xffff0000, v7
	v_pk_mul_f32 v[132:133], v[116:117], v[116:117]
	v_pk_fma_f32 v[132:133], v[118:119], v[118:119], v[132:133]
	v_pk_fma_f32 v[132:133], v[120:121], v[120:121], v[132:133]
	v_pk_fma_f32 v[132:133], v[122:123], v[122:123], v[132:133]
	v_pk_fma_f32 v[132:133], v[124:125], v[124:125], v[132:133]
	v_pk_fma_f32 v[132:133], v[126:127], v[126:127], v[132:133]
	v_pk_fma_f32 v[132:133], v[128:129], v[128:129], v[132:133]
	v_pk_fma_f32 v[132:133], v[130:131], v[130:131], v[132:133]
	v_lshlrev_b32_e32 v116, 16, v8
	v_and_b32_e32 v117, 0xffff0000, v8
	v_lshlrev_b32_e32 v118, 16, v9
	v_and_b32_e32 v119, 0xffff0000, v9
	v_lshlrev_b32_e32 v120, 16, v10
	v_and_b32_e32 v121, 0xffff0000, v10
	v_lshlrev_b32_e32 v122, 16, v11
	v_and_b32_e32 v123, 0xffff0000, v11
	v_lshlrev_b32_e32 v124, 16, v12
	v_and_b32_e32 v125, 0xffff0000, v12
	v_lshlrev_b32_e32 v126, 16, v13
	v_and_b32_e32 v127, 0xffff0000, v13
	v_lshlrev_b32_e32 v128, 16, v14
	v_and_b32_e32 v129, 0xffff0000, v14
	v_lshlrev_b32_e32 v130, 16, v15
	v_and_b32_e32 v131, 0xffff0000, v15
	v_pk_mul_f32 v[134:135], v[116:117], v[116:117]
	v_pk_fma_f32 v[134:135], v[118:119], v[118:119], v[134:135]
	v_pk_fma_f32 v[134:135], v[120:121], v[120:121], v[134:135]
	v_pk_fma_f32 v[134:135], v[122:123], v[122:123], v[134:135]
	v_pk_fma_f32 v[134:135], v[124:125], v[124:125], v[134:135]
	v_pk_fma_f32 v[134:135], v[126:127], v[126:127], v[134:135]
	v_pk_fma_f32 v[134:135], v[128:129], v[128:129], v[134:135]
	v_pk_fma_f32 v[134:135], v[130:131], v[130:131], v[134:135]
	v_lshlrev_b32_e32 v116, 16, v16
	v_and_b32_e32 v117, 0xffff0000, v16
	v_lshlrev_b32_e32 v118, 16, v17
	v_and_b32_e32 v119, 0xffff0000, v17
	v_lshlrev_b32_e32 v120, 16, v18
	v_and_b32_e32 v121, 0xffff0000, v18
	v_lshlrev_b32_e32 v122, 16, v19
	v_and_b32_e32 v123, 0xffff0000, v19
	v_lshlrev_b32_e32 v124, 16, v20
	v_and_b32_e32 v125, 0xffff0000, v20
	v_lshlrev_b32_e32 v126, 16, v21
	v_and_b32_e32 v127, 0xffff0000, v21
	v_lshlrev_b32_e32 v128, 16, v22
	v_and_b32_e32 v129, 0xffff0000, v22
	v_lshlrev_b32_e32 v130, 16, v23
	v_and_b32_e32 v131, 0xffff0000, v23
	v_pk_mul_f32 v[136:137], v[116:117], v[116:117]
	v_pk_fma_f32 v[136:137], v[118:119], v[118:119], v[136:137]
	v_pk_fma_f32 v[136:137], v[120:121], v[120:121], v[136:137]
	v_pk_fma_f32 v[136:137], v[122:123], v[122:123], v[136:137]
	v_pk_fma_f32 v[136:137], v[124:125], v[124:125], v[136:137]
	v_pk_fma_f32 v[136:137], v[126:127], v[126:127], v[136:137]
	v_pk_fma_f32 v[136:137], v[128:129], v[128:129], v[136:137]
	v_pk_fma_f32 v[136:137], v[130:131], v[130:131], v[136:137]
	v_lshlrev_b32_e32 v116, 16, v24
	v_and_b32_e32 v117, 0xffff0000, v24
	v_lshlrev_b32_e32 v118, 16, v25
	v_and_b32_e32 v119, 0xffff0000, v25
	v_lshlrev_b32_e32 v120, 16, v26
	v_and_b32_e32 v121, 0xffff0000, v26
	v_lshlrev_b32_e32 v122, 16, v27
	v_and_b32_e32 v123, 0xffff0000, v27
	v_lshlrev_b32_e32 v124, 16, v28
	v_and_b32_e32 v125, 0xffff0000, v28
	v_lshlrev_b32_e32 v126, 16, v29
	v_and_b32_e32 v127, 0xffff0000, v29
	v_lshlrev_b32_e32 v128, 16, v30
	v_and_b32_e32 v129, 0xffff0000, v30
	v_lshlrev_b32_e32 v130, 16, v31
	v_and_b32_e32 v131, 0xffff0000, v31
	v_pk_mul_f32 v[138:139], v[116:117], v[116:117]
	v_pk_fma_f32 v[138:139], v[118:119], v[118:119], v[138:139]
	v_pk_fma_f32 v[138:139], v[120:121], v[120:121], v[138:139]
	v_pk_fma_f32 v[138:139], v[122:123], v[122:123], v[138:139]
	v_pk_fma_f32 v[138:139], v[124:125], v[124:125], v[138:139]
	v_pk_fma_f32 v[138:139], v[126:127], v[126:127], v[138:139]
	v_pk_fma_f32 v[138:139], v[128:129], v[128:129], v[138:139]
	v_pk_fma_f32 v[138:139], v[130:131], v[130:131], v[138:139]
	v_add_f32_e32 v132, v132, v133
	v_add_f32_e32 v134, v134, v135
	v_add_f32_e32 v136, v136, v137
	v_add_f32_e32 v138, v138, v139
	s_nop 1
	v_add_f32_dpp v132, v132, v132 row_shr:1 row_mask:0xf bank_mask:0xf bound_ctrl:1
	v_add_f32_dpp v134, v134, v134 row_shr:1 row_mask:0xf bank_mask:0xf bound_ctrl:1
	v_add_f32_dpp v136, v136, v136 row_shr:1 row_mask:0xf bank_mask:0xf bound_ctrl:1
	v_add_f32_dpp v138, v138, v138 row_shr:1 row_mask:0xf bank_mask:0xf bound_ctrl:1
	v_add_f32_dpp v132, v132, v132 row_shr:2 row_mask:0xf bank_mask:0xf bound_ctrl:1
	v_add_f32_dpp v134, v134, v134 row_shr:2 row_mask:0xf bank_mask:0xf bound_ctrl:1
	v_add_f32_dpp v136, v136, v136 row_shr:2 row_mask:0xf bank_mask:0xf bound_ctrl:1
	v_add_f32_dpp v138, v138, v138 row_shr:2 row_mask:0xf bank_mask:0xf bound_ctrl:1
	v_add_f32_dpp v132, v132, v132 row_shr:4 row_mask:0xf bank_mask:0xf bound_ctrl:1
	v_add_f32_dpp v134, v134, v134 row_shr:4 row_mask:0xf bank_mask:0xf bound_ctrl:1
	v_add_f32_dpp v136, v136, v136 row_shr:4 row_mask:0xf bank_mask:0xf bound_ctrl:1
	v_add_f32_dpp v138, v138, v138 row_shr:4 row_mask:0xf bank_mask:0xf bound_ctrl:1
	v_add_f32_dpp v132, v132, v132 row_shr:8 row_mask:0xf bank_mask:0xf bound_ctrl:1
	v_add_f32_dpp v134, v134, v134 row_shr:8 row_mask:0xf bank_mask:0xf bound_ctrl:1
	v_add_f32_dpp v136, v136, v136 row_shr:8 row_mask:0xf bank_mask:0xf bound_ctrl:1
	v_add_f32_dpp v138, v138, v138 row_shr:8 row_mask:0xf bank_mask:0xf bound_ctrl:1
	v_add_f32_dpp v132, v132, v132 row_bcast:15 row_mask:0xa bank_mask:0xf
	v_add_f32_dpp v134, v134, v134 row_bcast:15 row_mask:0xa bank_mask:0xf
	v_add_f32_dpp v136, v136, v136 row_bcast:15 row_mask:0xa bank_mask:0xf
	v_add_f32_dpp v138, v138, v138 row_bcast:15 row_mask:0xa bank_mask:0xf
	v_add_f32_dpp v132, v132, v132 row_bcast:31 row_mask:0xc bank_mask:0xf
	v_add_f32_dpp v134, v134, v134 row_bcast:31 row_mask:0xc bank_mask:0xf
	v_add_f32_dpp v136, v136, v136 row_bcast:31 row_mask:0xc bank_mask:0xf
	v_add_f32_dpp v138, v138, v138 row_bcast:31 row_mask:0xc bank_mask:0xf
	s_nop 1
	v_readlane_b32 s32, v132, 63
	v_readlane_b32 s28, v134, 63
	v_readlane_b32 s29, v136, 63
	v_readlane_b32 s30, v138, 63
	s_nop 1
	v_mov_b32_e32 v140, s32
	v_mov_b32_e32 v142, s28
	v_mov_b32_e32 v144, s29
	v_mov_b32_e32 v146, s30
	v_fmaak_f32 v140, v140, v50, 0x358637bd
	v_fmaak_f32 v142, v142, v50, 0x358637bd
	v_fmaak_f32 v144, v144, v50, 0x358637bd
	v_fmaak_f32 v146, v146, v50, 0x358637bd
	v_rsq_f32_e32 v140, v140
	v_rsq_f32_e32 v142, v142
	v_rsq_f32_e32 v144, v144
	v_rsq_f32_e32 v146, v146
	s_nop 0
	v_lshlrev_b32_e32 v116, 16, v0
	v_and_b32_e32 v117, 0xffff0000, v0
	v_lshlrev_b32_e32 v118, 16, v1
	v_and_b32_e32 v119, 0xffff0000, v1
	v_lshlrev_b32_e32 v120, 16, v2
	v_and_b32_e32 v121, 0xffff0000, v2
	v_lshlrev_b32_e32 v122, 16, v3
	v_and_b32_e32 v123, 0xffff0000, v3
	v_lshlrev_b32_e32 v124, 16, v4
	v_and_b32_e32 v125, 0xffff0000, v4
	v_lshlrev_b32_e32 v126, 16, v5
	v_and_b32_e32 v127, 0xffff0000, v5
	v_lshlrev_b32_e32 v128, 16, v6
	v_and_b32_e32 v129, 0xffff0000, v6
	v_lshlrev_b32_e32 v130, 16, v7
	v_and_b32_e32 v131, 0xffff0000, v7
	v_pk_mul_f32 v[116:117], v[140:141], v[116:117] op_sel_hi:[0,1]
	v_pk_mul_f32 v[118:119], v[140:141], v[118:119] op_sel_hi:[0,1]
	v_pk_mul_f32 v[120:121], v[140:141], v[120:121] op_sel_hi:[0,1]
	v_pk_mul_f32 v[122:123], v[140:141], v[122:123] op_sel_hi:[0,1]
	v_pk_mul_f32 v[124:125], v[140:141], v[124:125] op_sel_hi:[0,1]
	v_pk_mul_f32 v[126:127], v[140:141], v[126:127] op_sel_hi:[0,1]
	v_pk_mul_f32 v[128:129], v[140:141], v[128:129] op_sel_hi:[0,1]
	v_pk_mul_f32 v[130:131], v[140:141], v[130:131] op_sel_hi:[0,1]
	v_pk_mul_f32 v[116:117], v[116:117], v[32:33]
	v_pk_mul_f32 v[118:119], v[118:119], v[34:35]
	v_pk_mul_f32 v[120:121], v[120:121], v[36:37]
	v_pk_mul_f32 v[122:123], v[122:123], v[38:39]
	v_pk_mul_f32 v[124:125], v[124:125], v[40:41]
	v_pk_mul_f32 v[126:127], v[126:127], v[42:43]
	v_pk_mul_f32 v[128:129], v[128:129], v[44:45]
	v_pk_mul_f32 v[130:131], v[130:131], v[46:47]
	v_pk_fma_f32 v[116:117], v[116:117], v[84:85], v[100:101]
	v_pk_fma_f32 v[118:119], v[118:119], v[86:87], v[102:103]
	v_pk_fma_f32 v[120:121], v[120:121], v[88:89], v[104:105]
	v_pk_fma_f32 v[122:123], v[122:123], v[90:91], v[106:107]
	v_pk_fma_f32 v[124:125], v[124:125], v[92:93], v[108:109]
	v_pk_fma_f32 v[126:127], v[126:127], v[94:95], v[110:111]
	v_pk_fma_f32 v[128:129], v[128:129], v[96:97], v[112:113]
	v_pk_fma_f32 v[130:131], v[130:131], v[98:99], v[114:115]
	v_cvt_pk_bf16_f32 v172, v116, v117
	v_cvt_pk_bf16_f32 v173, v118, v119
	v_cvt_pk_bf16_f32 v174, v120, v121
	v_cvt_pk_bf16_f32 v175, v122, v123
	v_cvt_pk_bf16_f32 v176, v124, v125
	v_cvt_pk_bf16_f32 v177, v126, v127
	v_cvt_pk_bf16_f32 v178, v128, v129
	v_cvt_pk_bf16_f32 v179, v130, v131
	global_store_dwordx4 v51, v[172:175], s[26:27] sc1
	global_store_dwordx4 v51, v[176:179], s[26:27] offset:1024 sc1
	v_lshlrev_b32_e32 v116, 16, v8
	v_and_b32_e32 v117, 0xffff0000, v8
	v_lshlrev_b32_e32 v118, 16, v9
	v_and_b32_e32 v119, 0xffff0000, v9
	v_lshlrev_b32_e32 v120, 16, v10
	v_and_b32_e32 v121, 0xffff0000, v10
	v_lshlrev_b32_e32 v122, 16, v11
	v_and_b32_e32 v123, 0xffff0000, v11
	v_lshlrev_b32_e32 v124, 16, v12
	v_and_b32_e32 v125, 0xffff0000, v12
	v_lshlrev_b32_e32 v126, 16, v13
	v_and_b32_e32 v127, 0xffff0000, v13
	v_lshlrev_b32_e32 v128, 16, v14
	v_and_b32_e32 v129, 0xffff0000, v14
	v_lshlrev_b32_e32 v130, 16, v15
	v_and_b32_e32 v131, 0xffff0000, v15
	v_pk_mul_f32 v[116:117], v[142:143], v[116:117] op_sel_hi:[0,1]
	v_pk_mul_f32 v[118:119], v[142:143], v[118:119] op_sel_hi:[0,1]
	v_pk_mul_f32 v[120:121], v[142:143], v[120:121] op_sel_hi:[0,1]
	v_pk_mul_f32 v[122:123], v[142:143], v[122:123] op_sel_hi:[0,1]
	v_pk_mul_f32 v[124:125], v[142:143], v[124:125] op_sel_hi:[0,1]
	v_pk_mul_f32 v[126:127], v[142:143], v[126:127] op_sel_hi:[0,1]
	v_pk_mul_f32 v[128:129], v[142:143], v[128:129] op_sel_hi:[0,1]
	v_pk_mul_f32 v[130:131], v[142:143], v[130:131] op_sel_hi:[0,1]
	v_pk_mul_f32 v[116:117], v[116:117], v[32:33]
	v_pk_mul_f32 v[118:119], v[118:119], v[34:35]
	v_pk_mul_f32 v[120:121], v[120:121], v[36:37]
	v_pk_mul_f32 v[122:123], v[122:123], v[38:39]
	v_pk_mul_f32 v[124:125], v[124:125], v[40:41]
	v_pk_mul_f32 v[126:127], v[126:127], v[42:43]
	v_pk_mul_f32 v[128:129], v[128:129], v[44:45]
	v_pk_mul_f32 v[130:131], v[130:131], v[46:47]
	v_pk_fma_f32 v[116:117], v[116:117], v[84:85], v[100:101]
	v_pk_fma_f32 v[118:119], v[118:119], v[86:87], v[102:103]
	v_pk_fma_f32 v[120:121], v[120:121], v[88:89], v[104:105]
	v_pk_fma_f32 v[122:123], v[122:123], v[90:91], v[106:107]
	v_pk_fma_f32 v[124:125], v[124:125], v[92:93], v[108:109]
	v_pk_fma_f32 v[126:127], v[126:127], v[94:95], v[110:111]
	v_pk_fma_f32 v[128:129], v[128:129], v[96:97], v[112:113]
	v_pk_fma_f32 v[130:131], v[130:131], v[98:99], v[114:115]
	v_cvt_pk_bf16_f32 v164, v116, v117
	v_cvt_pk_bf16_f32 v165, v118, v119
	v_cvt_pk_bf16_f32 v166, v120, v121
	v_cvt_pk_bf16_f32 v167, v122, v123
	v_cvt_pk_bf16_f32 v168, v124, v125
	v_cvt_pk_bf16_f32 v169, v126, v127
	v_cvt_pk_bf16_f32 v170, v128, v129
	v_cvt_pk_bf16_f32 v171, v130, v131
	global_store_dwordx4 v51, v[164:167], s[26:27] offset:2048 sc1
	global_store_dwordx4 v51, v[168:171], s[26:27] offset:3072 sc1
	v_lshlrev_b32_e32 v116, 16, v16
	v_and_b32_e32 v117, 0xffff0000, v16
	v_lshlrev_b32_e32 v118, 16, v17
	v_and_b32_e32 v119, 0xffff0000, v17
	v_lshlrev_b32_e32 v120, 16, v18
	v_and_b32_e32 v121, 0xffff0000, v18
	v_lshlrev_b32_e32 v122, 16, v19
	v_and_b32_e32 v123, 0xffff0000, v19
	v_lshlrev_b32_e32 v124, 16, v20
	v_and_b32_e32 v125, 0xffff0000, v20
	v_lshlrev_b32_e32 v126, 16, v21
	v_and_b32_e32 v127, 0xffff0000, v21
	v_lshlrev_b32_e32 v128, 16, v22
	v_and_b32_e32 v129, 0xffff0000, v22
	v_lshlrev_b32_e32 v130, 16, v23
	v_and_b32_e32 v131, 0xffff0000, v23
	v_pk_mul_f32 v[116:117], v[144:145], v[116:117] op_sel_hi:[0,1]
	v_pk_mul_f32 v[118:119], v[144:145], v[118:119] op_sel_hi:[0,1]
	v_pk_mul_f32 v[120:121], v[144:145], v[120:121] op_sel_hi:[0,1]
	v_pk_mul_f32 v[122:123], v[144:145], v[122:123] op_sel_hi:[0,1]
	v_pk_mul_f32 v[124:125], v[144:145], v[124:125] op_sel_hi:[0,1]
	v_pk_mul_f32 v[126:127], v[144:145], v[126:127] op_sel_hi:[0,1]
	v_pk_mul_f32 v[128:129], v[144:145], v[128:129] op_sel_hi:[0,1]
	v_pk_mul_f32 v[130:131], v[144:145], v[130:131] op_sel_hi:[0,1]
	v_pk_mul_f32 v[116:117], v[116:117], v[32:33]
	v_pk_mul_f32 v[118:119], v[118:119], v[34:35]
	v_pk_mul_f32 v[120:121], v[120:121], v[36:37]
	v_pk_mul_f32 v[122:123], v[122:123], v[38:39]
	v_pk_mul_f32 v[124:125], v[124:125], v[40:41]
	v_pk_mul_f32 v[126:127], v[126:127], v[42:43]
	v_pk_mul_f32 v[128:129], v[128:129], v[44:45]
	v_pk_mul_f32 v[130:131], v[130:131], v[46:47]
	v_pk_fma_f32 v[116:117], v[116:117], v[84:85], v[100:101]
	v_pk_fma_f32 v[118:119], v[118:119], v[86:87], v[102:103]
	v_pk_fma_f32 v[120:121], v[120:121], v[88:89], v[104:105]
	v_pk_fma_f32 v[122:123], v[122:123], v[90:91], v[106:107]
	v_pk_fma_f32 v[124:125], v[124:125], v[92:93], v[108:109]
	v_pk_fma_f32 v[126:127], v[126:127], v[94:95], v[110:111]
	v_pk_fma_f32 v[128:129], v[128:129], v[96:97], v[112:113]
	v_pk_fma_f32 v[130:131], v[130:131], v[98:99], v[114:115]
	v_cvt_pk_bf16_f32 v172, v116, v117
	v_cvt_pk_bf16_f32 v173, v118, v119
	v_cvt_pk_bf16_f32 v174, v120, v121
	v_cvt_pk_bf16_f32 v175, v122, v123
	v_cvt_pk_bf16_f32 v176, v124, v125
	v_cvt_pk_bf16_f32 v177, v126, v127
	v_cvt_pk_bf16_f32 v178, v128, v129
	v_cvt_pk_bf16_f32 v179, v130, v131
	global_store_dwordx4 v149, v[172:175], s[26:27] sc1
	global_store_dwordx4 v149, v[176:179], s[26:27] offset:1024 sc1
	v_lshlrev_b32_e32 v116, 16, v24
	v_and_b32_e32 v117, 0xffff0000, v24
	v_lshlrev_b32_e32 v118, 16, v25
	v_and_b32_e32 v119, 0xffff0000, v25
	v_lshlrev_b32_e32 v120, 16, v26
	v_and_b32_e32 v121, 0xffff0000, v26
	v_lshlrev_b32_e32 v122, 16, v27
	v_and_b32_e32 v123, 0xffff0000, v27
	v_lshlrev_b32_e32 v124, 16, v28
	v_and_b32_e32 v125, 0xffff0000, v28
	v_lshlrev_b32_e32 v126, 16, v29
	v_and_b32_e32 v127, 0xffff0000, v29
	v_lshlrev_b32_e32 v128, 16, v30
	v_and_b32_e32 v129, 0xffff0000, v30
	v_lshlrev_b32_e32 v130, 16, v31
	v_and_b32_e32 v131, 0xffff0000, v31
	v_pk_mul_f32 v[116:117], v[146:147], v[116:117] op_sel_hi:[0,1]
	v_pk_mul_f32 v[118:119], v[146:147], v[118:119] op_sel_hi:[0,1]
	v_pk_mul_f32 v[120:121], v[146:147], v[120:121] op_sel_hi:[0,1]
	v_pk_mul_f32 v[122:123], v[146:147], v[122:123] op_sel_hi:[0,1]
	v_pk_mul_f32 v[124:125], v[146:147], v[124:125] op_sel_hi:[0,1]
	v_pk_mul_f32 v[126:127], v[146:147], v[126:127] op_sel_hi:[0,1]
	v_pk_mul_f32 v[128:129], v[146:147], v[128:129] op_sel_hi:[0,1]
	v_pk_mul_f32 v[130:131], v[146:147], v[130:131] op_sel_hi:[0,1]
	v_pk_mul_f32 v[116:117], v[116:117], v[32:33]
	v_pk_mul_f32 v[118:119], v[118:119], v[34:35]
	v_pk_mul_f32 v[120:121], v[120:121], v[36:37]
	v_pk_mul_f32 v[122:123], v[122:123], v[38:39]
	v_pk_mul_f32 v[124:125], v[124:125], v[40:41]
	v_pk_mul_f32 v[126:127], v[126:127], v[42:43]
	v_pk_mul_f32 v[128:129], v[128:129], v[44:45]
	v_pk_mul_f32 v[130:131], v[130:131], v[46:47]
	v_pk_fma_f32 v[116:117], v[116:117], v[84:85], v[100:101]
	v_pk_fma_f32 v[118:119], v[118:119], v[86:87], v[102:103]
	v_pk_fma_f32 v[120:121], v[120:121], v[88:89], v[104:105]
	v_pk_fma_f32 v[122:123], v[122:123], v[90:91], v[106:107]
	v_pk_fma_f32 v[124:125], v[124:125], v[92:93], v[108:109]
	v_pk_fma_f32 v[126:127], v[126:127], v[94:95], v[110:111]
	v_pk_fma_f32 v[128:129], v[128:129], v[96:97], v[112:113]
	v_pk_fma_f32 v[130:131], v[130:131], v[98:99], v[114:115]
	v_cvt_pk_bf16_f32 v164, v116, v117
	v_cvt_pk_bf16_f32 v165, v118, v119
	v_cvt_pk_bf16_f32 v166, v120, v121
	v_cvt_pk_bf16_f32 v167, v122, v123
	v_cvt_pk_bf16_f32 v168, v124, v125
	v_cvt_pk_bf16_f32 v169, v126, v127
	v_cvt_pk_bf16_f32 v170, v128, v129
	v_cvt_pk_bf16_f32 v171, v130, v131
	global_store_dwordx4 v149, v[164:167], s[26:27] offset:2048 sc1
	global_store_dwordx4 v149, v[168:171], s[26:27] offset:3072 sc1
	s_add_u32 s26, s26, 0x2000
	s_addc_u32 s27, s27, 0
	s_branch .LBB0_238

.LBB0_1278:
	s_or_b64 exec, exec, s[0:1]
	s_mov_b64 s[0:1], s[78:79]
	s_mov_b64 s[6:7], s[78:79]
	s_mov_b64 s[12:13], s[78:79]
	s_mov_b64 s[14:15], s[78:79]
	s_waitcnt lgkmcnt(0)
	v_mov_b32_e32 v0, v224
	s_barrier
	s_mul_i32 s56, s80, 0x31800
	v_readfirstlane_b32 s5, v0
	s_ashr_i32 s5, s5, 6
	s_add_i32 s5, s5, s70
	s_and_b64 s[16:17], s[68:69], exec
	s_cselect_b32 s9, s89, 0x12000
	s_cmp_ge_i32 s5, s9
	s_cbranch_scc1 .LBB0_1297
	s_waitcnt lgkmcnt(0)
	s_load_dwordx2 s[0:1], s[78:79], 0x100
	s_load_dwordx2 s[14:15], s[78:79], 0x38
	v_readfirstlane_b32 s58, v224
	v_and_b32_e32 v51, 63, v224
	v_lshlrev_b32_e32 v108, 5, v51
	v_lshlrev_b32_e32 v51, 4, v51
	v_add_u32_e32 v109, 0x1000, v51
	v_mov_b32_e32 v50, 0x3a800000
	s_lshr_b32 s58, s58, 6
	s_add_i32 s58, s58, s70
	s_lshr_b32 s23, s58, 6
	s_and_b32 s58, s58, 63
	s_mul_i32 s59, s23, 0x900
	s_lshl_b32 s81, s58, 5
	s_add_i32 s81, s81, s59
	s_addk_i32 s81, 0x100
	s_lshl_b32 s22, s58, 2
	s_add_i32 s22, s22, s59
	s_lshl_b32 s58, s80, 12
	s_mul_i32 s59, s80, 0xc6000
	s_waitcnt lgkmcnt(0)
	s_add_u32 s14, s14, s58
	s_addc_u32 s15, s15, 0
	s_add_u32 s6, s0, 0x2db14000
	s_addc_u32 s7, s1, 0
	s_add_u32 s12, s0, 0x85b4000
	s_addc_u32 s13, s1, 0
	s_add_u32 s16, s0, 0x63cb000
	s_addc_u32 s17, s1, 0
	s_add_u32 s16, s16, s59
	s_addc_u32 s17, s17, 0
	s_and_b64 vcc, exec, s[68:69]
	s_cbranch_vccnz .Lnorm_P10_skip
	global_load_dwordx4 v[32:35], v108, s[14:15]
	global_load_dwordx4 v[36:39], v108, s[14:15] offset:16
	global_load_dwordx4 v[40:43], v108, s[14:15] offset:2048
	global_load_dwordx4 v[44:47], v108, s[14:15] offset:2064
	s_add_u32 s0, s16, 0xc0000
	s_addc_u32 s1, s17, 0
	s_add_u32 s14, s0, 0x1000
	s_addc_u32 s15, s1, 0
	global_load_dwordx4 v[124:127], v108, s[0:1]
	global_load_dwordx4 v[128:131], v108, s[0:1] offset:16
	global_load_dwordx4 v[132:135], v108, s[0:1] offset:2048
	global_load_dwordx4 v[136:139], v108, s[0:1] offset:2064
	global_load_dwordx4 v[84:87], v108, s[14:15]
	global_load_dwordx4 v[88:91], v108, s[14:15] offset:16
	global_load_dwordx4 v[92:95], v108, s[14:15] offset:2048
	global_load_dwordx4 v[96:99], v108, s[14:15] offset:2064
	s_lshl_b32 s58, s22, 11
	s_add_u32 s18, s6, s58
	s_addc_u32 s19, s7, 0
	s_add_u32 s20, s12, s58
	s_addc_u32 s21, s13, 0
	global_load_dwordx4 v[0:3], v51, s[18:19]
	global_load_dwordx4 v[4:7], v51, s[18:19] offset:1024
	global_load_dwordx4 v[8:11], v51, s[18:19] offset:2048
	global_load_dwordx4 v[12:15], v51, s[18:19] offset:3072
	global_load_dwordx4 v[16:19], v109, s[18:19]
	global_load_dwordx4 v[20:23], v109, s[18:19] offset:1024
	global_load_dwordx4 v[24:27], v109, s[18:19] offset:2048
	global_load_dwordx4 v[28:31], v109, s[18:19] offset:3072
	s_waitcnt vmcnt(0)
	v_pk_add_f32 v[84:85], v[84:85], 1.0 op_sel_hi:[1,0]
	v_pk_add_f32 v[86:87], v[86:87], 1.0 op_sel_hi:[1,0]
	v_pk_add_f32 v[88:89], v[88:89], 1.0 op_sel_hi:[1,0]
	v_pk_add_f32 v[90:91], v[90:91], 1.0 op_sel_hi:[1,0]
	v_pk_add_f32 v[92:93], v[92:93], 1.0 op_sel_hi:[1,0]
	v_pk_add_f32 v[94:95], v[94:95], 1.0 op_sel_hi:[1,0]
	v_pk_add_f32 v[96:97], v[96:97], 1.0 op_sel_hi:[1,0]
	v_pk_add_f32 v[98:99], v[98:99], 1.0 op_sel_hi:[1,0]
	v_lshlrev_b32_e32 v140, 16, v0
	v_and_b32_e32 v141, 0xffff0000, v0
	v_lshlrev_b32_e32 v142, 16, v1
	v_and_b32_e32 v143, 0xffff0000, v1
	v_lshlrev_b32_e32 v144, 16, v2
	v_and_b32_e32 v145, 0xffff0000, v2
	v_lshlrev_b32_e32 v146, 16, v3
	v_and_b32_e32 v147, 0xffff0000, v3
	v_lshlrev_b32_e32 v148, 16, v4
	v_and_b32_e32 v149, 0xffff0000, v4
	v_lshlrev_b32_e32 v150, 16, v5
	v_and_b32_e32 v151, 0xffff0000, v5
	v_lshlrev_b32_e32 v152, 16, v6
	v_and_b32_e32 v153, 0xffff0000, v6
	v_lshlrev_b32_e32 v154, 16, v7
	v_and_b32_e32 v155, 0xffff0000, v7
	v_pk_mul_f32 v[100:101], v[140:141], v[140:141]
	v_pk_fma_f32 v[100:101], v[142:143], v[142:143], v[100:101]
	v_pk_fma_f32 v[100:101], v[144:145], v[144:145], v[100:101]
	v_pk_fma_f32 v[100:101], v[146:147], v[146:147], v[100:101]
	v_pk_fma_f32 v[100:101], v[148:149], v[148:149], v[100:101]
	v_pk_fma_f32 v[100:101], v[150:151], v[150:151], v[100:101]
	v_pk_fma_f32 v[100:101], v[152:153], v[152:153], v[100:101]
	v_pk_fma_f32 v[100:101], v[154:155], v[154:155], v[100:101]
	v_lshlrev_b32_e32 v140, 16, v8
	v_and_b32_e32 v141, 0xffff0000, v8
	v_lshlrev_b32_e32 v142, 16, v9
	v_and_b32_e32 v143, 0xffff0000, v9
	v_lshlrev_b32_e32 v144, 16, v10
	v_and_b32_e32 v145, 0xffff0000, v10
	v_lshlrev_b32_e32 v146, 16, v11
	v_and_b32_e32 v147, 0xffff0000, v11
	v_lshlrev_b32_e32 v148, 16, v12
	v_and_b32_e32 v149, 0xffff0000, v12
	v_lshlrev_b32_e32 v150, 16, v13
	v_and_b32_e32 v151, 0xffff0000, v13
	v_lshlrev_b32_e32 v152, 16, v14
	v_and_b32_e32 v153, 0xffff0000, v14
	v_lshlrev_b32_e32 v154, 16, v15
	v_and_b32_e32 v155, 0xffff0000, v15
	v_pk_mul_f32 v[102:103], v[140:141], v[140:141]
	v_pk_fma_f32 v[102:103], v[142:143], v[142:143], v[102:103]
	v_pk_fma_f32 v[102:103], v[144:145], v[144:145], v[102:103]
	v_pk_fma_f32 v[102:103], v[146:147], v[146:147], v[102:103]
	v_pk_fma_f32 v[102:103], v[148:149], v[148:149], v[102:103]
	v_pk_fma_f32 v[102:103], v[150:151], v[150:151], v[102:103]
	v_pk_fma_f32 v[102:103], v[152:153], v[152:153], v[102:103]
	v_pk_fma_f32 v[102:103], v[154:155], v[154:155], v[102:103]
	v_lshlrev_b32_e32 v140, 16, v16
	v_and_b32_e32 v141, 0xffff0000, v16
	v_lshlrev_b32_e32 v142, 16, v17
	v_and_b32_e32 v143, 0xffff0000, v17
	v_lshlrev_b32_e32 v144, 16, v18
	v_and_b32_e32 v145, 0xffff0000, v18
	v_lshlrev_b32_e32 v146, 16, v19
	v_and_b32_e32 v147, 0xffff0000, v19
	v_lshlrev_b32_e32 v148, 16, v20
	v_and_b32_e32 v149, 0xffff0000, v20
	v_lshlrev_b32_e32 v150, 16, v21
	v_and_b32_e32 v151, 0xffff0000, v21
	v_lshlrev_b32_e32 v152, 16, v22
	v_and_b32_e32 v153, 0xffff0000, v22
	v_lshlrev_b32_e32 v154, 16, v23
	v_and_b32_e32 v155, 0xffff0000, v23
	v_pk_mul_f32 v[104:105], v[140:141], v[140:141]
	v_pk_fma_f32 v[104:105], v[142:143], v[142:143], v[104:105]
	v_pk_fma_f32 v[104:105], v[144:145], v[144:145], v[104:105]
	v_pk_fma_f32 v[104:105], v[146:147], v[146:147], v[104:105]
	v_pk_fma_f32 v[104:105], v[148:149], v[148:149], v[104:105]
	v_pk_fma_f32 v[104:105], v[150:151], v[150:151], v[104:105]
	v_pk_fma_f32 v[104:105], v[152:153], v[152:153], v[104:105]
	v_pk_fma_f32 v[104:105], v[154:155], v[154:155], v[104:105]
	v_lshlrev_b32_e32 v140, 16, v24
	v_and_b32_e32 v141, 0xffff0000, v24
	v_lshlrev_b32_e32 v142, 16, v25
	v_and_b32_e32 v143, 0xffff0000, v25
	v_lshlrev_b32_e32 v144, 16, v26
	v_and_b32_e32 v145, 0xffff0000, v26
	v_lshlrev_b32_e32 v146, 16, v27
	v_and_b32_e32 v147, 0xffff0000, v27
	v_lshlrev_b32_e32 v148, 16, v28
	v_and_b32_e32 v149, 0xffff0000, v28
	v_lshlrev_b32_e32 v150, 16, v29
	v_and_b32_e32 v151, 0xffff0000, v29
	v_lshlrev_b32_e32 v152, 16, v30
	v_and_b32_e32 v153, 0xffff0000, v30
	v_lshlrev_b32_e32 v154, 16, v31
	v_and_b32_e32 v155, 0xffff0000, v31
	v_pk_mul_f32 v[106:107], v[140:141], v[140:141]
	v_pk_fma_f32 v[106:107], v[142:143], v[142:143], v[106:107]
	v_pk_fma_f32 v[106:107], v[144:145], v[144:145], v[106:107]
	v_pk_fma_f32 v[106:107], v[146:147], v[146:147], v[106:107]
	v_pk_fma_f32 v[106:107], v[148:149], v[148:149], v[106:107]
	v_pk_fma_f32 v[106:107], v[150:151], v[150:151], v[106:107]
	v_pk_fma_f32 v[106:107], v[152:153], v[152:153], v[106:107]
	v_pk_fma_f32 v[106:107], v[154:155], v[154:155], v[106:107]
	v_add_f32_e32 v100, v100, v101
	v_add_f32_e32 v102, v102, v103
	v_add_f32_e32 v104, v104, v105
	v_add_f32_e32 v106, v106, v107
	s_nop 1
	v_add_f32_dpp v100, v100, v100 row_shr:1 row_mask:0xf bank_mask:0xf bound_ctrl:1
	v_add_f32_dpp v102, v102, v102 row_shr:1 row_mask:0xf bank_mask:0xf bound_ctrl:1
	v_add_f32_dpp v104, v104, v104 row_shr:1 row_mask:0xf bank_mask:0xf bound_ctrl:1
	v_add_f32_dpp v106, v106, v106 row_shr:1 row_mask:0xf bank_mask:0xf bound_ctrl:1
	v_add_f32_dpp v100, v100, v100 row_shr:2 row_mask:0xf bank_mask:0xf bound_ctrl:1
	v_add_f32_dpp v102, v102, v102 row_shr:2 row_mask:0xf bank_mask:0xf bound_ctrl:1
	v_add_f32_dpp v104, v104, v104 row_shr:2 row_mask:0xf bank_mask:0xf bound_ctrl:1
	v_add_f32_dpp v106, v106, v106 row_shr:2 row_mask:0xf bank_mask:0xf bound_ctrl:1
	v_add_f32_dpp v100, v100, v100 row_shr:4 row_mask:0xf bank_mask:0xf bound_ctrl:1
	v_add_f32_dpp v102, v102, v102 row_shr:4 row_mask:0xf bank_mask:0xf bound_ctrl:1
	v_add_f32_dpp v104, v104, v104 row_shr:4 row_mask:0xf bank_mask:0xf bound_ctrl:1
	v_add_f32_dpp v106, v106, v106 row_shr:4 row_mask:0xf bank_mask:0xf bound_ctrl:1
	v_add_f32_dpp v100, v100, v100 row_shr:8 row_mask:0xf bank_mask:0xf bound_ctrl:1
	v_add_f32_dpp v102, v102, v102 row_shr:8 row_mask:0xf bank_mask:0xf bound_ctrl:1
	v_add_f32_dpp v104, v104, v104 row_shr:8 row_mask:0xf bank_mask:0xf bound_ctrl:1
	v_add_f32_dpp v106, v106, v106 row_shr:8 row_mask:0xf bank_mask:0xf bound_ctrl:1
	v_add_f32_dpp v100, v100, v100 row_bcast:15 row_mask:0xa bank_mask:0xf
	v_add_f32_dpp v102, v102, v102 row_bcast:15 row_mask:0xa bank_mask:0xf
	v_add_f32_dpp v104, v104, v104 row_bcast:15 row_mask:0xa bank_mask:0xf
	v_add_f32_dpp v106, v106, v106 row_bcast:15 row_mask:0xa bank_mask:0xf
	v_add_f32_dpp v100, v100, v100 row_bcast:31 row_mask:0xc bank_mask:0xf
	v_add_f32_dpp v102, v102, v102 row_bcast:31 row_mask:0xc bank_mask:0xf
	v_add_f32_dpp v104, v104, v104 row_bcast:31 row_mask:0xc bank_mask:0xf
	v_add_f32_dpp v106, v106, v106 row_bcast:31 row_mask:0xc bank_mask:0xf
	s_nop 1
	v_readlane_b32 s5, v100, 63
	v_readlane_b32 s32, v102, 63
	v_readlane_b32 s54, v104, 63
	v_readlane_b32 s60, v106, 63
	s_nop 1
	v_mov_b32_e32 v156, s5
	v_mov_b32_e32 v158, s32
	v_mov_b32_e32 v160, s54
	v_mov_b32_e32 v162, s60
	v_fmaak_f32 v156, v156, v50, 0x358637bd
	v_fmaak_f32 v158, v158, v50, 0x358637bd
	v_fmaak_f32 v160, v160, v50, 0x358637bd
	v_fmaak_f32 v162, v162, v50, 0x358637bd
	v_rsq_f32_e32 v156, v156
	v_rsq_f32_e32 v158, v158
	v_rsq_f32_e32 v160, v160
	v_rsq_f32_e32 v162, v162
	s_nop 0
	v_lshlrev_b32_e32 v140, 16, v0
	v_and_b32_e32 v141, 0xffff0000, v0
	v_lshlrev_b32_e32 v142, 16, v1
	v_and_b32_e32 v143, 0xffff0000, v1
	v_lshlrev_b32_e32 v144, 16, v2
	v_and_b32_e32 v145, 0xffff0000, v2
	v_lshlrev_b32_e32 v146, 16, v3
	v_and_b32_e32 v147, 0xffff0000, v3
	v_lshlrev_b32_e32 v148, 16, v4
	v_and_b32_e32 v149, 0xffff0000, v4
	v_lshlrev_b32_e32 v150, 16, v5
	v_and_b32_e32 v151, 0xffff0000, v5
	v_lshlrev_b32_e32 v152, 16, v6
	v_and_b32_e32 v153, 0xffff0000, v6
	v_lshlrev_b32_e32 v154, 16, v7
	v_and_b32_e32 v155, 0xffff0000, v7
	v_pk_mul_f32 v[140:141], v[156:157], v[140:141] op_sel_hi:[0,1]
	v_pk_mul_f32 v[142:143], v[156:157], v[142:143] op_sel_hi:[0,1]
	v_pk_mul_f32 v[144:145], v[156:157], v[144:145] op_sel_hi:[0,1]
	v_pk_mul_f32 v[146:147], v[156:157], v[146:147] op_sel_hi:[0,1]
	v_pk_mul_f32 v[148:149], v[156:157], v[148:149] op_sel_hi:[0,1]
	v_pk_mul_f32 v[150:151], v[156:157], v[150:151] op_sel_hi:[0,1]
	v_pk_mul_f32 v[152:153], v[156:157], v[152:153] op_sel_hi:[0,1]
	v_pk_mul_f32 v[154:155], v[156:157], v[154:155] op_sel_hi:[0,1]
	v_pk_mul_f32 v[140:141], v[140:141], v[32:33]
	v_pk_mul_f32 v[142:143], v[142:143], v[34:35]
	v_pk_mul_f32 v[144:145], v[144:145], v[36:37]
	v_pk_mul_f32 v[146:147], v[146:147], v[38:39]
	v_pk_mul_f32 v[148:149], v[148:149], v[40:41]
	v_pk_mul_f32 v[150:151], v[150:151], v[42:43]
	v_pk_mul_f32 v[152:153], v[152:153], v[44:45]
	v_pk_mul_f32 v[154:155], v[154:155], v[46:47]
	v_pk_fma_f32 v[140:141], v[140:141], v[84:85], v[124:125]
	v_pk_fma_f32 v[142:143], v[142:143], v[86:87], v[126:127]
	v_pk_fma_f32 v[144:145], v[144:145], v[88:89], v[128:129]
	v_pk_fma_f32 v[146:147], v[146:147], v[90:91], v[130:131]
	v_pk_fma_f32 v[148:149], v[148:149], v[92:93], v[132:133]
	v_pk_fma_f32 v[150:151], v[150:151], v[94:95], v[134:135]
	v_pk_fma_f32 v[152:153], v[152:153], v[96:97], v[136:137]
	v_pk_fma_f32 v[154:155], v[154:155], v[98:99], v[138:139]
	v_cvt_pk_bf16_f32 v164, v140, v141
	v_cvt_pk_bf16_f32 v165, v142, v143
	v_cvt_pk_bf16_f32 v166, v144, v145
	v_cvt_pk_bf16_f32 v167, v146, v147
	v_cvt_pk_bf16_f32 v168, v148, v149
	v_cvt_pk_bf16_f32 v169, v150, v151
	v_cvt_pk_bf16_f32 v170, v152, v153
	v_cvt_pk_bf16_f32 v171, v154, v155
	global_store_dwordx4 v51, v[164:167], s[20:21] sc1
	global_store_dwordx4 v51, v[168:171], s[20:21] offset:1024 sc1
	v_lshlrev_b32_e32 v140, 16, v8
	v_and_b32_e32 v141, 0xffff0000, v8
	v_lshlrev_b32_e32 v142, 16, v9
	v_and_b32_e32 v143, 0xffff0000, v9
	v_lshlrev_b32_e32 v144, 16, v10
	v_and_b32_e32 v145, 0xffff0000, v10
	v_lshlrev_b32_e32 v146, 16, v11
	v_and_b32_e32 v147, 0xffff0000, v11
	v_lshlrev_b32_e32 v148, 16, v12
	v_and_b32_e32 v149, 0xffff0000, v12
	v_lshlrev_b32_e32 v150, 16, v13
	v_and_b32_e32 v151, 0xffff0000, v13
	v_lshlrev_b32_e32 v152, 16, v14
	v_and_b32_e32 v153, 0xffff0000, v14
	v_lshlrev_b32_e32 v154, 16, v15
	v_and_b32_e32 v155, 0xffff0000, v15
	v_pk_mul_f32 v[140:141], v[158:159], v[140:141] op_sel_hi:[0,1]
	v_pk_mul_f32 v[142:143], v[158:159], v[142:143] op_sel_hi:[0,1]
	v_pk_mul_f32 v[144:145], v[158:159], v[144:145] op_sel_hi:[0,1]
	v_pk_mul_f32 v[146:147], v[158:159], v[146:147] op_sel_hi:[0,1]
	v_pk_mul_f32 v[148:149], v[158:159], v[148:149] op_sel_hi:[0,1]
	v_pk_mul_f32 v[150:151], v[158:159], v[150:151] op_sel_hi:[0,1]
	v_pk_mul_f32 v[152:153], v[158:159], v[152:153] op_sel_hi:[0,1]
	v_pk_mul_f32 v[154:155], v[158:159], v[154:155] op_sel_hi:[0,1]
	v_pk_mul_f32 v[140:141], v[140:141], v[32:33]
	v_pk_mul_f32 v[142:143], v[142:143], v[34:35]
	v_pk_mul_f32 v[144:145], v[144:145], v[36:37]
	v_pk_mul_f32 v[146:147], v[146:147], v[38:39]
	v_pk_mul_f32 v[148:149], v[148:149], v[40:41]
	v_pk_mul_f32 v[150:151], v[150:151], v[42:43]
	v_pk_mul_f32 v[152:153], v[152:153], v[44:45]
	v_pk_mul_f32 v[154:155], v[154:155], v[46:47]
	v_pk_fma_f32 v[140:141], v[140:141], v[84:85], v[124:125]
	v_pk_fma_f32 v[142:143], v[142:143], v[86:87], v[126:127]
	v_pk_fma_f32 v[144:145], v[144:145], v[88:89], v[128:129]
	v_pk_fma_f32 v[146:147], v[146:147], v[90:91], v[130:131]
	v_pk_fma_f32 v[148:149], v[148:149], v[92:93], v[132:133]
	v_pk_fma_f32 v[150:151], v[150:151], v[94:95], v[134:135]
	v_pk_fma_f32 v[152:153], v[152:153], v[96:97], v[136:137]
	v_pk_fma_f32 v[154:155], v[154:155], v[98:99], v[138:139]
	v_cvt_pk_bf16_f32 v172, v140, v141
	v_cvt_pk_bf16_f32 v173, v142, v143
	v_cvt_pk_bf16_f32 v174, v144, v145
	v_cvt_pk_bf16_f32 v175, v146, v147
	v_cvt_pk_bf16_f32 v176, v148, v149
	v_cvt_pk_bf16_f32 v177, v150, v151
	v_cvt_pk_bf16_f32 v178, v152, v153
	v_cvt_pk_bf16_f32 v179, v154, v155
	global_store_dwordx4 v51, v[172:175], s[20:21] offset:2048 sc1
	global_store_dwordx4 v51, v[176:179], s[20:21] offset:3072 sc1
	v_lshlrev_b32_e32 v140, 16, v16
	v_and_b32_e32 v141, 0xffff0000, v16
	v_lshlrev_b32_e32 v142, 16, v17
	v_and_b32_e32 v143, 0xffff0000, v17
	v_lshlrev_b32_e32 v144, 16, v18
	v_and_b32_e32 v145, 0xffff0000, v18
	v_lshlrev_b32_e32 v146, 16, v19
	v_and_b32_e32 v147, 0xffff0000, v19
	v_lshlrev_b32_e32 v148, 16, v20
	v_and_b32_e32 v149, 0xffff0000, v20
	v_lshlrev_b32_e32 v150, 16, v21
	v_and_b32_e32 v151, 0xffff0000, v21
	v_lshlrev_b32_e32 v152, 16, v22
	v_and_b32_e32 v153, 0xffff0000, v22
	v_lshlrev_b32_e32 v154, 16, v23
	v_and_b32_e32 v155, 0xffff0000, v23
	v_pk_mul_f32 v[140:141], v[160:161], v[140:141] op_sel_hi:[0,1]
	v_pk_mul_f32 v[142:143], v[160:161], v[142:143] op_sel_hi:[0,1]
	v_pk_mul_f32 v[144:145], v[160:161], v[144:145] op_sel_hi:[0,1]
	v_pk_mul_f32 v[146:147], v[160:161], v[146:147] op_sel_hi:[0,1]
	v_pk_mul_f32 v[148:149], v[160:161], v[148:149] op_sel_hi:[0,1]
	v_pk_mul_f32 v[150:151], v[160:161], v[150:151] op_sel_hi:[0,1]
	v_pk_mul_f32 v[152:153], v[160:161], v[152:153] op_sel_hi:[0,1]
	v_pk_mul_f32 v[154:155], v[160:161], v[154:155] op_sel_hi:[0,1]
	v_pk_mul_f32 v[140:141], v[140:141], v[32:33]
	v_pk_mul_f32 v[142:143], v[142:143], v[34:35]
	v_pk_mul_f32 v[144:145], v[144:145], v[36:37]
	v_pk_mul_f32 v[146:147], v[146:147], v[38:39]
	v_pk_mul_f32 v[148:149], v[148:149], v[40:41]
	v_pk_mul_f32 v[150:151], v[150:151], v[42:43]
	v_pk_mul_f32 v[152:153], v[152:153], v[44:45]
	v_pk_mul_f32 v[154:155], v[154:155], v[46:47]
	v_pk_fma_f32 v[140:141], v[140:141], v[84:85], v[124:125]
	v_pk_fma_f32 v[142:143], v[142:143], v[86:87], v[126:127]
	v_pk_fma_f32 v[144:145], v[144:145], v[88:89], v[128:129]
	v_pk_fma_f32 v[146:147], v[146:147], v[90:91], v[130:131]
	v_pk_fma_f32 v[148:149], v[148:149], v[92:93], v[132:133]
	v_pk_fma_f32 v[150:151], v[150:151], v[94:95], v[134:135]
	v_pk_fma_f32 v[152:153], v[152:153], v[96:97], v[136:137]
	v_pk_fma_f32 v[154:155], v[154:155], v[98:99], v[138:139]
	v_cvt_pk_bf16_f32 v164, v140, v141
	v_cvt_pk_bf16_f32 v165, v142, v143
	v_cvt_pk_bf16_f32 v166, v144, v145
	v_cvt_pk_bf16_f32 v167, v146, v147
	v_cvt_pk_bf16_f32 v168, v148, v149
	v_cvt_pk_bf16_f32 v169, v150, v151
	v_cvt_pk_bf16_f32 v170, v152, v153
	v_cvt_pk_bf16_f32 v171, v154, v155
	global_store_dwordx4 v109, v[164:167], s[20:21] sc1
	global_store_dwordx4 v109, v[168:171], s[20:21] offset:1024 sc1
	v_lshlrev_b32_e32 v140, 16, v24
	v_and_b32_e32 v141, 0xffff0000, v24
	v_lshlrev_b32_e32 v142, 16, v25
	v_and_b32_e32 v143, 0xffff0000, v25
	v_lshlrev_b32_e32 v144, 16, v26
	v_and_b32_e32 v145, 0xffff0000, v26
	v_lshlrev_b32_e32 v146, 16, v27
	v_and_b32_e32 v147, 0xffff0000, v27
	v_lshlrev_b32_e32 v148, 16, v28
	v_and_b32_e32 v149, 0xffff0000, v28
	v_lshlrev_b32_e32 v150, 16, v29
	v_and_b32_e32 v151, 0xffff0000, v29
	v_lshlrev_b32_e32 v152, 16, v30
	v_and_b32_e32 v153, 0xffff0000, v30
	v_lshlrev_b32_e32 v154, 16, v31
	v_and_b32_e32 v155, 0xffff0000, v31
	v_pk_mul_f32 v[140:141], v[162:163], v[140:141] op_sel_hi:[0,1]
	v_pk_mul_f32 v[142:143], v[162:163], v[142:143] op_sel_hi:[0,1]
	v_pk_mul_f32 v[144:145], v[162:163], v[144:145] op_sel_hi:[0,1]
	v_pk_mul_f32 v[146:147], v[162:163], v[146:147] op_sel_hi:[0,1]
	v_pk_mul_f32 v[148:149], v[162:163], v[148:149] op_sel_hi:[0,1]
	v_pk_mul_f32 v[150:151], v[162:163], v[150:151] op_sel_hi:[0,1]
	v_pk_mul_f32 v[152:153], v[162:163], v[152:153] op_sel_hi:[0,1]
	v_pk_mul_f32 v[154:155], v[162:163], v[154:155] op_sel_hi:[0,1]
	v_pk_mul_f32 v[140:141], v[140:141], v[32:33]
	v_pk_mul_f32 v[142:143], v[142:143], v[34:35]
	v_pk_mul_f32 v[144:145], v[144:145], v[36:37]
	v_pk_mul_f32 v[146:147], v[146:147], v[38:39]
	v_pk_mul_f32 v[148:149], v[148:149], v[40:41]
	v_pk_mul_f32 v[150:151], v[150:151], v[42:43]
	v_pk_mul_f32 v[152:153], v[152:153], v[44:45]
	v_pk_mul_f32 v[154:155], v[154:155], v[46:47]
	v_pk_fma_f32 v[140:141], v[140:141], v[84:85], v[124:125]
	v_pk_fma_f32 v[142:143], v[142:143], v[86:87], v[126:127]
	v_pk_fma_f32 v[144:145], v[144:145], v[88:89], v[128:129]
	v_pk_fma_f32 v[146:147], v[146:147], v[90:91], v[130:131]
	v_pk_fma_f32 v[148:149], v[148:149], v[92:93], v[132:133]
	v_pk_fma_f32 v[150:151], v[150:151], v[94:95], v[134:135]
	v_pk_fma_f32 v[152:153], v[152:153], v[96:97], v[136:137]
	v_pk_fma_f32 v[154:155], v[154:155], v[98:99], v[138:139]
	v_cvt_pk_bf16_f32 v172, v140, v141
	v_cvt_pk_bf16_f32 v173, v142, v143
	v_cvt_pk_bf16_f32 v174, v144, v145
	v_cvt_pk_bf16_f32 v175, v146, v147
	v_cvt_pk_bf16_f32 v176, v148, v149
	v_cvt_pk_bf16_f32 v177, v150, v151
	v_cvt_pk_bf16_f32 v178, v152, v153
	v_cvt_pk_bf16_f32 v179, v154, v155
	global_store_dwordx4 v109, v[172:175], s[20:21] offset:2048 sc1
	global_store_dwordx4 v109, v[176:179], s[20:21] offset:3072 sc1
	s_mul_i32 s58, s23, 0x6000
	s_add_u32 s0, s16, s58
	s_addc_u32 s1, s17, 0
	s_add_u32 s14, s0, 0x1000
	s_addc_u32 s15, s1, 0
	global_load_dwordx4 v[124:127], v108, s[0:1]
	global_load_dwordx4 v[128:131], v108, s[0:1] offset:16
	global_load_dwordx4 v[132:135], v108, s[0:1] offset:2048
	global_load_dwordx4 v[136:139], v108, s[0:1] offset:2064
	global_load_dwordx4 v[84:87], v108, s[14:15]
	global_load_dwordx4 v[88:91], v108, s[14:15] offset:16
	global_load_dwordx4 v[92:95], v108, s[14:15] offset:2048
	global_load_dwordx4 v[96:99], v108, s[14:15] offset:2064
	s_lshl_b32 s58, s81, 11
	s_add_u32 s18, s6, s58
	s_addc_u32 s19, s7, 0
	s_add_u32 s20, s12, s58
	s_addc_u32 s21, s13, 0
	global_load_dwordx4 v[52:55], v51, s[18:19]
	global_load_dwordx4 v[56:59], v51, s[18:19] offset:1024
	global_load_dwordx4 v[60:63], v51, s[18:19] offset:2048
	global_load_dwordx4 v[64:67], v51, s[18:19] offset:3072
	global_load_dwordx4 v[68:71], v109, s[18:19]
	global_load_dwordx4 v[72:75], v109, s[18:19] offset:1024
	global_load_dwordx4 v[76:79], v109, s[18:19] offset:2048
	global_load_dwordx4 v[80:83], v109, s[18:19] offset:3072
	s_waitcnt vmcnt(0)
	v_pk_add_f32 v[84:85], v[84:85], 1.0 op_sel_hi:[1,0]
	v_pk_add_f32 v[86:87], v[86:87], 1.0 op_sel_hi:[1,0]
	v_pk_add_f32 v[88:89], v[88:89], 1.0 op_sel_hi:[1,0]
	v_pk_add_f32 v[90:91], v[90:91], 1.0 op_sel_hi:[1,0]
	v_pk_add_f32 v[92:93], v[92:93], 1.0 op_sel_hi:[1,0]
	v_pk_add_f32 v[94:95], v[94:95], 1.0 op_sel_hi:[1,0]
	v_pk_add_f32 v[96:97], v[96:97], 1.0 op_sel_hi:[1,0]
	v_pk_add_f32 v[98:99], v[98:99], 1.0 op_sel_hi:[1,0]
	s_add_u32 s18, s18, 0x2000
	s_addc_u32 s19, s19, 0
	global_load_dwordx4 v[0:3], v51, s[18:19]
	global_load_dwordx4 v[4:7], v51, s[18:19] offset:1024
	global_load_dwordx4 v[8:11], v51, s[18:19] offset:2048
	global_load_dwordx4 v[12:15], v51, s[18:19] offset:3072
	global_load_dwordx4 v[16:19], v109, s[18:19]
	global_load_dwordx4 v[20:23], v109, s[18:19] offset:1024
	global_load_dwordx4 v[24:27], v109, s[18:19] offset:2048
	global_load_dwordx4 v[28:31], v109, s[18:19] offset:3072
	v_lshlrev_b32_e32 v140, 16, v52
	v_and_b32_e32 v141, 0xffff0000, v52
	v_lshlrev_b32_e32 v142, 16, v53
	v_and_b32_e32 v143, 0xffff0000, v53
	v_lshlrev_b32_e32 v144, 16, v54
	v_and_b32_e32 v145, 0xffff0000, v54
	v_lshlrev_b32_e32 v146, 16, v55
	v_and_b32_e32 v147, 0xffff0000, v55
	v_lshlrev_b32_e32 v148, 16, v56
	v_and_b32_e32 v149, 0xffff0000, v56
	v_lshlrev_b32_e32 v150, 16, v57
	v_and_b32_e32 v151, 0xffff0000, v57
	v_lshlrev_b32_e32 v152, 16, v58
	v_and_b32_e32 v153, 0xffff0000, v58
	v_lshlrev_b32_e32 v154, 16, v59
	v_and_b32_e32 v155, 0xffff0000, v59
	v_pk_mul_f32 v[100:101], v[140:141], v[140:141]
	v_pk_fma_f32 v[100:101], v[142:143], v[142:143], v[100:101]
	v_pk_fma_f32 v[100:101], v[144:145], v[144:145], v[100:101]
	v_pk_fma_f32 v[100:101], v[146:147], v[146:147], v[100:101]
	v_pk_fma_f32 v[100:101], v[148:149], v[148:149], v[100:101]
	v_pk_fma_f32 v[100:101], v[150:151], v[150:151], v[100:101]
	v_pk_fma_f32 v[100:101], v[152:153], v[152:153], v[100:101]
	v_pk_fma_f32 v[100:101], v[154:155], v[154:155], v[100:101]
	v_lshlrev_b32_e32 v140, 16, v60
	v_and_b32_e32 v141, 0xffff0000, v60
	v_lshlrev_b32_e32 v142, 16, v61
	v_and_b32_e32 v143, 0xffff0000, v61
	v_lshlrev_b32_e32 v144, 16, v62
	v_and_b32_e32 v145, 0xffff0000, v62
	v_lshlrev_b32_e32 v146, 16, v63
	v_and_b32_e32 v147, 0xffff0000, v63
	v_lshlrev_b32_e32 v148, 16, v64
	v_and_b32_e32 v149, 0xffff0000, v64
	v_lshlrev_b32_e32 v150, 16, v65
	v_and_b32_e32 v151, 0xffff0000, v65
	v_lshlrev_b32_e32 v152, 16, v66
	v_and_b32_e32 v153, 0xffff0000, v66
	v_lshlrev_b32_e32 v154, 16, v67
	v_and_b32_e32 v155, 0xffff0000, v67
	v_pk_mul_f32 v[102:103], v[140:141], v[140:141]
	v_pk_fma_f32 v[102:103], v[142:143], v[142:143], v[102:103]
	v_pk_fma_f32 v[102:103], v[144:145], v[144:145], v[102:103]
	v_pk_fma_f32 v[102:103], v[146:147], v[146:147], v[102:103]
	v_pk_fma_f32 v[102:103], v[148:149], v[148:149], v[102:103]
	v_pk_fma_f32 v[102:103], v[150:151], v[150:151], v[102:103]
	v_pk_fma_f32 v[102:103], v[152:153], v[152:153], v[102:103]
	v_pk_fma_f32 v[102:103], v[154:155], v[154:155], v[102:103]
	v_lshlrev_b32_e32 v140, 16, v68
	v_and_b32_e32 v141, 0xffff0000, v68
	v_lshlrev_b32_e32 v142, 16, v69
	v_and_b32_e32 v143, 0xffff0000, v69
	v_lshlrev_b32_e32 v144, 16, v70
	v_and_b32_e32 v145, 0xffff0000, v70
	v_lshlrev_b32_e32 v146, 16, v71
	v_and_b32_e32 v147, 0xffff0000, v71
	v_lshlrev_b32_e32 v148, 16, v72
	v_and_b32_e32 v149, 0xffff0000, v72
	v_lshlrev_b32_e32 v150, 16, v73
	v_and_b32_e32 v151, 0xffff0000, v73
	v_lshlrev_b32_e32 v152, 16, v74
	v_and_b32_e32 v153, 0xffff0000, v74
	v_lshlrev_b32_e32 v154, 16, v75
	v_and_b32_e32 v155, 0xffff0000, v75
	v_pk_mul_f32 v[104:105], v[140:141], v[140:141]
	v_pk_fma_f32 v[104:105], v[142:143], v[142:143], v[104:105]
	v_pk_fma_f32 v[104:105], v[144:145], v[144:145], v[104:105]
	v_pk_fma_f32 v[104:105], v[146:147], v[146:147], v[104:105]
	v_pk_fma_f32 v[104:105], v[148:149], v[148:149], v[104:105]
	v_pk_fma_f32 v[104:105], v[150:151], v[150:151], v[104:105]
	v_pk_fma_f32 v[104:105], v[152:153], v[152:153], v[104:105]
	v_pk_fma_f32 v[104:105], v[154:155], v[154:155], v[104:105]
	v_lshlrev_b32_e32 v140, 16, v76
	v_and_b32_e32 v141, 0xffff0000, v76
	v_lshlrev_b32_e32 v142, 16, v77
	v_and_b32_e32 v143, 0xffff0000, v77
	v_lshlrev_b32_e32 v144, 16, v78
	v_and_b32_e32 v145, 0xffff0000, v78
	v_lshlrev_b32_e32 v146, 16, v79
	v_and_b32_e32 v147, 0xffff0000, v79
	v_lshlrev_b32_e32 v148, 16, v80
	v_and_b32_e32 v149, 0xffff0000, v80
	v_lshlrev_b32_e32 v150, 16, v81
	v_and_b32_e32 v151, 0xffff0000, v81
	v_lshlrev_b32_e32 v152, 16, v82
	v_and_b32_e32 v153, 0xffff0000, v82
	v_lshlrev_b32_e32 v154, 16, v83
	v_and_b32_e32 v155, 0xffff0000, v83
	v_pk_mul_f32 v[106:107], v[140:141], v[140:141]
	v_pk_fma_f32 v[106:107], v[142:143], v[142:143], v[106:107]
	v_pk_fma_f32 v[106:107], v[144:145], v[144:145], v[106:107]
	v_pk_fma_f32 v[106:107], v[146:147], v[146:147], v[106:107]
	v_pk_fma_f32 v[106:107], v[148:149], v[148:149], v[106:107]
	v_pk_fma_f32 v[106:107], v[150:151], v[150:151], v[106:107]
	v_pk_fma_f32 v[106:107], v[152:153], v[152:153], v[106:107]
	v_pk_fma_f32 v[106:107], v[154:155], v[154:155], v[106:107]
	v_add_f32_e32 v100, v100, v101
	v_add_f32_e32 v102, v102, v103
	v_add_f32_e32 v104, v104, v105
	v_add_f32_e32 v106, v106, v107
	s_nop 1
	v_add_f32_dpp v100, v100, v100 row_shr:1 row_mask:0xf bank_mask:0xf bound_ctrl:1
	v_add_f32_dpp v102, v102, v102 row_shr:1 row_mask:0xf bank_mask:0xf bound_ctrl:1
	v_add_f32_dpp v104, v104, v104 row_shr:1 row_mask:0xf bank_mask:0xf bound_ctrl:1
	v_add_f32_dpp v106, v106, v106 row_shr:1 row_mask:0xf bank_mask:0xf bound_ctrl:1
	v_add_f32_dpp v100, v100, v100 row_shr:2 row_mask:0xf bank_mask:0xf bound_ctrl:1
	v_add_f32_dpp v102, v102, v102 row_shr:2 row_mask:0xf bank_mask:0xf bound_ctrl:1
	v_add_f32_dpp v104, v104, v104 row_shr:2 row_mask:0xf bank_mask:0xf bound_ctrl:1
	v_add_f32_dpp v106, v106, v106 row_shr:2 row_mask:0xf bank_mask:0xf bound_ctrl:1
	v_add_f32_dpp v100, v100, v100 row_shr:4 row_mask:0xf bank_mask:0xf bound_ctrl:1
	v_add_f32_dpp v102, v102, v102 row_shr:4 row_mask:0xf bank_mask:0xf bound_ctrl:1
	v_add_f32_dpp v104, v104, v104 row_shr:4 row_mask:0xf bank_mask:0xf bound_ctrl:1
	v_add_f32_dpp v106, v106, v106 row_shr:4 row_mask:0xf bank_mask:0xf bound_ctrl:1
	v_add_f32_dpp v100, v100, v100 row_shr:8 row_mask:0xf bank_mask:0xf bound_ctrl:1
	v_add_f32_dpp v102, v102, v102 row_shr:8 row_mask:0xf bank_mask:0xf bound_ctrl:1
	v_add_f32_dpp v104, v104, v104 row_shr:8 row_mask:0xf bank_mask:0xf bound_ctrl:1
	v_add_f32_dpp v106, v106, v106 row_shr:8 row_mask:0xf bank_mask:0xf bound_ctrl:1
	v_add_f32_dpp v100, v100, v100 row_bcast:15 row_mask:0xa bank_mask:0xf
	v_add_f32_dpp v102, v102, v102 row_bcast:15 row_mask:0xa bank_mask:0xf
	v_add_f32_dpp v104, v104, v104 row_bcast:15 row_mask:0xa bank_mask:0xf
	v_add_f32_dpp v106, v106, v106 row_bcast:15 row_mask:0xa bank_mask:0xf
	v_add_f32_dpp v100, v100, v100 row_bcast:31 row_mask:0xc bank_mask:0xf
	v_add_f32_dpp v102, v102, v102 row_bcast:31 row_mask:0xc bank_mask:0xf
	v_add_f32_dpp v104, v104, v104 row_bcast:31 row_mask:0xc bank_mask:0xf
	v_add_f32_dpp v106, v106, v106 row_bcast:31 row_mask:0xc bank_mask:0xf
	s_nop 1
	v_readlane_b32 s5, v100, 63
	v_readlane_b32 s32, v102, 63
	v_readlane_b32 s54, v104, 63
	v_readlane_b32 s60, v106, 63
	s_nop 1
	v_mov_b32_e32 v156, s5
	v_mov_b32_e32 v158, s32
	v_mov_b32_e32 v160, s54
	v_mov_b32_e32 v162, s60
	v_fmaak_f32 v156, v156, v50, 0x358637bd
	v_fmaak_f32 v158, v158, v50, 0x358637bd
	v_fmaak_f32 v160, v160, v50, 0x358637bd
	v_fmaak_f32 v162, v162, v50, 0x358637bd
	v_rsq_f32_e32 v156, v156
	v_rsq_f32_e32 v158, v158
	v_rsq_f32_e32 v160, v160
	v_rsq_f32_e32 v162, v162
	s_nop 0
	v_lshlrev_b32_e32 v140, 16, v52
	v_and_b32_e32 v141, 0xffff0000, v52
	v_lshlrev_b32_e32 v142, 16, v53
	v_and_b32_e32 v143, 0xffff0000, v53
	v_lshlrev_b32_e32 v144, 16, v54
	v_and_b32_e32 v145, 0xffff0000, v54
	v_lshlrev_b32_e32 v146, 16, v55
	v_and_b32_e32 v147, 0xffff0000, v55
	v_lshlrev_b32_e32 v148, 16, v56
	v_and_b32_e32 v149, 0xffff0000, v56
	v_lshlrev_b32_e32 v150, 16, v57
	v_and_b32_e32 v151, 0xffff0000, v57
	v_lshlrev_b32_e32 v152, 16, v58
	v_and_b32_e32 v153, 0xffff0000, v58
	v_lshlrev_b32_e32 v154, 16, v59
	v_and_b32_e32 v155, 0xffff0000, v59
	v_pk_mul_f32 v[140:141], v[156:157], v[140:141] op_sel_hi:[0,1]
	v_pk_mul_f32 v[142:143], v[156:157], v[142:143] op_sel_hi:[0,1]
	v_pk_mul_f32 v[144:145], v[156:157], v[144:145] op_sel_hi:[0,1]
	v_pk_mul_f32 v[146:147], v[156:157], v[146:147] op_sel_hi:[0,1]
	v_pk_mul_f32 v[148:149], v[156:157], v[148:149] op_sel_hi:[0,1]
	v_pk_mul_f32 v[150:151], v[156:157], v[150:151] op_sel_hi:[0,1]
	v_pk_mul_f32 v[152:153], v[156:157], v[152:153] op_sel_hi:[0,1]
	v_pk_mul_f32 v[154:155], v[156:157], v[154:155] op_sel_hi:[0,1]
	v_pk_mul_f32 v[140:141], v[140:141], v[32:33]
	v_pk_mul_f32 v[142:143], v[142:143], v[34:35]
	v_pk_mul_f32 v[144:145], v[144:145], v[36:37]
	v_pk_mul_f32 v[146:147], v[146:147], v[38:39]
	v_pk_mul_f32 v[148:149], v[148:149], v[40:41]
	v_pk_mul_f32 v[150:151], v[150:151], v[42:43]
	v_pk_mul_f32 v[152:153], v[152:153], v[44:45]
	v_pk_mul_f32 v[154:155], v[154:155], v[46:47]
	v_pk_fma_f32 v[140:141], v[140:141], v[84:85], v[124:125]
	v_pk_fma_f32 v[142:143], v[142:143], v[86:87], v[126:127]
	v_pk_fma_f32 v[144:145], v[144:145], v[88:89], v[128:129]
	v_pk_fma_f32 v[146:147], v[146:147], v[90:91], v[130:131]
	v_pk_fma_f32 v[148:149], v[148:149], v[92:93], v[132:133]
	v_pk_fma_f32 v[150:151], v[150:151], v[94:95], v[134:135]
	v_pk_fma_f32 v[152:153], v[152:153], v[96:97], v[136:137]
	v_pk_fma_f32 v[154:155], v[154:155], v[98:99], v[138:139]
	v_cvt_pk_bf16_f32 v164, v140, v141
	v_cvt_pk_bf16_f32 v165, v142, v143
	v_cvt_pk_bf16_f32 v166, v144, v145
	v_cvt_pk_bf16_f32 v167, v146, v147
	v_cvt_pk_bf16_f32 v168, v148, v149
	v_cvt_pk_bf16_f32 v169, v150, v151
	v_cvt_pk_bf16_f32 v170, v152, v153
	v_cvt_pk_bf16_f32 v171, v154, v155
	global_store_dwordx4 v51, v[164:167], s[20:21] sc1
	global_store_dwordx4 v51, v[168:171], s[20:21] offset:1024 sc1
	v_lshlrev_b32_e32 v140, 16, v60
	v_and_b32_e32 v141, 0xffff0000, v60
	v_lshlrev_b32_e32 v142, 16, v61
	v_and_b32_e32 v143, 0xffff0000, v61
	v_lshlrev_b32_e32 v144, 16, v62
	v_and_b32_e32 v145, 0xffff0000, v62
	v_lshlrev_b32_e32 v146, 16, v63
	v_and_b32_e32 v147, 0xffff0000, v63
	v_lshlrev_b32_e32 v148, 16, v64
	v_and_b32_e32 v149, 0xffff0000, v64
	v_lshlrev_b32_e32 v150, 16, v65
	v_and_b32_e32 v151, 0xffff0000, v65
	v_lshlrev_b32_e32 v152, 16, v66
	v_and_b32_e32 v153, 0xffff0000, v66
	v_lshlrev_b32_e32 v154, 16, v67
	v_and_b32_e32 v155, 0xffff0000, v67
	v_pk_mul_f32 v[140:141], v[158:159], v[140:141] op_sel_hi:[0,1]
	v_pk_mul_f32 v[142:143], v[158:159], v[142:143] op_sel_hi:[0,1]
	v_pk_mul_f32 v[144:145], v[158:159], v[144:145] op_sel_hi:[0,1]
	v_pk_mul_f32 v[146:147], v[158:159], v[146:147] op_sel_hi:[0,1]
	v_pk_mul_f32 v[148:149], v[158:159], v[148:149] op_sel_hi:[0,1]
	v_pk_mul_f32 v[150:151], v[158:159], v[150:151] op_sel_hi:[0,1]
	v_pk_mul_f32 v[152:153], v[158:159], v[152:153] op_sel_hi:[0,1]
	v_pk_mul_f32 v[154:155], v[158:159], v[154:155] op_sel_hi:[0,1]
	v_pk_mul_f32 v[140:141], v[140:141], v[32:33]
	v_pk_mul_f32 v[142:143], v[142:143], v[34:35]
	v_pk_mul_f32 v[144:145], v[144:145], v[36:37]
	v_pk_mul_f32 v[146:147], v[146:147], v[38:39]
	v_pk_mul_f32 v[148:149], v[148:149], v[40:41]
	v_pk_mul_f32 v[150:151], v[150:151], v[42:43]
	v_pk_mul_f32 v[152:153], v[152:153], v[44:45]
	v_pk_mul_f32 v[154:155], v[154:155], v[46:47]
	v_pk_fma_f32 v[140:141], v[140:141], v[84:85], v[124:125]
	v_pk_fma_f32 v[142:143], v[142:143], v[86:87], v[126:127]
	v_pk_fma_f32 v[144:145], v[144:145], v[88:89], v[128:129]
	v_pk_fma_f32 v[146:147], v[146:147], v[90:91], v[130:131]
	v_pk_fma_f32 v[148:149], v[148:149], v[92:93], v[132:133]
	v_pk_fma_f32 v[150:151], v[150:151], v[94:95], v[134:135]
	v_pk_fma_f32 v[152:153], v[152:153], v[96:97], v[136:137]
	v_pk_fma_f32 v[154:155], v[154:155], v[98:99], v[138:139]
	v_cvt_pk_bf16_f32 v172, v140, v141
	v_cvt_pk_bf16_f32 v173, v142, v143
	v_cvt_pk_bf16_f32 v174, v144, v145
	v_cvt_pk_bf16_f32 v175, v146, v147
	v_cvt_pk_bf16_f32 v176, v148, v149
	v_cvt_pk_bf16_f32 v177, v150, v151
	v_cvt_pk_bf16_f32 v178, v152, v153
	v_cvt_pk_bf16_f32 v179, v154, v155
	global_store_dwordx4 v51, v[172:175], s[20:21] offset:2048 sc1
	global_store_dwordx4 v51, v[176:179], s[20:21] offset:3072 sc1
	v_lshlrev_b32_e32 v140, 16, v68
	v_and_b32_e32 v141, 0xffff0000, v68
	v_lshlrev_b32_e32 v142, 16, v69
	v_and_b32_e32 v143, 0xffff0000, v69
	v_lshlrev_b32_e32 v144, 16, v70
	v_and_b32_e32 v145, 0xffff0000, v70
	v_lshlrev_b32_e32 v146, 16, v71
	v_and_b32_e32 v147, 0xffff0000, v71
	v_lshlrev_b32_e32 v148, 16, v72
	v_and_b32_e32 v149, 0xffff0000, v72
	v_lshlrev_b32_e32 v150, 16, v73
	v_and_b32_e32 v151, 0xffff0000, v73
	v_lshlrev_b32_e32 v152, 16, v74
	v_and_b32_e32 v153, 0xffff0000, v74
	v_lshlrev_b32_e32 v154, 16, v75
	v_and_b32_e32 v155, 0xffff0000, v75
	v_pk_mul_f32 v[140:141], v[160:161], v[140:141] op_sel_hi:[0,1]
	v_pk_mul_f32 v[142:143], v[160:161], v[142:143] op_sel_hi:[0,1]
	v_pk_mul_f32 v[144:145], v[160:161], v[144:145] op_sel_hi:[0,1]
	v_pk_mul_f32 v[146:147], v[160:161], v[146:147] op_sel_hi:[0,1]
	v_pk_mul_f32 v[148:149], v[160:161], v[148:149] op_sel_hi:[0,1]
	v_pk_mul_f32 v[150:151], v[160:161], v[150:151] op_sel_hi:[0,1]
	v_pk_mul_f32 v[152:153], v[160:161], v[152:153] op_sel_hi:[0,1]
	v_pk_mul_f32 v[154:155], v[160:161], v[154:155] op_sel_hi:[0,1]
	v_pk_mul_f32 v[140:141], v[140:141], v[32:33]
	v_pk_mul_f32 v[142:143], v[142:143], v[34:35]
	v_pk_mul_f32 v[144:145], v[144:145], v[36:37]
	v_pk_mul_f32 v[146:147], v[146:147], v[38:39]
	v_pk_mul_f32 v[148:149], v[148:149], v[40:41]
	v_pk_mul_f32 v[150:151], v[150:151], v[42:43]
	v_pk_mul_f32 v[152:153], v[152:153], v[44:45]
	v_pk_mul_f32 v[154:155], v[154:155], v[46:47]
	v_pk_fma_f32 v[140:141], v[140:141], v[84:85], v[124:125]
	v_pk_fma_f32 v[142:143], v[142:143], v[86:87], v[126:127]
	v_pk_fma_f32 v[144:145], v[144:145], v[88:89], v[128:129]
	v_pk_fma_f32 v[146:147], v[146:147], v[90:91], v[130:131]
	v_pk_fma_f32 v[148:149], v[148:149], v[92:93], v[132:133]
	v_pk_fma_f32 v[150:151], v[150:151], v[94:95], v[134:135]
	v_pk_fma_f32 v[152:153], v[152:153], v[96:97], v[136:137]
	v_pk_fma_f32 v[154:155], v[154:155], v[98:99], v[138:139]
	v_cvt_pk_bf16_f32 v164, v140, v141
	v_cvt_pk_bf16_f32 v165, v142, v143
	v_cvt_pk_bf16_f32 v166, v144, v145
	v_cvt_pk_bf16_f32 v167, v146, v147
	v_cvt_pk_bf16_f32 v168, v148, v149
	v_cvt_pk_bf16_f32 v169, v150, v151
	v_cvt_pk_bf16_f32 v170, v152, v153
	v_cvt_pk_bf16_f32 v171, v154, v155
	global_store_dwordx4 v109, v[164:167], s[20:21] sc1
	global_store_dwordx4 v109, v[168:171], s[20:21] offset:1024 sc1
	v_lshlrev_b32_e32 v140, 16, v76
	v_and_b32_e32 v141, 0xffff0000, v76
	v_lshlrev_b32_e32 v142, 16, v77
	v_and_b32_e32 v143, 0xffff0000, v77
	v_lshlrev_b32_e32 v144, 16, v78
	v_and_b32_e32 v145, 0xffff0000, v78
	v_lshlrev_b32_e32 v146, 16, v79
	v_and_b32_e32 v147, 0xffff0000, v79
	v_lshlrev_b32_e32 v148, 16, v80
	v_and_b32_e32 v149, 0xffff0000, v80
	v_lshlrev_b32_e32 v150, 16, v81
	v_and_b32_e32 v151, 0xffff0000, v81
	v_lshlrev_b32_e32 v152, 16, v82
	v_and_b32_e32 v153, 0xffff0000, v82
	v_lshlrev_b32_e32 v154, 16, v83
	v_and_b32_e32 v155, 0xffff0000, v83
	v_pk_mul_f32 v[140:141], v[162:163], v[140:141] op_sel_hi:[0,1]
	v_pk_mul_f32 v[142:143], v[162:163], v[142:143] op_sel_hi:[0,1]
	v_pk_mul_f32 v[144:145], v[162:163], v[144:145] op_sel_hi:[0,1]
	v_pk_mul_f32 v[146:147], v[162:163], v[146:147] op_sel_hi:[0,1]
	v_pk_mul_f32 v[148:149], v[162:163], v[148:149] op_sel_hi:[0,1]
	v_pk_mul_f32 v[150:151], v[162:163], v[150:151] op_sel_hi:[0,1]
	v_pk_mul_f32 v[152:153], v[162:163], v[152:153] op_sel_hi:[0,1]
	v_pk_mul_f32 v[154:155], v[162:163], v[154:155] op_sel_hi:[0,1]
	v_pk_mul_f32 v[140:141], v[140:141], v[32:33]
	v_pk_mul_f32 v[142:143], v[142:143], v[34:35]
	v_pk_mul_f32 v[144:145], v[144:145], v[36:37]
	v_pk_mul_f32 v[146:147], v[146:147], v[38:39]
	v_pk_mul_f32 v[148:149], v[148:149], v[40:41]
	v_pk_mul_f32 v[150:151], v[150:151], v[42:43]
	v_pk_mul_f32 v[152:153], v[152:153], v[44:45]
	v_pk_mul_f32 v[154:155], v[154:155], v[46:47]
	v_pk_fma_f32 v[140:141], v[140:141], v[84:85], v[124:125]
	v_pk_fma_f32 v[142:143], v[142:143], v[86:87], v[126:127]
	v_pk_fma_f32 v[144:145], v[144:145], v[88:89], v[128:129]
	v_pk_fma_f32 v[146:147], v[146:147], v[90:91], v[130:131]
	v_pk_fma_f32 v[148:149], v[148:149], v[92:93], v[132:133]
	v_pk_fma_f32 v[150:151], v[150:151], v[94:95], v[134:135]
	v_pk_fma_f32 v[152:153], v[152:153], v[96:97], v[136:137]
	v_pk_fma_f32 v[154:155], v[154:155], v[98:99], v[138:139]
	v_cvt_pk_bf16_f32 v172, v140, v141
	v_cvt_pk_bf16_f32 v173, v142, v143
	v_cvt_pk_bf16_f32 v174, v144, v145
	v_cvt_pk_bf16_f32 v175, v146, v147
	v_cvt_pk_bf16_f32 v176, v148, v149
	v_cvt_pk_bf16_f32 v177, v150, v151
	v_cvt_pk_bf16_f32 v178, v152, v153
	v_cvt_pk_bf16_f32 v179, v154, v155
	global_store_dwordx4 v109, v[172:175], s[20:21] offset:2048 sc1
	global_store_dwordx4 v109, v[176:179], s[20:21] offset:3072 sc1
	s_add_u32 s20, s20, 0x2000
	s_addc_u32 s21, s21, 0
	s_add_u32 s18, s18, 0x2000
	s_addc_u32 s19, s19, 0
	global_load_dwordx4 v[52:55], v51, s[18:19]
	global_load_dwordx4 v[56:59], v51, s[18:19] offset:1024
	global_load_dwordx4 v[60:63], v51, s[18:19] offset:2048
	global_load_dwordx4 v[64:67], v51, s[18:19] offset:3072
	global_load_dwordx4 v[68:71], v109, s[18:19]
	global_load_dwordx4 v[72:75], v109, s[18:19] offset:1024
	global_load_dwordx4 v[76:79], v109, s[18:19] offset:2048
	global_load_dwordx4 v[80:83], v109, s[18:19] offset:3072
	s_waitcnt vmcnt(16)
	v_lshlrev_b32_e32 v140, 16, v0
	v_and_b32_e32 v141, 0xffff0000, v0
	v_lshlrev_b32_e32 v142, 16, v1
	v_and_b32_e32 v143, 0xffff0000, v1
	v_lshlrev_b32_e32 v144, 16, v2
	v_and_b32_e32 v145, 0xffff0000, v2
	v_lshlrev_b32_e32 v146, 16, v3
	v_and_b32_e32 v147, 0xffff0000, v3
	v_lshlrev_b32_e32 v148, 16, v4
	v_and_b32_e32 v149, 0xffff0000, v4
	v_lshlrev_b32_e32 v150, 16, v5
	v_and_b32_e32 v151, 0xffff0000, v5
	v_lshlrev_b32_e32 v152, 16, v6
	v_and_b32_e32 v153, 0xffff0000, v6
	v_lshlrev_b32_e32 v154, 16, v7
	v_and_b32_e32 v155, 0xffff0000, v7
	v_pk_mul_f32 v[100:101], v[140:141], v[140:141]
	v_pk_fma_f32 v[100:101], v[142:143], v[142:143], v[100:101]
	v_pk_fma_f32 v[100:101], v[144:145], v[144:145], v[100:101]
	v_pk_fma_f32 v[100:101], v[146:147], v[146:147], v[100:101]
	v_pk_fma_f32 v[100:101], v[148:149], v[148:149], v[100:101]
	v_pk_fma_f32 v[100:101], v[150:151], v[150:151], v[100:101]
	v_pk_fma_f32 v[100:101], v[152:153], v[152:153], v[100:101]
	v_pk_fma_f32 v[100:101], v[154:155], v[154:155], v[100:101]
	v_lshlrev_b32_e32 v140, 16, v8
	v_and_b32_e32 v141, 0xffff0000, v8
	v_lshlrev_b32_e32 v142, 16, v9
	v_and_b32_e32 v143, 0xffff0000, v9
	v_lshlrev_b32_e32 v144, 16, v10
	v_and_b32_e32 v145, 0xffff0000, v10
	v_lshlrev_b32_e32 v146, 16, v11
	v_and_b32_e32 v147, 0xffff0000, v11
	v_lshlrev_b32_e32 v148, 16, v12
	v_and_b32_e32 v149, 0xffff0000, v12
	v_lshlrev_b32_e32 v150, 16, v13
	v_and_b32_e32 v151, 0xffff0000, v13
	v_lshlrev_b32_e32 v152, 16, v14
	v_and_b32_e32 v153, 0xffff0000, v14
	v_lshlrev_b32_e32 v154, 16, v15
	v_and_b32_e32 v155, 0xffff0000, v15
	v_pk_mul_f32 v[102:103], v[140:141], v[140:141]
	v_pk_fma_f32 v[102:103], v[142:143], v[142:143], v[102:103]
	v_pk_fma_f32 v[102:103], v[144:145], v[144:145], v[102:103]
	v_pk_fma_f32 v[102:103], v[146:147], v[146:147], v[102:103]
	v_pk_fma_f32 v[102:103], v[148:149], v[148:149], v[102:103]
	v_pk_fma_f32 v[102:103], v[150:151], v[150:151], v[102:103]
	v_pk_fma_f32 v[102:103], v[152:153], v[152:153], v[102:103]
	v_pk_fma_f32 v[102:103], v[154:155], v[154:155], v[102:103]
	v_lshlrev_b32_e32 v140, 16, v16
	v_and_b32_e32 v141, 0xffff0000, v16
	v_lshlrev_b32_e32 v142, 16, v17
	v_and_b32_e32 v143, 0xffff0000, v17
	v_lshlrev_b32_e32 v144, 16, v18
	v_and_b32_e32 v145, 0xffff0000, v18
	v_lshlrev_b32_e32 v146, 16, v19
	v_and_b32_e32 v147, 0xffff0000, v19
	v_lshlrev_b32_e32 v148, 16, v20
	v_and_b32_e32 v149, 0xffff0000, v20
	v_lshlrev_b32_e32 v150, 16, v21
	v_and_b32_e32 v151, 0xffff0000, v21
	v_lshlrev_b32_e32 v152, 16, v22
	v_and_b32_e32 v153, 0xffff0000, v22
	v_lshlrev_b32_e32 v154, 16, v23
	v_and_b32_e32 v155, 0xffff0000, v23
	v_pk_mul_f32 v[104:105], v[140:141], v[140:141]
	v_pk_fma_f32 v[104:105], v[142:143], v[142:143], v[104:105]
	v_pk_fma_f32 v[104:105], v[144:145], v[144:145], v[104:105]
	v_pk_fma_f32 v[104:105], v[146:147], v[146:147], v[104:105]
	v_pk_fma_f32 v[104:105], v[148:149], v[148:149], v[104:105]
	v_pk_fma_f32 v[104:105], v[150:151], v[150:151], v[104:105]
	v_pk_fma_f32 v[104:105], v[152:153], v[152:153], v[104:105]
	v_pk_fma_f32 v[104:105], v[154:155], v[154:155], v[104:105]
	v_lshlrev_b32_e32 v140, 16, v24
	v_and_b32_e32 v141, 0xffff0000, v24
	v_lshlrev_b32_e32 v142, 16, v25
	v_and_b32_e32 v143, 0xffff0000, v25
	v_lshlrev_b32_e32 v144, 16, v26
	v_and_b32_e32 v145, 0xffff0000, v26
	v_lshlrev_b32_e32 v146, 16, v27
	v_and_b32_e32 v147, 0xffff0000, v27
	v_lshlrev_b32_e32 v148, 16, v28
	v_and_b32_e32 v149, 0xffff0000, v28
	v_lshlrev_b32_e32 v150, 16, v29
	v_and_b32_e32 v151, 0xffff0000, v29
	v_lshlrev_b32_e32 v152, 16, v30
	v_and_b32_e32 v153, 0xffff0000, v30
	v_lshlrev_b32_e32 v154, 16, v31
	v_and_b32_e32 v155, 0xffff0000, v31
	v_pk_mul_f32 v[106:107], v[140:141], v[140:141]
	v_pk_fma_f32 v[106:107], v[142:143], v[142:143], v[106:107]
	v_pk_fma_f32 v[106:107], v[144:145], v[144:145], v[106:107]
	v_pk_fma_f32 v[106:107], v[146:147], v[146:147], v[106:107]
	v_pk_fma_f32 v[106:107], v[148:149], v[148:149], v[106:107]
	v_pk_fma_f32 v[106:107], v[150:151], v[150:151], v[106:107]
	v_pk_fma_f32 v[106:107], v[152:153], v[152:153], v[106:107]
	v_pk_fma_f32 v[106:107], v[154:155], v[154:155], v[106:107]
	v_add_f32_e32 v100, v100, v101
	v_add_f32_e32 v102, v102, v103
	v_add_f32_e32 v104, v104, v105
	v_add_f32_e32 v106, v106, v107
	s_nop 1
	v_add_f32_dpp v100, v100, v100 row_shr:1 row_mask:0xf bank_mask:0xf bound_ctrl:1
	v_add_f32_dpp v102, v102, v102 row_shr:1 row_mask:0xf bank_mask:0xf bound_ctrl:1
	v_add_f32_dpp v104, v104, v104 row_shr:1 row_mask:0xf bank_mask:0xf bound_ctrl:1
	v_add_f32_dpp v106, v106, v106 row_shr:1 row_mask:0xf bank_mask:0xf bound_ctrl:1
	v_add_f32_dpp v100, v100, v100 row_shr:2 row_mask:0xf bank_mask:0xf bound_ctrl:1
	v_add_f32_dpp v102, v102, v102 row_shr:2 row_mask:0xf bank_mask:0xf bound_ctrl:1
	v_add_f32_dpp v104, v104, v104 row_shr:2 row_mask:0xf bank_mask:0xf bound_ctrl:1
	v_add_f32_dpp v106, v106, v106 row_shr:2 row_mask:0xf bank_mask:0xf bound_ctrl:1
	v_add_f32_dpp v100, v100, v100 row_shr:4 row_mask:0xf bank_mask:0xf bound_ctrl:1
	v_add_f32_dpp v102, v102, v102 row_shr:4 row_mask:0xf bank_mask:0xf bound_ctrl:1
	v_add_f32_dpp v104, v104, v104 row_shr:4 row_mask:0xf bank_mask:0xf bound_ctrl:1
	v_add_f32_dpp v106, v106, v106 row_shr:4 row_mask:0xf bank_mask:0xf bound_ctrl:1
	v_add_f32_dpp v100, v100, v100 row_shr:8 row_mask:0xf bank_mask:0xf bound_ctrl:1
	v_add_f32_dpp v102, v102, v102 row_shr:8 row_mask:0xf bank_mask:0xf bound_ctrl:1
	v_add_f32_dpp v104, v104, v104 row_shr:8 row_mask:0xf bank_mask:0xf bound_ctrl:1
	v_add_f32_dpp v106, v106, v106 row_shr:8 row_mask:0xf bank_mask:0xf bound_ctrl:1
	v_add_f32_dpp v100, v100, v100 row_bcast:15 row_mask:0xa bank_mask:0xf
	v_add_f32_dpp v102, v102, v102 row_bcast:15 row_mask:0xa bank_mask:0xf
	v_add_f32_dpp v104, v104, v104 row_bcast:15 row_mask:0xa bank_mask:0xf
	v_add_f32_dpp v106, v106, v106 row_bcast:15 row_mask:0xa bank_mask:0xf
	v_add_f32_dpp v100, v100, v100 row_bcast:31 row_mask:0xc bank_mask:0xf
	v_add_f32_dpp v102, v102, v102 row_bcast:31 row_mask:0xc bank_mask:0xf
	v_add_f32_dpp v104, v104, v104 row_bcast:31 row_mask:0xc bank_mask:0xf
	v_add_f32_dpp v106, v106, v106 row_bcast:31 row_mask:0xc bank_mask:0xf
	s_nop 1
	v_readlane_b32 s5, v100, 63
	v_readlane_b32 s32, v102, 63
	v_readlane_b32 s54, v104, 63
	v_readlane_b32 s60, v106, 63
	s_nop 1
	v_mov_b32_e32 v156, s5
	v_mov_b32_e32 v158, s32
	v_mov_b32_e32 v160, s54
	v_mov_b32_e32 v162, s60
	v_fmaak_f32 v156, v156, v50, 0x358637bd
	v_fmaak_f32 v158, v158, v50, 0x358637bd
	v_fmaak_f32 v160, v160, v50, 0x358637bd
	v_fmaak_f32 v162, v162, v50, 0x358637bd
	v_rsq_f32_e32 v156, v156
	v_rsq_f32_e32 v158, v158
	v_rsq_f32_e32 v160, v160
	v_rsq_f32_e32 v162, v162
	s_nop 0
	v_lshlrev_b32_e32 v140, 16, v0
	v_and_b32_e32 v141, 0xffff0000, v0
	v_lshlrev_b32_e32 v142, 16, v1
	v_and_b32_e32 v143, 0xffff0000, v1
	v_lshlrev_b32_e32 v144, 16, v2
	v_and_b32_e32 v145, 0xffff0000, v2
	v_lshlrev_b32_e32 v146, 16, v3
	v_and_b32_e32 v147, 0xffff0000, v3
	v_lshlrev_b32_e32 v148, 16, v4
	v_and_b32_e32 v149, 0xffff0000, v4
	v_lshlrev_b32_e32 v150, 16, v5
	v_and_b32_e32 v151, 0xffff0000, v5
	v_lshlrev_b32_e32 v152, 16, v6
	v_and_b32_e32 v153, 0xffff0000, v6
	v_lshlrev_b32_e32 v154, 16, v7
	v_and_b32_e32 v155, 0xffff0000, v7
	v_pk_mul_f32 v[140:141], v[156:157], v[140:141] op_sel_hi:[0,1]
	v_pk_mul_f32 v[142:143], v[156:157], v[142:143] op_sel_hi:[0,1]
	v_pk_mul_f32 v[144:145], v[156:157], v[144:145] op_sel_hi:[0,1]
	v_pk_mul_f32 v[146:147], v[156:157], v[146:147] op_sel_hi:[0,1]
	v_pk_mul_f32 v[148:149], v[156:157], v[148:149] op_sel_hi:[0,1]
	v_pk_mul_f32 v[150:151], v[156:157], v[150:151] op_sel_hi:[0,1]
	v_pk_mul_f32 v[152:153], v[156:157], v[152:153] op_sel_hi:[0,1]
	v_pk_mul_f32 v[154:155], v[156:157], v[154:155] op_sel_hi:[0,1]
	v_pk_mul_f32 v[140:141], v[140:141], v[32:33]
	v_pk_mul_f32 v[142:143], v[142:143], v[34:35]
	v_pk_mul_f32 v[144:145], v[144:145], v[36:37]
	v_pk_mul_f32 v[146:147], v[146:147], v[38:39]
	v_pk_mul_f32 v[148:149], v[148:149], v[40:41]
	v_pk_mul_f32 v[150:151], v[150:151], v[42:43]
	v_pk_mul_f32 v[152:153], v[152:153], v[44:45]
	v_pk_mul_f32 v[154:155], v[154:155], v[46:47]
	v_pk_fma_f32 v[140:141], v[140:141], v[84:85], v[124:125]
	v_pk_fma_f32 v[142:143], v[142:143], v[86:87], v[126:127]
	v_pk_fma_f32 v[144:145], v[144:145], v[88:89], v[128:129]
	v_pk_fma_f32 v[146:147], v[146:147], v[90:91], v[130:131]
	v_pk_fma_f32 v[148:149], v[148:149], v[92:93], v[132:133]
	v_pk_fma_f32 v[150:151], v[150:151], v[94:95], v[134:135]
	v_pk_fma_f32 v[152:153], v[152:153], v[96:97], v[136:137]
	v_pk_fma_f32 v[154:155], v[154:155], v[98:99], v[138:139]
	v_cvt_pk_bf16_f32 v172, v140, v141
	v_cvt_pk_bf16_f32 v173, v142, v143
	v_cvt_pk_bf16_f32 v174, v144, v145
	v_cvt_pk_bf16_f32 v175, v146, v147
	v_cvt_pk_bf16_f32 v176, v148, v149
	v_cvt_pk_bf16_f32 v177, v150, v151
	v_cvt_pk_bf16_f32 v178, v152, v153
	v_cvt_pk_bf16_f32 v179, v154, v155
	global_store_dwordx4 v51, v[172:175], s[20:21] sc1
	global_store_dwordx4 v51, v[176:179], s[20:21] offset:1024 sc1
	v_lshlrev_b32_e32 v140, 16, v8
	v_and_b32_e32 v141, 0xffff0000, v8
	v_lshlrev_b32_e32 v142, 16, v9
	v_and_b32_e32 v143, 0xffff0000, v9
	v_lshlrev_b32_e32 v144, 16, v10
	v_and_b32_e32 v145, 0xffff0000, v10
	v_lshlrev_b32_e32 v146, 16, v11
	v_and_b32_e32 v147, 0xffff0000, v11
	v_lshlrev_b32_e32 v148, 16, v12
	v_and_b32_e32 v149, 0xffff0000, v12
	v_lshlrev_b32_e32 v150, 16, v13
	v_and_b32_e32 v151, 0xffff0000, v13
	v_lshlrev_b32_e32 v152, 16, v14
	v_and_b32_e32 v153, 0xffff0000, v14
	v_lshlrev_b32_e32 v154, 16, v15
	v_and_b32_e32 v155, 0xffff0000, v15
	v_pk_mul_f32 v[140:141], v[158:159], v[140:141] op_sel_hi:[0,1]
	v_pk_mul_f32 v[142:143], v[158:159], v[142:143] op_sel_hi:[0,1]
	v_pk_mul_f32 v[144:145], v[158:159], v[144:145] op_sel_hi:[0,1]
	v_pk_mul_f32 v[146:147], v[158:159], v[146:147] op_sel_hi:[0,1]
	v_pk_mul_f32 v[148:149], v[158:159], v[148:149] op_sel_hi:[0,1]
	v_pk_mul_f32 v[150:151], v[158:159], v[150:151] op_sel_hi:[0,1]
	v_pk_mul_f32 v[152:153], v[158:159], v[152:153] op_sel_hi:[0,1]
	v_pk_mul_f32 v[154:155], v[158:159], v[154:155] op_sel_hi:[0,1]
	v_pk_mul_f32 v[140:141], v[140:141], v[32:33]
	v_pk_mul_f32 v[142:143], v[142:143], v[34:35]
	v_pk_mul_f32 v[144:145], v[144:145], v[36:37]
	v_pk_mul_f32 v[146:147], v[146:147], v[38:39]
	v_pk_mul_f32 v[148:149], v[148:149], v[40:41]
	v_pk_mul_f32 v[150:151], v[150:151], v[42:43]
	v_pk_mul_f32 v[152:153], v[152:153], v[44:45]
	v_pk_mul_f32 v[154:155], v[154:155], v[46:47]
	v_pk_fma_f32 v[140:141], v[140:141], v[84:85], v[124:125]
	v_pk_fma_f32 v[142:143], v[142:143], v[86:87], v[126:127]
	v_pk_fma_f32 v[144:145], v[144:145], v[88:89], v[128:129]
	v_pk_fma_f32 v[146:147], v[146:147], v[90:91], v[130:131]
	v_pk_fma_f32 v[148:149], v[148:149], v[92:93], v[132:133]
	v_pk_fma_f32 v[150:151], v[150:151], v[94:95], v[134:135]
	v_pk_fma_f32 v[152:153], v[152:153], v[96:97], v[136:137]
	v_pk_fma_f32 v[154:155], v[154:155], v[98:99], v[138:139]
	v_cvt_pk_bf16_f32 v164, v140, v141
	v_cvt_pk_bf16_f32 v165, v142, v143
	v_cvt_pk_bf16_f32 v166, v144, v145
	v_cvt_pk_bf16_f32 v167, v146, v147
	v_cvt_pk_bf16_f32 v168, v148, v149
	v_cvt_pk_bf16_f32 v169, v150, v151
	v_cvt_pk_bf16_f32 v170, v152, v153
	v_cvt_pk_bf16_f32 v171, v154, v155
	global_store_dwordx4 v51, v[164:167], s[20:21] offset:2048 sc1
	global_store_dwordx4 v51, v[168:171], s[20:21] offset:3072 sc1
	v_lshlrev_b32_e32 v140, 16, v16
	v_and_b32_e32 v141, 0xffff0000, v16
	v_lshlrev_b32_e32 v142, 16, v17
	v_and_b32_e32 v143, 0xffff0000, v17
	v_lshlrev_b32_e32 v144, 16, v18
	v_and_b32_e32 v145, 0xffff0000, v18
	v_lshlrev_b32_e32 v146, 16, v19
	v_and_b32_e32 v147, 0xffff0000, v19
	v_lshlrev_b32_e32 v148, 16, v20
	v_and_b32_e32 v149, 0xffff0000, v20
	v_lshlrev_b32_e32 v150, 16, v21
	v_and_b32_e32 v151, 0xffff0000, v21
	v_lshlrev_b32_e32 v152, 16, v22
	v_and_b32_e32 v153, 0xffff0000, v22
	v_lshlrev_b32_e32 v154, 16, v23
	v_and_b32_e32 v155, 0xffff0000, v23
	v_pk_mul_f32 v[140:141], v[160:161], v[140:141] op_sel_hi:[0,1]
	v_pk_mul_f32 v[142:143], v[160:161], v[142:143] op_sel_hi:[0,1]
	v_pk_mul_f32 v[144:145], v[160:161], v[144:145] op_sel_hi:[0,1]
	v_pk_mul_f32 v[146:147], v[160:161], v[146:147] op_sel_hi:[0,1]
	v_pk_mul_f32 v[148:149], v[160:161], v[148:149] op_sel_hi:[0,1]
	v_pk_mul_f32 v[150:151], v[160:161], v[150:151] op_sel_hi:[0,1]
	v_pk_mul_f32 v[152:153], v[160:161], v[152:153] op_sel_hi:[0,1]
	v_pk_mul_f32 v[154:155], v[160:161], v[154:155] op_sel_hi:[0,1]
	v_pk_mul_f32 v[140:141], v[140:141], v[32:33]
	v_pk_mul_f32 v[142:143], v[142:143], v[34:35]
	v_pk_mul_f32 v[144:145], v[144:145], v[36:37]
	v_pk_mul_f32 v[146:147], v[146:147], v[38:39]
	v_pk_mul_f32 v[148:149], v[148:149], v[40:41]
	v_pk_mul_f32 v[150:151], v[150:151], v[42:43]
	v_pk_mul_f32 v[152:153], v[152:153], v[44:45]
	v_pk_mul_f32 v[154:155], v[154:155], v[46:47]
	v_pk_fma_f32 v[140:141], v[140:141], v[84:85], v[124:125]
	v_pk_fma_f32 v[142:143], v[142:143], v[86:87], v[126:127]
	v_pk_fma_f32 v[144:145], v[144:145], v[88:89], v[128:129]
	v_pk_fma_f32 v[146:147], v[146:147], v[90:91], v[130:131]
	v_pk_fma_f32 v[148:149], v[148:149], v[92:93], v[132:133]
	v_pk_fma_f32 v[150:151], v[150:151], v[94:95], v[134:135]
	v_pk_fma_f32 v[152:153], v[152:153], v[96:97], v[136:137]
	v_pk_fma_f32 v[154:155], v[154:155], v[98:99], v[138:139]
	v_cvt_pk_bf16_f32 v172, v140, v141
	v_cvt_pk_bf16_f32 v173, v142, v143
	v_cvt_pk_bf16_f32 v174, v144, v145
	v_cvt_pk_bf16_f32 v175, v146, v147
	v_cvt_pk_bf16_f32 v176, v148, v149
	v_cvt_pk_bf16_f32 v177, v150, v151
	v_cvt_pk_bf16_f32 v178, v152, v153
	v_cvt_pk_bf16_f32 v179, v154, v155
	global_store_dwordx4 v109, v[172:175], s[20:21] sc1
	global_store_dwordx4 v109, v[176:179], s[20:21] offset:1024 sc1
	v_lshlrev_b32_e32 v140, 16, v24
	v_and_b32_e32 v141, 0xffff0000, v24
	v_lshlrev_b32_e32 v142, 16, v25
	v_and_b32_e32 v143, 0xffff0000, v25
	v_lshlrev_b32_e32 v144, 16, v26
	v_and_b32_e32 v145, 0xffff0000, v26
	v_lshlrev_b32_e32 v146, 16, v27
	v_and_b32_e32 v147, 0xffff0000, v27
	v_lshlrev_b32_e32 v148, 16, v28
	v_and_b32_e32 v149, 0xffff0000, v28
	v_lshlrev_b32_e32 v150, 16, v29
	v_and_b32_e32 v151, 0xffff0000, v29
	v_lshlrev_b32_e32 v152, 16, v30
	v_and_b32_e32 v153, 0xffff0000, v30
	v_lshlrev_b32_e32 v154, 16, v31
	v_and_b32_e32 v155, 0xffff0000, v31
	v_pk_mul_f32 v[140:141], v[162:163], v[140:141] op_sel_hi:[0,1]
	v_pk_mul_f32 v[142:143], v[162:163], v[142:143] op_sel_hi:[0,1]
	v_pk_mul_f32 v[144:145], v[162:163], v[144:145] op_sel_hi:[0,1]
	v_pk_mul_f32 v[146:147], v[162:163], v[146:147] op_sel_hi:[0,1]
	v_pk_mul_f32 v[148:149], v[162:163], v[148:149] op_sel_hi:[0,1]
	v_pk_mul_f32 v[150:151], v[162:163], v[150:151] op_sel_hi:[0,1]
	v_pk_mul_f32 v[152:153], v[162:163], v[152:153] op_sel_hi:[0,1]
	v_pk_mul_f32 v[154:155], v[162:163], v[154:155] op_sel_hi:[0,1]
	v_pk_mul_f32 v[140:141], v[140:141], v[32:33]
	v_pk_mul_f32 v[142:143], v[142:143], v[34:35]
	v_pk_mul_f32 v[144:145], v[144:145], v[36:37]
	v_pk_mul_f32 v[146:147], v[146:147], v[38:39]
	v_pk_mul_f32 v[148:149], v[148:149], v[40:41]
	v_pk_mul_f32 v[150:151], v[150:151], v[42:43]
	v_pk_mul_f32 v[152:153], v[152:153], v[44:45]
	v_pk_mul_f32 v[154:155], v[154:155], v[46:47]
	v_pk_fma_f32 v[140:141], v[140:141], v[84:85], v[124:125]
	v_pk_fma_f32 v[142:143], v[142:143], v[86:87], v[126:127]
	v_pk_fma_f32 v[144:145], v[144:145], v[88:89], v[128:129]
	v_pk_fma_f32 v[146:147], v[146:147], v[90:91], v[130:131]
	v_pk_fma_f32 v[148:149], v[148:149], v[92:93], v[132:133]
	v_pk_fma_f32 v[150:151], v[150:151], v[94:95], v[134:135]
	v_pk_fma_f32 v[152:153], v[152:153], v[96:97], v[136:137]
	v_pk_fma_f32 v[154:155], v[154:155], v[98:99], v[138:139]
	v_cvt_pk_bf16_f32 v164, v140, v141
	v_cvt_pk_bf16_f32 v165, v142, v143
	v_cvt_pk_bf16_f32 v166, v144, v145
	v_cvt_pk_bf16_f32 v167, v146, v147
	v_cvt_pk_bf16_f32 v168, v148, v149
	v_cvt_pk_bf16_f32 v169, v150, v151
	v_cvt_pk_bf16_f32 v170, v152, v153
	v_cvt_pk_bf16_f32 v171, v154, v155
	global_store_dwordx4 v109, v[164:167], s[20:21] offset:2048 sc1
	global_store_dwordx4 v109, v[168:171], s[20:21] offset:3072 sc1
	s_add_u32 s20, s20, 0x2000
	s_addc_u32 s21, s21, 0
	s_add_u32 s18, s18, 0x2000
	s_addc_u32 s19, s19, 0
	global_load_dwordx4 v[0:3], v51, s[18:19]
	global_load_dwordx4 v[4:7], v51, s[18:19] offset:1024
	global_load_dwordx4 v[8:11], v51, s[18:19] offset:2048
	global_load_dwordx4 v[12:15], v51, s[18:19] offset:3072
	global_load_dwordx4 v[16:19], v109, s[18:19]
	global_load_dwordx4 v[20:23], v109, s[18:19] offset:1024
	global_load_dwordx4 v[24:27], v109, s[18:19] offset:2048
	global_load_dwordx4 v[28:31], v109, s[18:19] offset:3072
	s_waitcnt vmcnt(16)
	v_lshlrev_b32_e32 v140, 16, v52
	v_and_b32_e32 v141, 0xffff0000, v52
	v_lshlrev_b32_e32 v142, 16, v53
	v_and_b32_e32 v143, 0xffff0000, v53
	v_lshlrev_b32_e32 v144, 16, v54
	v_and_b32_e32 v145, 0xffff0000, v54
	v_lshlrev_b32_e32 v146, 16, v55
	v_and_b32_e32 v147, 0xffff0000, v55
	v_lshlrev_b32_e32 v148, 16, v56
	v_and_b32_e32 v149, 0xffff0000, v56
	v_lshlrev_b32_e32 v150, 16, v57
	v_and_b32_e32 v151, 0xffff0000, v57
	v_lshlrev_b32_e32 v152, 16, v58
	v_and_b32_e32 v153, 0xffff0000, v58
	v_lshlrev_b32_e32 v154, 16, v59
	v_and_b32_e32 v155, 0xffff0000, v59
	v_pk_mul_f32 v[100:101], v[140:141], v[140:141]
	v_pk_fma_f32 v[100:101], v[142:143], v[142:143], v[100:101]
	v_pk_fma_f32 v[100:101], v[144:145], v[144:145], v[100:101]
	v_pk_fma_f32 v[100:101], v[146:147], v[146:147], v[100:101]
	v_pk_fma_f32 v[100:101], v[148:149], v[148:149], v[100:101]
	v_pk_fma_f32 v[100:101], v[150:151], v[150:151], v[100:101]
	v_pk_fma_f32 v[100:101], v[152:153], v[152:153], v[100:101]
	v_pk_fma_f32 v[100:101], v[154:155], v[154:155], v[100:101]
	v_lshlrev_b32_e32 v140, 16, v60
	v_and_b32_e32 v141, 0xffff0000, v60
	v_lshlrev_b32_e32 v142, 16, v61
	v_and_b32_e32 v143, 0xffff0000, v61
	v_lshlrev_b32_e32 v144, 16, v62
	v_and_b32_e32 v145, 0xffff0000, v62
	v_lshlrev_b32_e32 v146, 16, v63
	v_and_b32_e32 v147, 0xffff0000, v63
	v_lshlrev_b32_e32 v148, 16, v64
	v_and_b32_e32 v149, 0xffff0000, v64
	v_lshlrev_b32_e32 v150, 16, v65
	v_and_b32_e32 v151, 0xffff0000, v65
	v_lshlrev_b32_e32 v152, 16, v66
	v_and_b32_e32 v153, 0xffff0000, v66
	v_lshlrev_b32_e32 v154, 16, v67
	v_and_b32_e32 v155, 0xffff0000, v67
	v_pk_mul_f32 v[102:103], v[140:141], v[140:141]
	v_pk_fma_f32 v[102:103], v[142:143], v[142:143], v[102:103]
	v_pk_fma_f32 v[102:103], v[144:145], v[144:145], v[102:103]
	v_pk_fma_f32 v[102:103], v[146:147], v[146:147], v[102:103]
	v_pk_fma_f32 v[102:103], v[148:149], v[148:149], v[102:103]
	v_pk_fma_f32 v[102:103], v[150:151], v[150:151], v[102:103]
	v_pk_fma_f32 v[102:103], v[152:153], v[152:153], v[102:103]
	v_pk_fma_f32 v[102:103], v[154:155], v[154:155], v[102:103]
	v_lshlrev_b32_e32 v140, 16, v68
	v_and_b32_e32 v141, 0xffff0000, v68
	v_lshlrev_b32_e32 v142, 16, v69
	v_and_b32_e32 v143, 0xffff0000, v69
	v_lshlrev_b32_e32 v144, 16, v70
	v_and_b32_e32 v145, 0xffff0000, v70
	v_lshlrev_b32_e32 v146, 16, v71
	v_and_b32_e32 v147, 0xffff0000, v71
	v_lshlrev_b32_e32 v148, 16, v72
	v_and_b32_e32 v149, 0xffff0000, v72
	v_lshlrev_b32_e32 v150, 16, v73
	v_and_b32_e32 v151, 0xffff0000, v73
	v_lshlrev_b32_e32 v152, 16, v74
	v_and_b32_e32 v153, 0xffff0000, v74
	v_lshlrev_b32_e32 v154, 16, v75
	v_and_b32_e32 v155, 0xffff0000, v75
	v_pk_mul_f32 v[104:105], v[140:141], v[140:141]
	v_pk_fma_f32 v[104:105], v[142:143], v[142:143], v[104:105]
	v_pk_fma_f32 v[104:105], v[144:145], v[144:145], v[104:105]
	v_pk_fma_f32 v[104:105], v[146:147], v[146:147], v[104:105]
	v_pk_fma_f32 v[104:105], v[148:149], v[148:149], v[104:105]
	v_pk_fma_f32 v[104:105], v[150:151], v[150:151], v[104:105]
	v_pk_fma_f32 v[104:105], v[152:153], v[152:153], v[104:105]
	v_pk_fma_f32 v[104:105], v[154:155], v[154:155], v[104:105]
	v_lshlrev_b32_e32 v140, 16, v76
	v_and_b32_e32 v141, 0xffff0000, v76
	v_lshlrev_b32_e32 v142, 16, v77
	v_and_b32_e32 v143, 0xffff0000, v77
	v_lshlrev_b32_e32 v144, 16, v78
	v_and_b32_e32 v145, 0xffff0000, v78
	v_lshlrev_b32_e32 v146, 16, v79
	v_and_b32_e32 v147, 0xffff0000, v79
	v_lshlrev_b32_e32 v148, 16, v80
	v_and_b32_e32 v149, 0xffff0000, v80
	v_lshlrev_b32_e32 v150, 16, v81
	v_and_b32_e32 v151, 0xffff0000, v81
	v_lshlrev_b32_e32 v152, 16, v82
	v_and_b32_e32 v153, 0xffff0000, v82
	v_lshlrev_b32_e32 v154, 16, v83
	v_and_b32_e32 v155, 0xffff0000, v83
	v_pk_mul_f32 v[106:107], v[140:141], v[140:141]
	v_pk_fma_f32 v[106:107], v[142:143], v[142:143], v[106:107]
	v_pk_fma_f32 v[106:107], v[144:145], v[144:145], v[106:107]
	v_pk_fma_f32 v[106:107], v[146:147], v[146:147], v[106:107]
	v_pk_fma_f32 v[106:107], v[148:149], v[148:149], v[106:107]
	v_pk_fma_f32 v[106:107], v[150:151], v[150:151], v[106:107]
	v_pk_fma_f32 v[106:107], v[152:153], v[152:153], v[106:107]
	v_pk_fma_f32 v[106:107], v[154:155], v[154:155], v[106:107]
	v_add_f32_e32 v100, v100, v101
	v_add_f32_e32 v102, v102, v103
	v_add_f32_e32 v104, v104, v105
	v_add_f32_e32 v106, v106, v107
	s_nop 1
	v_add_f32_dpp v100, v100, v100 row_shr:1 row_mask:0xf bank_mask:0xf bound_ctrl:1
	v_add_f32_dpp v102, v102, v102 row_shr:1 row_mask:0xf bank_mask:0xf bound_ctrl:1
	v_add_f32_dpp v104, v104, v104 row_shr:1 row_mask:0xf bank_mask:0xf bound_ctrl:1
	v_add_f32_dpp v106, v106, v106 row_shr:1 row_mask:0xf bank_mask:0xf bound_ctrl:1
	v_add_f32_dpp v100, v100, v100 row_shr:2 row_mask:0xf bank_mask:0xf bound_ctrl:1
	v_add_f32_dpp v102, v102, v102 row_shr:2 row_mask:0xf bank_mask:0xf bound_ctrl:1
	v_add_f32_dpp v104, v104, v104 row_shr:2 row_mask:0xf bank_mask:0xf bound_ctrl:1
	v_add_f32_dpp v106, v106, v106 row_shr:2 row_mask:0xf bank_mask:0xf bound_ctrl:1
	v_add_f32_dpp v100, v100, v100 row_shr:4 row_mask:0xf bank_mask:0xf bound_ctrl:1
	v_add_f32_dpp v102, v102, v102 row_shr:4 row_mask:0xf bank_mask:0xf bound_ctrl:1
	v_add_f32_dpp v104, v104, v104 row_shr:4 row_mask:0xf bank_mask:0xf bound_ctrl:1
	v_add_f32_dpp v106, v106, v106 row_shr:4 row_mask:0xf bank_mask:0xf bound_ctrl:1
	v_add_f32_dpp v100, v100, v100 row_shr:8 row_mask:0xf bank_mask:0xf bound_ctrl:1
	v_add_f32_dpp v102, v102, v102 row_shr:8 row_mask:0xf bank_mask:0xf bound_ctrl:1
	v_add_f32_dpp v104, v104, v104 row_shr:8 row_mask:0xf bank_mask:0xf bound_ctrl:1
	v_add_f32_dpp v106, v106, v106 row_shr:8 row_mask:0xf bank_mask:0xf bound_ctrl:1
	v_add_f32_dpp v100, v100, v100 row_bcast:15 row_mask:0xa bank_mask:0xf
	v_add_f32_dpp v102, v102, v102 row_bcast:15 row_mask:0xa bank_mask:0xf
	v_add_f32_dpp v104, v104, v104 row_bcast:15 row_mask:0xa bank_mask:0xf
	v_add_f32_dpp v106, v106, v106 row_bcast:15 row_mask:0xa bank_mask:0xf
	v_add_f32_dpp v100, v100, v100 row_bcast:31 row_mask:0xc bank_mask:0xf
	v_add_f32_dpp v102, v102, v102 row_bcast:31 row_mask:0xc bank_mask:0xf
	v_add_f32_dpp v104, v104, v104 row_bcast:31 row_mask:0xc bank_mask:0xf
	v_add_f32_dpp v106, v106, v106 row_bcast:31 row_mask:0xc bank_mask:0xf
	s_nop 1
	v_readlane_b32 s5, v100, 63
	v_readlane_b32 s32, v102, 63
	v_readlane_b32 s54, v104, 63
	v_readlane_b32 s60, v106, 63
	s_nop 1
	v_mov_b32_e32 v156, s5
	v_mov_b32_e32 v158, s32
	v_mov_b32_e32 v160, s54
	v_mov_b32_e32 v162, s60
	v_fmaak_f32 v156, v156, v50, 0x358637bd
	v_fmaak_f32 v158, v158, v50, 0x358637bd
	v_fmaak_f32 v160, v160, v50, 0x358637bd
	v_fmaak_f32 v162, v162, v50, 0x358637bd
	v_rsq_f32_e32 v156, v156
	v_rsq_f32_e32 v158, v158
	v_rsq_f32_e32 v160, v160
	v_rsq_f32_e32 v162, v162
	s_nop 0
	v_lshlrev_b32_e32 v140, 16, v52
	v_and_b32_e32 v141, 0xffff0000, v52
	v_lshlrev_b32_e32 v142, 16, v53
	v_and_b32_e32 v143, 0xffff0000, v53
	v_lshlrev_b32_e32 v144, 16, v54
	v_and_b32_e32 v145, 0xffff0000, v54
	v_lshlrev_b32_e32 v146, 16, v55
	v_and_b32_e32 v147, 0xffff0000, v55
	v_lshlrev_b32_e32 v148, 16, v56
	v_and_b32_e32 v149, 0xffff0000, v56
	v_lshlrev_b32_e32 v150, 16, v57
	v_and_b32_e32 v151, 0xffff0000, v57
	v_lshlrev_b32_e32 v152, 16, v58
	v_and_b32_e32 v153, 0xffff0000, v58
	v_lshlrev_b32_e32 v154, 16, v59
	v_and_b32_e32 v155, 0xffff0000, v59
	v_pk_mul_f32 v[140:141], v[156:157], v[140:141] op_sel_hi:[0,1]
	v_pk_mul_f32 v[142:143], v[156:157], v[142:143] op_sel_hi:[0,1]
	v_pk_mul_f32 v[144:145], v[156:157], v[144:145] op_sel_hi:[0,1]
	v_pk_mul_f32 v[146:147], v[156:157], v[146:147] op_sel_hi:[0,1]
	v_pk_mul_f32 v[148:149], v[156:157], v[148:149] op_sel_hi:[0,1]
	v_pk_mul_f32 v[150:151], v[156:157], v[150:151] op_sel_hi:[0,1]
	v_pk_mul_f32 v[152:153], v[156:157], v[152:153] op_sel_hi:[0,1]
	v_pk_mul_f32 v[154:155], v[156:157], v[154:155] op_sel_hi:[0,1]
	v_pk_mul_f32 v[140:141], v[140:141], v[32:33]
	v_pk_mul_f32 v[142:143], v[142:143], v[34:35]
	v_pk_mul_f32 v[144:145], v[144:145], v[36:37]
	v_pk_mul_f32 v[146:147], v[146:147], v[38:39]
	v_pk_mul_f32 v[148:149], v[148:149], v[40:41]
	v_pk_mul_f32 v[150:151], v[150:151], v[42:43]
	v_pk_mul_f32 v[152:153], v[152:153], v[44:45]
	v_pk_mul_f32 v[154:155], v[154:155], v[46:47]
	v_pk_fma_f32 v[140:141], v[140:141], v[84:85], v[124:125]
	v_pk_fma_f32 v[142:143], v[142:143], v[86:87], v[126:127]
	v_pk_fma_f32 v[144:145], v[144:145], v[88:89], v[128:129]
	v_pk_fma_f32 v[146:147], v[146:147], v[90:91], v[130:131]
	v_pk_fma_f32 v[148:149], v[148:149], v[92:93], v[132:133]
	v_pk_fma_f32 v[150:151], v[150:151], v[94:95], v[134:135]
	v_pk_fma_f32 v[152:153], v[152:153], v[96:97], v[136:137]
	v_pk_fma_f32 v[154:155], v[154:155], v[98:99], v[138:139]
	v_cvt_pk_bf16_f32 v164, v140, v141
	v_cvt_pk_bf16_f32 v165, v142, v143
	v_cvt_pk_bf16_f32 v166, v144, v145
	v_cvt_pk_bf16_f32 v167, v146, v147
	v_cvt_pk_bf16_f32 v168, v148, v149
	v_cvt_pk_bf16_f32 v169, v150, v151
	v_cvt_pk_bf16_f32 v170, v152, v153
	v_cvt_pk_bf16_f32 v171, v154, v155
	global_store_dwordx4 v51, v[164:167], s[20:21] sc1
	global_store_dwordx4 v51, v[168:171], s[20:21] offset:1024 sc1
	v_lshlrev_b32_e32 v140, 16, v60
	v_and_b32_e32 v141, 0xffff0000, v60
	v_lshlrev_b32_e32 v142, 16, v61
	v_and_b32_e32 v143, 0xffff0000, v61
	v_lshlrev_b32_e32 v144, 16, v62
	v_and_b32_e32 v145, 0xffff0000, v62
	v_lshlrev_b32_e32 v146, 16, v63
	v_and_b32_e32 v147, 0xffff0000, v63
	v_lshlrev_b32_e32 v148, 16, v64
	v_and_b32_e32 v149, 0xffff0000, v64
	v_lshlrev_b32_e32 v150, 16, v65
	v_and_b32_e32 v151, 0xffff0000, v65
	v_lshlrev_b32_e32 v152, 16, v66
	v_and_b32_e32 v153, 0xffff0000, v66
	v_lshlrev_b32_e32 v154, 16, v67
	v_and_b32_e32 v155, 0xffff0000, v67
	v_pk_mul_f32 v[140:141], v[158:159], v[140:141] op_sel_hi:[0,1]
	v_pk_mul_f32 v[142:143], v[158:159], v[142:143] op_sel_hi:[0,1]
	v_pk_mul_f32 v[144:145], v[158:159], v[144:145] op_sel_hi:[0,1]
	v_pk_mul_f32 v[146:147], v[158:159], v[146:147] op_sel_hi:[0,1]
	v_pk_mul_f32 v[148:149], v[158:159], v[148:149] op_sel_hi:[0,1]
	v_pk_mul_f32 v[150:151], v[158:159], v[150:151] op_sel_hi:[0,1]
	v_pk_mul_f32 v[152:153], v[158:159], v[152:153] op_sel_hi:[0,1]
	v_pk_mul_f32 v[154:155], v[158:159], v[154:155] op_sel_hi:[0,1]
	v_pk_mul_f32 v[140:141], v[140:141], v[32:33]
	v_pk_mul_f32 v[142:143], v[142:143], v[34:35]
	v_pk_mul_f32 v[144:145], v[144:145], v[36:37]
	v_pk_mul_f32 v[146:147], v[146:147], v[38:39]
	v_pk_mul_f32 v[148:149], v[148:149], v[40:41]
	v_pk_mul_f32 v[150:151], v[150:151], v[42:43]
	v_pk_mul_f32 v[152:153], v[152:153], v[44:45]
	v_pk_mul_f32 v[154:155], v[154:155], v[46:47]
	v_pk_fma_f32 v[140:141], v[140:141], v[84:85], v[124:125]
	v_pk_fma_f32 v[142:143], v[142:143], v[86:87], v[126:127]
	v_pk_fma_f32 v[144:145], v[144:145], v[88:89], v[128:129]
	v_pk_fma_f32 v[146:147], v[146:147], v[90:91], v[130:131]
	v_pk_fma_f32 v[148:149], v[148:149], v[92:93], v[132:133]
	v_pk_fma_f32 v[150:151], v[150:151], v[94:95], v[134:135]
	v_pk_fma_f32 v[152:153], v[152:153], v[96:97], v[136:137]
	v_pk_fma_f32 v[154:155], v[154:155], v[98:99], v[138:139]
	v_cvt_pk_bf16_f32 v172, v140, v141
	v_cvt_pk_bf16_f32 v173, v142, v143
	v_cvt_pk_bf16_f32 v174, v144, v145
	v_cvt_pk_bf16_f32 v175, v146, v147
	v_cvt_pk_bf16_f32 v176, v148, v149
	v_cvt_pk_bf16_f32 v177, v150, v151
	v_cvt_pk_bf16_f32 v178, v152, v153
	v_cvt_pk_bf16_f32 v179, v154, v155
	global_store_dwordx4 v51, v[172:175], s[20:21] offset:2048 sc1
	global_store_dwordx4 v51, v[176:179], s[20:21] offset:3072 sc1
	v_lshlrev_b32_e32 v140, 16, v68
	v_and_b32_e32 v141, 0xffff0000, v68
	v_lshlrev_b32_e32 v142, 16, v69
	v_and_b32_e32 v143, 0xffff0000, v69
	v_lshlrev_b32_e32 v144, 16, v70
	v_and_b32_e32 v145, 0xffff0000, v70
	v_lshlrev_b32_e32 v146, 16, v71
	v_and_b32_e32 v147, 0xffff0000, v71
	v_lshlrev_b32_e32 v148, 16, v72
	v_and_b32_e32 v149, 0xffff0000, v72
	v_lshlrev_b32_e32 v150, 16, v73
	v_and_b32_e32 v151, 0xffff0000, v73
	v_lshlrev_b32_e32 v152, 16, v74
	v_and_b32_e32 v153, 0xffff0000, v74
	v_lshlrev_b32_e32 v154, 16, v75
	v_and_b32_e32 v155, 0xffff0000, v75
	v_pk_mul_f32 v[140:141], v[160:161], v[140:141] op_sel_hi:[0,1]
	v_pk_mul_f32 v[142:143], v[160:161], v[142:143] op_sel_hi:[0,1]
	v_pk_mul_f32 v[144:145], v[160:161], v[144:145] op_sel_hi:[0,1]
	v_pk_mul_f32 v[146:147], v[160:161], v[146:147] op_sel_hi:[0,1]
	v_pk_mul_f32 v[148:149], v[160:161], v[148:149] op_sel_hi:[0,1]
	v_pk_mul_f32 v[150:151], v[160:161], v[150:151] op_sel_hi:[0,1]
	v_pk_mul_f32 v[152:153], v[160:161], v[152:153] op_sel_hi:[0,1]
	v_pk_mul_f32 v[154:155], v[160:161], v[154:155] op_sel_hi:[0,1]
	v_pk_mul_f32 v[140:141], v[140:141], v[32:33]
	v_pk_mul_f32 v[142:143], v[142:143], v[34:35]
	v_pk_mul_f32 v[144:145], v[144:145], v[36:37]
	v_pk_mul_f32 v[146:147], v[146:147], v[38:39]
	v_pk_mul_f32 v[148:149], v[148:149], v[40:41]
	v_pk_mul_f32 v[150:151], v[150:151], v[42:43]
	v_pk_mul_f32 v[152:153], v[152:153], v[44:45]
	v_pk_mul_f32 v[154:155], v[154:155], v[46:47]
	v_pk_fma_f32 v[140:141], v[140:141], v[84:85], v[124:125]
	v_pk_fma_f32 v[142:143], v[142:143], v[86:87], v[126:127]
	v_pk_fma_f32 v[144:145], v[144:145], v[88:89], v[128:129]
	v_pk_fma_f32 v[146:147], v[146:147], v[90:91], v[130:131]
	v_pk_fma_f32 v[148:149], v[148:149], v[92:93], v[132:133]
	v_pk_fma_f32 v[150:151], v[150:151], v[94:95], v[134:135]
	v_pk_fma_f32 v[152:153], v[152:153], v[96:97], v[136:137]
	v_pk_fma_f32 v[154:155], v[154:155], v[98:99], v[138:139]
	v_cvt_pk_bf16_f32 v164, v140, v141
	v_cvt_pk_bf16_f32 v165, v142, v143
	v_cvt_pk_bf16_f32 v166, v144, v145
	v_cvt_pk_bf16_f32 v167, v146, v147
	v_cvt_pk_bf16_f32 v168, v148, v149
	v_cvt_pk_bf16_f32 v169, v150, v151
	v_cvt_pk_bf16_f32 v170, v152, v153
	v_cvt_pk_bf16_f32 v171, v154, v155
	global_store_dwordx4 v109, v[164:167], s[20:21] sc1
	global_store_dwordx4 v109, v[168:171], s[20:21] offset:1024 sc1
	v_lshlrev_b32_e32 v140, 16, v76
	v_and_b32_e32 v141, 0xffff0000, v76
	v_lshlrev_b32_e32 v142, 16, v77
	v_and_b32_e32 v143, 0xffff0000, v77
	v_lshlrev_b32_e32 v144, 16, v78
	v_and_b32_e32 v145, 0xffff0000, v78
	v_lshlrev_b32_e32 v146, 16, v79
	v_and_b32_e32 v147, 0xffff0000, v79
	v_lshlrev_b32_e32 v148, 16, v80
	v_and_b32_e32 v149, 0xffff0000, v80
	v_lshlrev_b32_e32 v150, 16, v81
	v_and_b32_e32 v151, 0xffff0000, v81
	v_lshlrev_b32_e32 v152, 16, v82
	v_and_b32_e32 v153, 0xffff0000, v82
	v_lshlrev_b32_e32 v154, 16, v83
	v_and_b32_e32 v155, 0xffff0000, v83
	v_pk_mul_f32 v[140:141], v[162:163], v[140:141] op_sel_hi:[0,1]
	v_pk_mul_f32 v[142:143], v[162:163], v[142:143] op_sel_hi:[0,1]
	v_pk_mul_f32 v[144:145], v[162:163], v[144:145] op_sel_hi:[0,1]
	v_pk_mul_f32 v[146:147], v[162:163], v[146:147] op_sel_hi:[0,1]
	v_pk_mul_f32 v[148:149], v[162:163], v[148:149] op_sel_hi:[0,1]
	v_pk_mul_f32 v[150:151], v[162:163], v[150:151] op_sel_hi:[0,1]
	v_pk_mul_f32 v[152:153], v[162:163], v[152:153] op_sel_hi:[0,1]
	v_pk_mul_f32 v[154:155], v[162:163], v[154:155] op_sel_hi:[0,1]
	v_pk_mul_f32 v[140:141], v[140:141], v[32:33]
	v_pk_mul_f32 v[142:143], v[142:143], v[34:35]
	v_pk_mul_f32 v[144:145], v[144:145], v[36:37]
	v_pk_mul_f32 v[146:147], v[146:147], v[38:39]
	v_pk_mul_f32 v[148:149], v[148:149], v[40:41]
	v_pk_mul_f32 v[150:151], v[150:151], v[42:43]
	v_pk_mul_f32 v[152:153], v[152:153], v[44:45]
	v_pk_mul_f32 v[154:155], v[154:155], v[46:47]
	v_pk_fma_f32 v[140:141], v[140:141], v[84:85], v[124:125]
	v_pk_fma_f32 v[142:143], v[142:143], v[86:87], v[126:127]
	v_pk_fma_f32 v[144:145], v[144:145], v[88:89], v[128:129]
	v_pk_fma_f32 v[146:147], v[146:147], v[90:91], v[130:131]
	v_pk_fma_f32 v[148:149], v[148:149], v[92:93], v[132:133]
	v_pk_fma_f32 v[150:151], v[150:151], v[94:95], v[134:135]
	v_pk_fma_f32 v[152:153], v[152:153], v[96:97], v[136:137]
	v_pk_fma_f32 v[154:155], v[154:155], v[98:99], v[138:139]
	v_cvt_pk_bf16_f32 v172, v140, v141
	v_cvt_pk_bf16_f32 v173, v142, v143
	v_cvt_pk_bf16_f32 v174, v144, v145
	v_cvt_pk_bf16_f32 v175, v146, v147
	v_cvt_pk_bf16_f32 v176, v148, v149
	v_cvt_pk_bf16_f32 v177, v150, v151
	v_cvt_pk_bf16_f32 v178, v152, v153
	v_cvt_pk_bf16_f32 v179, v154, v155
	global_store_dwordx4 v109, v[172:175], s[20:21] offset:2048 sc1
	global_store_dwordx4 v109, v[176:179], s[20:21] offset:3072 sc1
	s_add_u32 s20, s20, 0x2000
	s_addc_u32 s21, s21, 0
	s_add_u32 s18, s18, 0x2000
	s_addc_u32 s19, s19, 0
	global_load_dwordx4 v[52:55], v51, s[18:19]
	global_load_dwordx4 v[56:59], v51, s[18:19] offset:1024
	global_load_dwordx4 v[60:63], v51, s[18:19] offset:2048
	global_load_dwordx4 v[64:67], v51, s[18:19] offset:3072
	global_load_dwordx4 v[68:71], v109, s[18:19]
	global_load_dwordx4 v[72:75], v109, s[18:19] offset:1024
	global_load_dwordx4 v[76:79], v109, s[18:19] offset:2048
	global_load_dwordx4 v[80:83], v109, s[18:19] offset:3072
	s_waitcnt vmcnt(16)
	v_lshlrev_b32_e32 v140, 16, v0
	v_and_b32_e32 v141, 0xffff0000, v0
	v_lshlrev_b32_e32 v142, 16, v1
	v_and_b32_e32 v143, 0xffff0000, v1
	v_lshlrev_b32_e32 v144, 16, v2
	v_and_b32_e32 v145, 0xffff0000, v2
	v_lshlrev_b32_e32 v146, 16, v3
	v_and_b32_e32 v147, 0xffff0000, v3
	v_lshlrev_b32_e32 v148, 16, v4
	v_and_b32_e32 v149, 0xffff0000, v4
	v_lshlrev_b32_e32 v150, 16, v5
	v_and_b32_e32 v151, 0xffff0000, v5
	v_lshlrev_b32_e32 v152, 16, v6
	v_and_b32_e32 v153, 0xffff0000, v6
	v_lshlrev_b32_e32 v154, 16, v7
	v_and_b32_e32 v155, 0xffff0000, v7
	v_pk_mul_f32 v[100:101], v[140:141], v[140:141]
	v_pk_fma_f32 v[100:101], v[142:143], v[142:143], v[100:101]
	v_pk_fma_f32 v[100:101], v[144:145], v[144:145], v[100:101]
	v_pk_fma_f32 v[100:101], v[146:147], v[146:147], v[100:101]
	v_pk_fma_f32 v[100:101], v[148:149], v[148:149], v[100:101]
	v_pk_fma_f32 v[100:101], v[150:151], v[150:151], v[100:101]
	v_pk_fma_f32 v[100:101], v[152:153], v[152:153], v[100:101]
	v_pk_fma_f32 v[100:101], v[154:155], v[154:155], v[100:101]
	v_lshlrev_b32_e32 v140, 16, v8
	v_and_b32_e32 v141, 0xffff0000, v8
	v_lshlrev_b32_e32 v142, 16, v9
	v_and_b32_e32 v143, 0xffff0000, v9
	v_lshlrev_b32_e32 v144, 16, v10
	v_and_b32_e32 v145, 0xffff0000, v10
	v_lshlrev_b32_e32 v146, 16, v11
	v_and_b32_e32 v147, 0xffff0000, v11
	v_lshlrev_b32_e32 v148, 16, v12
	v_and_b32_e32 v149, 0xffff0000, v12
	v_lshlrev_b32_e32 v150, 16, v13
	v_and_b32_e32 v151, 0xffff0000, v13
	v_lshlrev_b32_e32 v152, 16, v14
	v_and_b32_e32 v153, 0xffff0000, v14
	v_lshlrev_b32_e32 v154, 16, v15
	v_and_b32_e32 v155, 0xffff0000, v15
	v_pk_mul_f32 v[102:103], v[140:141], v[140:141]
	v_pk_fma_f32 v[102:103], v[142:143], v[142:143], v[102:103]
	v_pk_fma_f32 v[102:103], v[144:145], v[144:145], v[102:103]
	v_pk_fma_f32 v[102:103], v[146:147], v[146:147], v[102:103]
	v_pk_fma_f32 v[102:103], v[148:149], v[148:149], v[102:103]
	v_pk_fma_f32 v[102:103], v[150:151], v[150:151], v[102:103]
	v_pk_fma_f32 v[102:103], v[152:153], v[152:153], v[102:103]
	v_pk_fma_f32 v[102:103], v[154:155], v[154:155], v[102:103]
	v_lshlrev_b32_e32 v140, 16, v16
	v_and_b32_e32 v141, 0xffff0000, v16
	v_lshlrev_b32_e32 v142, 16, v17
	v_and_b32_e32 v143, 0xffff0000, v17
	v_lshlrev_b32_e32 v144, 16, v18
	v_and_b32_e32 v145, 0xffff0000, v18
	v_lshlrev_b32_e32 v146, 16, v19
	v_and_b32_e32 v147, 0xffff0000, v19
	v_lshlrev_b32_e32 v148, 16, v20
	v_and_b32_e32 v149, 0xffff0000, v20
	v_lshlrev_b32_e32 v150, 16, v21
	v_and_b32_e32 v151, 0xffff0000, v21
	v_lshlrev_b32_e32 v152, 16, v22
	v_and_b32_e32 v153, 0xffff0000, v22
	v_lshlrev_b32_e32 v154, 16, v23
	v_and_b32_e32 v155, 0xffff0000, v23
	v_pk_mul_f32 v[104:105], v[140:141], v[140:141]
	v_pk_fma_f32 v[104:105], v[142:143], v[142:143], v[104:105]
	v_pk_fma_f32 v[104:105], v[144:145], v[144:145], v[104:105]
	v_pk_fma_f32 v[104:105], v[146:147], v[146:147], v[104:105]
	v_pk_fma_f32 v[104:105], v[148:149], v[148:149], v[104:105]
	v_pk_fma_f32 v[104:105], v[150:151], v[150:151], v[104:105]
	v_pk_fma_f32 v[104:105], v[152:153], v[152:153], v[104:105]
	v_pk_fma_f32 v[104:105], v[154:155], v[154:155], v[104:105]
	v_lshlrev_b32_e32 v140, 16, v24
	v_and_b32_e32 v141, 0xffff0000, v24
	v_lshlrev_b32_e32 v142, 16, v25
	v_and_b32_e32 v143, 0xffff0000, v25
	v_lshlrev_b32_e32 v144, 16, v26
	v_and_b32_e32 v145, 0xffff0000, v26
	v_lshlrev_b32_e32 v146, 16, v27
	v_and_b32_e32 v147, 0xffff0000, v27
	v_lshlrev_b32_e32 v148, 16, v28
	v_and_b32_e32 v149, 0xffff0000, v28
	v_lshlrev_b32_e32 v150, 16, v29
	v_and_b32_e32 v151, 0xffff0000, v29
	v_lshlrev_b32_e32 v152, 16, v30
	v_and_b32_e32 v153, 0xffff0000, v30
	v_lshlrev_b32_e32 v154, 16, v31
	v_and_b32_e32 v155, 0xffff0000, v31
	v_pk_mul_f32 v[106:107], v[140:141], v[140:141]
	v_pk_fma_f32 v[106:107], v[142:143], v[142:143], v[106:107]
	v_pk_fma_f32 v[106:107], v[144:145], v[144:145], v[106:107]
	v_pk_fma_f32 v[106:107], v[146:147], v[146:147], v[106:107]
	v_pk_fma_f32 v[106:107], v[148:149], v[148:149], v[106:107]
	v_pk_fma_f32 v[106:107], v[150:151], v[150:151], v[106:107]
	v_pk_fma_f32 v[106:107], v[152:153], v[152:153], v[106:107]
	v_pk_fma_f32 v[106:107], v[154:155], v[154:155], v[106:107]
	v_add_f32_e32 v100, v100, v101
	v_add_f32_e32 v102, v102, v103
	v_add_f32_e32 v104, v104, v105
	v_add_f32_e32 v106, v106, v107
	s_nop 1
	v_add_f32_dpp v100, v100, v100 row_shr:1 row_mask:0xf bank_mask:0xf bound_ctrl:1
	v_add_f32_dpp v102, v102, v102 row_shr:1 row_mask:0xf bank_mask:0xf bound_ctrl:1
	v_add_f32_dpp v104, v104, v104 row_shr:1 row_mask:0xf bank_mask:0xf bound_ctrl:1
	v_add_f32_dpp v106, v106, v106 row_shr:1 row_mask:0xf bank_mask:0xf bound_ctrl:1
	v_add_f32_dpp v100, v100, v100 row_shr:2 row_mask:0xf bank_mask:0xf bound_ctrl:1
	v_add_f32_dpp v102, v102, v102 row_shr:2 row_mask:0xf bank_mask:0xf bound_ctrl:1
	v_add_f32_dpp v104, v104, v104 row_shr:2 row_mask:0xf bank_mask:0xf bound_ctrl:1
	v_add_f32_dpp v106, v106, v106 row_shr:2 row_mask:0xf bank_mask:0xf bound_ctrl:1
	v_add_f32_dpp v100, v100, v100 row_shr:4 row_mask:0xf bank_mask:0xf bound_ctrl:1
	v_add_f32_dpp v102, v102, v102 row_shr:4 row_mask:0xf bank_mask:0xf bound_ctrl:1
	v_add_f32_dpp v104, v104, v104 row_shr:4 row_mask:0xf bank_mask:0xf bound_ctrl:1
	v_add_f32_dpp v106, v106, v106 row_shr:4 row_mask:0xf bank_mask:0xf bound_ctrl:1
	v_add_f32_dpp v100, v100, v100 row_shr:8 row_mask:0xf bank_mask:0xf bound_ctrl:1
	v_add_f32_dpp v102, v102, v102 row_shr:8 row_mask:0xf bank_mask:0xf bound_ctrl:1
	v_add_f32_dpp v104, v104, v104 row_shr:8 row_mask:0xf bank_mask:0xf bound_ctrl:1
	v_add_f32_dpp v106, v106, v106 row_shr:8 row_mask:0xf bank_mask:0xf bound_ctrl:1
	v_add_f32_dpp v100, v100, v100 row_bcast:15 row_mask:0xa bank_mask:0xf
	v_add_f32_dpp v102, v102, v102 row_bcast:15 row_mask:0xa bank_mask:0xf
	v_add_f32_dpp v104, v104, v104 row_bcast:15 row_mask:0xa bank_mask:0xf
	v_add_f32_dpp v106, v106, v106 row_bcast:15 row_mask:0xa bank_mask:0xf
	v_add_f32_dpp v100, v100, v100 row_bcast:31 row_mask:0xc bank_mask:0xf
	v_add_f32_dpp v102, v102, v102 row_bcast:31 row_mask:0xc bank_mask:0xf
	v_add_f32_dpp v104, v104, v104 row_bcast:31 row_mask:0xc bank_mask:0xf
	v_add_f32_dpp v106, v106, v106 row_bcast:31 row_mask:0xc bank_mask:0xf
	s_nop 1
	v_readlane_b32 s5, v100, 63
	v_readlane_b32 s32, v102, 63
	v_readlane_b32 s54, v104, 63
	v_readlane_b32 s60, v106, 63
	s_nop 1
	v_mov_b32_e32 v156, s5
	v_mov_b32_e32 v158, s32
	v_mov_b32_e32 v160, s54
	v_mov_b32_e32 v162, s60
	v_fmaak_f32 v156, v156, v50, 0x358637bd
	v_fmaak_f32 v158, v158, v50, 0x358637bd
	v_fmaak_f32 v160, v160, v50, 0x358637bd
	v_fmaak_f32 v162, v162, v50, 0x358637bd
	v_rsq_f32_e32 v156, v156
	v_rsq_f32_e32 v158, v158
	v_rsq_f32_e32 v160, v160
	v_rsq_f32_e32 v162, v162
	s_nop 0
	v_lshlrev_b32_e32 v140, 16, v0
	v_and_b32_e32 v141, 0xffff0000, v0
	v_lshlrev_b32_e32 v142, 16, v1
	v_and_b32_e32 v143, 0xffff0000, v1
	v_lshlrev_b32_e32 v144, 16, v2
	v_and_b32_e32 v145, 0xffff0000, v2
	v_lshlrev_b32_e32 v146, 16, v3
	v_and_b32_e32 v147, 0xffff0000, v3
	v_lshlrev_b32_e32 v148, 16, v4
	v_and_b32_e32 v149, 0xffff0000, v4
	v_lshlrev_b32_e32 v150, 16, v5
	v_and_b32_e32 v151, 0xffff0000, v5
	v_lshlrev_b32_e32 v152, 16, v6
	v_and_b32_e32 v153, 0xffff0000, v6
	v_lshlrev_b32_e32 v154, 16, v7
	v_and_b32_e32 v155, 0xffff0000, v7
	v_pk_mul_f32 v[140:141], v[156:157], v[140:141] op_sel_hi:[0,1]
	v_pk_mul_f32 v[142:143], v[156:157], v[142:143] op_sel_hi:[0,1]
	v_pk_mul_f32 v[144:145], v[156:157], v[144:145] op_sel_hi:[0,1]
	v_pk_mul_f32 v[146:147], v[156:157], v[146:147] op_sel_hi:[0,1]
	v_pk_mul_f32 v[148:149], v[156:157], v[148:149] op_sel_hi:[0,1]
	v_pk_mul_f32 v[150:151], v[156:157], v[150:151] op_sel_hi:[0,1]
	v_pk_mul_f32 v[152:153], v[156:157], v[152:153] op_sel_hi:[0,1]
	v_pk_mul_f32 v[154:155], v[156:157], v[154:155] op_sel_hi:[0,1]
	v_pk_mul_f32 v[140:141], v[140:141], v[32:33]
	v_pk_mul_f32 v[142:143], v[142:143], v[34:35]
	v_pk_mul_f32 v[144:145], v[144:145], v[36:37]
	v_pk_mul_f32 v[146:147], v[146:147], v[38:39]
	v_pk_mul_f32 v[148:149], v[148:149], v[40:41]
	v_pk_mul_f32 v[150:151], v[150:151], v[42:43]
	v_pk_mul_f32 v[152:153], v[152:153], v[44:45]
	v_pk_mul_f32 v[154:155], v[154:155], v[46:47]
	v_pk_fma_f32 v[140:141], v[140:141], v[84:85], v[124:125]
	v_pk_fma_f32 v[142:143], v[142:143], v[86:87], v[126:127]
	v_pk_fma_f32 v[144:145], v[144:145], v[88:89], v[128:129]
	v_pk_fma_f32 v[146:147], v[146:147], v[90:91], v[130:131]
	v_pk_fma_f32 v[148:149], v[148:149], v[92:93], v[132:133]
	v_pk_fma_f32 v[150:151], v[150:151], v[94:95], v[134:135]
	v_pk_fma_f32 v[152:153], v[152:153], v[96:97], v[136:137]
	v_pk_fma_f32 v[154:155], v[154:155], v[98:99], v[138:139]
	v_cvt_pk_bf16_f32 v172, v140, v141
	v_cvt_pk_bf16_f32 v173, v142, v143
	v_cvt_pk_bf16_f32 v174, v144, v145
	v_cvt_pk_bf16_f32 v175, v146, v147
	v_cvt_pk_bf16_f32 v176, v148, v149
	v_cvt_pk_bf16_f32 v177, v150, v151
	v_cvt_pk_bf16_f32 v178, v152, v153
	v_cvt_pk_bf16_f32 v179, v154, v155
	global_store_dwordx4 v51, v[172:175], s[20:21] sc1
	global_store_dwordx4 v51, v[176:179], s[20:21] offset:1024 sc1
	v_lshlrev_b32_e32 v140, 16, v8
	v_and_b32_e32 v141, 0xffff0000, v8
	v_lshlrev_b32_e32 v142, 16, v9
	v_and_b32_e32 v143, 0xffff0000, v9
	v_lshlrev_b32_e32 v144, 16, v10
	v_and_b32_e32 v145, 0xffff0000, v10
	v_lshlrev_b32_e32 v146, 16, v11
	v_and_b32_e32 v147, 0xffff0000, v11
	v_lshlrev_b32_e32 v148, 16, v12
	v_and_b32_e32 v149, 0xffff0000, v12
	v_lshlrev_b32_e32 v150, 16, v13
	v_and_b32_e32 v151, 0xffff0000, v13
	v_lshlrev_b32_e32 v152, 16, v14
	v_and_b32_e32 v153, 0xffff0000, v14
	v_lshlrev_b32_e32 v154, 16, v15
	v_and_b32_e32 v155, 0xffff0000, v15
	v_pk_mul_f32 v[140:141], v[158:159], v[140:141] op_sel_hi:[0,1]
	v_pk_mul_f32 v[142:143], v[158:159], v[142:143] op_sel_hi:[0,1]
	v_pk_mul_f32 v[144:145], v[158:159], v[144:145] op_sel_hi:[0,1]
	v_pk_mul_f32 v[146:147], v[158:159], v[146:147] op_sel_hi:[0,1]
	v_pk_mul_f32 v[148:149], v[158:159], v[148:149] op_sel_hi:[0,1]
	v_pk_mul_f32 v[150:151], v[158:159], v[150:151] op_sel_hi:[0,1]
	v_pk_mul_f32 v[152:153], v[158:159], v[152:153] op_sel_hi:[0,1]
	v_pk_mul_f32 v[154:155], v[158:159], v[154:155] op_sel_hi:[0,1]
	v_pk_mul_f32 v[140:141], v[140:141], v[32:33]
	v_pk_mul_f32 v[142:143], v[142:143], v[34:35]
	v_pk_mul_f32 v[144:145], v[144:145], v[36:37]
	v_pk_mul_f32 v[146:147], v[146:147], v[38:39]
	v_pk_mul_f32 v[148:149], v[148:149], v[40:41]
	v_pk_mul_f32 v[150:151], v[150:151], v[42:43]
	v_pk_mul_f32 v[152:153], v[152:153], v[44:45]
	v_pk_mul_f32 v[154:155], v[154:155], v[46:47]
	v_pk_fma_f32 v[140:141], v[140:141], v[84:85], v[124:125]
	v_pk_fma_f32 v[142:143], v[142:143], v[86:87], v[126:127]
	v_pk_fma_f32 v[144:145], v[144:145], v[88:89], v[128:129]
	v_pk_fma_f32 v[146:147], v[146:147], v[90:91], v[130:131]
	v_pk_fma_f32 v[148:149], v[148:149], v[92:93], v[132:133]
	v_pk_fma_f32 v[150:151], v[150:151], v[94:95], v[134:135]
	v_pk_fma_f32 v[152:153], v[152:153], v[96:97], v[136:137]
	v_pk_fma_f32 v[154:155], v[154:155], v[98:99], v[138:139]
	v_cvt_pk_bf16_f32 v164, v140, v141
	v_cvt_pk_bf16_f32 v165, v142, v143
	v_cvt_pk_bf16_f32 v166, v144, v145
	v_cvt_pk_bf16_f32 v167, v146, v147
	v_cvt_pk_bf16_f32 v168, v148, v149
	v_cvt_pk_bf16_f32 v169, v150, v151
	v_cvt_pk_bf16_f32 v170, v152, v153
	v_cvt_pk_bf16_f32 v171, v154, v155
	global_store_dwordx4 v51, v[164:167], s[20:21] offset:2048 sc1
	global_store_dwordx4 v51, v[168:171], s[20:21] offset:3072 sc1
	v_lshlrev_b32_e32 v140, 16, v16
	v_and_b32_e32 v141, 0xffff0000, v16
	v_lshlrev_b32_e32 v142, 16, v17
	v_and_b32_e32 v143, 0xffff0000, v17
	v_lshlrev_b32_e32 v144, 16, v18
	v_and_b32_e32 v145, 0xffff0000, v18
	v_lshlrev_b32_e32 v146, 16, v19
	v_and_b32_e32 v147, 0xffff0000, v19
	v_lshlrev_b32_e32 v148, 16, v20
	v_and_b32_e32 v149, 0xffff0000, v20
	v_lshlrev_b32_e32 v150, 16, v21
	v_and_b32_e32 v151, 0xffff0000, v21
	v_lshlrev_b32_e32 v152, 16, v22
	v_and_b32_e32 v153, 0xffff0000, v22
	v_lshlrev_b32_e32 v154, 16, v23
	v_and_b32_e32 v155, 0xffff0000, v23
	v_pk_mul_f32 v[140:141], v[160:161], v[140:141] op_sel_hi:[0,1]
	v_pk_mul_f32 v[142:143], v[160:161], v[142:143] op_sel_hi:[0,1]
	v_pk_mul_f32 v[144:145], v[160:161], v[144:145] op_sel_hi:[0,1]
	v_pk_mul_f32 v[146:147], v[160:161], v[146:147] op_sel_hi:[0,1]
	v_pk_mul_f32 v[148:149], v[160:161], v[148:149] op_sel_hi:[0,1]
	v_pk_mul_f32 v[150:151], v[160:161], v[150:151] op_sel_hi:[0,1]
	v_pk_mul_f32 v[152:153], v[160:161], v[152:153] op_sel_hi:[0,1]
	v_pk_mul_f32 v[154:155], v[160:161], v[154:155] op_sel_hi:[0,1]
	v_pk_mul_f32 v[140:141], v[140:141], v[32:33]
	v_pk_mul_f32 v[142:143], v[142:143], v[34:35]
	v_pk_mul_f32 v[144:145], v[144:145], v[36:37]
	v_pk_mul_f32 v[146:147], v[146:147], v[38:39]
	v_pk_mul_f32 v[148:149], v[148:149], v[40:41]
	v_pk_mul_f32 v[150:151], v[150:151], v[42:43]
	v_pk_mul_f32 v[152:153], v[152:153], v[44:45]
	v_pk_mul_f32 v[154:155], v[154:155], v[46:47]
	v_pk_fma_f32 v[140:141], v[140:141], v[84:85], v[124:125]
	v_pk_fma_f32 v[142:143], v[142:143], v[86:87], v[126:127]
	v_pk_fma_f32 v[144:145], v[144:145], v[88:89], v[128:129]
	v_pk_fma_f32 v[146:147], v[146:147], v[90:91], v[130:131]
	v_pk_fma_f32 v[148:149], v[148:149], v[92:93], v[132:133]
	v_pk_fma_f32 v[150:151], v[150:151], v[94:95], v[134:135]
	v_pk_fma_f32 v[152:153], v[152:153], v[96:97], v[136:137]
	v_pk_fma_f32 v[154:155], v[154:155], v[98:99], v[138:139]
	v_cvt_pk_bf16_f32 v172, v140, v141
	v_cvt_pk_bf16_f32 v173, v142, v143
	v_cvt_pk_bf16_f32 v174, v144, v145
	v_cvt_pk_bf16_f32 v175, v146, v147
	v_cvt_pk_bf16_f32 v176, v148, v149
	v_cvt_pk_bf16_f32 v177, v150, v151
	v_cvt_pk_bf16_f32 v178, v152, v153
	v_cvt_pk_bf16_f32 v179, v154, v155
	global_store_dwordx4 v109, v[172:175], s[20:21] sc1
	global_store_dwordx4 v109, v[176:179], s[20:21] offset:1024 sc1
	v_lshlrev_b32_e32 v140, 16, v24
	v_and_b32_e32 v141, 0xffff0000, v24
	v_lshlrev_b32_e32 v142, 16, v25
	v_and_b32_e32 v143, 0xffff0000, v25
	v_lshlrev_b32_e32 v144, 16, v26
	v_and_b32_e32 v145, 0xffff0000, v26
	v_lshlrev_b32_e32 v146, 16, v27
	v_and_b32_e32 v147, 0xffff0000, v27
	v_lshlrev_b32_e32 v148, 16, v28
	v_and_b32_e32 v149, 0xffff0000, v28
	v_lshlrev_b32_e32 v150, 16, v29
	v_and_b32_e32 v151, 0xffff0000, v29
	v_lshlrev_b32_e32 v152, 16, v30
	v_and_b32_e32 v153, 0xffff0000, v30
	v_lshlrev_b32_e32 v154, 16, v31
	v_and_b32_e32 v155, 0xffff0000, v31
	v_pk_mul_f32 v[140:141], v[162:163], v[140:141] op_sel_hi:[0,1]
	v_pk_mul_f32 v[142:143], v[162:163], v[142:143] op_sel_hi:[0,1]
	v_pk_mul_f32 v[144:145], v[162:163], v[144:145] op_sel_hi:[0,1]
	v_pk_mul_f32 v[146:147], v[162:163], v[146:147] op_sel_hi:[0,1]
	v_pk_mul_f32 v[148:149], v[162:163], v[148:149] op_sel_hi:[0,1]
	v_pk_mul_f32 v[150:151], v[162:163], v[150:151] op_sel_hi:[0,1]
	v_pk_mul_f32 v[152:153], v[162:163], v[152:153] op_sel_hi:[0,1]
	v_pk_mul_f32 v[154:155], v[162:163], v[154:155] op_sel_hi:[0,1]
	v_pk_mul_f32 v[140:141], v[140:141], v[32:33]
	v_pk_mul_f32 v[142:143], v[142:143], v[34:35]
	v_pk_mul_f32 v[144:145], v[144:145], v[36:37]
	v_pk_mul_f32 v[146:147], v[146:147], v[38:39]
	v_pk_mul_f32 v[148:149], v[148:149], v[40:41]
	v_pk_mul_f32 v[150:151], v[150:151], v[42:43]
	v_pk_mul_f32 v[152:153], v[152:153], v[44:45]
	v_pk_mul_f32 v[154:155], v[154:155], v[46:47]
	v_pk_fma_f32 v[140:141], v[140:141], v[84:85], v[124:125]
	v_pk_fma_f32 v[142:143], v[142:143], v[86:87], v[126:127]
	v_pk_fma_f32 v[144:145], v[144:145], v[88:89], v[128:129]
	v_pk_fma_f32 v[146:147], v[146:147], v[90:91], v[130:131]
	v_pk_fma_f32 v[148:149], v[148:149], v[92:93], v[132:133]
	v_pk_fma_f32 v[150:151], v[150:151], v[94:95], v[134:135]
	v_pk_fma_f32 v[152:153], v[152:153], v[96:97], v[136:137]
	v_pk_fma_f32 v[154:155], v[154:155], v[98:99], v[138:139]
	v_cvt_pk_bf16_f32 v164, v140, v141
	v_cvt_pk_bf16_f32 v165, v142, v143
	v_cvt_pk_bf16_f32 v166, v144, v145
	v_cvt_pk_bf16_f32 v167, v146, v147
	v_cvt_pk_bf16_f32 v168, v148, v149
	v_cvt_pk_bf16_f32 v169, v150, v151
	v_cvt_pk_bf16_f32 v170, v152, v153
	v_cvt_pk_bf16_f32 v171, v154, v155
	global_store_dwordx4 v109, v[164:167], s[20:21] offset:2048 sc1
	global_store_dwordx4 v109, v[168:171], s[20:21] offset:3072 sc1
	s_add_u32 s20, s20, 0x2000
	s_addc_u32 s21, s21, 0
	s_add_u32 s18, s18, 0x2000
	s_addc_u32 s19, s19, 0
	global_load_dwordx4 v[0:3], v51, s[18:19]
	global_load_dwordx4 v[4:7], v51, s[18:19] offset:1024
	global_load_dwordx4 v[8:11], v51, s[18:19] offset:2048
	global_load_dwordx4 v[12:15], v51, s[18:19] offset:3072
	global_load_dwordx4 v[16:19], v109, s[18:19]
	global_load_dwordx4 v[20:23], v109, s[18:19] offset:1024
	global_load_dwordx4 v[24:27], v109, s[18:19] offset:2048
	global_load_dwordx4 v[28:31], v109, s[18:19] offset:3072
	s_waitcnt vmcnt(16)
	v_lshlrev_b32_e32 v140, 16, v52
	v_and_b32_e32 v141, 0xffff0000, v52
	v_lshlrev_b32_e32 v142, 16, v53
	v_and_b32_e32 v143, 0xffff0000, v53
	v_lshlrev_b32_e32 v144, 16, v54
	v_and_b32_e32 v145, 0xffff0000, v54
	v_lshlrev_b32_e32 v146, 16, v55
	v_and_b32_e32 v147, 0xffff0000, v55
	v_lshlrev_b32_e32 v148, 16, v56
	v_and_b32_e32 v149, 0xffff0000, v56
	v_lshlrev_b32_e32 v150, 16, v57
	v_and_b32_e32 v151, 0xffff0000, v57
	v_lshlrev_b32_e32 v152, 16, v58
	v_and_b32_e32 v153, 0xffff0000, v58
	v_lshlrev_b32_e32 v154, 16, v59
	v_and_b32_e32 v155, 0xffff0000, v59
	v_pk_mul_f32 v[100:101], v[140:141], v[140:141]
	v_pk_fma_f32 v[100:101], v[142:143], v[142:143], v[100:101]
	v_pk_fma_f32 v[100:101], v[144:145], v[144:145], v[100:101]
	v_pk_fma_f32 v[100:101], v[146:147], v[146:147], v[100:101]
	v_pk_fma_f32 v[100:101], v[148:149], v[148:149], v[100:101]
	v_pk_fma_f32 v[100:101], v[150:151], v[150:151], v[100:101]
	v_pk_fma_f32 v[100:101], v[152:153], v[152:153], v[100:101]
	v_pk_fma_f32 v[100:101], v[154:155], v[154:155], v[100:101]
	v_lshlrev_b32_e32 v140, 16, v60
	v_and_b32_e32 v141, 0xffff0000, v60
	v_lshlrev_b32_e32 v142, 16, v61
	v_and_b32_e32 v143, 0xffff0000, v61
	v_lshlrev_b32_e32 v144, 16, v62
	v_and_b32_e32 v145, 0xffff0000, v62
	v_lshlrev_b32_e32 v146, 16, v63
	v_and_b32_e32 v147, 0xffff0000, v63
	v_lshlrev_b32_e32 v148, 16, v64
	v_and_b32_e32 v149, 0xffff0000, v64
	v_lshlrev_b32_e32 v150, 16, v65
	v_and_b32_e32 v151, 0xffff0000, v65
	v_lshlrev_b32_e32 v152, 16, v66
	v_and_b32_e32 v153, 0xffff0000, v66
	v_lshlrev_b32_e32 v154, 16, v67
	v_and_b32_e32 v155, 0xffff0000, v67
	v_pk_mul_f32 v[102:103], v[140:141], v[140:141]
	v_pk_fma_f32 v[102:103], v[142:143], v[142:143], v[102:103]
	v_pk_fma_f32 v[102:103], v[144:145], v[144:145], v[102:103]
	v_pk_fma_f32 v[102:103], v[146:147], v[146:147], v[102:103]
	v_pk_fma_f32 v[102:103], v[148:149], v[148:149], v[102:103]
	v_pk_fma_f32 v[102:103], v[150:151], v[150:151], v[102:103]
	v_pk_fma_f32 v[102:103], v[152:153], v[152:153], v[102:103]
	v_pk_fma_f32 v[102:103], v[154:155], v[154:155], v[102:103]
	v_lshlrev_b32_e32 v140, 16, v68
	v_and_b32_e32 v141, 0xffff0000, v68
	v_lshlrev_b32_e32 v142, 16, v69
	v_and_b32_e32 v143, 0xffff0000, v69
	v_lshlrev_b32_e32 v144, 16, v70
	v_and_b32_e32 v145, 0xffff0000, v70
	v_lshlrev_b32_e32 v146, 16, v71
	v_and_b32_e32 v147, 0xffff0000, v71
	v_lshlrev_b32_e32 v148, 16, v72
	v_and_b32_e32 v149, 0xffff0000, v72
	v_lshlrev_b32_e32 v150, 16, v73
	v_and_b32_e32 v151, 0xffff0000, v73
	v_lshlrev_b32_e32 v152, 16, v74
	v_and_b32_e32 v153, 0xffff0000, v74
	v_lshlrev_b32_e32 v154, 16, v75
	v_and_b32_e32 v155, 0xffff0000, v75
	v_pk_mul_f32 v[104:105], v[140:141], v[140:141]
	v_pk_fma_f32 v[104:105], v[142:143], v[142:143], v[104:105]
	v_pk_fma_f32 v[104:105], v[144:145], v[144:145], v[104:105]
	v_pk_fma_f32 v[104:105], v[146:147], v[146:147], v[104:105]
	v_pk_fma_f32 v[104:105], v[148:149], v[148:149], v[104:105]
	v_pk_fma_f32 v[104:105], v[150:151], v[150:151], v[104:105]
	v_pk_fma_f32 v[104:105], v[152:153], v[152:153], v[104:105]
	v_pk_fma_f32 v[104:105], v[154:155], v[154:155], v[104:105]
	v_lshlrev_b32_e32 v140, 16, v76
	v_and_b32_e32 v141, 0xffff0000, v76
	v_lshlrev_b32_e32 v142, 16, v77
	v_and_b32_e32 v143, 0xffff0000, v77
	v_lshlrev_b32_e32 v144, 16, v78
	v_and_b32_e32 v145, 0xffff0000, v78
	v_lshlrev_b32_e32 v146, 16, v79
	v_and_b32_e32 v147, 0xffff0000, v79
	v_lshlrev_b32_e32 v148, 16, v80
	v_and_b32_e32 v149, 0xffff0000, v80
	v_lshlrev_b32_e32 v150, 16, v81
	v_and_b32_e32 v151, 0xffff0000, v81
	v_lshlrev_b32_e32 v152, 16, v82
	v_and_b32_e32 v153, 0xffff0000, v82
	v_lshlrev_b32_e32 v154, 16, v83
	v_and_b32_e32 v155, 0xffff0000, v83
	v_pk_mul_f32 v[106:107], v[140:141], v[140:141]
	v_pk_fma_f32 v[106:107], v[142:143], v[142:143], v[106:107]
	v_pk_fma_f32 v[106:107], v[144:145], v[144:145], v[106:107]
	v_pk_fma_f32 v[106:107], v[146:147], v[146:147], v[106:107]
	v_pk_fma_f32 v[106:107], v[148:149], v[148:149], v[106:107]
	v_pk_fma_f32 v[106:107], v[150:151], v[150:151], v[106:107]
	v_pk_fma_f32 v[106:107], v[152:153], v[152:153], v[106:107]
	v_pk_fma_f32 v[106:107], v[154:155], v[154:155], v[106:107]
	v_add_f32_e32 v100, v100, v101
	v_add_f32_e32 v102, v102, v103
	v_add_f32_e32 v104, v104, v105
	v_add_f32_e32 v106, v106, v107
	s_nop 1
	v_add_f32_dpp v100, v100, v100 row_shr:1 row_mask:0xf bank_mask:0xf bound_ctrl:1
	v_add_f32_dpp v102, v102, v102 row_shr:1 row_mask:0xf bank_mask:0xf bound_ctrl:1
	v_add_f32_dpp v104, v104, v104 row_shr:1 row_mask:0xf bank_mask:0xf bound_ctrl:1
	v_add_f32_dpp v106, v106, v106 row_shr:1 row_mask:0xf bank_mask:0xf bound_ctrl:1
	v_add_f32_dpp v100, v100, v100 row_shr:2 row_mask:0xf bank_mask:0xf bound_ctrl:1
	v_add_f32_dpp v102, v102, v102 row_shr:2 row_mask:0xf bank_mask:0xf bound_ctrl:1
	v_add_f32_dpp v104, v104, v104 row_shr:2 row_mask:0xf bank_mask:0xf bound_ctrl:1
	v_add_f32_dpp v106, v106, v106 row_shr:2 row_mask:0xf bank_mask:0xf bound_ctrl:1
	v_add_f32_dpp v100, v100, v100 row_shr:4 row_mask:0xf bank_mask:0xf bound_ctrl:1
	v_add_f32_dpp v102, v102, v102 row_shr:4 row_mask:0xf bank_mask:0xf bound_ctrl:1
	v_add_f32_dpp v104, v104, v104 row_shr:4 row_mask:0xf bank_mask:0xf bound_ctrl:1
	v_add_f32_dpp v106, v106, v106 row_shr:4 row_mask:0xf bank_mask:0xf bound_ctrl:1
	v_add_f32_dpp v100, v100, v100 row_shr:8 row_mask:0xf bank_mask:0xf bound_ctrl:1
	v_add_f32_dpp v102, v102, v102 row_shr:8 row_mask:0xf bank_mask:0xf bound_ctrl:1
	v_add_f32_dpp v104, v104, v104 row_shr:8 row_mask:0xf bank_mask:0xf bound_ctrl:1
	v_add_f32_dpp v106, v106, v106 row_shr:8 row_mask:0xf bank_mask:0xf bound_ctrl:1
	v_add_f32_dpp v100, v100, v100 row_bcast:15 row_mask:0xa bank_mask:0xf
	v_add_f32_dpp v102, v102, v102 row_bcast:15 row_mask:0xa bank_mask:0xf
	v_add_f32_dpp v104, v104, v104 row_bcast:15 row_mask:0xa bank_mask:0xf
	v_add_f32_dpp v106, v106, v106 row_bcast:15 row_mask:0xa bank_mask:0xf
	v_add_f32_dpp v100, v100, v100 row_bcast:31 row_mask:0xc bank_mask:0xf
	v_add_f32_dpp v102, v102, v102 row_bcast:31 row_mask:0xc bank_mask:0xf
	v_add_f32_dpp v104, v104, v104 row_bcast:31 row_mask:0xc bank_mask:0xf
	v_add_f32_dpp v106, v106, v106 row_bcast:31 row_mask:0xc bank_mask:0xf
	s_nop 1
	v_readlane_b32 s5, v100, 63
	v_readlane_b32 s32, v102, 63
	v_readlane_b32 s54, v104, 63
	v_readlane_b32 s60, v106, 63
	s_nop 1
	v_mov_b32_e32 v156, s5
	v_mov_b32_e32 v158, s32
	v_mov_b32_e32 v160, s54
	v_mov_b32_e32 v162, s60
	v_fmaak_f32 v156, v156, v50, 0x358637bd
	v_fmaak_f32 v158, v158, v50, 0x358637bd
	v_fmaak_f32 v160, v160, v50, 0x358637bd
	v_fmaak_f32 v162, v162, v50, 0x358637bd
	v_rsq_f32_e32 v156, v156
	v_rsq_f32_e32 v158, v158
	v_rsq_f32_e32 v160, v160
	v_rsq_f32_e32 v162, v162
	s_nop 0
	v_lshlrev_b32_e32 v140, 16, v52
	v_and_b32_e32 v141, 0xffff0000, v52
	v_lshlrev_b32_e32 v142, 16, v53
	v_and_b32_e32 v143, 0xffff0000, v53
	v_lshlrev_b32_e32 v144, 16, v54
	v_and_b32_e32 v145, 0xffff0000, v54
	v_lshlrev_b32_e32 v146, 16, v55
	v_and_b32_e32 v147, 0xffff0000, v55
	v_lshlrev_b32_e32 v148, 16, v56
	v_and_b32_e32 v149, 0xffff0000, v56
	v_lshlrev_b32_e32 v150, 16, v57
	v_and_b32_e32 v151, 0xffff0000, v57
	v_lshlrev_b32_e32 v152, 16, v58
	v_and_b32_e32 v153, 0xffff0000, v58
	v_lshlrev_b32_e32 v154, 16, v59
	v_and_b32_e32 v155, 0xffff0000, v59
	v_pk_mul_f32 v[140:141], v[156:157], v[140:141] op_sel_hi:[0,1]
	v_pk_mul_f32 v[142:143], v[156:157], v[142:143] op_sel_hi:[0,1]
	v_pk_mul_f32 v[144:145], v[156:157], v[144:145] op_sel_hi:[0,1]
	v_pk_mul_f32 v[146:147], v[156:157], v[146:147] op_sel_hi:[0,1]
	v_pk_mul_f32 v[148:149], v[156:157], v[148:149] op_sel_hi:[0,1]
	v_pk_mul_f32 v[150:151], v[156:157], v[150:151] op_sel_hi:[0,1]
	v_pk_mul_f32 v[152:153], v[156:157], v[152:153] op_sel_hi:[0,1]
	v_pk_mul_f32 v[154:155], v[156:157], v[154:155] op_sel_hi:[0,1]
	v_pk_mul_f32 v[140:141], v[140:141], v[32:33]
	v_pk_mul_f32 v[142:143], v[142:143], v[34:35]
	v_pk_mul_f32 v[144:145], v[144:145], v[36:37]
	v_pk_mul_f32 v[146:147], v[146:147], v[38:39]
	v_pk_mul_f32 v[148:149], v[148:149], v[40:41]
	v_pk_mul_f32 v[150:151], v[150:151], v[42:43]
	v_pk_mul_f32 v[152:153], v[152:153], v[44:45]
	v_pk_mul_f32 v[154:155], v[154:155], v[46:47]
	v_pk_fma_f32 v[140:141], v[140:141], v[84:85], v[124:125]
	v_pk_fma_f32 v[142:143], v[142:143], v[86:87], v[126:127]
	v_pk_fma_f32 v[144:145], v[144:145], v[88:89], v[128:129]
	v_pk_fma_f32 v[146:147], v[146:147], v[90:91], v[130:131]
	v_pk_fma_f32 v[148:149], v[148:149], v[92:93], v[132:133]
	v_pk_fma_f32 v[150:151], v[150:151], v[94:95], v[134:135]
	v_pk_fma_f32 v[152:153], v[152:153], v[96:97], v[136:137]
	v_pk_fma_f32 v[154:155], v[154:155], v[98:99], v[138:139]
	v_cvt_pk_bf16_f32 v164, v140, v141
	v_cvt_pk_bf16_f32 v165, v142, v143
	v_cvt_pk_bf16_f32 v166, v144, v145
	v_cvt_pk_bf16_f32 v167, v146, v147
	v_cvt_pk_bf16_f32 v168, v148, v149
	v_cvt_pk_bf16_f32 v169, v150, v151
	v_cvt_pk_bf16_f32 v170, v152, v153
	v_cvt_pk_bf16_f32 v171, v154, v155
	global_store_dwordx4 v51, v[164:167], s[20:21] sc1
	global_store_dwordx4 v51, v[168:171], s[20:21] offset:1024 sc1
	v_lshlrev_b32_e32 v140, 16, v60
	v_and_b32_e32 v141, 0xffff0000, v60
	v_lshlrev_b32_e32 v142, 16, v61
	v_and_b32_e32 v143, 0xffff0000, v61
	v_lshlrev_b32_e32 v144, 16, v62
	v_and_b32_e32 v145, 0xffff0000, v62
	v_lshlrev_b32_e32 v146, 16, v63
	v_and_b32_e32 v147, 0xffff0000, v63
	v_lshlrev_b32_e32 v148, 16, v64
	v_and_b32_e32 v149, 0xffff0000, v64
	v_lshlrev_b32_e32 v150, 16, v65
	v_and_b32_e32 v151, 0xffff0000, v65
	v_lshlrev_b32_e32 v152, 16, v66
	v_and_b32_e32 v153, 0xffff0000, v66
	v_lshlrev_b32_e32 v154, 16, v67
	v_and_b32_e32 v155, 0xffff0000, v67
	v_pk_mul_f32 v[140:141], v[158:159], v[140:141] op_sel_hi:[0,1]
	v_pk_mul_f32 v[142:143], v[158:159], v[142:143] op_sel_hi:[0,1]
	v_pk_mul_f32 v[144:145], v[158:159], v[144:145] op_sel_hi:[0,1]
	v_pk_mul_f32 v[146:147], v[158:159], v[146:147] op_sel_hi:[0,1]
	v_pk_mul_f32 v[148:149], v[158:159], v[148:149] op_sel_hi:[0,1]
	v_pk_mul_f32 v[150:151], v[158:159], v[150:151] op_sel_hi:[0,1]
	v_pk_mul_f32 v[152:153], v[158:159], v[152:153] op_sel_hi:[0,1]
	v_pk_mul_f32 v[154:155], v[158:159], v[154:155] op_sel_hi:[0,1]
	v_pk_mul_f32 v[140:141], v[140:141], v[32:33]
	v_pk_mul_f32 v[142:143], v[142:143], v[34:35]
	v_pk_mul_f32 v[144:145], v[144:145], v[36:37]
	v_pk_mul_f32 v[146:147], v[146:147], v[38:39]
	v_pk_mul_f32 v[148:149], v[148:149], v[40:41]
	v_pk_mul_f32 v[150:151], v[150:151], v[42:43]
	v_pk_mul_f32 v[152:153], v[152:153], v[44:45]
	v_pk_mul_f32 v[154:155], v[154:155], v[46:47]
	v_pk_fma_f32 v[140:141], v[140:141], v[84:85], v[124:125]
	v_pk_fma_f32 v[142:143], v[142:143], v[86:87], v[126:127]
	v_pk_fma_f32 v[144:145], v[144:145], v[88:89], v[128:129]
	v_pk_fma_f32 v[146:147], v[146:147], v[90:91], v[130:131]
	v_pk_fma_f32 v[148:149], v[148:149], v[92:93], v[132:133]
	v_pk_fma_f32 v[150:151], v[150:151], v[94:95], v[134:135]
	v_pk_fma_f32 v[152:153], v[152:153], v[96:97], v[136:137]
	v_pk_fma_f32 v[154:155], v[154:155], v[98:99], v[138:139]
	v_cvt_pk_bf16_f32 v172, v140, v141
	v_cvt_pk_bf16_f32 v173, v142, v143
	v_cvt_pk_bf16_f32 v174, v144, v145
	v_cvt_pk_bf16_f32 v175, v146, v147
	v_cvt_pk_bf16_f32 v176, v148, v149
	v_cvt_pk_bf16_f32 v177, v150, v151
	v_cvt_pk_bf16_f32 v178, v152, v153
	v_cvt_pk_bf16_f32 v179, v154, v155
	global_store_dwordx4 v51, v[172:175], s[20:21] offset:2048 sc1
	global_store_dwordx4 v51, v[176:179], s[20:21] offset:3072 sc1
	v_lshlrev_b32_e32 v140, 16, v68
	v_and_b32_e32 v141, 0xffff0000, v68
	v_lshlrev_b32_e32 v142, 16, v69
	v_and_b32_e32 v143, 0xffff0000, v69
	v_lshlrev_b32_e32 v144, 16, v70
	v_and_b32_e32 v145, 0xffff0000, v70
	v_lshlrev_b32_e32 v146, 16, v71
	v_and_b32_e32 v147, 0xffff0000, v71
	v_lshlrev_b32_e32 v148, 16, v72
	v_and_b32_e32 v149, 0xffff0000, v72
	v_lshlrev_b32_e32 v150, 16, v73
	v_and_b32_e32 v151, 0xffff0000, v73
	v_lshlrev_b32_e32 v152, 16, v74
	v_and_b32_e32 v153, 0xffff0000, v74
	v_lshlrev_b32_e32 v154, 16, v75
	v_and_b32_e32 v155, 0xffff0000, v75
	v_pk_mul_f32 v[140:141], v[160:161], v[140:141] op_sel_hi:[0,1]
	v_pk_mul_f32 v[142:143], v[160:161], v[142:143] op_sel_hi:[0,1]
	v_pk_mul_f32 v[144:145], v[160:161], v[144:145] op_sel_hi:[0,1]
	v_pk_mul_f32 v[146:147], v[160:161], v[146:147] op_sel_hi:[0,1]
	v_pk_mul_f32 v[148:149], v[160:161], v[148:149] op_sel_hi:[0,1]
	v_pk_mul_f32 v[150:151], v[160:161], v[150:151] op_sel_hi:[0,1]
	v_pk_mul_f32 v[152:153], v[160:161], v[152:153] op_sel_hi:[0,1]
	v_pk_mul_f32 v[154:155], v[160:161], v[154:155] op_sel_hi:[0,1]
	v_pk_mul_f32 v[140:141], v[140:141], v[32:33]
	v_pk_mul_f32 v[142:143], v[142:143], v[34:35]
	v_pk_mul_f32 v[144:145], v[144:145], v[36:37]
	v_pk_mul_f32 v[146:147], v[146:147], v[38:39]
	v_pk_mul_f32 v[148:149], v[148:149], v[40:41]
	v_pk_mul_f32 v[150:151], v[150:151], v[42:43]
	v_pk_mul_f32 v[152:153], v[152:153], v[44:45]
	v_pk_mul_f32 v[154:155], v[154:155], v[46:47]
	v_pk_fma_f32 v[140:141], v[140:141], v[84:85], v[124:125]
	v_pk_fma_f32 v[142:143], v[142:143], v[86:87], v[126:127]
	v_pk_fma_f32 v[144:145], v[144:145], v[88:89], v[128:129]
	v_pk_fma_f32 v[146:147], v[146:147], v[90:91], v[130:131]
	v_pk_fma_f32 v[148:149], v[148:149], v[92:93], v[132:133]
	v_pk_fma_f32 v[150:151], v[150:151], v[94:95], v[134:135]
	v_pk_fma_f32 v[152:153], v[152:153], v[96:97], v[136:137]
	v_pk_fma_f32 v[154:155], v[154:155], v[98:99], v[138:139]
	v_cvt_pk_bf16_f32 v164, v140, v141
	v_cvt_pk_bf16_f32 v165, v142, v143
	v_cvt_pk_bf16_f32 v166, v144, v145
	v_cvt_pk_bf16_f32 v167, v146, v147
	v_cvt_pk_bf16_f32 v168, v148, v149
	v_cvt_pk_bf16_f32 v169, v150, v151
	v_cvt_pk_bf16_f32 v170, v152, v153
	v_cvt_pk_bf16_f32 v171, v154, v155
	global_store_dwordx4 v109, v[164:167], s[20:21] sc1
	global_store_dwordx4 v109, v[168:171], s[20:21] offset:1024 sc1
	v_lshlrev_b32_e32 v140, 16, v76
	v_and_b32_e32 v141, 0xffff0000, v76
	v_lshlrev_b32_e32 v142, 16, v77
	v_and_b32_e32 v143, 0xffff0000, v77
	v_lshlrev_b32_e32 v144, 16, v78
	v_and_b32_e32 v145, 0xffff0000, v78
	v_lshlrev_b32_e32 v146, 16, v79
	v_and_b32_e32 v147, 0xffff0000, v79
	v_lshlrev_b32_e32 v148, 16, v80
	v_and_b32_e32 v149, 0xffff0000, v80
	v_lshlrev_b32_e32 v150, 16, v81
	v_and_b32_e32 v151, 0xffff0000, v81
	v_lshlrev_b32_e32 v152, 16, v82
	v_and_b32_e32 v153, 0xffff0000, v82
	v_lshlrev_b32_e32 v154, 16, v83
	v_and_b32_e32 v155, 0xffff0000, v83
	v_pk_mul_f32 v[140:141], v[162:163], v[140:141] op_sel_hi:[0,1]
	v_pk_mul_f32 v[142:143], v[162:163], v[142:143] op_sel_hi:[0,1]
	v_pk_mul_f32 v[144:145], v[162:163], v[144:145] op_sel_hi:[0,1]
	v_pk_mul_f32 v[146:147], v[162:163], v[146:147] op_sel_hi:[0,1]
	v_pk_mul_f32 v[148:149], v[162:163], v[148:149] op_sel_hi:[0,1]
	v_pk_mul_f32 v[150:151], v[162:163], v[150:151] op_sel_hi:[0,1]
	v_pk_mul_f32 v[152:153], v[162:163], v[152:153] op_sel_hi:[0,1]
	v_pk_mul_f32 v[154:155], v[162:163], v[154:155] op_sel_hi:[0,1]
	v_pk_mul_f32 v[140:141], v[140:141], v[32:33]
	v_pk_mul_f32 v[142:143], v[142:143], v[34:35]
	v_pk_mul_f32 v[144:145], v[144:145], v[36:37]
	v_pk_mul_f32 v[146:147], v[146:147], v[38:39]
	v_pk_mul_f32 v[148:149], v[148:149], v[40:41]
	v_pk_mul_f32 v[150:151], v[150:151], v[42:43]
	v_pk_mul_f32 v[152:153], v[152:153], v[44:45]
	v_pk_mul_f32 v[154:155], v[154:155], v[46:47]
	v_pk_fma_f32 v[140:141], v[140:141], v[84:85], v[124:125]
	v_pk_fma_f32 v[142:143], v[142:143], v[86:87], v[126:127]
	v_pk_fma_f32 v[144:145], v[144:145], v[88:89], v[128:129]
	v_pk_fma_f32 v[146:147], v[146:147], v[90:91], v[130:131]
	v_pk_fma_f32 v[148:149], v[148:149], v[92:93], v[132:133]
	v_pk_fma_f32 v[150:151], v[150:151], v[94:95], v[134:135]
	v_pk_fma_f32 v[152:153], v[152:153], v[96:97], v[136:137]
	v_pk_fma_f32 v[154:155], v[154:155], v[98:99], v[138:139]
	v_cvt_pk_bf16_f32 v172, v140, v141
	v_cvt_pk_bf16_f32 v173, v142, v143
	v_cvt_pk_bf16_f32 v174, v144, v145
	v_cvt_pk_bf16_f32 v175, v146, v147
	v_cvt_pk_bf16_f32 v176, v148, v149
	v_cvt_pk_bf16_f32 v177, v150, v151
	v_cvt_pk_bf16_f32 v178, v152, v153
	v_cvt_pk_bf16_f32 v179, v154, v155
	global_store_dwordx4 v109, v[172:175], s[20:21] offset:2048 sc1
	global_store_dwordx4 v109, v[176:179], s[20:21] offset:3072 sc1
	s_add_u32 s20, s20, 0x2000
	s_addc_u32 s21, s21, 0
	s_add_u32 s18, s18, 0x2000
	s_addc_u32 s19, s19, 0
	global_load_dwordx4 v[52:55], v51, s[18:19]
	global_load_dwordx4 v[56:59], v51, s[18:19] offset:1024
	global_load_dwordx4 v[60:63], v51, s[18:19] offset:2048
	global_load_dwordx4 v[64:67], v51, s[18:19] offset:3072
	global_load_dwordx4 v[68:71], v109, s[18:19]
	global_load_dwordx4 v[72:75], v109, s[18:19] offset:1024
	global_load_dwordx4 v[76:79], v109, s[18:19] offset:2048
	global_load_dwordx4 v[80:83], v109, s[18:19] offset:3072
	s_waitcnt vmcnt(16)
	v_lshlrev_b32_e32 v140, 16, v0
	v_and_b32_e32 v141, 0xffff0000, v0
	v_lshlrev_b32_e32 v142, 16, v1
	v_and_b32_e32 v143, 0xffff0000, v1
	v_lshlrev_b32_e32 v144, 16, v2
	v_and_b32_e32 v145, 0xffff0000, v2
	v_lshlrev_b32_e32 v146, 16, v3
	v_and_b32_e32 v147, 0xffff0000, v3
	v_lshlrev_b32_e32 v148, 16, v4
	v_and_b32_e32 v149, 0xffff0000, v4
	v_lshlrev_b32_e32 v150, 16, v5
	v_and_b32_e32 v151, 0xffff0000, v5
	v_lshlrev_b32_e32 v152, 16, v6
	v_and_b32_e32 v153, 0xffff0000, v6
	v_lshlrev_b32_e32 v154, 16, v7
	v_and_b32_e32 v155, 0xffff0000, v7
	v_pk_mul_f32 v[100:101], v[140:141], v[140:141]
	v_pk_fma_f32 v[100:101], v[142:143], v[142:143], v[100:101]
	v_pk_fma_f32 v[100:101], v[144:145], v[144:145], v[100:101]
	v_pk_fma_f32 v[100:101], v[146:147], v[146:147], v[100:101]
	v_pk_fma_f32 v[100:101], v[148:149], v[148:149], v[100:101]
	v_pk_fma_f32 v[100:101], v[150:151], v[150:151], v[100:101]
	v_pk_fma_f32 v[100:101], v[152:153], v[152:153], v[100:101]
	v_pk_fma_f32 v[100:101], v[154:155], v[154:155], v[100:101]
	v_lshlrev_b32_e32 v140, 16, v8
	v_and_b32_e32 v141, 0xffff0000, v8
	v_lshlrev_b32_e32 v142, 16, v9
	v_and_b32_e32 v143, 0xffff0000, v9
	v_lshlrev_b32_e32 v144, 16, v10
	v_and_b32_e32 v145, 0xffff0000, v10
	v_lshlrev_b32_e32 v146, 16, v11
	v_and_b32_e32 v147, 0xffff0000, v11
	v_lshlrev_b32_e32 v148, 16, v12
	v_and_b32_e32 v149, 0xffff0000, v12
	v_lshlrev_b32_e32 v150, 16, v13
	v_and_b32_e32 v151, 0xffff0000, v13
	v_lshlrev_b32_e32 v152, 16, v14
	v_and_b32_e32 v153, 0xffff0000, v14
	v_lshlrev_b32_e32 v154, 16, v15
	v_and_b32_e32 v155, 0xffff0000, v15
	v_pk_mul_f32 v[102:103], v[140:141], v[140:141]
	v_pk_fma_f32 v[102:103], v[142:143], v[142:143], v[102:103]
	v_pk_fma_f32 v[102:103], v[144:145], v[144:145], v[102:103]
	v_pk_fma_f32 v[102:103], v[146:147], v[146:147], v[102:103]
	v_pk_fma_f32 v[102:103], v[148:149], v[148:149], v[102:103]
	v_pk_fma_f32 v[102:103], v[150:151], v[150:151], v[102:103]
	v_pk_fma_f32 v[102:103], v[152:153], v[152:153], v[102:103]
	v_pk_fma_f32 v[102:103], v[154:155], v[154:155], v[102:103]
	v_lshlrev_b32_e32 v140, 16, v16
	v_and_b32_e32 v141, 0xffff0000, v16
	v_lshlrev_b32_e32 v142, 16, v17
	v_and_b32_e32 v143, 0xffff0000, v17
	v_lshlrev_b32_e32 v144, 16, v18
	v_and_b32_e32 v145, 0xffff0000, v18
	v_lshlrev_b32_e32 v146, 16, v19
	v_and_b32_e32 v147, 0xffff0000, v19
	v_lshlrev_b32_e32 v148, 16, v20
	v_and_b32_e32 v149, 0xffff0000, v20
	v_lshlrev_b32_e32 v150, 16, v21
	v_and_b32_e32 v151, 0xffff0000, v21
	v_lshlrev_b32_e32 v152, 16, v22
	v_and_b32_e32 v153, 0xffff0000, v22
	v_lshlrev_b32_e32 v154, 16, v23
	v_and_b32_e32 v155, 0xffff0000, v23
	v_pk_mul_f32 v[104:105], v[140:141], v[140:141]
	v_pk_fma_f32 v[104:105], v[142:143], v[142:143], v[104:105]
	v_pk_fma_f32 v[104:105], v[144:145], v[144:145], v[104:105]
	v_pk_fma_f32 v[104:105], v[146:147], v[146:147], v[104:105]
	v_pk_fma_f32 v[104:105], v[148:149], v[148:149], v[104:105]
	v_pk_fma_f32 v[104:105], v[150:151], v[150:151], v[104:105]
	v_pk_fma_f32 v[104:105], v[152:153], v[152:153], v[104:105]
	v_pk_fma_f32 v[104:105], v[154:155], v[154:155], v[104:105]
	v_lshlrev_b32_e32 v140, 16, v24
	v_and_b32_e32 v141, 0xffff0000, v24
	v_lshlrev_b32_e32 v142, 16, v25
	v_and_b32_e32 v143, 0xffff0000, v25
	v_lshlrev_b32_e32 v144, 16, v26
	v_and_b32_e32 v145, 0xffff0000, v26
	v_lshlrev_b32_e32 v146, 16, v27
	v_and_b32_e32 v147, 0xffff0000, v27
	v_lshlrev_b32_e32 v148, 16, v28
	v_and_b32_e32 v149, 0xffff0000, v28
	v_lshlrev_b32_e32 v150, 16, v29
	v_and_b32_e32 v151, 0xffff0000, v29
	v_lshlrev_b32_e32 v152, 16, v30
	v_and_b32_e32 v153, 0xffff0000, v30
	v_lshlrev_b32_e32 v154, 16, v31
	v_and_b32_e32 v155, 0xffff0000, v31
	v_pk_mul_f32 v[106:107], v[140:141], v[140:141]
	v_pk_fma_f32 v[106:107], v[142:143], v[142:143], v[106:107]
	v_pk_fma_f32 v[106:107], v[144:145], v[144:145], v[106:107]
	v_pk_fma_f32 v[106:107], v[146:147], v[146:147], v[106:107]
	v_pk_fma_f32 v[106:107], v[148:149], v[148:149], v[106:107]
	v_pk_fma_f32 v[106:107], v[150:151], v[150:151], v[106:107]
	v_pk_fma_f32 v[106:107], v[152:153], v[152:153], v[106:107]
	v_pk_fma_f32 v[106:107], v[154:155], v[154:155], v[106:107]
	v_add_f32_e32 v100, v100, v101
	v_add_f32_e32 v102, v102, v103
	v_add_f32_e32 v104, v104, v105
	v_add_f32_e32 v106, v106, v107
	s_nop 1
	v_add_f32_dpp v100, v100, v100 row_shr:1 row_mask:0xf bank_mask:0xf bound_ctrl:1
	v_add_f32_dpp v102, v102, v102 row_shr:1 row_mask:0xf bank_mask:0xf bound_ctrl:1
	v_add_f32_dpp v104, v104, v104 row_shr:1 row_mask:0xf bank_mask:0xf bound_ctrl:1
	v_add_f32_dpp v106, v106, v106 row_shr:1 row_mask:0xf bank_mask:0xf bound_ctrl:1
	v_add_f32_dpp v100, v100, v100 row_shr:2 row_mask:0xf bank_mask:0xf bound_ctrl:1
	v_add_f32_dpp v102, v102, v102 row_shr:2 row_mask:0xf bank_mask:0xf bound_ctrl:1
	v_add_f32_dpp v104, v104, v104 row_shr:2 row_mask:0xf bank_mask:0xf bound_ctrl:1
	v_add_f32_dpp v106, v106, v106 row_shr:2 row_mask:0xf bank_mask:0xf bound_ctrl:1
	v_add_f32_dpp v100, v100, v100 row_shr:4 row_mask:0xf bank_mask:0xf bound_ctrl:1
	v_add_f32_dpp v102, v102, v102 row_shr:4 row_mask:0xf bank_mask:0xf bound_ctrl:1
	v_add_f32_dpp v104, v104, v104 row_shr:4 row_mask:0xf bank_mask:0xf bound_ctrl:1
	v_add_f32_dpp v106, v106, v106 row_shr:4 row_mask:0xf bank_mask:0xf bound_ctrl:1
	v_add_f32_dpp v100, v100, v100 row_shr:8 row_mask:0xf bank_mask:0xf bound_ctrl:1
	v_add_f32_dpp v102, v102, v102 row_shr:8 row_mask:0xf bank_mask:0xf bound_ctrl:1
	v_add_f32_dpp v104, v104, v104 row_shr:8 row_mask:0xf bank_mask:0xf bound_ctrl:1
	v_add_f32_dpp v106, v106, v106 row_shr:8 row_mask:0xf bank_mask:0xf bound_ctrl:1
	v_add_f32_dpp v100, v100, v100 row_bcast:15 row_mask:0xa bank_mask:0xf
	v_add_f32_dpp v102, v102, v102 row_bcast:15 row_mask:0xa bank_mask:0xf
	v_add_f32_dpp v104, v104, v104 row_bcast:15 row_mask:0xa bank_mask:0xf
	v_add_f32_dpp v106, v106, v106 row_bcast:15 row_mask:0xa bank_mask:0xf
	v_add_f32_dpp v100, v100, v100 row_bcast:31 row_mask:0xc bank_mask:0xf
	v_add_f32_dpp v102, v102, v102 row_bcast:31 row_mask:0xc bank_mask:0xf
	v_add_f32_dpp v104, v104, v104 row_bcast:31 row_mask:0xc bank_mask:0xf
	v_add_f32_dpp v106, v106, v106 row_bcast:31 row_mask:0xc bank_mask:0xf
	s_nop 1
	v_readlane_b32 s5, v100, 63
	v_readlane_b32 s32, v102, 63
	v_readlane_b32 s54, v104, 63
	v_readlane_b32 s60, v106, 63
	s_nop 1
	v_mov_b32_e32 v156, s5
	v_mov_b32_e32 v158, s32
	v_mov_b32_e32 v160, s54
	v_mov_b32_e32 v162, s60
	v_fmaak_f32 v156, v156, v50, 0x358637bd
	v_fmaak_f32 v158, v158, v50, 0x358637bd
	v_fmaak_f32 v160, v160, v50, 0x358637bd
	v_fmaak_f32 v162, v162, v50, 0x358637bd
	v_rsq_f32_e32 v156, v156
	v_rsq_f32_e32 v158, v158
	v_rsq_f32_e32 v160, v160
	v_rsq_f32_e32 v162, v162
	s_nop 0
	v_lshlrev_b32_e32 v140, 16, v0
	v_and_b32_e32 v141, 0xffff0000, v0
	v_lshlrev_b32_e32 v142, 16, v1
	v_and_b32_e32 v143, 0xffff0000, v1
	v_lshlrev_b32_e32 v144, 16, v2
	v_and_b32_e32 v145, 0xffff0000, v2
	v_lshlrev_b32_e32 v146, 16, v3
	v_and_b32_e32 v147, 0xffff0000, v3
	v_lshlrev_b32_e32 v148, 16, v4
	v_and_b32_e32 v149, 0xffff0000, v4
	v_lshlrev_b32_e32 v150, 16, v5
	v_and_b32_e32 v151, 0xffff0000, v5
	v_lshlrev_b32_e32 v152, 16, v6
	v_and_b32_e32 v153, 0xffff0000, v6
	v_lshlrev_b32_e32 v154, 16, v7
	v_and_b32_e32 v155, 0xffff0000, v7
	v_pk_mul_f32 v[140:141], v[156:157], v[140:141] op_sel_hi:[0,1]
	v_pk_mul_f32 v[142:143], v[156:157], v[142:143] op_sel_hi:[0,1]
	v_pk_mul_f32 v[144:145], v[156:157], v[144:145] op_sel_hi:[0,1]
	v_pk_mul_f32 v[146:147], v[156:157], v[146:147] op_sel_hi:[0,1]
	v_pk_mul_f32 v[148:149], v[156:157], v[148:149] op_sel_hi:[0,1]
	v_pk_mul_f32 v[150:151], v[156:157], v[150:151] op_sel_hi:[0,1]
	v_pk_mul_f32 v[152:153], v[156:157], v[152:153] op_sel_hi:[0,1]
	v_pk_mul_f32 v[154:155], v[156:157], v[154:155] op_sel_hi:[0,1]
	v_pk_mul_f32 v[140:141], v[140:141], v[32:33]
	v_pk_mul_f32 v[142:143], v[142:143], v[34:35]
	v_pk_mul_f32 v[144:145], v[144:145], v[36:37]
	v_pk_mul_f32 v[146:147], v[146:147], v[38:39]
	v_pk_mul_f32 v[148:149], v[148:149], v[40:41]
	v_pk_mul_f32 v[150:151], v[150:151], v[42:43]
	v_pk_mul_f32 v[152:153], v[152:153], v[44:45]
	v_pk_mul_f32 v[154:155], v[154:155], v[46:47]
	v_pk_fma_f32 v[140:141], v[140:141], v[84:85], v[124:125]
	v_pk_fma_f32 v[142:143], v[142:143], v[86:87], v[126:127]
	v_pk_fma_f32 v[144:145], v[144:145], v[88:89], v[128:129]
	v_pk_fma_f32 v[146:147], v[146:147], v[90:91], v[130:131]
	v_pk_fma_f32 v[148:149], v[148:149], v[92:93], v[132:133]
	v_pk_fma_f32 v[150:151], v[150:151], v[94:95], v[134:135]
	v_pk_fma_f32 v[152:153], v[152:153], v[96:97], v[136:137]
	v_pk_fma_f32 v[154:155], v[154:155], v[98:99], v[138:139]
	v_cvt_pk_bf16_f32 v172, v140, v141
	v_cvt_pk_bf16_f32 v173, v142, v143
	v_cvt_pk_bf16_f32 v174, v144, v145
	v_cvt_pk_bf16_f32 v175, v146, v147
	v_cvt_pk_bf16_f32 v176, v148, v149
	v_cvt_pk_bf16_f32 v177, v150, v151
	v_cvt_pk_bf16_f32 v178, v152, v153
	v_cvt_pk_bf16_f32 v179, v154, v155
	global_store_dwordx4 v51, v[172:175], s[20:21] sc1
	global_store_dwordx4 v51, v[176:179], s[20:21] offset:1024 sc1
	v_lshlrev_b32_e32 v140, 16, v8
	v_and_b32_e32 v141, 0xffff0000, v8
	v_lshlrev_b32_e32 v142, 16, v9
	v_and_b32_e32 v143, 0xffff0000, v9
	v_lshlrev_b32_e32 v144, 16, v10
	v_and_b32_e32 v145, 0xffff0000, v10
	v_lshlrev_b32_e32 v146, 16, v11
	v_and_b32_e32 v147, 0xffff0000, v11
	v_lshlrev_b32_e32 v148, 16, v12
	v_and_b32_e32 v149, 0xffff0000, v12
	v_lshlrev_b32_e32 v150, 16, v13
	v_and_b32_e32 v151, 0xffff0000, v13
	v_lshlrev_b32_e32 v152, 16, v14
	v_and_b32_e32 v153, 0xffff0000, v14
	v_lshlrev_b32_e32 v154, 16, v15
	v_and_b32_e32 v155, 0xffff0000, v15
	v_pk_mul_f32 v[140:141], v[158:159], v[140:141] op_sel_hi:[0,1]
	v_pk_mul_f32 v[142:143], v[158:159], v[142:143] op_sel_hi:[0,1]
	v_pk_mul_f32 v[144:145], v[158:159], v[144:145] op_sel_hi:[0,1]
	v_pk_mul_f32 v[146:147], v[158:159], v[146:147] op_sel_hi:[0,1]
	v_pk_mul_f32 v[148:149], v[158:159], v[148:149] op_sel_hi:[0,1]
	v_pk_mul_f32 v[150:151], v[158:159], v[150:151] op_sel_hi:[0,1]
	v_pk_mul_f32 v[152:153], v[158:159], v[152:153] op_sel_hi:[0,1]
	v_pk_mul_f32 v[154:155], v[158:159], v[154:155] op_sel_hi:[0,1]
	v_pk_mul_f32 v[140:141], v[140:141], v[32:33]
	v_pk_mul_f32 v[142:143], v[142:143], v[34:35]
	v_pk_mul_f32 v[144:145], v[144:145], v[36:37]
	v_pk_mul_f32 v[146:147], v[146:147], v[38:39]
	v_pk_mul_f32 v[148:149], v[148:149], v[40:41]
	v_pk_mul_f32 v[150:151], v[150:151], v[42:43]
	v_pk_mul_f32 v[152:153], v[152:153], v[44:45]
	v_pk_mul_f32 v[154:155], v[154:155], v[46:47]
	v_pk_fma_f32 v[140:141], v[140:141], v[84:85], v[124:125]
	v_pk_fma_f32 v[142:143], v[142:143], v[86:87], v[126:127]
	v_pk_fma_f32 v[144:145], v[144:145], v[88:89], v[128:129]
	v_pk_fma_f32 v[146:147], v[146:147], v[90:91], v[130:131]
	v_pk_fma_f32 v[148:149], v[148:149], v[92:93], v[132:133]
	v_pk_fma_f32 v[150:151], v[150:151], v[94:95], v[134:135]
	v_pk_fma_f32 v[152:153], v[152:153], v[96:97], v[136:137]
	v_pk_fma_f32 v[154:155], v[154:155], v[98:99], v[138:139]
	v_cvt_pk_bf16_f32 v164, v140, v141
	v_cvt_pk_bf16_f32 v165, v142, v143
	v_cvt_pk_bf16_f32 v166, v144, v145
	v_cvt_pk_bf16_f32 v167, v146, v147
	v_cvt_pk_bf16_f32 v168, v148, v149
	v_cvt_pk_bf16_f32 v169, v150, v151
	v_cvt_pk_bf16_f32 v170, v152, v153
	v_cvt_pk_bf16_f32 v171, v154, v155
	global_store_dwordx4 v51, v[164:167], s[20:21] offset:2048 sc1
	global_store_dwordx4 v51, v[168:171], s[20:21] offset:3072 sc1
	v_lshlrev_b32_e32 v140, 16, v16
	v_and_b32_e32 v141, 0xffff0000, v16
	v_lshlrev_b32_e32 v142, 16, v17
	v_and_b32_e32 v143, 0xffff0000, v17
	v_lshlrev_b32_e32 v144, 16, v18
	v_and_b32_e32 v145, 0xffff0000, v18
	v_lshlrev_b32_e32 v146, 16, v19
	v_and_b32_e32 v147, 0xffff0000, v19
	v_lshlrev_b32_e32 v148, 16, v20
	v_and_b32_e32 v149, 0xffff0000, v20
	v_lshlrev_b32_e32 v150, 16, v21
	v_and_b32_e32 v151, 0xffff0000, v21
	v_lshlrev_b32_e32 v152, 16, v22
	v_and_b32_e32 v153, 0xffff0000, v22
	v_lshlrev_b32_e32 v154, 16, v23
	v_and_b32_e32 v155, 0xffff0000, v23
	v_pk_mul_f32 v[140:141], v[160:161], v[140:141] op_sel_hi:[0,1]
	v_pk_mul_f32 v[142:143], v[160:161], v[142:143] op_sel_hi:[0,1]
	v_pk_mul_f32 v[144:145], v[160:161], v[144:145] op_sel_hi:[0,1]
	v_pk_mul_f32 v[146:147], v[160:161], v[146:147] op_sel_hi:[0,1]
	v_pk_mul_f32 v[148:149], v[160:161], v[148:149] op_sel_hi:[0,1]
	v_pk_mul_f32 v[150:151], v[160:161], v[150:151] op_sel_hi:[0,1]
	v_pk_mul_f32 v[152:153], v[160:161], v[152:153] op_sel_hi:[0,1]
	v_pk_mul_f32 v[154:155], v[160:161], v[154:155] op_sel_hi:[0,1]
	v_pk_mul_f32 v[140:141], v[140:141], v[32:33]
	v_pk_mul_f32 v[142:143], v[142:143], v[34:35]
	v_pk_mul_f32 v[144:145], v[144:145], v[36:37]
	v_pk_mul_f32 v[146:147], v[146:147], v[38:39]
	v_pk_mul_f32 v[148:149], v[148:149], v[40:41]
	v_pk_mul_f32 v[150:151], v[150:151], v[42:43]
	v_pk_mul_f32 v[152:153], v[152:153], v[44:45]
	v_pk_mul_f32 v[154:155], v[154:155], v[46:47]
	v_pk_fma_f32 v[140:141], v[140:141], v[84:85], v[124:125]
	v_pk_fma_f32 v[142:143], v[142:143], v[86:87], v[126:127]
	v_pk_fma_f32 v[144:145], v[144:145], v[88:89], v[128:129]
	v_pk_fma_f32 v[146:147], v[146:147], v[90:91], v[130:131]
	v_pk_fma_f32 v[148:149], v[148:149], v[92:93], v[132:133]
	v_pk_fma_f32 v[150:151], v[150:151], v[94:95], v[134:135]
	v_pk_fma_f32 v[152:153], v[152:153], v[96:97], v[136:137]
	v_pk_fma_f32 v[154:155], v[154:155], v[98:99], v[138:139]
	v_cvt_pk_bf16_f32 v172, v140, v141
	v_cvt_pk_bf16_f32 v173, v142, v143
	v_cvt_pk_bf16_f32 v174, v144, v145
	v_cvt_pk_bf16_f32 v175, v146, v147
	v_cvt_pk_bf16_f32 v176, v148, v149
	v_cvt_pk_bf16_f32 v177, v150, v151
	v_cvt_pk_bf16_f32 v178, v152, v153
	v_cvt_pk_bf16_f32 v179, v154, v155
	global_store_dwordx4 v109, v[172:175], s[20:21] sc1
	global_store_dwordx4 v109, v[176:179], s[20:21] offset:1024 sc1
	v_lshlrev_b32_e32 v140, 16, v24
	v_and_b32_e32 v141, 0xffff0000, v24
	v_lshlrev_b32_e32 v142, 16, v25
	v_and_b32_e32 v143, 0xffff0000, v25
	v_lshlrev_b32_e32 v144, 16, v26
	v_and_b32_e32 v145, 0xffff0000, v26
	v_lshlrev_b32_e32 v146, 16, v27
	v_and_b32_e32 v147, 0xffff0000, v27
	v_lshlrev_b32_e32 v148, 16, v28
	v_and_b32_e32 v149, 0xffff0000, v28
	v_lshlrev_b32_e32 v150, 16, v29
	v_and_b32_e32 v151, 0xffff0000, v29
	v_lshlrev_b32_e32 v152, 16, v30
	v_and_b32_e32 v153, 0xffff0000, v30
	v_lshlrev_b32_e32 v154, 16, v31
	v_and_b32_e32 v155, 0xffff0000, v31
	v_pk_mul_f32 v[140:141], v[162:163], v[140:141] op_sel_hi:[0,1]
	v_pk_mul_f32 v[142:143], v[162:163], v[142:143] op_sel_hi:[0,1]
	v_pk_mul_f32 v[144:145], v[162:163], v[144:145] op_sel_hi:[0,1]
	v_pk_mul_f32 v[146:147], v[162:163], v[146:147] op_sel_hi:[0,1]
	v_pk_mul_f32 v[148:149], v[162:163], v[148:149] op_sel_hi:[0,1]
	v_pk_mul_f32 v[150:151], v[162:163], v[150:151] op_sel_hi:[0,1]
	v_pk_mul_f32 v[152:153], v[162:163], v[152:153] op_sel_hi:[0,1]
	v_pk_mul_f32 v[154:155], v[162:163], v[154:155] op_sel_hi:[0,1]
	v_pk_mul_f32 v[140:141], v[140:141], v[32:33]
	v_pk_mul_f32 v[142:143], v[142:143], v[34:35]
	v_pk_mul_f32 v[144:145], v[144:145], v[36:37]
	v_pk_mul_f32 v[146:147], v[146:147], v[38:39]
	v_pk_mul_f32 v[148:149], v[148:149], v[40:41]
	v_pk_mul_f32 v[150:151], v[150:151], v[42:43]
	v_pk_mul_f32 v[152:153], v[152:153], v[44:45]
	v_pk_mul_f32 v[154:155], v[154:155], v[46:47]
	v_pk_fma_f32 v[140:141], v[140:141], v[84:85], v[124:125]
	v_pk_fma_f32 v[142:143], v[142:143], v[86:87], v[126:127]
	v_pk_fma_f32 v[144:145], v[144:145], v[88:89], v[128:129]
	v_pk_fma_f32 v[146:147], v[146:147], v[90:91], v[130:131]
	v_pk_fma_f32 v[148:149], v[148:149], v[92:93], v[132:133]
	v_pk_fma_f32 v[150:151], v[150:151], v[94:95], v[134:135]
	v_pk_fma_f32 v[152:153], v[152:153], v[96:97], v[136:137]
	v_pk_fma_f32 v[154:155], v[154:155], v[98:99], v[138:139]
	v_cvt_pk_bf16_f32 v164, v140, v141
	v_cvt_pk_bf16_f32 v165, v142, v143
	v_cvt_pk_bf16_f32 v166, v144, v145
	v_cvt_pk_bf16_f32 v167, v146, v147
	v_cvt_pk_bf16_f32 v168, v148, v149
	v_cvt_pk_bf16_f32 v169, v150, v151
	v_cvt_pk_bf16_f32 v170, v152, v153
	v_cvt_pk_bf16_f32 v171, v154, v155
	global_store_dwordx4 v109, v[164:167], s[20:21] offset:2048 sc1
	global_store_dwordx4 v109, v[168:171], s[20:21] offset:3072 sc1
	s_add_u32 s20, s20, 0x2000
	s_addc_u32 s21, s21, 0
	s_add_u32 s18, s18, 0x2000
	s_addc_u32 s19, s19, 0
	global_load_dwordx4 v[0:3], v51, s[18:19]
	global_load_dwordx4 v[4:7], v51, s[18:19] offset:1024
	global_load_dwordx4 v[8:11], v51, s[18:19] offset:2048
	global_load_dwordx4 v[12:15], v51, s[18:19] offset:3072
	global_load_dwordx4 v[16:19], v109, s[18:19]
	global_load_dwordx4 v[20:23], v109, s[18:19] offset:1024
	global_load_dwordx4 v[24:27], v109, s[18:19] offset:2048
	global_load_dwordx4 v[28:31], v109, s[18:19] offset:3072
	s_waitcnt vmcnt(16)
	v_lshlrev_b32_e32 v140, 16, v52
	v_and_b32_e32 v141, 0xffff0000, v52
	v_lshlrev_b32_e32 v142, 16, v53
	v_and_b32_e32 v143, 0xffff0000, v53
	v_lshlrev_b32_e32 v144, 16, v54
	v_and_b32_e32 v145, 0xffff0000, v54
	v_lshlrev_b32_e32 v146, 16, v55
	v_and_b32_e32 v147, 0xffff0000, v55
	v_lshlrev_b32_e32 v148, 16, v56
	v_and_b32_e32 v149, 0xffff0000, v56
	v_lshlrev_b32_e32 v150, 16, v57
	v_and_b32_e32 v151, 0xffff0000, v57
	v_lshlrev_b32_e32 v152, 16, v58
	v_and_b32_e32 v153, 0xffff0000, v58
	v_lshlrev_b32_e32 v154, 16, v59
	v_and_b32_e32 v155, 0xffff0000, v59
	v_pk_mul_f32 v[100:101], v[140:141], v[140:141]
	v_pk_fma_f32 v[100:101], v[142:143], v[142:143], v[100:101]
	v_pk_fma_f32 v[100:101], v[144:145], v[144:145], v[100:101]
	v_pk_fma_f32 v[100:101], v[146:147], v[146:147], v[100:101]
	v_pk_fma_f32 v[100:101], v[148:149], v[148:149], v[100:101]
	v_pk_fma_f32 v[100:101], v[150:151], v[150:151], v[100:101]
	v_pk_fma_f32 v[100:101], v[152:153], v[152:153], v[100:101]
	v_pk_fma_f32 v[100:101], v[154:155], v[154:155], v[100:101]
	v_lshlrev_b32_e32 v140, 16, v60
	v_and_b32_e32 v141, 0xffff0000, v60
	v_lshlrev_b32_e32 v142, 16, v61
	v_and_b32_e32 v143, 0xffff0000, v61
	v_lshlrev_b32_e32 v144, 16, v62
	v_and_b32_e32 v145, 0xffff0000, v62
	v_lshlrev_b32_e32 v146, 16, v63
	v_and_b32_e32 v147, 0xffff0000, v63
	v_lshlrev_b32_e32 v148, 16, v64
	v_and_b32_e32 v149, 0xffff0000, v64
	v_lshlrev_b32_e32 v150, 16, v65
	v_and_b32_e32 v151, 0xffff0000, v65
	v_lshlrev_b32_e32 v152, 16, v66
	v_and_b32_e32 v153, 0xffff0000, v66
	v_lshlrev_b32_e32 v154, 16, v67
	v_and_b32_e32 v155, 0xffff0000, v67
	v_pk_mul_f32 v[102:103], v[140:141], v[140:141]
	v_pk_fma_f32 v[102:103], v[142:143], v[142:143], v[102:103]
	v_pk_fma_f32 v[102:103], v[144:145], v[144:145], v[102:103]
	v_pk_fma_f32 v[102:103], v[146:147], v[146:147], v[102:103]
	v_pk_fma_f32 v[102:103], v[148:149], v[148:149], v[102:103]
	v_pk_fma_f32 v[102:103], v[150:151], v[150:151], v[102:103]
	v_pk_fma_f32 v[102:103], v[152:153], v[152:153], v[102:103]
	v_pk_fma_f32 v[102:103], v[154:155], v[154:155], v[102:103]
	v_lshlrev_b32_e32 v140, 16, v68
	v_and_b32_e32 v141, 0xffff0000, v68
	v_lshlrev_b32_e32 v142, 16, v69
	v_and_b32_e32 v143, 0xffff0000, v69
	v_lshlrev_b32_e32 v144, 16, v70
	v_and_b32_e32 v145, 0xffff0000, v70
	v_lshlrev_b32_e32 v146, 16, v71
	v_and_b32_e32 v147, 0xffff0000, v71
	v_lshlrev_b32_e32 v148, 16, v72
	v_and_b32_e32 v149, 0xffff0000, v72
	v_lshlrev_b32_e32 v150, 16, v73
	v_and_b32_e32 v151, 0xffff0000, v73
	v_lshlrev_b32_e32 v152, 16, v74
	v_and_b32_e32 v153, 0xffff0000, v74
	v_lshlrev_b32_e32 v154, 16, v75
	v_and_b32_e32 v155, 0xffff0000, v75
	v_pk_mul_f32 v[104:105], v[140:141], v[140:141]
	v_pk_fma_f32 v[104:105], v[142:143], v[142:143], v[104:105]
	v_pk_fma_f32 v[104:105], v[144:145], v[144:145], v[104:105]
	v_pk_fma_f32 v[104:105], v[146:147], v[146:147], v[104:105]
	v_pk_fma_f32 v[104:105], v[148:149], v[148:149], v[104:105]
	v_pk_fma_f32 v[104:105], v[150:151], v[150:151], v[104:105]
	v_pk_fma_f32 v[104:105], v[152:153], v[152:153], v[104:105]
	v_pk_fma_f32 v[104:105], v[154:155], v[154:155], v[104:105]
	v_lshlrev_b32_e32 v140, 16, v76
	v_and_b32_e32 v141, 0xffff0000, v76
	v_lshlrev_b32_e32 v142, 16, v77
	v_and_b32_e32 v143, 0xffff0000, v77
	v_lshlrev_b32_e32 v144, 16, v78
	v_and_b32_e32 v145, 0xffff0000, v78
	v_lshlrev_b32_e32 v146, 16, v79
	v_and_b32_e32 v147, 0xffff0000, v79
	v_lshlrev_b32_e32 v148, 16, v80
	v_and_b32_e32 v149, 0xffff0000, v80
	v_lshlrev_b32_e32 v150, 16, v81
	v_and_b32_e32 v151, 0xffff0000, v81
	v_lshlrev_b32_e32 v152, 16, v82
	v_and_b32_e32 v153, 0xffff0000, v82
	v_lshlrev_b32_e32 v154, 16, v83
	v_and_b32_e32 v155, 0xffff0000, v83
	v_pk_mul_f32 v[106:107], v[140:141], v[140:141]
	v_pk_fma_f32 v[106:107], v[142:143], v[142:143], v[106:107]
	v_pk_fma_f32 v[106:107], v[144:145], v[144:145], v[106:107]
	v_pk_fma_f32 v[106:107], v[146:147], v[146:147], v[106:107]
	v_pk_fma_f32 v[106:107], v[148:149], v[148:149], v[106:107]
	v_pk_fma_f32 v[106:107], v[150:151], v[150:151], v[106:107]
	v_pk_fma_f32 v[106:107], v[152:153], v[152:153], v[106:107]
	v_pk_fma_f32 v[106:107], v[154:155], v[154:155], v[106:107]
	v_add_f32_e32 v100, v100, v101
	v_add_f32_e32 v102, v102, v103
	v_add_f32_e32 v104, v104, v105
	v_add_f32_e32 v106, v106, v107
	s_nop 1
	v_add_f32_dpp v100, v100, v100 row_shr:1 row_mask:0xf bank_mask:0xf bound_ctrl:1
	v_add_f32_dpp v102, v102, v102 row_shr:1 row_mask:0xf bank_mask:0xf bound_ctrl:1
	v_add_f32_dpp v104, v104, v104 row_shr:1 row_mask:0xf bank_mask:0xf bound_ctrl:1
	v_add_f32_dpp v106, v106, v106 row_shr:1 row_mask:0xf bank_mask:0xf bound_ctrl:1
	v_add_f32_dpp v100, v100, v100 row_shr:2 row_mask:0xf bank_mask:0xf bound_ctrl:1
	v_add_f32_dpp v102, v102, v102 row_shr:2 row_mask:0xf bank_mask:0xf bound_ctrl:1
	v_add_f32_dpp v104, v104, v104 row_shr:2 row_mask:0xf bank_mask:0xf bound_ctrl:1
	v_add_f32_dpp v106, v106, v106 row_shr:2 row_mask:0xf bank_mask:0xf bound_ctrl:1
	v_add_f32_dpp v100, v100, v100 row_shr:4 row_mask:0xf bank_mask:0xf bound_ctrl:1
	v_add_f32_dpp v102, v102, v102 row_shr:4 row_mask:0xf bank_mask:0xf bound_ctrl:1
	v_add_f32_dpp v104, v104, v104 row_shr:4 row_mask:0xf bank_mask:0xf bound_ctrl:1
	v_add_f32_dpp v106, v106, v106 row_shr:4 row_mask:0xf bank_mask:0xf bound_ctrl:1
	v_add_f32_dpp v100, v100, v100 row_shr:8 row_mask:0xf bank_mask:0xf bound_ctrl:1
	v_add_f32_dpp v102, v102, v102 row_shr:8 row_mask:0xf bank_mask:0xf bound_ctrl:1
	v_add_f32_dpp v104, v104, v104 row_shr:8 row_mask:0xf bank_mask:0xf bound_ctrl:1
	v_add_f32_dpp v106, v106, v106 row_shr:8 row_mask:0xf bank_mask:0xf bound_ctrl:1
	v_add_f32_dpp v100, v100, v100 row_bcast:15 row_mask:0xa bank_mask:0xf
	v_add_f32_dpp v102, v102, v102 row_bcast:15 row_mask:0xa bank_mask:0xf
	v_add_f32_dpp v104, v104, v104 row_bcast:15 row_mask:0xa bank_mask:0xf
	v_add_f32_dpp v106, v106, v106 row_bcast:15 row_mask:0xa bank_mask:0xf
	v_add_f32_dpp v100, v100, v100 row_bcast:31 row_mask:0xc bank_mask:0xf
	v_add_f32_dpp v102, v102, v102 row_bcast:31 row_mask:0xc bank_mask:0xf
	v_add_f32_dpp v104, v104, v104 row_bcast:31 row_mask:0xc bank_mask:0xf
	v_add_f32_dpp v106, v106, v106 row_bcast:31 row_mask:0xc bank_mask:0xf
	s_nop 1
	v_readlane_b32 s5, v100, 63
	v_readlane_b32 s32, v102, 63
	v_readlane_b32 s54, v104, 63
	v_readlane_b32 s60, v106, 63
	s_nop 1
	v_mov_b32_e32 v156, s5
	v_mov_b32_e32 v158, s32
	v_mov_b32_e32 v160, s54
	v_mov_b32_e32 v162, s60
	v_fmaak_f32 v156, v156, v50, 0x358637bd
	v_fmaak_f32 v158, v158, v50, 0x358637bd
	v_fmaak_f32 v160, v160, v50, 0x358637bd
	v_fmaak_f32 v162, v162, v50, 0x358637bd
	v_rsq_f32_e32 v156, v156
	v_rsq_f32_e32 v158, v158
	v_rsq_f32_e32 v160, v160
	v_rsq_f32_e32 v162, v162
	s_nop 0
	v_lshlrev_b32_e32 v140, 16, v52
	v_and_b32_e32 v141, 0xffff0000, v52
	v_lshlrev_b32_e32 v142, 16, v53
	v_and_b32_e32 v143, 0xffff0000, v53
	v_lshlrev_b32_e32 v144, 16, v54
	v_and_b32_e32 v145, 0xffff0000, v54
	v_lshlrev_b32_e32 v146, 16, v55
	v_and_b32_e32 v147, 0xffff0000, v55
	v_lshlrev_b32_e32 v148, 16, v56
	v_and_b32_e32 v149, 0xffff0000, v56
	v_lshlrev_b32_e32 v150, 16, v57
	v_and_b32_e32 v151, 0xffff0000, v57
	v_lshlrev_b32_e32 v152, 16, v58
	v_and_b32_e32 v153, 0xffff0000, v58
	v_lshlrev_b32_e32 v154, 16, v59
	v_and_b32_e32 v155, 0xffff0000, v59
	v_pk_mul_f32 v[140:141], v[156:157], v[140:141] op_sel_hi:[0,1]
	v_pk_mul_f32 v[142:143], v[156:157], v[142:143] op_sel_hi:[0,1]
	v_pk_mul_f32 v[144:145], v[156:157], v[144:145] op_sel_hi:[0,1]
	v_pk_mul_f32 v[146:147], v[156:157], v[146:147] op_sel_hi:[0,1]
	v_pk_mul_f32 v[148:149], v[156:157], v[148:149] op_sel_hi:[0,1]
	v_pk_mul_f32 v[150:151], v[156:157], v[150:151] op_sel_hi:[0,1]
	v_pk_mul_f32 v[152:153], v[156:157], v[152:153] op_sel_hi:[0,1]
	v_pk_mul_f32 v[154:155], v[156:157], v[154:155] op_sel_hi:[0,1]
	v_pk_mul_f32 v[140:141], v[140:141], v[32:33]
	v_pk_mul_f32 v[142:143], v[142:143], v[34:35]
	v_pk_mul_f32 v[144:145], v[144:145], v[36:37]
	v_pk_mul_f32 v[146:147], v[146:147], v[38:39]
	v_pk_mul_f32 v[148:149], v[148:149], v[40:41]
	v_pk_mul_f32 v[150:151], v[150:151], v[42:43]
	v_pk_mul_f32 v[152:153], v[152:153], v[44:45]
	v_pk_mul_f32 v[154:155], v[154:155], v[46:47]
	v_pk_fma_f32 v[140:141], v[140:141], v[84:85], v[124:125]
	v_pk_fma_f32 v[142:143], v[142:143], v[86:87], v[126:127]
	v_pk_fma_f32 v[144:145], v[144:145], v[88:89], v[128:129]
	v_pk_fma_f32 v[146:147], v[146:147], v[90:91], v[130:131]
	v_pk_fma_f32 v[148:149], v[148:149], v[92:93], v[132:133]
	v_pk_fma_f32 v[150:151], v[150:151], v[94:95], v[134:135]
	v_pk_fma_f32 v[152:153], v[152:153], v[96:97], v[136:137]
	v_pk_fma_f32 v[154:155], v[154:155], v[98:99], v[138:139]
	v_cvt_pk_bf16_f32 v164, v140, v141
	v_cvt_pk_bf16_f32 v165, v142, v143
	v_cvt_pk_bf16_f32 v166, v144, v145
	v_cvt_pk_bf16_f32 v167, v146, v147
	v_cvt_pk_bf16_f32 v168, v148, v149
	v_cvt_pk_bf16_f32 v169, v150, v151
	v_cvt_pk_bf16_f32 v170, v152, v153
	v_cvt_pk_bf16_f32 v171, v154, v155
	global_store_dwordx4 v51, v[164:167], s[20:21] sc1
	global_store_dwordx4 v51, v[168:171], s[20:21] offset:1024 sc1
	v_lshlrev_b32_e32 v140, 16, v60
	v_and_b32_e32 v141, 0xffff0000, v60
	v_lshlrev_b32_e32 v142, 16, v61
	v_and_b32_e32 v143, 0xffff0000, v61
	v_lshlrev_b32_e32 v144, 16, v62
	v_and_b32_e32 v145, 0xffff0000, v62
	v_lshlrev_b32_e32 v146, 16, v63
	v_and_b32_e32 v147, 0xffff0000, v63
	v_lshlrev_b32_e32 v148, 16, v64
	v_and_b32_e32 v149, 0xffff0000, v64
	v_lshlrev_b32_e32 v150, 16, v65
	v_and_b32_e32 v151, 0xffff0000, v65
	v_lshlrev_b32_e32 v152, 16, v66
	v_and_b32_e32 v153, 0xffff0000, v66
	v_lshlrev_b32_e32 v154, 16, v67
	v_and_b32_e32 v155, 0xffff0000, v67
	v_pk_mul_f32 v[140:141], v[158:159], v[140:141] op_sel_hi:[0,1]
	v_pk_mul_f32 v[142:143], v[158:159], v[142:143] op_sel_hi:[0,1]
	v_pk_mul_f32 v[144:145], v[158:159], v[144:145] op_sel_hi:[0,1]
	v_pk_mul_f32 v[146:147], v[158:159], v[146:147] op_sel_hi:[0,1]
	v_pk_mul_f32 v[148:149], v[158:159], v[148:149] op_sel_hi:[0,1]
	v_pk_mul_f32 v[150:151], v[158:159], v[150:151] op_sel_hi:[0,1]
	v_pk_mul_f32 v[152:153], v[158:159], v[152:153] op_sel_hi:[0,1]
	v_pk_mul_f32 v[154:155], v[158:159], v[154:155] op_sel_hi:[0,1]
	v_pk_mul_f32 v[140:141], v[140:141], v[32:33]
	v_pk_mul_f32 v[142:143], v[142:143], v[34:35]
	v_pk_mul_f32 v[144:145], v[144:145], v[36:37]
	v_pk_mul_f32 v[146:147], v[146:147], v[38:39]
	v_pk_mul_f32 v[148:149], v[148:149], v[40:41]
	v_pk_mul_f32 v[150:151], v[150:151], v[42:43]
	v_pk_mul_f32 v[152:153], v[152:153], v[44:45]
	v_pk_mul_f32 v[154:155], v[154:155], v[46:47]
	v_pk_fma_f32 v[140:141], v[140:141], v[84:85], v[124:125]
	v_pk_fma_f32 v[142:143], v[142:143], v[86:87], v[126:127]
	v_pk_fma_f32 v[144:145], v[144:145], v[88:89], v[128:129]
	v_pk_fma_f32 v[146:147], v[146:147], v[90:91], v[130:131]
	v_pk_fma_f32 v[148:149], v[148:149], v[92:93], v[132:133]
	v_pk_fma_f32 v[150:151], v[150:151], v[94:95], v[134:135]
	v_pk_fma_f32 v[152:153], v[152:153], v[96:97], v[136:137]
	v_pk_fma_f32 v[154:155], v[154:155], v[98:99], v[138:139]
	v_cvt_pk_bf16_f32 v172, v140, v141
	v_cvt_pk_bf16_f32 v173, v142, v143
	v_cvt_pk_bf16_f32 v174, v144, v145
	v_cvt_pk_bf16_f32 v175, v146, v147
	v_cvt_pk_bf16_f32 v176, v148, v149
	v_cvt_pk_bf16_f32 v177, v150, v151
	v_cvt_pk_bf16_f32 v178, v152, v153
	v_cvt_pk_bf16_f32 v179, v154, v155
	global_store_dwordx4 v51, v[172:175], s[20:21] offset:2048 sc1
	global_store_dwordx4 v51, v[176:179], s[20:21] offset:3072 sc1
	v_lshlrev_b32_e32 v140, 16, v68
	v_and_b32_e32 v141, 0xffff0000, v68
	v_lshlrev_b32_e32 v142, 16, v69
	v_and_b32_e32 v143, 0xffff0000, v69
	v_lshlrev_b32_e32 v144, 16, v70
	v_and_b32_e32 v145, 0xffff0000, v70
	v_lshlrev_b32_e32 v146, 16, v71
	v_and_b32_e32 v147, 0xffff0000, v71
	v_lshlrev_b32_e32 v148, 16, v72
	v_and_b32_e32 v149, 0xffff0000, v72
	v_lshlrev_b32_e32 v150, 16, v73
	v_and_b32_e32 v151, 0xffff0000, v73
	v_lshlrev_b32_e32 v152, 16, v74
	v_and_b32_e32 v153, 0xffff0000, v74
	v_lshlrev_b32_e32 v154, 16, v75
	v_and_b32_e32 v155, 0xffff0000, v75
	v_pk_mul_f32 v[140:141], v[160:161], v[140:141] op_sel_hi:[0,1]
	v_pk_mul_f32 v[142:143], v[160:161], v[142:143] op_sel_hi:[0,1]
	v_pk_mul_f32 v[144:145], v[160:161], v[144:145] op_sel_hi:[0,1]
	v_pk_mul_f32 v[146:147], v[160:161], v[146:147] op_sel_hi:[0,1]
	v_pk_mul_f32 v[148:149], v[160:161], v[148:149] op_sel_hi:[0,1]
	v_pk_mul_f32 v[150:151], v[160:161], v[150:151] op_sel_hi:[0,1]
	v_pk_mul_f32 v[152:153], v[160:161], v[152:153] op_sel_hi:[0,1]
	v_pk_mul_f32 v[154:155], v[160:161], v[154:155] op_sel_hi:[0,1]
	v_pk_mul_f32 v[140:141], v[140:141], v[32:33]
	v_pk_mul_f32 v[142:143], v[142:143], v[34:35]
	v_pk_mul_f32 v[144:145], v[144:145], v[36:37]
	v_pk_mul_f32 v[146:147], v[146:147], v[38:39]
	v_pk_mul_f32 v[148:149], v[148:149], v[40:41]
	v_pk_mul_f32 v[150:151], v[150:151], v[42:43]
	v_pk_mul_f32 v[152:153], v[152:153], v[44:45]
	v_pk_mul_f32 v[154:155], v[154:155], v[46:47]
	v_pk_fma_f32 v[140:141], v[140:141], v[84:85], v[124:125]
	v_pk_fma_f32 v[142:143], v[142:143], v[86:87], v[126:127]
	v_pk_fma_f32 v[144:145], v[144:145], v[88:89], v[128:129]
	v_pk_fma_f32 v[146:147], v[146:147], v[90:91], v[130:131]
	v_pk_fma_f32 v[148:149], v[148:149], v[92:93], v[132:133]
	v_pk_fma_f32 v[150:151], v[150:151], v[94:95], v[134:135]
	v_pk_fma_f32 v[152:153], v[152:153], v[96:97], v[136:137]
	v_pk_fma_f32 v[154:155], v[154:155], v[98:99], v[138:139]
	v_cvt_pk_bf16_f32 v164, v140, v141
	v_cvt_pk_bf16_f32 v165, v142, v143
	v_cvt_pk_bf16_f32 v166, v144, v145
	v_cvt_pk_bf16_f32 v167, v146, v147
	v_cvt_pk_bf16_f32 v168, v148, v149
	v_cvt_pk_bf16_f32 v169, v150, v151
	v_cvt_pk_bf16_f32 v170, v152, v153
	v_cvt_pk_bf16_f32 v171, v154, v155
	global_store_dwordx4 v109, v[164:167], s[20:21] sc1
	global_store_dwordx4 v109, v[168:171], s[20:21] offset:1024 sc1
	v_lshlrev_b32_e32 v140, 16, v76
	v_and_b32_e32 v141, 0xffff0000, v76
	v_lshlrev_b32_e32 v142, 16, v77
	v_and_b32_e32 v143, 0xffff0000, v77
	v_lshlrev_b32_e32 v144, 16, v78
	v_and_b32_e32 v145, 0xffff0000, v78
	v_lshlrev_b32_e32 v146, 16, v79
	v_and_b32_e32 v147, 0xffff0000, v79
	v_lshlrev_b32_e32 v148, 16, v80
	v_and_b32_e32 v149, 0xffff0000, v80
	v_lshlrev_b32_e32 v150, 16, v81
	v_and_b32_e32 v151, 0xffff0000, v81
	v_lshlrev_b32_e32 v152, 16, v82
	v_and_b32_e32 v153, 0xffff0000, v82
	v_lshlrev_b32_e32 v154, 16, v83
	v_and_b32_e32 v155, 0xffff0000, v83
	v_pk_mul_f32 v[140:141], v[162:163], v[140:141] op_sel_hi:[0,1]
	v_pk_mul_f32 v[142:143], v[162:163], v[142:143] op_sel_hi:[0,1]
	v_pk_mul_f32 v[144:145], v[162:163], v[144:145] op_sel_hi:[0,1]
	v_pk_mul_f32 v[146:147], v[162:163], v[146:147] op_sel_hi:[0,1]
	v_pk_mul_f32 v[148:149], v[162:163], v[148:149] op_sel_hi:[0,1]
	v_pk_mul_f32 v[150:151], v[162:163], v[150:151] op_sel_hi:[0,1]
	v_pk_mul_f32 v[152:153], v[162:163], v[152:153] op_sel_hi:[0,1]
	v_pk_mul_f32 v[154:155], v[162:163], v[154:155] op_sel_hi:[0,1]
	v_pk_mul_f32 v[140:141], v[140:141], v[32:33]
	v_pk_mul_f32 v[142:143], v[142:143], v[34:35]
	v_pk_mul_f32 v[144:145], v[144:145], v[36:37]
	v_pk_mul_f32 v[146:147], v[146:147], v[38:39]
	v_pk_mul_f32 v[148:149], v[148:149], v[40:41]
	v_pk_mul_f32 v[150:151], v[150:151], v[42:43]
	v_pk_mul_f32 v[152:153], v[152:153], v[44:45]
	v_pk_mul_f32 v[154:155], v[154:155], v[46:47]
	v_pk_fma_f32 v[140:141], v[140:141], v[84:85], v[124:125]
	v_pk_fma_f32 v[142:143], v[142:143], v[86:87], v[126:127]
	v_pk_fma_f32 v[144:145], v[144:145], v[88:89], v[128:129]
	v_pk_fma_f32 v[146:147], v[146:147], v[90:91], v[130:131]
	v_pk_fma_f32 v[148:149], v[148:149], v[92:93], v[132:133]
	v_pk_fma_f32 v[150:151], v[150:151], v[94:95], v[134:135]
	v_pk_fma_f32 v[152:153], v[152:153], v[96:97], v[136:137]
	v_pk_fma_f32 v[154:155], v[154:155], v[98:99], v[138:139]
	v_cvt_pk_bf16_f32 v172, v140, v141
	v_cvt_pk_bf16_f32 v173, v142, v143
	v_cvt_pk_bf16_f32 v174, v144, v145
	v_cvt_pk_bf16_f32 v175, v146, v147
	v_cvt_pk_bf16_f32 v176, v148, v149
	v_cvt_pk_bf16_f32 v177, v150, v151
	v_cvt_pk_bf16_f32 v178, v152, v153
	v_cvt_pk_bf16_f32 v179, v154, v155
	global_store_dwordx4 v109, v[172:175], s[20:21] offset:2048 sc1
	global_store_dwordx4 v109, v[176:179], s[20:21] offset:3072 sc1
	s_add_u32 s20, s20, 0x2000
	s_addc_u32 s21, s21, 0
	s_waitcnt vmcnt(8)
	v_lshlrev_b32_e32 v140, 16, v0
	v_and_b32_e32 v141, 0xffff0000, v0
	v_lshlrev_b32_e32 v142, 16, v1
	v_and_b32_e32 v143, 0xffff0000, v1
	v_lshlrev_b32_e32 v144, 16, v2
	v_and_b32_e32 v145, 0xffff0000, v2
	v_lshlrev_b32_e32 v146, 16, v3
	v_and_b32_e32 v147, 0xffff0000, v3
	v_lshlrev_b32_e32 v148, 16, v4
	v_and_b32_e32 v149, 0xffff0000, v4
	v_lshlrev_b32_e32 v150, 16, v5
	v_and_b32_e32 v151, 0xffff0000, v5
	v_lshlrev_b32_e32 v152, 16, v6
	v_and_b32_e32 v153, 0xffff0000, v6
	v_lshlrev_b32_e32 v154, 16, v7
	v_and_b32_e32 v155, 0xffff0000, v7
	v_pk_mul_f32 v[100:101], v[140:141], v[140:141]
	v_pk_fma_f32 v[100:101], v[142:143], v[142:143], v[100:101]
	v_pk_fma_f32 v[100:101], v[144:145], v[144:145], v[100:101]
	v_pk_fma_f32 v[100:101], v[146:147], v[146:147], v[100:101]
	v_pk_fma_f32 v[100:101], v[148:149], v[148:149], v[100:101]
	v_pk_fma_f32 v[100:101], v[150:151], v[150:151], v[100:101]
	v_pk_fma_f32 v[100:101], v[152:153], v[152:153], v[100:101]
	v_pk_fma_f32 v[100:101], v[154:155], v[154:155], v[100:101]
	v_lshlrev_b32_e32 v140, 16, v8
	v_and_b32_e32 v141, 0xffff0000, v8
	v_lshlrev_b32_e32 v142, 16, v9
	v_and_b32_e32 v143, 0xffff0000, v9
	v_lshlrev_b32_e32 v144, 16, v10
	v_and_b32_e32 v145, 0xffff0000, v10
	v_lshlrev_b32_e32 v146, 16, v11
	v_and_b32_e32 v147, 0xffff0000, v11
	v_lshlrev_b32_e32 v148, 16, v12
	v_and_b32_e32 v149, 0xffff0000, v12
	v_lshlrev_b32_e32 v150, 16, v13
	v_and_b32_e32 v151, 0xffff0000, v13
	v_lshlrev_b32_e32 v152, 16, v14
	v_and_b32_e32 v153, 0xffff0000, v14
	v_lshlrev_b32_e32 v154, 16, v15
	v_and_b32_e32 v155, 0xffff0000, v15
	v_pk_mul_f32 v[102:103], v[140:141], v[140:141]
	v_pk_fma_f32 v[102:103], v[142:143], v[142:143], v[102:103]
	v_pk_fma_f32 v[102:103], v[144:145], v[144:145], v[102:103]
	v_pk_fma_f32 v[102:103], v[146:147], v[146:147], v[102:103]
	v_pk_fma_f32 v[102:103], v[148:149], v[148:149], v[102:103]
	v_pk_fma_f32 v[102:103], v[150:151], v[150:151], v[102:103]
	v_pk_fma_f32 v[102:103], v[152:153], v[152:153], v[102:103]
	v_pk_fma_f32 v[102:103], v[154:155], v[154:155], v[102:103]
	v_lshlrev_b32_e32 v140, 16, v16
	v_and_b32_e32 v141, 0xffff0000, v16
	v_lshlrev_b32_e32 v142, 16, v17
	v_and_b32_e32 v143, 0xffff0000, v17
	v_lshlrev_b32_e32 v144, 16, v18
	v_and_b32_e32 v145, 0xffff0000, v18
	v_lshlrev_b32_e32 v146, 16, v19
	v_and_b32_e32 v147, 0xffff0000, v19
	v_lshlrev_b32_e32 v148, 16, v20
	v_and_b32_e32 v149, 0xffff0000, v20
	v_lshlrev_b32_e32 v150, 16, v21
	v_and_b32_e32 v151, 0xffff0000, v21
	v_lshlrev_b32_e32 v152, 16, v22
	v_and_b32_e32 v153, 0xffff0000, v22
	v_lshlrev_b32_e32 v154, 16, v23
	v_and_b32_e32 v155, 0xffff0000, v23
	v_pk_mul_f32 v[104:105], v[140:141], v[140:141]
	v_pk_fma_f32 v[104:105], v[142:143], v[142:143], v[104:105]
	v_pk_fma_f32 v[104:105], v[144:145], v[144:145], v[104:105]
	v_pk_fma_f32 v[104:105], v[146:147], v[146:147], v[104:105]
	v_pk_fma_f32 v[104:105], v[148:149], v[148:149], v[104:105]
	v_pk_fma_f32 v[104:105], v[150:151], v[150:151], v[104:105]
	v_pk_fma_f32 v[104:105], v[152:153], v[152:153], v[104:105]
	v_pk_fma_f32 v[104:105], v[154:155], v[154:155], v[104:105]
	v_lshlrev_b32_e32 v140, 16, v24
	v_and_b32_e32 v141, 0xffff0000, v24
	v_lshlrev_b32_e32 v142, 16, v25
	v_and_b32_e32 v143, 0xffff0000, v25
	v_lshlrev_b32_e32 v144, 16, v26
	v_and_b32_e32 v145, 0xffff0000, v26
	v_lshlrev_b32_e32 v146, 16, v27
	v_and_b32_e32 v147, 0xffff0000, v27
	v_lshlrev_b32_e32 v148, 16, v28
	v_and_b32_e32 v149, 0xffff0000, v28
	v_lshlrev_b32_e32 v150, 16, v29
	v_and_b32_e32 v151, 0xffff0000, v29
	v_lshlrev_b32_e32 v152, 16, v30
	v_and_b32_e32 v153, 0xffff0000, v30
	v_lshlrev_b32_e32 v154, 16, v31
	v_and_b32_e32 v155, 0xffff0000, v31
	v_pk_mul_f32 v[106:107], v[140:141], v[140:141]
	v_pk_fma_f32 v[106:107], v[142:143], v[142:143], v[106:107]
	v_pk_fma_f32 v[106:107], v[144:145], v[144:145], v[106:107]
	v_pk_fma_f32 v[106:107], v[146:147], v[146:147], v[106:107]
	v_pk_fma_f32 v[106:107], v[148:149], v[148:149], v[106:107]
	v_pk_fma_f32 v[106:107], v[150:151], v[150:151], v[106:107]
	v_pk_fma_f32 v[106:107], v[152:153], v[152:153], v[106:107]
	v_pk_fma_f32 v[106:107], v[154:155], v[154:155], v[106:107]
	v_add_f32_e32 v100, v100, v101
	v_add_f32_e32 v102, v102, v103
	v_add_f32_e32 v104, v104, v105
	v_add_f32_e32 v106, v106, v107
	s_nop 1
	v_add_f32_dpp v100, v100, v100 row_shr:1 row_mask:0xf bank_mask:0xf bound_ctrl:1
	v_add_f32_dpp v102, v102, v102 row_shr:1 row_mask:0xf bank_mask:0xf bound_ctrl:1
	v_add_f32_dpp v104, v104, v104 row_shr:1 row_mask:0xf bank_mask:0xf bound_ctrl:1
	v_add_f32_dpp v106, v106, v106 row_shr:1 row_mask:0xf bank_mask:0xf bound_ctrl:1
	v_add_f32_dpp v100, v100, v100 row_shr:2 row_mask:0xf bank_mask:0xf bound_ctrl:1
	v_add_f32_dpp v102, v102, v102 row_shr:2 row_mask:0xf bank_mask:0xf bound_ctrl:1
	v_add_f32_dpp v104, v104, v104 row_shr:2 row_mask:0xf bank_mask:0xf bound_ctrl:1
	v_add_f32_dpp v106, v106, v106 row_shr:2 row_mask:0xf bank_mask:0xf bound_ctrl:1
	v_add_f32_dpp v100, v100, v100 row_shr:4 row_mask:0xf bank_mask:0xf bound_ctrl:1
	v_add_f32_dpp v102, v102, v102 row_shr:4 row_mask:0xf bank_mask:0xf bound_ctrl:1
	v_add_f32_dpp v104, v104, v104 row_shr:4 row_mask:0xf bank_mask:0xf bound_ctrl:1
	v_add_f32_dpp v106, v106, v106 row_shr:4 row_mask:0xf bank_mask:0xf bound_ctrl:1
	v_add_f32_dpp v100, v100, v100 row_shr:8 row_mask:0xf bank_mask:0xf bound_ctrl:1
	v_add_f32_dpp v102, v102, v102 row_shr:8 row_mask:0xf bank_mask:0xf bound_ctrl:1
	v_add_f32_dpp v104, v104, v104 row_shr:8 row_mask:0xf bank_mask:0xf bound_ctrl:1
	v_add_f32_dpp v106, v106, v106 row_shr:8 row_mask:0xf bank_mask:0xf bound_ctrl:1
	v_add_f32_dpp v100, v100, v100 row_bcast:15 row_mask:0xa bank_mask:0xf
	v_add_f32_dpp v102, v102, v102 row_bcast:15 row_mask:0xa bank_mask:0xf
	v_add_f32_dpp v104, v104, v104 row_bcast:15 row_mask:0xa bank_mask:0xf
	v_add_f32_dpp v106, v106, v106 row_bcast:15 row_mask:0xa bank_mask:0xf
	v_add_f32_dpp v100, v100, v100 row_bcast:31 row_mask:0xc bank_mask:0xf
	v_add_f32_dpp v102, v102, v102 row_bcast:31 row_mask:0xc bank_mask:0xf
	v_add_f32_dpp v104, v104, v104 row_bcast:31 row_mask:0xc bank_mask:0xf
	v_add_f32_dpp v106, v106, v106 row_bcast:31 row_mask:0xc bank_mask:0xf
	s_nop 1
	v_readlane_b32 s5, v100, 63
	v_readlane_b32 s32, v102, 63
	v_readlane_b32 s54, v104, 63
	v_readlane_b32 s60, v106, 63
	s_nop 1
	v_mov_b32_e32 v156, s5
	v_mov_b32_e32 v158, s32
	v_mov_b32_e32 v160, s54
	v_mov_b32_e32 v162, s60
	v_fmaak_f32 v156, v156, v50, 0x358637bd
	v_fmaak_f32 v158, v158, v50, 0x358637bd
	v_fmaak_f32 v160, v160, v50, 0x358637bd
	v_fmaak_f32 v162, v162, v50, 0x358637bd
	v_rsq_f32_e32 v156, v156
	v_rsq_f32_e32 v158, v158
	v_rsq_f32_e32 v160, v160
	v_rsq_f32_e32 v162, v162
	s_nop 0
	v_lshlrev_b32_e32 v140, 16, v0
	v_and_b32_e32 v141, 0xffff0000, v0
	v_lshlrev_b32_e32 v142, 16, v1
	v_and_b32_e32 v143, 0xffff0000, v1
	v_lshlrev_b32_e32 v144, 16, v2
	v_and_b32_e32 v145, 0xffff0000, v2
	v_lshlrev_b32_e32 v146, 16, v3
	v_and_b32_e32 v147, 0xffff0000, v3
	v_lshlrev_b32_e32 v148, 16, v4
	v_and_b32_e32 v149, 0xffff0000, v4
	v_lshlrev_b32_e32 v150, 16, v5
	v_and_b32_e32 v151, 0xffff0000, v5
	v_lshlrev_b32_e32 v152, 16, v6
	v_and_b32_e32 v153, 0xffff0000, v6
	v_lshlrev_b32_e32 v154, 16, v7
	v_and_b32_e32 v155, 0xffff0000, v7
	v_pk_mul_f32 v[140:141], v[156:157], v[140:141] op_sel_hi:[0,1]
	v_pk_mul_f32 v[142:143], v[156:157], v[142:143] op_sel_hi:[0,1]
	v_pk_mul_f32 v[144:145], v[156:157], v[144:145] op_sel_hi:[0,1]
	v_pk_mul_f32 v[146:147], v[156:157], v[146:147] op_sel_hi:[0,1]
	v_pk_mul_f32 v[148:149], v[156:157], v[148:149] op_sel_hi:[0,1]
	v_pk_mul_f32 v[150:151], v[156:157], v[150:151] op_sel_hi:[0,1]
	v_pk_mul_f32 v[152:153], v[156:157], v[152:153] op_sel_hi:[0,1]
	v_pk_mul_f32 v[154:155], v[156:157], v[154:155] op_sel_hi:[0,1]
	v_pk_mul_f32 v[140:141], v[140:141], v[32:33]
	v_pk_mul_f32 v[142:143], v[142:143], v[34:35]
	v_pk_mul_f32 v[144:145], v[144:145], v[36:37]
	v_pk_mul_f32 v[146:147], v[146:147], v[38:39]
	v_pk_mul_f32 v[148:149], v[148:149], v[40:41]
	v_pk_mul_f32 v[150:151], v[150:151], v[42:43]
	v_pk_mul_f32 v[152:153], v[152:153], v[44:45]
	v_pk_mul_f32 v[154:155], v[154:155], v[46:47]
	v_pk_fma_f32 v[140:141], v[140:141], v[84:85], v[124:125]
	v_pk_fma_f32 v[142:143], v[142:143], v[86:87], v[126:127]
	v_pk_fma_f32 v[144:145], v[144:145], v[88:89], v[128:129]
	v_pk_fma_f32 v[146:147], v[146:147], v[90:91], v[130:131]
	v_pk_fma_f32 v[148:149], v[148:149], v[92:93], v[132:133]
	v_pk_fma_f32 v[150:151], v[150:151], v[94:95], v[134:135]
	v_pk_fma_f32 v[152:153], v[152:153], v[96:97], v[136:137]
	v_pk_fma_f32 v[154:155], v[154:155], v[98:99], v[138:139]
	v_cvt_pk_bf16_f32 v172, v140, v141
	v_cvt_pk_bf16_f32 v173, v142, v143
	v_cvt_pk_bf16_f32 v174, v144, v145
	v_cvt_pk_bf16_f32 v175, v146, v147
	v_cvt_pk_bf16_f32 v176, v148, v149
	v_cvt_pk_bf16_f32 v177, v150, v151
	v_cvt_pk_bf16_f32 v178, v152, v153
	v_cvt_pk_bf16_f32 v179, v154, v155
	global_store_dwordx4 v51, v[172:175], s[20:21] sc1
	global_store_dwordx4 v51, v[176:179], s[20:21] offset:1024 sc1
	v_lshlrev_b32_e32 v140, 16, v8
	v_and_b32_e32 v141, 0xffff0000, v8
	v_lshlrev_b32_e32 v142, 16, v9
	v_and_b32_e32 v143, 0xffff0000, v9
	v_lshlrev_b32_e32 v144, 16, v10
	v_and_b32_e32 v145, 0xffff0000, v10
	v_lshlrev_b32_e32 v146, 16, v11
	v_and_b32_e32 v147, 0xffff0000, v11
	v_lshlrev_b32_e32 v148, 16, v12
	v_and_b32_e32 v149, 0xffff0000, v12
	v_lshlrev_b32_e32 v150, 16, v13
	v_and_b32_e32 v151, 0xffff0000, v13
	v_lshlrev_b32_e32 v152, 16, v14
	v_and_b32_e32 v153, 0xffff0000, v14
	v_lshlrev_b32_e32 v154, 16, v15
	v_and_b32_e32 v155, 0xffff0000, v15
	v_pk_mul_f32 v[140:141], v[158:159], v[140:141] op_sel_hi:[0,1]
	v_pk_mul_f32 v[142:143], v[158:159], v[142:143] op_sel_hi:[0,1]
	v_pk_mul_f32 v[144:145], v[158:159], v[144:145] op_sel_hi:[0,1]
	v_pk_mul_f32 v[146:147], v[158:159], v[146:147] op_sel_hi:[0,1]
	v_pk_mul_f32 v[148:149], v[158:159], v[148:149] op_sel_hi:[0,1]
	v_pk_mul_f32 v[150:151], v[158:159], v[150:151] op_sel_hi:[0,1]
	v_pk_mul_f32 v[152:153], v[158:159], v[152:153] op_sel_hi:[0,1]
	v_pk_mul_f32 v[154:155], v[158:159], v[154:155] op_sel_hi:[0,1]
	v_pk_mul_f32 v[140:141], v[140:141], v[32:33]
	v_pk_mul_f32 v[142:143], v[142:143], v[34:35]
	v_pk_mul_f32 v[144:145], v[144:145], v[36:37]
	v_pk_mul_f32 v[146:147], v[146:147], v[38:39]
	v_pk_mul_f32 v[148:149], v[148:149], v[40:41]
	v_pk_mul_f32 v[150:151], v[150:151], v[42:43]
	v_pk_mul_f32 v[152:153], v[152:153], v[44:45]
	v_pk_mul_f32 v[154:155], v[154:155], v[46:47]
	v_pk_fma_f32 v[140:141], v[140:141], v[84:85], v[124:125]
	v_pk_fma_f32 v[142:143], v[142:143], v[86:87], v[126:127]
	v_pk_fma_f32 v[144:145], v[144:145], v[88:89], v[128:129]
	v_pk_fma_f32 v[146:147], v[146:147], v[90:91], v[130:131]
	v_pk_fma_f32 v[148:149], v[148:149], v[92:93], v[132:133]
	v_pk_fma_f32 v[150:151], v[150:151], v[94:95], v[134:135]
	v_pk_fma_f32 v[152:153], v[152:153], v[96:97], v[136:137]
	v_pk_fma_f32 v[154:155], v[154:155], v[98:99], v[138:139]
	v_cvt_pk_bf16_f32 v164, v140, v141
	v_cvt_pk_bf16_f32 v165, v142, v143
	v_cvt_pk_bf16_f32 v166, v144, v145
	v_cvt_pk_bf16_f32 v167, v146, v147
	v_cvt_pk_bf16_f32 v168, v148, v149
	v_cvt_pk_bf16_f32 v169, v150, v151
	v_cvt_pk_bf16_f32 v170, v152, v153
	v_cvt_pk_bf16_f32 v171, v154, v155
	global_store_dwordx4 v51, v[164:167], s[20:21] offset:2048 sc1
	global_store_dwordx4 v51, v[168:171], s[20:21] offset:3072 sc1
	v_lshlrev_b32_e32 v140, 16, v16
	v_and_b32_e32 v141, 0xffff0000, v16
	v_lshlrev_b32_e32 v142, 16, v17
	v_and_b32_e32 v143, 0xffff0000, v17
	v_lshlrev_b32_e32 v144, 16, v18
	v_and_b32_e32 v145, 0xffff0000, v18
	v_lshlrev_b32_e32 v146, 16, v19
	v_and_b32_e32 v147, 0xffff0000, v19
	v_lshlrev_b32_e32 v148, 16, v20
	v_and_b32_e32 v149, 0xffff0000, v20
	v_lshlrev_b32_e32 v150, 16, v21
	v_and_b32_e32 v151, 0xffff0000, v21
	v_lshlrev_b32_e32 v152, 16, v22
	v_and_b32_e32 v153, 0xffff0000, v22
	v_lshlrev_b32_e32 v154, 16, v23
	v_and_b32_e32 v155, 0xffff0000, v23
	v_pk_mul_f32 v[140:141], v[160:161], v[140:141] op_sel_hi:[0,1]
	v_pk_mul_f32 v[142:143], v[160:161], v[142:143] op_sel_hi:[0,1]
	v_pk_mul_f32 v[144:145], v[160:161], v[144:145] op_sel_hi:[0,1]
	v_pk_mul_f32 v[146:147], v[160:161], v[146:147] op_sel_hi:[0,1]
	v_pk_mul_f32 v[148:149], v[160:161], v[148:149] op_sel_hi:[0,1]
	v_pk_mul_f32 v[150:151], v[160:161], v[150:151] op_sel_hi:[0,1]
	v_pk_mul_f32 v[152:153], v[160:161], v[152:153] op_sel_hi:[0,1]
	v_pk_mul_f32 v[154:155], v[160:161], v[154:155] op_sel_hi:[0,1]
	v_pk_mul_f32 v[140:141], v[140:141], v[32:33]
	v_pk_mul_f32 v[142:143], v[142:143], v[34:35]
	v_pk_mul_f32 v[144:145], v[144:145], v[36:37]
	v_pk_mul_f32 v[146:147], v[146:147], v[38:39]
	v_pk_mul_f32 v[148:149], v[148:149], v[40:41]
	v_pk_mul_f32 v[150:151], v[150:151], v[42:43]
	v_pk_mul_f32 v[152:153], v[152:153], v[44:45]
	v_pk_mul_f32 v[154:155], v[154:155], v[46:47]
	v_pk_fma_f32 v[140:141], v[140:141], v[84:85], v[124:125]
	v_pk_fma_f32 v[142:143], v[142:143], v[86:87], v[126:127]
	v_pk_fma_f32 v[144:145], v[144:145], v[88:89], v[128:129]
	v_pk_fma_f32 v[146:147], v[146:147], v[90:91], v[130:131]
	v_pk_fma_f32 v[148:149], v[148:149], v[92:93], v[132:133]
	v_pk_fma_f32 v[150:151], v[150:151], v[94:95], v[134:135]
	v_pk_fma_f32 v[152:153], v[152:153], v[96:97], v[136:137]
	v_pk_fma_f32 v[154:155], v[154:155], v[98:99], v[138:139]
	v_cvt_pk_bf16_f32 v172, v140, v141
	v_cvt_pk_bf16_f32 v173, v142, v143
	v_cvt_pk_bf16_f32 v174, v144, v145
	v_cvt_pk_bf16_f32 v175, v146, v147
	v_cvt_pk_bf16_f32 v176, v148, v149
	v_cvt_pk_bf16_f32 v177, v150, v151
	v_cvt_pk_bf16_f32 v178, v152, v153
	v_cvt_pk_bf16_f32 v179, v154, v155
	global_store_dwordx4 v109, v[172:175], s[20:21] sc1
	global_store_dwordx4 v109, v[176:179], s[20:21] offset:1024 sc1
	v_lshlrev_b32_e32 v140, 16, v24
	v_and_b32_e32 v141, 0xffff0000, v24
	v_lshlrev_b32_e32 v142, 16, v25
	v_and_b32_e32 v143, 0xffff0000, v25
	v_lshlrev_b32_e32 v144, 16, v26
	v_and_b32_e32 v145, 0xffff0000, v26
	v_lshlrev_b32_e32 v146, 16, v27
	v_and_b32_e32 v147, 0xffff0000, v27
	v_lshlrev_b32_e32 v148, 16, v28
	v_and_b32_e32 v149, 0xffff0000, v28
	v_lshlrev_b32_e32 v150, 16, v29
	v_and_b32_e32 v151, 0xffff0000, v29
	v_lshlrev_b32_e32 v152, 16, v30
	v_and_b32_e32 v153, 0xffff0000, v30
	v_lshlrev_b32_e32 v154, 16, v31
	v_and_b32_e32 v155, 0xffff0000, v31
	v_pk_mul_f32 v[140:141], v[162:163], v[140:141] op_sel_hi:[0,1]
	v_pk_mul_f32 v[142:143], v[162:163], v[142:143] op_sel_hi:[0,1]
	v_pk_mul_f32 v[144:145], v[162:163], v[144:145] op_sel_hi:[0,1]
	v_pk_mul_f32 v[146:147], v[162:163], v[146:147] op_sel_hi:[0,1]
	v_pk_mul_f32 v[148:149], v[162:163], v[148:149] op_sel_hi:[0,1]
	v_pk_mul_f32 v[150:151], v[162:163], v[150:151] op_sel_hi:[0,1]
	v_pk_mul_f32 v[152:153], v[162:163], v[152:153] op_sel_hi:[0,1]
	v_pk_mul_f32 v[154:155], v[162:163], v[154:155] op_sel_hi:[0,1]
	v_pk_mul_f32 v[140:141], v[140:141], v[32:33]
	v_pk_mul_f32 v[142:143], v[142:143], v[34:35]
	v_pk_mul_f32 v[144:145], v[144:145], v[36:37]
	v_pk_mul_f32 v[146:147], v[146:147], v[38:39]
	v_pk_mul_f32 v[148:149], v[148:149], v[40:41]
	v_pk_mul_f32 v[150:151], v[150:151], v[42:43]
	v_pk_mul_f32 v[152:153], v[152:153], v[44:45]
	v_pk_mul_f32 v[154:155], v[154:155], v[46:47]
	v_pk_fma_f32 v[140:141], v[140:141], v[84:85], v[124:125]
	v_pk_fma_f32 v[142:143], v[142:143], v[86:87], v[126:127]
	v_pk_fma_f32 v[144:145], v[144:145], v[88:89], v[128:129]
	v_pk_fma_f32 v[146:147], v[146:147], v[90:91], v[130:131]
	v_pk_fma_f32 v[148:149], v[148:149], v[92:93], v[132:133]
	v_pk_fma_f32 v[150:151], v[150:151], v[94:95], v[134:135]
	v_pk_fma_f32 v[152:153], v[152:153], v[96:97], v[136:137]
	v_pk_fma_f32 v[154:155], v[154:155], v[98:99], v[138:139]
	v_cvt_pk_bf16_f32 v164, v140, v141
	v_cvt_pk_bf16_f32 v165, v142, v143
	v_cvt_pk_bf16_f32 v166, v144, v145
	v_cvt_pk_bf16_f32 v167, v146, v147
	v_cvt_pk_bf16_f32 v168, v148, v149
	v_cvt_pk_bf16_f32 v169, v150, v151
	v_cvt_pk_bf16_f32 v170, v152, v153
	v_cvt_pk_bf16_f32 v171, v154, v155
	global_store_dwordx4 v109, v[164:167], s[20:21] offset:2048 sc1
	global_store_dwordx4 v109, v[168:171], s[20:21] offset:3072 sc1
	s_add_u32 s20, s20, 0x2000
	s_addc_u32 s21, s21, 0
	s_branch .LBB0_1297
